# P4 patch + P3 stream regenerated with an 8-quad ring: exactly 64 row-group loads per item (hipcc's loop re-reads 8 of them on the last trip)
# speedup vs baseline: 1.0051x; 1.0020x over previous
; #define LAS __attribute__((address_space(3)))
; #define RS_LOAD(dst, it0) do { _Pragma("unroll") for (int u = 0; u < 8; ++u) dst[u] = __builtin_nontemporal_load((const f32x4*)(S0 + (size_t)(4 * ((it0) + u)) * DV)); } while (0)
; __device__ __forceinline__ void ret_sample_item(Frame& F, int item) {
;     ...
;     const float gam = 1.0f - exp2f(-5.0f - (float)h);
;     const float g7 = exp2f(7.0f * log2f(gam)), g8 = g7 * gam;
;     ...
;     f32x4 v4[8];
; #pragma unroll
;     for (int m = 0; m < 8; ++m) v4[m] = *(const LAS f32x4*)(vs + m * 512 + e4);
;     f32x4 oacc[4];
; #pragma unroll
;     for (int i = 0; i < 4; ++i) oacc[i] = (f32x4){0.f, 0.f, 0.f, 0.f};
;     ...
;     for (int it0 = 0; it0 < 64; it0 += 16) {
;         RS_LOAD(sb, it0 + 8);
;         RS_PROC(sa, it0);
;         { const int itn = it0 + 16 < 64 ? it0 + 16 : it0; RS_LOAD(sa, itn); }
;         RS_PROC(sb, it0 + 8);
;     }
.LBB0_584:
	s_or_b64 exec, exec, s[78:79]
	v_cvt_f32_ubyte0_e32 v2, s10
	v_sub_f32_e32 v2, 0xc0a00000, v2
	v_cmp_gt_f32_e32 vcc, s82, v2
	s_and_b64 s[68:69], vcc, exec
	s_cselect_b32 s10, 0xffffffc0, 0
	v_cndmask_b32_e32 v3, 0, v169, vcc
	v_add_f32_e32 v2, v2, v3
	v_exp_f32_e32 v2, v2
	s_waitcnt lgkmcnt(0)
	s_barrier
	v_ldexp_f32 v2, v2, s10
	v_sub_f32_e32 v138, 1.0, v2
	v_cmp_gt_f32_e32 vcc, s83, v138
	s_and_b64 s[68:69], vcc, exec
	s_cselect_b32 s10, 32, 0
	v_ldexp_f32 v3, v138, s10
	v_log_f32_e32 v3, v3
	v_cndmask_b32_e32 v2, 0, v170, vcc
	v_mov_b32_e32 v98, 0
	s_mov_b32 s10, 0
	v_sub_f32_e32 v2, v3, v2
	v_mul_f32_e32 v3, 0x40e00000, v2
	v_cmp_gt_f32_e32 vcc, s82, v3
	s_and_b64 s[68:69], vcc, exec
	s_cselect_b32 s22, 0xffffffc0, 0
	v_cndmask_b32_e32 v3, 0, v169, vcc
	v_fmac_f32_e32 v3, 0x40e00000, v2
	v_exp_f32_e32 v2, v3
	v_mov_b64_e32 v[148:149], v[130:131]
	v_mov_b64_e32 v[150:151], v[128:129]
	v_mov_b32_e32 v171, v161
	v_ldexp_f32 v140, v2, s22
	ds_read_b128 v[30:33], v139 offset:16512
	ds_read_b128 v[26:29], v139 offset:18560
	ds_read_b128 v[22:25], v139 offset:20608
	ds_read_b128 v[18:21], v139 offset:22656
	ds_read_b128 v[14:17], v139 offset:24704
	ds_read_b128 v[10:13], v139 offset:26752
	ds_read_b128 v[6:9], v139 offset:28800
	ds_read_b128 v[2:5], v139 offset:30848
	v_mul_f32_e32 v142, v138, v140
	v_mov_b32_e32 v144, v142
	v_mov_b32_e32 v145, v142
	v_mov_b32_e32 v146, v140
	v_mov_b32_e32 v147, v140
	v_mov_b32_e32 v172, v160
	v_mov_b32_e32 v99, v98
	v_mov_b32_e32 v100, v98
	v_mov_b32_e32 v101, v98
	v_mov_b32_e32 v102, v98
	v_mov_b32_e32 v103, v98
	v_mov_b32_e32 v104, v98
	v_mov_b32_e32 v105, v98
	v_mov_b32_e32 v106, v98
	v_mov_b32_e32 v107, v98
	v_mov_b32_e32 v108, v98
	v_mov_b32_e32 v109, v98
	v_mov_b32_e32 v110, v98
	v_mov_b32_e32 v111, v98
	v_mov_b32_e32 v112, v98
	v_mov_b32_e32 v113, v98
	v_lshl_add_u64 v[148:149], v[130:131], 0, v[122:123]
	v_lshl_add_u64 v[150:151], v[128:129], 0, v[122:123]
	s_mov_b32 s74, 0x10000
	s_mov_b32 s75, 0
	v_add_co_u32_e32 v150, vcc, 0x5878000, v150
	v_lshl_add_u64 v[148:149], v[148:149], 0, s[74:75]
	s_mov_b32 s74, 0x2000
	v_addc_co_u32_e32 v151, vcc, 0, v151, vcc
	ds_read_b32 v141, v160
	ds_read_b128 v[114:117], v161
	ds_read_b128 v[176:179], v161 offset:16
	ds_read_b32 v143, v160 offset:16
	ds_read_b128 v[172:175], v161 offset:128
	ds_read_b128 v[232:235], v161 offset:144
	s_waitcnt lgkmcnt(3)
	v_cndmask_b32_e64 v141, 0, v141, s[8:9]
	v_pk_mul_f32 v[180:181], v[26:27], v[114:115] op_sel:[0,1]
	v_pk_mul_f32 v[192:193], v[28:29], v[114:115] op_sel:[0,1]
	v_mfma_f32_16x16x4_f32 v[110:113], v141, v70, v[110:113]
	v_pk_fma_f32 v[180:181], v[30:31], v[114:115], v[180:181] op_sel_hi:[1,0,1]
	v_pk_fma_f32 v[192:193], v[32:33], v[114:115], v[192:193] op_sel_hi:[1,0,1]
	v_pk_fma_f32 v[180:181], v[22:23], v[116:117], v[180:181] op_sel_hi:[1,0,1]
	v_pk_fma_f32 v[192:193], v[24:25], v[116:117], v[192:193] op_sel_hi:[1,0,1]
	v_mfma_f32_16x16x4_f32 v[106:109], v141, v71, v[106:109]
	v_pk_fma_f32 v[180:181], v[18:19], v[116:117], v[180:181] op_sel:[0,1,0]
	v_pk_fma_f32 v[192:193], v[20:21], v[116:117], v[192:193] op_sel:[0,1,0]
	v_pk_fma_f32 v[180:181], v[14:15], v[176:177], v[180:181] op_sel_hi:[1,0,1]
	v_pk_fma_f32 v[192:193], v[16:17], v[176:177], v[192:193] op_sel_hi:[1,0,1]
	v_mfma_f32_16x16x4_f32 v[102:105], v141, v72, v[102:105]
	v_pk_fma_f32 v[180:181], v[10:11], v[176:177], v[180:181] op_sel:[0,1,0]
	v_pk_fma_f32 v[192:193], v[12:13], v[176:177], v[192:193] op_sel:[0,1,0]
	v_pk_fma_f32 v[180:181], v[6:7], v[178:179], v[180:181] op_sel_hi:[1,0,1]
	v_pk_fma_f32 v[192:193], v[8:9], v[178:179], v[192:193] op_sel_hi:[1,0,1]
	v_mfma_f32_16x16x4_f32 v[98:101], v141, v73, v[98:101]
	v_pk_fma_f32 v[180:181], v[2:3], v[178:179], v[180:181] op_sel:[0,1,0]
	v_pk_fma_f32 v[192:193], v[4:5], v[178:179], v[192:193] op_sel:[0,1,0]
	v_pk_mul_f32 v[180:181], v[146:147], v[180:181]
	v_pk_mul_f32 v[192:193], v[146:147], v[192:193]
	v_pk_fma_f32 v[236:237], v[144:145], v[70:71], v[180:181]
	v_pk_fma_f32 v[238:239], v[144:145], v[72:73], v[192:193]
	global_store_dwordx4 v[150:151], v[236:239], off nt
	v_lshl_add_u64 v[150:151], v[150:151], 0, s[74:75]
	global_load_dwordx4 v[70:73], v[148:149], off nt
	v_lshl_add_u64 v[148:149], v[148:149], 0, s[74:75]
	ds_read_b32 v141, v160 offset:32
	ds_read_b128 v[114:117], v161 offset:256
	ds_read_b128 v[176:179], v161 offset:272
	s_waitcnt lgkmcnt(3)
	v_cndmask_b32_e64 v143, 0, v143, s[8:9]
	v_pk_mul_f32 v[180:181], v[26:27], v[172:173] op_sel:[0,1]
	v_pk_mul_f32 v[192:193], v[28:29], v[172:173] op_sel:[0,1]
	v_mfma_f32_16x16x4_f32 v[110:113], v143, v62, v[110:113]
	v_pk_fma_f32 v[180:181], v[30:31], v[172:173], v[180:181] op_sel_hi:[1,0,1]
	v_pk_fma_f32 v[192:193], v[32:33], v[172:173], v[192:193] op_sel_hi:[1,0,1]
	v_pk_fma_f32 v[180:181], v[22:23], v[174:175], v[180:181] op_sel_hi:[1,0,1]
	v_pk_fma_f32 v[192:193], v[24:25], v[174:175], v[192:193] op_sel_hi:[1,0,1]
	v_mfma_f32_16x16x4_f32 v[106:109], v143, v63, v[106:109]
	v_pk_fma_f32 v[180:181], v[18:19], v[174:175], v[180:181] op_sel:[0,1,0]
	v_pk_fma_f32 v[192:193], v[20:21], v[174:175], v[192:193] op_sel:[0,1,0]
	v_pk_fma_f32 v[180:181], v[14:15], v[232:233], v[180:181] op_sel_hi:[1,0,1]
	v_pk_fma_f32 v[192:193], v[16:17], v[232:233], v[192:193] op_sel_hi:[1,0,1]
	v_mfma_f32_16x16x4_f32 v[102:105], v143, v64, v[102:105]
	v_pk_fma_f32 v[180:181], v[10:11], v[232:233], v[180:181] op_sel:[0,1,0]
	v_pk_fma_f32 v[192:193], v[12:13], v[232:233], v[192:193] op_sel:[0,1,0]
	v_pk_fma_f32 v[180:181], v[6:7], v[234:235], v[180:181] op_sel_hi:[1,0,1]
	v_pk_fma_f32 v[192:193], v[8:9], v[234:235], v[192:193] op_sel_hi:[1,0,1]
	v_mfma_f32_16x16x4_f32 v[98:101], v143, v65, v[98:101]
	v_pk_fma_f32 v[180:181], v[2:3], v[234:235], v[180:181] op_sel:[0,1,0]
	v_pk_fma_f32 v[192:193], v[4:5], v[234:235], v[192:193] op_sel:[0,1,0]
	v_pk_mul_f32 v[180:181], v[146:147], v[180:181]
	v_pk_mul_f32 v[192:193], v[146:147], v[192:193]
	v_pk_fma_f32 v[236:237], v[144:145], v[62:63], v[180:181]
	v_pk_fma_f32 v[238:239], v[144:145], v[64:65], v[192:193]
	global_store_dwordx4 v[150:151], v[236:239], off nt
	v_lshl_add_u64 v[150:151], v[150:151], 0, s[74:75]
	global_load_dwordx4 v[62:65], v[148:149], off nt
	v_lshl_add_u64 v[148:149], v[148:149], 0, s[74:75]
	ds_read_b32 v143, v160 offset:48
	ds_read_b128 v[172:175], v161 offset:384
	ds_read_b128 v[232:235], v161 offset:400
	s_waitcnt lgkmcnt(3)
; #define RS_LOAD(dst, it0) do { _Pragma("unroll") for (int u = 0; u < 8; ++u) dst[u] = __builtin_nontemporal_load((const f32x4*)(S0 + (size_t)(4 * ((it0) + u)) * DV)); } while (0)
; __device__ __forceinline__ void ret_sample_item(Frame& F, int item) {
;     ...
;     for (int it0 = 0; it0 < 64; it0 += 16) {
;         RS_LOAD(sb, it0 + 8);
;         RS_PROC(sa, it0);
;         { const int itn = it0 + 16 < 64 ? it0 + 16 : it0; RS_LOAD(sa, itn); }
;         RS_PROC(sb, it0 + 8);
;     }
	v_cndmask_b32_e64 v141, 0, v141, s[8:9]
	v_pk_mul_f32 v[180:181], v[26:27], v[114:115] op_sel:[0,1]
	v_pk_mul_f32 v[192:193], v[28:29], v[114:115] op_sel:[0,1]
	v_mfma_f32_16x16x4_f32 v[110:113], v141, v54, v[110:113]
	v_pk_fma_f32 v[180:181], v[30:31], v[114:115], v[180:181] op_sel_hi:[1,0,1]
	v_pk_fma_f32 v[192:193], v[32:33], v[114:115], v[192:193] op_sel_hi:[1,0,1]
	v_pk_fma_f32 v[180:181], v[22:23], v[116:117], v[180:181] op_sel_hi:[1,0,1]
	v_pk_fma_f32 v[192:193], v[24:25], v[116:117], v[192:193] op_sel_hi:[1,0,1]
	v_mfma_f32_16x16x4_f32 v[106:109], v141, v55, v[106:109]
	v_pk_fma_f32 v[180:181], v[18:19], v[116:117], v[180:181] op_sel:[0,1,0]
	v_pk_fma_f32 v[192:193], v[20:21], v[116:117], v[192:193] op_sel:[0,1,0]
	v_pk_fma_f32 v[180:181], v[14:15], v[176:177], v[180:181] op_sel_hi:[1,0,1]
	v_pk_fma_f32 v[192:193], v[16:17], v[176:177], v[192:193] op_sel_hi:[1,0,1]
	v_mfma_f32_16x16x4_f32 v[102:105], v141, v56, v[102:105]
	v_pk_fma_f32 v[180:181], v[10:11], v[176:177], v[180:181] op_sel:[0,1,0]
	v_pk_fma_f32 v[192:193], v[12:13], v[176:177], v[192:193] op_sel:[0,1,0]
	v_pk_fma_f32 v[180:181], v[6:7], v[178:179], v[180:181] op_sel_hi:[1,0,1]
	v_pk_fma_f32 v[192:193], v[8:9], v[178:179], v[192:193] op_sel_hi:[1,0,1]
	v_mfma_f32_16x16x4_f32 v[98:101], v141, v57, v[98:101]
	v_pk_fma_f32 v[180:181], v[2:3], v[178:179], v[180:181] op_sel:[0,1,0]
	v_pk_fma_f32 v[192:193], v[4:5], v[178:179], v[192:193] op_sel:[0,1,0]
	v_pk_mul_f32 v[180:181], v[146:147], v[180:181]
	v_pk_mul_f32 v[192:193], v[146:147], v[192:193]
	v_pk_fma_f32 v[236:237], v[144:145], v[54:55], v[180:181]
	v_pk_fma_f32 v[238:239], v[144:145], v[56:57], v[192:193]
	global_store_dwordx4 v[150:151], v[236:239], off nt
	v_lshl_add_u64 v[150:151], v[150:151], 0, s[74:75]
	global_load_dwordx4 v[54:57], v[148:149], off nt
	v_lshl_add_u64 v[148:149], v[148:149], 0, s[74:75]
	ds_read_b32 v141, v160 offset:64
	ds_read_b128 v[114:117], v161 offset:512
	ds_read_b128 v[176:179], v161 offset:528
	s_waitcnt lgkmcnt(3)
	v_cndmask_b32_e64 v143, 0, v143, s[8:9]
	v_pk_mul_f32 v[180:181], v[26:27], v[172:173] op_sel:[0,1]
	v_pk_mul_f32 v[192:193], v[28:29], v[172:173] op_sel:[0,1]
	v_mfma_f32_16x16x4_f32 v[110:113], v143, v50, v[110:113]
	v_pk_fma_f32 v[180:181], v[30:31], v[172:173], v[180:181] op_sel_hi:[1,0,1]
	v_pk_fma_f32 v[192:193], v[32:33], v[172:173], v[192:193] op_sel_hi:[1,0,1]
	v_pk_fma_f32 v[180:181], v[22:23], v[174:175], v[180:181] op_sel_hi:[1,0,1]
	v_pk_fma_f32 v[192:193], v[24:25], v[174:175], v[192:193] op_sel_hi:[1,0,1]
	v_mfma_f32_16x16x4_f32 v[106:109], v143, v51, v[106:109]
	v_pk_fma_f32 v[180:181], v[18:19], v[174:175], v[180:181] op_sel:[0,1,0]
	v_pk_fma_f32 v[192:193], v[20:21], v[174:175], v[192:193] op_sel:[0,1,0]
	v_pk_fma_f32 v[180:181], v[14:15], v[232:233], v[180:181] op_sel_hi:[1,0,1]
	v_pk_fma_f32 v[192:193], v[16:17], v[232:233], v[192:193] op_sel_hi:[1,0,1]
	v_mfma_f32_16x16x4_f32 v[102:105], v143, v52, v[102:105]
	v_pk_fma_f32 v[180:181], v[10:11], v[232:233], v[180:181] op_sel:[0,1,0]
	v_pk_fma_f32 v[192:193], v[12:13], v[232:233], v[192:193] op_sel:[0,1,0]
	v_pk_fma_f32 v[180:181], v[6:7], v[234:235], v[180:181] op_sel_hi:[1,0,1]
	v_pk_fma_f32 v[192:193], v[8:9], v[234:235], v[192:193] op_sel_hi:[1,0,1]
	v_mfma_f32_16x16x4_f32 v[98:101], v143, v53, v[98:101]
	v_pk_fma_f32 v[180:181], v[2:3], v[234:235], v[180:181] op_sel:[0,1,0]
	v_pk_fma_f32 v[192:193], v[4:5], v[234:235], v[192:193] op_sel:[0,1,0]
	v_pk_mul_f32 v[180:181], v[146:147], v[180:181]
	v_pk_mul_f32 v[192:193], v[146:147], v[192:193]
	v_pk_fma_f32 v[236:237], v[144:145], v[50:51], v[180:181]
	v_pk_fma_f32 v[238:239], v[144:145], v[52:53], v[192:193]
	global_store_dwordx4 v[150:151], v[236:239], off nt
	v_lshl_add_u64 v[150:151], v[150:151], 0, s[74:75]
	global_load_dwordx4 v[50:53], v[148:149], off nt
	v_lshl_add_u64 v[148:149], v[148:149], 0, s[74:75]
	ds_read_b32 v143, v160 offset:80
	ds_read_b128 v[172:175], v161 offset:640
	ds_read_b128 v[232:235], v161 offset:656
	s_waitcnt lgkmcnt(3)
	v_cndmask_b32_e64 v141, 0, v141, s[8:9]
	v_pk_mul_f32 v[180:181], v[26:27], v[114:115] op_sel:[0,1]
	v_pk_mul_f32 v[192:193], v[28:29], v[114:115] op_sel:[0,1]
	v_mfma_f32_16x16x4_f32 v[110:113], v141, v46, v[110:113]
	v_pk_fma_f32 v[180:181], v[30:31], v[114:115], v[180:181] op_sel_hi:[1,0,1]
	v_pk_fma_f32 v[192:193], v[32:33], v[114:115], v[192:193] op_sel_hi:[1,0,1]
	v_pk_fma_f32 v[180:181], v[22:23], v[116:117], v[180:181] op_sel_hi:[1,0,1]
	v_pk_fma_f32 v[192:193], v[24:25], v[116:117], v[192:193] op_sel_hi:[1,0,1]
	v_mfma_f32_16x16x4_f32 v[106:109], v141, v47, v[106:109]
	v_pk_fma_f32 v[180:181], v[18:19], v[116:117], v[180:181] op_sel:[0,1,0]
	v_pk_fma_f32 v[192:193], v[20:21], v[116:117], v[192:193] op_sel:[0,1,0]
	v_pk_fma_f32 v[180:181], v[14:15], v[176:177], v[180:181] op_sel_hi:[1,0,1]
	v_pk_fma_f32 v[192:193], v[16:17], v[176:177], v[192:193] op_sel_hi:[1,0,1]
	v_mfma_f32_16x16x4_f32 v[102:105], v141, v48, v[102:105]
	v_pk_fma_f32 v[180:181], v[10:11], v[176:177], v[180:181] op_sel:[0,1,0]
	v_pk_fma_f32 v[192:193], v[12:13], v[176:177], v[192:193] op_sel:[0,1,0]
	v_pk_fma_f32 v[180:181], v[6:7], v[178:179], v[180:181] op_sel_hi:[1,0,1]
	v_pk_fma_f32 v[192:193], v[8:9], v[178:179], v[192:193] op_sel_hi:[1,0,1]
	v_mfma_f32_16x16x4_f32 v[98:101], v141, v49, v[98:101]
	v_pk_fma_f32 v[180:181], v[2:3], v[178:179], v[180:181] op_sel:[0,1,0]
	v_pk_fma_f32 v[192:193], v[4:5], v[178:179], v[192:193] op_sel:[0,1,0]
	v_pk_mul_f32 v[180:181], v[146:147], v[180:181]
	v_pk_mul_f32 v[192:193], v[146:147], v[192:193]
	v_pk_fma_f32 v[236:237], v[144:145], v[46:47], v[180:181]
	v_pk_fma_f32 v[238:239], v[144:145], v[48:49], v[192:193]
	global_store_dwordx4 v[150:151], v[236:239], off nt
	v_lshl_add_u64 v[150:151], v[150:151], 0, s[74:75]
	global_load_dwordx4 v[46:49], v[148:149], off nt
	v_lshl_add_u64 v[148:149], v[148:149], 0, s[74:75]
	ds_read_b32 v141, v160 offset:96
	ds_read_b128 v[114:117], v161 offset:768
	ds_read_b128 v[176:179], v161 offset:784
	s_waitcnt lgkmcnt(3)
; #define RS_LOAD(dst, it0) do { _Pragma("unroll") for (int u = 0; u < 8; ++u) dst[u] = __builtin_nontemporal_load((const f32x4*)(S0 + (size_t)(4 * ((it0) + u)) * DV)); } while (0)
; __device__ __forceinline__ void ret_sample_item(Frame& F, int item) {
;     ...
;     for (int it0 = 0; it0 < 64; it0 += 16) {
;         RS_LOAD(sb, it0 + 8);
;         RS_PROC(sa, it0);
;         { const int itn = it0 + 16 < 64 ? it0 + 16 : it0; RS_LOAD(sa, itn); }
;         RS_PROC(sb, it0 + 8);
;     }
	v_cndmask_b32_e64 v143, 0, v143, s[8:9]
	v_pk_mul_f32 v[180:181], v[26:27], v[172:173] op_sel:[0,1]
	v_pk_mul_f32 v[192:193], v[28:29], v[172:173] op_sel:[0,1]
	v_mfma_f32_16x16x4_f32 v[110:113], v143, v42, v[110:113]
	v_pk_fma_f32 v[180:181], v[30:31], v[172:173], v[180:181] op_sel_hi:[1,0,1]
	v_pk_fma_f32 v[192:193], v[32:33], v[172:173], v[192:193] op_sel_hi:[1,0,1]
	v_pk_fma_f32 v[180:181], v[22:23], v[174:175], v[180:181] op_sel_hi:[1,0,1]
	v_pk_fma_f32 v[192:193], v[24:25], v[174:175], v[192:193] op_sel_hi:[1,0,1]
	v_mfma_f32_16x16x4_f32 v[106:109], v143, v43, v[106:109]
	v_pk_fma_f32 v[180:181], v[18:19], v[174:175], v[180:181] op_sel:[0,1,0]
	v_pk_fma_f32 v[192:193], v[20:21], v[174:175], v[192:193] op_sel:[0,1,0]
	v_pk_fma_f32 v[180:181], v[14:15], v[232:233], v[180:181] op_sel_hi:[1,0,1]
	v_pk_fma_f32 v[192:193], v[16:17], v[232:233], v[192:193] op_sel_hi:[1,0,1]
	v_mfma_f32_16x16x4_f32 v[102:105], v143, v44, v[102:105]
	v_pk_fma_f32 v[180:181], v[10:11], v[232:233], v[180:181] op_sel:[0,1,0]
	v_pk_fma_f32 v[192:193], v[12:13], v[232:233], v[192:193] op_sel:[0,1,0]
	v_pk_fma_f32 v[180:181], v[6:7], v[234:235], v[180:181] op_sel_hi:[1,0,1]
	v_pk_fma_f32 v[192:193], v[8:9], v[234:235], v[192:193] op_sel_hi:[1,0,1]
	v_mfma_f32_16x16x4_f32 v[98:101], v143, v45, v[98:101]
	v_pk_fma_f32 v[180:181], v[2:3], v[234:235], v[180:181] op_sel:[0,1,0]
	v_pk_fma_f32 v[192:193], v[4:5], v[234:235], v[192:193] op_sel:[0,1,0]
	v_pk_mul_f32 v[180:181], v[146:147], v[180:181]
	v_pk_mul_f32 v[192:193], v[146:147], v[192:193]
	v_pk_fma_f32 v[236:237], v[144:145], v[42:43], v[180:181]
	v_pk_fma_f32 v[238:239], v[144:145], v[44:45], v[192:193]
	global_store_dwordx4 v[150:151], v[236:239], off nt
	v_lshl_add_u64 v[150:151], v[150:151], 0, s[74:75]
	global_load_dwordx4 v[42:45], v[148:149], off nt
	v_lshl_add_u64 v[148:149], v[148:149], 0, s[74:75]
	ds_read_b32 v143, v160 offset:112
	ds_read_b128 v[172:175], v161 offset:896
	ds_read_b128 v[232:235], v161 offset:912
	s_waitcnt lgkmcnt(3)
	v_cndmask_b32_e64 v141, 0, v141, s[8:9]
	v_pk_mul_f32 v[180:181], v[26:27], v[114:115] op_sel:[0,1]
	v_pk_mul_f32 v[192:193], v[28:29], v[114:115] op_sel:[0,1]
	v_mfma_f32_16x16x4_f32 v[110:113], v141, v38, v[110:113]
	v_pk_fma_f32 v[180:181], v[30:31], v[114:115], v[180:181] op_sel_hi:[1,0,1]
	v_pk_fma_f32 v[192:193], v[32:33], v[114:115], v[192:193] op_sel_hi:[1,0,1]
	v_pk_fma_f32 v[180:181], v[22:23], v[116:117], v[180:181] op_sel_hi:[1,0,1]
	v_pk_fma_f32 v[192:193], v[24:25], v[116:117], v[192:193] op_sel_hi:[1,0,1]
	v_mfma_f32_16x16x4_f32 v[106:109], v141, v39, v[106:109]
	v_pk_fma_f32 v[180:181], v[18:19], v[116:117], v[180:181] op_sel:[0,1,0]
	v_pk_fma_f32 v[192:193], v[20:21], v[116:117], v[192:193] op_sel:[0,1,0]
	v_pk_fma_f32 v[180:181], v[14:15], v[176:177], v[180:181] op_sel_hi:[1,0,1]
	v_pk_fma_f32 v[192:193], v[16:17], v[176:177], v[192:193] op_sel_hi:[1,0,1]
	v_mfma_f32_16x16x4_f32 v[102:105], v141, v40, v[102:105]
	v_pk_fma_f32 v[180:181], v[10:11], v[176:177], v[180:181] op_sel:[0,1,0]
	v_pk_fma_f32 v[192:193], v[12:13], v[176:177], v[192:193] op_sel:[0,1,0]
	v_pk_fma_f32 v[180:181], v[6:7], v[178:179], v[180:181] op_sel_hi:[1,0,1]
	v_pk_fma_f32 v[192:193], v[8:9], v[178:179], v[192:193] op_sel_hi:[1,0,1]
	v_mfma_f32_16x16x4_f32 v[98:101], v141, v41, v[98:101]
	v_pk_fma_f32 v[180:181], v[2:3], v[178:179], v[180:181] op_sel:[0,1,0]
	v_pk_fma_f32 v[192:193], v[4:5], v[178:179], v[192:193] op_sel:[0,1,0]
	v_pk_mul_f32 v[180:181], v[146:147], v[180:181]
	v_pk_mul_f32 v[192:193], v[146:147], v[192:193]
	v_pk_fma_f32 v[236:237], v[144:145], v[38:39], v[180:181]
	v_pk_fma_f32 v[238:239], v[144:145], v[40:41], v[192:193]
	global_store_dwordx4 v[150:151], v[236:239], off nt
	v_lshl_add_u64 v[150:151], v[150:151], 0, s[74:75]
	global_load_dwordx4 v[38:41], v[148:149], off nt
	v_lshl_add_u64 v[148:149], v[148:149], 0, s[74:75]
	ds_read_b32 v141, v160 offset:128
	ds_read_b128 v[114:117], v161 offset:1024
	ds_read_b128 v[176:179], v161 offset:1040
	s_waitcnt lgkmcnt(3)
	v_cndmask_b32_e64 v143, 0, v143, s[8:9]
	v_pk_mul_f32 v[180:181], v[26:27], v[172:173] op_sel:[0,1]
	v_pk_mul_f32 v[192:193], v[28:29], v[172:173] op_sel:[0,1]
	v_mfma_f32_16x16x4_f32 v[110:113], v143, v34, v[110:113]
	v_pk_fma_f32 v[180:181], v[30:31], v[172:173], v[180:181] op_sel_hi:[1,0,1]
	v_pk_fma_f32 v[192:193], v[32:33], v[172:173], v[192:193] op_sel_hi:[1,0,1]
	v_pk_fma_f32 v[180:181], v[22:23], v[174:175], v[180:181] op_sel_hi:[1,0,1]
	v_pk_fma_f32 v[192:193], v[24:25], v[174:175], v[192:193] op_sel_hi:[1,0,1]
	v_mfma_f32_16x16x4_f32 v[106:109], v143, v35, v[106:109]
	v_pk_fma_f32 v[180:181], v[18:19], v[174:175], v[180:181] op_sel:[0,1,0]
	v_pk_fma_f32 v[192:193], v[20:21], v[174:175], v[192:193] op_sel:[0,1,0]
	v_pk_fma_f32 v[180:181], v[14:15], v[232:233], v[180:181] op_sel_hi:[1,0,1]
	v_pk_fma_f32 v[192:193], v[16:17], v[232:233], v[192:193] op_sel_hi:[1,0,1]
	v_mfma_f32_16x16x4_f32 v[102:105], v143, v36, v[102:105]
	v_pk_fma_f32 v[180:181], v[10:11], v[232:233], v[180:181] op_sel:[0,1,0]
	v_pk_fma_f32 v[192:193], v[12:13], v[232:233], v[192:193] op_sel:[0,1,0]
	v_pk_fma_f32 v[180:181], v[6:7], v[234:235], v[180:181] op_sel_hi:[1,0,1]
	v_pk_fma_f32 v[192:193], v[8:9], v[234:235], v[192:193] op_sel_hi:[1,0,1]
	v_mfma_f32_16x16x4_f32 v[98:101], v143, v37, v[98:101]
	v_pk_fma_f32 v[180:181], v[2:3], v[234:235], v[180:181] op_sel:[0,1,0]
	v_pk_fma_f32 v[192:193], v[4:5], v[234:235], v[192:193] op_sel:[0,1,0]
	v_pk_mul_f32 v[180:181], v[146:147], v[180:181]
	v_pk_mul_f32 v[192:193], v[146:147], v[192:193]
	v_pk_fma_f32 v[236:237], v[144:145], v[34:35], v[180:181]
	v_pk_fma_f32 v[238:239], v[144:145], v[36:37], v[192:193]
	global_store_dwordx4 v[150:151], v[236:239], off nt
	v_lshl_add_u64 v[150:151], v[150:151], 0, s[74:75]
	global_load_dwordx4 v[34:37], v[148:149], off nt
	v_lshl_add_u64 v[148:149], v[148:149], 0, s[74:75]
	ds_read_b32 v143, v160 offset:144
	ds_read_b128 v[172:175], v161 offset:1152
	ds_read_b128 v[232:235], v161 offset:1168
	s_waitcnt vmcnt(14)
; #define RS_LOAD(dst, it0) do { _Pragma("unroll") for (int u = 0; u < 8; ++u) dst[u] = __builtin_nontemporal_load((const f32x4*)(S0 + (size_t)(4 * ((it0) + u)) * DV)); } while (0)
; __device__ __forceinline__ void ret_sample_item(Frame& F, int item) {
;     ...
;     for (int it0 = 0; it0 < 64; it0 += 16) {
;         RS_LOAD(sb, it0 + 8);
;         RS_PROC(sa, it0);
;         { const int itn = it0 + 16 < 64 ? it0 + 16 : it0; RS_LOAD(sa, itn); }
;         RS_PROC(sb, it0 + 8);
;     }
	s_waitcnt lgkmcnt(3)
	v_cndmask_b32_e64 v141, 0, v141, s[8:9]
	v_pk_mul_f32 v[180:181], v[26:27], v[114:115] op_sel:[0,1]
	v_pk_mul_f32 v[192:193], v[28:29], v[114:115] op_sel:[0,1]
	v_mfma_f32_16x16x4_f32 v[110:113], v141, v70, v[110:113]
	v_pk_fma_f32 v[180:181], v[30:31], v[114:115], v[180:181] op_sel_hi:[1,0,1]
	v_pk_fma_f32 v[192:193], v[32:33], v[114:115], v[192:193] op_sel_hi:[1,0,1]
	v_pk_fma_f32 v[180:181], v[22:23], v[116:117], v[180:181] op_sel_hi:[1,0,1]
	v_pk_fma_f32 v[192:193], v[24:25], v[116:117], v[192:193] op_sel_hi:[1,0,1]
	v_mfma_f32_16x16x4_f32 v[106:109], v141, v71, v[106:109]
	v_pk_fma_f32 v[180:181], v[18:19], v[116:117], v[180:181] op_sel:[0,1,0]
	v_pk_fma_f32 v[192:193], v[20:21], v[116:117], v[192:193] op_sel:[0,1,0]
	v_pk_fma_f32 v[180:181], v[14:15], v[176:177], v[180:181] op_sel_hi:[1,0,1]
	v_pk_fma_f32 v[192:193], v[16:17], v[176:177], v[192:193] op_sel_hi:[1,0,1]
	v_mfma_f32_16x16x4_f32 v[102:105], v141, v72, v[102:105]
	v_pk_fma_f32 v[180:181], v[10:11], v[176:177], v[180:181] op_sel:[0,1,0]
	v_pk_fma_f32 v[192:193], v[12:13], v[176:177], v[192:193] op_sel:[0,1,0]
	v_pk_fma_f32 v[180:181], v[6:7], v[178:179], v[180:181] op_sel_hi:[1,0,1]
	v_pk_fma_f32 v[192:193], v[8:9], v[178:179], v[192:193] op_sel_hi:[1,0,1]
	v_mfma_f32_16x16x4_f32 v[98:101], v141, v73, v[98:101]
	v_pk_fma_f32 v[180:181], v[2:3], v[178:179], v[180:181] op_sel:[0,1,0]
	v_pk_fma_f32 v[192:193], v[4:5], v[178:179], v[192:193] op_sel:[0,1,0]
	v_pk_mul_f32 v[180:181], v[146:147], v[180:181]
	v_pk_mul_f32 v[192:193], v[146:147], v[192:193]
	v_pk_fma_f32 v[236:237], v[144:145], v[70:71], v[180:181]
	v_pk_fma_f32 v[238:239], v[144:145], v[72:73], v[192:193]
	global_store_dwordx4 v[150:151], v[236:239], off nt
	v_lshl_add_u64 v[150:151], v[150:151], 0, s[74:75]
	global_load_dwordx4 v[70:73], v[148:149], off nt
	v_lshl_add_u64 v[148:149], v[148:149], 0, s[74:75]
	ds_read_b32 v141, v160 offset:160
	ds_read_b128 v[114:117], v161 offset:1280
	ds_read_b128 v[176:179], v161 offset:1296
	s_waitcnt vmcnt(14)
	s_waitcnt lgkmcnt(3)
	v_cndmask_b32_e64 v143, 0, v143, s[8:9]
	v_pk_mul_f32 v[180:181], v[26:27], v[172:173] op_sel:[0,1]
	v_pk_mul_f32 v[192:193], v[28:29], v[172:173] op_sel:[0,1]
	v_mfma_f32_16x16x4_f32 v[110:113], v143, v62, v[110:113]
	v_pk_fma_f32 v[180:181], v[30:31], v[172:173], v[180:181] op_sel_hi:[1,0,1]
	v_pk_fma_f32 v[192:193], v[32:33], v[172:173], v[192:193] op_sel_hi:[1,0,1]
	v_pk_fma_f32 v[180:181], v[22:23], v[174:175], v[180:181] op_sel_hi:[1,0,1]
	v_pk_fma_f32 v[192:193], v[24:25], v[174:175], v[192:193] op_sel_hi:[1,0,1]
	v_mfma_f32_16x16x4_f32 v[106:109], v143, v63, v[106:109]
	v_pk_fma_f32 v[180:181], v[18:19], v[174:175], v[180:181] op_sel:[0,1,0]
	v_pk_fma_f32 v[192:193], v[20:21], v[174:175], v[192:193] op_sel:[0,1,0]
	v_pk_fma_f32 v[180:181], v[14:15], v[232:233], v[180:181] op_sel_hi:[1,0,1]
	v_pk_fma_f32 v[192:193], v[16:17], v[232:233], v[192:193] op_sel_hi:[1,0,1]
	v_mfma_f32_16x16x4_f32 v[102:105], v143, v64, v[102:105]
	v_pk_fma_f32 v[180:181], v[10:11], v[232:233], v[180:181] op_sel:[0,1,0]
	v_pk_fma_f32 v[192:193], v[12:13], v[232:233], v[192:193] op_sel:[0,1,0]
	v_pk_fma_f32 v[180:181], v[6:7], v[234:235], v[180:181] op_sel_hi:[1,0,1]
	v_pk_fma_f32 v[192:193], v[8:9], v[234:235], v[192:193] op_sel_hi:[1,0,1]
	v_mfma_f32_16x16x4_f32 v[98:101], v143, v65, v[98:101]
	v_pk_fma_f32 v[180:181], v[2:3], v[234:235], v[180:181] op_sel:[0,1,0]
	v_pk_fma_f32 v[192:193], v[4:5], v[234:235], v[192:193] op_sel:[0,1,0]
	v_pk_mul_f32 v[180:181], v[146:147], v[180:181]
	v_pk_mul_f32 v[192:193], v[146:147], v[192:193]
	v_pk_fma_f32 v[236:237], v[144:145], v[62:63], v[180:181]
	v_pk_fma_f32 v[238:239], v[144:145], v[64:65], v[192:193]
	global_store_dwordx4 v[150:151], v[236:239], off nt
	v_lshl_add_u64 v[150:151], v[150:151], 0, s[74:75]
	global_load_dwordx4 v[62:65], v[148:149], off nt
	v_lshl_add_u64 v[148:149], v[148:149], 0, s[74:75]
	ds_read_b32 v143, v160 offset:176
	ds_read_b128 v[172:175], v161 offset:1408
	ds_read_b128 v[232:235], v161 offset:1424
	s_waitcnt vmcnt(14)
	s_waitcnt lgkmcnt(3)
	v_cndmask_b32_e64 v141, 0, v141, s[8:9]
	v_pk_mul_f32 v[180:181], v[26:27], v[114:115] op_sel:[0,1]
	v_pk_mul_f32 v[192:193], v[28:29], v[114:115] op_sel:[0,1]
	v_mfma_f32_16x16x4_f32 v[110:113], v141, v54, v[110:113]
	v_pk_fma_f32 v[180:181], v[30:31], v[114:115], v[180:181] op_sel_hi:[1,0,1]
	v_pk_fma_f32 v[192:193], v[32:33], v[114:115], v[192:193] op_sel_hi:[1,0,1]
	v_pk_fma_f32 v[180:181], v[22:23], v[116:117], v[180:181] op_sel_hi:[1,0,1]
	v_pk_fma_f32 v[192:193], v[24:25], v[116:117], v[192:193] op_sel_hi:[1,0,1]
	v_mfma_f32_16x16x4_f32 v[106:109], v141, v55, v[106:109]
	v_pk_fma_f32 v[180:181], v[18:19], v[116:117], v[180:181] op_sel:[0,1,0]
	v_pk_fma_f32 v[192:193], v[20:21], v[116:117], v[192:193] op_sel:[0,1,0]
	v_pk_fma_f32 v[180:181], v[14:15], v[176:177], v[180:181] op_sel_hi:[1,0,1]
	v_pk_fma_f32 v[192:193], v[16:17], v[176:177], v[192:193] op_sel_hi:[1,0,1]
	v_mfma_f32_16x16x4_f32 v[102:105], v141, v56, v[102:105]
	v_pk_fma_f32 v[180:181], v[10:11], v[176:177], v[180:181] op_sel:[0,1,0]
	v_pk_fma_f32 v[192:193], v[12:13], v[176:177], v[192:193] op_sel:[0,1,0]
	v_pk_fma_f32 v[180:181], v[6:7], v[178:179], v[180:181] op_sel_hi:[1,0,1]
	v_pk_fma_f32 v[192:193], v[8:9], v[178:179], v[192:193] op_sel_hi:[1,0,1]
	v_mfma_f32_16x16x4_f32 v[98:101], v141, v57, v[98:101]
	v_pk_fma_f32 v[180:181], v[2:3], v[178:179], v[180:181] op_sel:[0,1,0]
	v_pk_fma_f32 v[192:193], v[4:5], v[178:179], v[192:193] op_sel:[0,1,0]
	v_pk_mul_f32 v[180:181], v[146:147], v[180:181]
	v_pk_mul_f32 v[192:193], v[146:147], v[192:193]
	v_pk_fma_f32 v[236:237], v[144:145], v[54:55], v[180:181]
	v_pk_fma_f32 v[238:239], v[144:145], v[56:57], v[192:193]
	global_store_dwordx4 v[150:151], v[236:239], off nt
	v_lshl_add_u64 v[150:151], v[150:151], 0, s[74:75]
	global_load_dwordx4 v[54:57], v[148:149], off nt
	v_lshl_add_u64 v[148:149], v[148:149], 0, s[74:75]
	ds_read_b32 v141, v160 offset:192
	ds_read_b128 v[114:117], v161 offset:1536
	ds_read_b128 v[176:179], v161 offset:1552
	s_waitcnt vmcnt(14)
; #define RS_LOAD(dst, it0) do { _Pragma("unroll") for (int u = 0; u < 8; ++u) dst[u] = __builtin_nontemporal_load((const f32x4*)(S0 + (size_t)(4 * ((it0) + u)) * DV)); } while (0)
; __device__ __forceinline__ void ret_sample_item(Frame& F, int item) {
;     ...
;     for (int it0 = 0; it0 < 64; it0 += 16) {
;         RS_LOAD(sb, it0 + 8);
;         RS_PROC(sa, it0);
;         { const int itn = it0 + 16 < 64 ? it0 + 16 : it0; RS_LOAD(sa, itn); }
;         RS_PROC(sb, it0 + 8);
;     }
	s_waitcnt lgkmcnt(3)
	v_cndmask_b32_e64 v143, 0, v143, s[8:9]
	v_pk_mul_f32 v[180:181], v[26:27], v[172:173] op_sel:[0,1]
	v_pk_mul_f32 v[192:193], v[28:29], v[172:173] op_sel:[0,1]
	v_mfma_f32_16x16x4_f32 v[110:113], v143, v50, v[110:113]
	v_pk_fma_f32 v[180:181], v[30:31], v[172:173], v[180:181] op_sel_hi:[1,0,1]
	v_pk_fma_f32 v[192:193], v[32:33], v[172:173], v[192:193] op_sel_hi:[1,0,1]
	v_pk_fma_f32 v[180:181], v[22:23], v[174:175], v[180:181] op_sel_hi:[1,0,1]
	v_pk_fma_f32 v[192:193], v[24:25], v[174:175], v[192:193] op_sel_hi:[1,0,1]
	v_mfma_f32_16x16x4_f32 v[106:109], v143, v51, v[106:109]
	v_pk_fma_f32 v[180:181], v[18:19], v[174:175], v[180:181] op_sel:[0,1,0]
	v_pk_fma_f32 v[192:193], v[20:21], v[174:175], v[192:193] op_sel:[0,1,0]
	v_pk_fma_f32 v[180:181], v[14:15], v[232:233], v[180:181] op_sel_hi:[1,0,1]
	v_pk_fma_f32 v[192:193], v[16:17], v[232:233], v[192:193] op_sel_hi:[1,0,1]
	v_mfma_f32_16x16x4_f32 v[102:105], v143, v52, v[102:105]
	v_pk_fma_f32 v[180:181], v[10:11], v[232:233], v[180:181] op_sel:[0,1,0]
	v_pk_fma_f32 v[192:193], v[12:13], v[232:233], v[192:193] op_sel:[0,1,0]
	v_pk_fma_f32 v[180:181], v[6:7], v[234:235], v[180:181] op_sel_hi:[1,0,1]
	v_pk_fma_f32 v[192:193], v[8:9], v[234:235], v[192:193] op_sel_hi:[1,0,1]
	v_mfma_f32_16x16x4_f32 v[98:101], v143, v53, v[98:101]
	v_pk_fma_f32 v[180:181], v[2:3], v[234:235], v[180:181] op_sel:[0,1,0]
	v_pk_fma_f32 v[192:193], v[4:5], v[234:235], v[192:193] op_sel:[0,1,0]
	v_pk_mul_f32 v[180:181], v[146:147], v[180:181]
	v_pk_mul_f32 v[192:193], v[146:147], v[192:193]
	v_pk_fma_f32 v[236:237], v[144:145], v[50:51], v[180:181]
	v_pk_fma_f32 v[238:239], v[144:145], v[52:53], v[192:193]
	global_store_dwordx4 v[150:151], v[236:239], off nt
	v_lshl_add_u64 v[150:151], v[150:151], 0, s[74:75]
	global_load_dwordx4 v[50:53], v[148:149], off nt
	v_lshl_add_u64 v[148:149], v[148:149], 0, s[74:75]
	ds_read_b32 v143, v160 offset:208
	ds_read_b128 v[172:175], v161 offset:1664
	ds_read_b128 v[232:235], v161 offset:1680
	s_waitcnt vmcnt(14)
	s_waitcnt lgkmcnt(3)
	v_cndmask_b32_e64 v141, 0, v141, s[8:9]
	v_pk_mul_f32 v[180:181], v[26:27], v[114:115] op_sel:[0,1]
	v_pk_mul_f32 v[192:193], v[28:29], v[114:115] op_sel:[0,1]
	v_mfma_f32_16x16x4_f32 v[110:113], v141, v46, v[110:113]
	v_pk_fma_f32 v[180:181], v[30:31], v[114:115], v[180:181] op_sel_hi:[1,0,1]
	v_pk_fma_f32 v[192:193], v[32:33], v[114:115], v[192:193] op_sel_hi:[1,0,1]
	v_pk_fma_f32 v[180:181], v[22:23], v[116:117], v[180:181] op_sel_hi:[1,0,1]
	v_pk_fma_f32 v[192:193], v[24:25], v[116:117], v[192:193] op_sel_hi:[1,0,1]
	v_mfma_f32_16x16x4_f32 v[106:109], v141, v47, v[106:109]
	v_pk_fma_f32 v[180:181], v[18:19], v[116:117], v[180:181] op_sel:[0,1,0]
	v_pk_fma_f32 v[192:193], v[20:21], v[116:117], v[192:193] op_sel:[0,1,0]
	v_pk_fma_f32 v[180:181], v[14:15], v[176:177], v[180:181] op_sel_hi:[1,0,1]
	v_pk_fma_f32 v[192:193], v[16:17], v[176:177], v[192:193] op_sel_hi:[1,0,1]
	v_mfma_f32_16x16x4_f32 v[102:105], v141, v48, v[102:105]
	v_pk_fma_f32 v[180:181], v[10:11], v[176:177], v[180:181] op_sel:[0,1,0]
	v_pk_fma_f32 v[192:193], v[12:13], v[176:177], v[192:193] op_sel:[0,1,0]
	v_pk_fma_f32 v[180:181], v[6:7], v[178:179], v[180:181] op_sel_hi:[1,0,1]
	v_pk_fma_f32 v[192:193], v[8:9], v[178:179], v[192:193] op_sel_hi:[1,0,1]
	v_mfma_f32_16x16x4_f32 v[98:101], v141, v49, v[98:101]
	v_pk_fma_f32 v[180:181], v[2:3], v[178:179], v[180:181] op_sel:[0,1,0]
	v_pk_fma_f32 v[192:193], v[4:5], v[178:179], v[192:193] op_sel:[0,1,0]
	v_pk_mul_f32 v[180:181], v[146:147], v[180:181]
	v_pk_mul_f32 v[192:193], v[146:147], v[192:193]
	v_pk_fma_f32 v[236:237], v[144:145], v[46:47], v[180:181]
	v_pk_fma_f32 v[238:239], v[144:145], v[48:49], v[192:193]
	global_store_dwordx4 v[150:151], v[236:239], off nt
	v_lshl_add_u64 v[150:151], v[150:151], 0, s[74:75]
	global_load_dwordx4 v[46:49], v[148:149], off nt
	v_lshl_add_u64 v[148:149], v[148:149], 0, s[74:75]
	ds_read_b32 v141, v160 offset:224
	ds_read_b128 v[114:117], v161 offset:1792
	ds_read_b128 v[176:179], v161 offset:1808
	s_waitcnt vmcnt(14)
	s_waitcnt lgkmcnt(3)
	v_cndmask_b32_e64 v143, 0, v143, s[8:9]
	v_pk_mul_f32 v[180:181], v[26:27], v[172:173] op_sel:[0,1]
	v_pk_mul_f32 v[192:193], v[28:29], v[172:173] op_sel:[0,1]
	v_mfma_f32_16x16x4_f32 v[110:113], v143, v42, v[110:113]
	v_pk_fma_f32 v[180:181], v[30:31], v[172:173], v[180:181] op_sel_hi:[1,0,1]
	v_pk_fma_f32 v[192:193], v[32:33], v[172:173], v[192:193] op_sel_hi:[1,0,1]
	v_pk_fma_f32 v[180:181], v[22:23], v[174:175], v[180:181] op_sel_hi:[1,0,1]
	v_pk_fma_f32 v[192:193], v[24:25], v[174:175], v[192:193] op_sel_hi:[1,0,1]
	v_mfma_f32_16x16x4_f32 v[106:109], v143, v43, v[106:109]
	v_pk_fma_f32 v[180:181], v[18:19], v[174:175], v[180:181] op_sel:[0,1,0]
	v_pk_fma_f32 v[192:193], v[20:21], v[174:175], v[192:193] op_sel:[0,1,0]
	v_pk_fma_f32 v[180:181], v[14:15], v[232:233], v[180:181] op_sel_hi:[1,0,1]
	v_pk_fma_f32 v[192:193], v[16:17], v[232:233], v[192:193] op_sel_hi:[1,0,1]
	v_mfma_f32_16x16x4_f32 v[102:105], v143, v44, v[102:105]
	v_pk_fma_f32 v[180:181], v[10:11], v[232:233], v[180:181] op_sel:[0,1,0]
	v_pk_fma_f32 v[192:193], v[12:13], v[232:233], v[192:193] op_sel:[0,1,0]
	v_pk_fma_f32 v[180:181], v[6:7], v[234:235], v[180:181] op_sel_hi:[1,0,1]
	v_pk_fma_f32 v[192:193], v[8:9], v[234:235], v[192:193] op_sel_hi:[1,0,1]
	v_mfma_f32_16x16x4_f32 v[98:101], v143, v45, v[98:101]
	v_pk_fma_f32 v[180:181], v[2:3], v[234:235], v[180:181] op_sel:[0,1,0]
	v_pk_fma_f32 v[192:193], v[4:5], v[234:235], v[192:193] op_sel:[0,1,0]
	v_pk_mul_f32 v[180:181], v[146:147], v[180:181]
	v_pk_mul_f32 v[192:193], v[146:147], v[192:193]
	v_pk_fma_f32 v[236:237], v[144:145], v[42:43], v[180:181]
	v_pk_fma_f32 v[238:239], v[144:145], v[44:45], v[192:193]
	global_store_dwordx4 v[150:151], v[236:239], off nt
	v_lshl_add_u64 v[150:151], v[150:151], 0, s[74:75]
	global_load_dwordx4 v[42:45], v[148:149], off nt
	v_lshl_add_u64 v[148:149], v[148:149], 0, s[74:75]
	ds_read_b32 v143, v160 offset:240
	ds_read_b128 v[172:175], v161 offset:1920
	ds_read_b128 v[232:235], v161 offset:1936
	s_waitcnt vmcnt(14)
; #define RS_LOAD(dst, it0) do { _Pragma("unroll") for (int u = 0; u < 8; ++u) dst[u] = __builtin_nontemporal_load((const f32x4*)(S0 + (size_t)(4 * ((it0) + u)) * DV)); } while (0)
; __device__ __forceinline__ void ret_sample_item(Frame& F, int item) {
;     ...
;     for (int it0 = 0; it0 < 64; it0 += 16) {
;         RS_LOAD(sb, it0 + 8);
;         RS_PROC(sa, it0);
;         { const int itn = it0 + 16 < 64 ? it0 + 16 : it0; RS_LOAD(sa, itn); }
;         RS_PROC(sb, it0 + 8);
;     }
	s_waitcnt lgkmcnt(3)
	v_cndmask_b32_e64 v141, 0, v141, s[8:9]
	v_pk_mul_f32 v[180:181], v[26:27], v[114:115] op_sel:[0,1]
	v_pk_mul_f32 v[192:193], v[28:29], v[114:115] op_sel:[0,1]
	v_mfma_f32_16x16x4_f32 v[110:113], v141, v38, v[110:113]
	v_pk_fma_f32 v[180:181], v[30:31], v[114:115], v[180:181] op_sel_hi:[1,0,1]
	v_pk_fma_f32 v[192:193], v[32:33], v[114:115], v[192:193] op_sel_hi:[1,0,1]
	v_pk_fma_f32 v[180:181], v[22:23], v[116:117], v[180:181] op_sel_hi:[1,0,1]
	v_pk_fma_f32 v[192:193], v[24:25], v[116:117], v[192:193] op_sel_hi:[1,0,1]
	v_mfma_f32_16x16x4_f32 v[106:109], v141, v39, v[106:109]
	v_pk_fma_f32 v[180:181], v[18:19], v[116:117], v[180:181] op_sel:[0,1,0]
	v_pk_fma_f32 v[192:193], v[20:21], v[116:117], v[192:193] op_sel:[0,1,0]
	v_pk_fma_f32 v[180:181], v[14:15], v[176:177], v[180:181] op_sel_hi:[1,0,1]
	v_pk_fma_f32 v[192:193], v[16:17], v[176:177], v[192:193] op_sel_hi:[1,0,1]
	v_mfma_f32_16x16x4_f32 v[102:105], v141, v40, v[102:105]
	v_pk_fma_f32 v[180:181], v[10:11], v[176:177], v[180:181] op_sel:[0,1,0]
	v_pk_fma_f32 v[192:193], v[12:13], v[176:177], v[192:193] op_sel:[0,1,0]
	v_pk_fma_f32 v[180:181], v[6:7], v[178:179], v[180:181] op_sel_hi:[1,0,1]
	v_pk_fma_f32 v[192:193], v[8:9], v[178:179], v[192:193] op_sel_hi:[1,0,1]
	v_mfma_f32_16x16x4_f32 v[98:101], v141, v41, v[98:101]
	v_pk_fma_f32 v[180:181], v[2:3], v[178:179], v[180:181] op_sel:[0,1,0]
	v_pk_fma_f32 v[192:193], v[4:5], v[178:179], v[192:193] op_sel:[0,1,0]
	v_pk_mul_f32 v[180:181], v[146:147], v[180:181]
	v_pk_mul_f32 v[192:193], v[146:147], v[192:193]
	v_pk_fma_f32 v[236:237], v[144:145], v[38:39], v[180:181]
	v_pk_fma_f32 v[238:239], v[144:145], v[40:41], v[192:193]
	global_store_dwordx4 v[150:151], v[236:239], off nt
	v_lshl_add_u64 v[150:151], v[150:151], 0, s[74:75]
	global_load_dwordx4 v[38:41], v[148:149], off nt
	v_lshl_add_u64 v[148:149], v[148:149], 0, s[74:75]
	ds_read_b32 v141, v160 offset:256
	ds_read_b128 v[114:117], v161 offset:2048
	ds_read_b128 v[176:179], v161 offset:2064
	s_waitcnt vmcnt(14)
	s_waitcnt lgkmcnt(3)
	v_cndmask_b32_e64 v143, 0, v143, s[8:9]
	v_pk_mul_f32 v[180:181], v[26:27], v[172:173] op_sel:[0,1]
	v_pk_mul_f32 v[192:193], v[28:29], v[172:173] op_sel:[0,1]
	v_mfma_f32_16x16x4_f32 v[110:113], v143, v34, v[110:113]
	v_pk_fma_f32 v[180:181], v[30:31], v[172:173], v[180:181] op_sel_hi:[1,0,1]
	v_pk_fma_f32 v[192:193], v[32:33], v[172:173], v[192:193] op_sel_hi:[1,0,1]
	v_pk_fma_f32 v[180:181], v[22:23], v[174:175], v[180:181] op_sel_hi:[1,0,1]
	v_pk_fma_f32 v[192:193], v[24:25], v[174:175], v[192:193] op_sel_hi:[1,0,1]
	v_mfma_f32_16x16x4_f32 v[106:109], v143, v35, v[106:109]
	v_pk_fma_f32 v[180:181], v[18:19], v[174:175], v[180:181] op_sel:[0,1,0]
	v_pk_fma_f32 v[192:193], v[20:21], v[174:175], v[192:193] op_sel:[0,1,0]
	v_pk_fma_f32 v[180:181], v[14:15], v[232:233], v[180:181] op_sel_hi:[1,0,1]
	v_pk_fma_f32 v[192:193], v[16:17], v[232:233], v[192:193] op_sel_hi:[1,0,1]
	v_mfma_f32_16x16x4_f32 v[102:105], v143, v36, v[102:105]
	v_pk_fma_f32 v[180:181], v[10:11], v[232:233], v[180:181] op_sel:[0,1,0]
	v_pk_fma_f32 v[192:193], v[12:13], v[232:233], v[192:193] op_sel:[0,1,0]
	v_pk_fma_f32 v[180:181], v[6:7], v[234:235], v[180:181] op_sel_hi:[1,0,1]
	v_pk_fma_f32 v[192:193], v[8:9], v[234:235], v[192:193] op_sel_hi:[1,0,1]
	v_mfma_f32_16x16x4_f32 v[98:101], v143, v37, v[98:101]
	v_pk_fma_f32 v[180:181], v[2:3], v[234:235], v[180:181] op_sel:[0,1,0]
	v_pk_fma_f32 v[192:193], v[4:5], v[234:235], v[192:193] op_sel:[0,1,0]
	v_pk_mul_f32 v[180:181], v[146:147], v[180:181]
	v_pk_mul_f32 v[192:193], v[146:147], v[192:193]
	v_pk_fma_f32 v[236:237], v[144:145], v[34:35], v[180:181]
	v_pk_fma_f32 v[238:239], v[144:145], v[36:37], v[192:193]
	global_store_dwordx4 v[150:151], v[236:239], off nt
	v_lshl_add_u64 v[150:151], v[150:151], 0, s[74:75]
	global_load_dwordx4 v[34:37], v[148:149], off nt
	v_lshl_add_u64 v[148:149], v[148:149], 0, s[74:75]
	ds_read_b32 v143, v160 offset:272
	ds_read_b128 v[172:175], v161 offset:2176
	ds_read_b128 v[232:235], v161 offset:2192
	s_waitcnt vmcnt(14)
	s_waitcnt lgkmcnt(3)
	v_cndmask_b32_e64 v141, 0, v141, s[8:9]
	v_pk_mul_f32 v[180:181], v[26:27], v[114:115] op_sel:[0,1]
	v_pk_mul_f32 v[192:193], v[28:29], v[114:115] op_sel:[0,1]
	v_mfma_f32_16x16x4_f32 v[110:113], v141, v70, v[110:113]
	v_pk_fma_f32 v[180:181], v[30:31], v[114:115], v[180:181] op_sel_hi:[1,0,1]
	v_pk_fma_f32 v[192:193], v[32:33], v[114:115], v[192:193] op_sel_hi:[1,0,1]
	v_pk_fma_f32 v[180:181], v[22:23], v[116:117], v[180:181] op_sel_hi:[1,0,1]
	v_pk_fma_f32 v[192:193], v[24:25], v[116:117], v[192:193] op_sel_hi:[1,0,1]
	v_mfma_f32_16x16x4_f32 v[106:109], v141, v71, v[106:109]
	v_pk_fma_f32 v[180:181], v[18:19], v[116:117], v[180:181] op_sel:[0,1,0]
	v_pk_fma_f32 v[192:193], v[20:21], v[116:117], v[192:193] op_sel:[0,1,0]
	v_pk_fma_f32 v[180:181], v[14:15], v[176:177], v[180:181] op_sel_hi:[1,0,1]
	v_pk_fma_f32 v[192:193], v[16:17], v[176:177], v[192:193] op_sel_hi:[1,0,1]
	v_mfma_f32_16x16x4_f32 v[102:105], v141, v72, v[102:105]
	v_pk_fma_f32 v[180:181], v[10:11], v[176:177], v[180:181] op_sel:[0,1,0]
	v_pk_fma_f32 v[192:193], v[12:13], v[176:177], v[192:193] op_sel:[0,1,0]
	v_pk_fma_f32 v[180:181], v[6:7], v[178:179], v[180:181] op_sel_hi:[1,0,1]
	v_pk_fma_f32 v[192:193], v[8:9], v[178:179], v[192:193] op_sel_hi:[1,0,1]
	v_mfma_f32_16x16x4_f32 v[98:101], v141, v73, v[98:101]
	v_pk_fma_f32 v[180:181], v[2:3], v[178:179], v[180:181] op_sel:[0,1,0]
	v_pk_fma_f32 v[192:193], v[4:5], v[178:179], v[192:193] op_sel:[0,1,0]
	v_pk_mul_f32 v[180:181], v[146:147], v[180:181]
	v_pk_mul_f32 v[192:193], v[146:147], v[192:193]
	v_pk_fma_f32 v[236:237], v[144:145], v[70:71], v[180:181]
	v_pk_fma_f32 v[238:239], v[144:145], v[72:73], v[192:193]
	global_store_dwordx4 v[150:151], v[236:239], off nt
	v_lshl_add_u64 v[150:151], v[150:151], 0, s[74:75]
	global_load_dwordx4 v[70:73], v[148:149], off nt
	v_lshl_add_u64 v[148:149], v[148:149], 0, s[74:75]
	ds_read_b32 v141, v160 offset:288
	ds_read_b128 v[114:117], v161 offset:2304
	ds_read_b128 v[176:179], v161 offset:2320
	s_waitcnt vmcnt(14)
; #define RS_LOAD(dst, it0) do { _Pragma("unroll") for (int u = 0; u < 8; ++u) dst[u] = __builtin_nontemporal_load((const f32x4*)(S0 + (size_t)(4 * ((it0) + u)) * DV)); } while (0)
; __device__ __forceinline__ void ret_sample_item(Frame& F, int item) {
;     ...
;     for (int it0 = 0; it0 < 64; it0 += 16) {
;         RS_LOAD(sb, it0 + 8);
;         RS_PROC(sa, it0);
;         { const int itn = it0 + 16 < 64 ? it0 + 16 : it0; RS_LOAD(sa, itn); }
;         RS_PROC(sb, it0 + 8);
;     }
	s_waitcnt lgkmcnt(3)
	v_cndmask_b32_e64 v143, 0, v143, s[8:9]
	v_pk_mul_f32 v[180:181], v[26:27], v[172:173] op_sel:[0,1]
	v_pk_mul_f32 v[192:193], v[28:29], v[172:173] op_sel:[0,1]
	v_mfma_f32_16x16x4_f32 v[110:113], v143, v62, v[110:113]
	v_pk_fma_f32 v[180:181], v[30:31], v[172:173], v[180:181] op_sel_hi:[1,0,1]
	v_pk_fma_f32 v[192:193], v[32:33], v[172:173], v[192:193] op_sel_hi:[1,0,1]
	v_pk_fma_f32 v[180:181], v[22:23], v[174:175], v[180:181] op_sel_hi:[1,0,1]
	v_pk_fma_f32 v[192:193], v[24:25], v[174:175], v[192:193] op_sel_hi:[1,0,1]
	v_mfma_f32_16x16x4_f32 v[106:109], v143, v63, v[106:109]
	v_pk_fma_f32 v[180:181], v[18:19], v[174:175], v[180:181] op_sel:[0,1,0]
	v_pk_fma_f32 v[192:193], v[20:21], v[174:175], v[192:193] op_sel:[0,1,0]
	v_pk_fma_f32 v[180:181], v[14:15], v[232:233], v[180:181] op_sel_hi:[1,0,1]
	v_pk_fma_f32 v[192:193], v[16:17], v[232:233], v[192:193] op_sel_hi:[1,0,1]
	v_mfma_f32_16x16x4_f32 v[102:105], v143, v64, v[102:105]
	v_pk_fma_f32 v[180:181], v[10:11], v[232:233], v[180:181] op_sel:[0,1,0]
	v_pk_fma_f32 v[192:193], v[12:13], v[232:233], v[192:193] op_sel:[0,1,0]
	v_pk_fma_f32 v[180:181], v[6:7], v[234:235], v[180:181] op_sel_hi:[1,0,1]
	v_pk_fma_f32 v[192:193], v[8:9], v[234:235], v[192:193] op_sel_hi:[1,0,1]
	v_mfma_f32_16x16x4_f32 v[98:101], v143, v65, v[98:101]
	v_pk_fma_f32 v[180:181], v[2:3], v[234:235], v[180:181] op_sel:[0,1,0]
	v_pk_fma_f32 v[192:193], v[4:5], v[234:235], v[192:193] op_sel:[0,1,0]
	v_pk_mul_f32 v[180:181], v[146:147], v[180:181]
	v_pk_mul_f32 v[192:193], v[146:147], v[192:193]
	v_pk_fma_f32 v[236:237], v[144:145], v[62:63], v[180:181]
	v_pk_fma_f32 v[238:239], v[144:145], v[64:65], v[192:193]
	global_store_dwordx4 v[150:151], v[236:239], off nt
	v_lshl_add_u64 v[150:151], v[150:151], 0, s[74:75]
	global_load_dwordx4 v[62:65], v[148:149], off nt
	v_lshl_add_u64 v[148:149], v[148:149], 0, s[74:75]
	ds_read_b32 v143, v160 offset:304
	ds_read_b128 v[172:175], v161 offset:2432
	ds_read_b128 v[232:235], v161 offset:2448
	s_waitcnt vmcnt(14)
	s_waitcnt lgkmcnt(3)
	v_cndmask_b32_e64 v141, 0, v141, s[8:9]
	v_pk_mul_f32 v[180:181], v[26:27], v[114:115] op_sel:[0,1]
	v_pk_mul_f32 v[192:193], v[28:29], v[114:115] op_sel:[0,1]
	v_mfma_f32_16x16x4_f32 v[110:113], v141, v54, v[110:113]
	v_pk_fma_f32 v[180:181], v[30:31], v[114:115], v[180:181] op_sel_hi:[1,0,1]
	v_pk_fma_f32 v[192:193], v[32:33], v[114:115], v[192:193] op_sel_hi:[1,0,1]
	v_pk_fma_f32 v[180:181], v[22:23], v[116:117], v[180:181] op_sel_hi:[1,0,1]
	v_pk_fma_f32 v[192:193], v[24:25], v[116:117], v[192:193] op_sel_hi:[1,0,1]
	v_mfma_f32_16x16x4_f32 v[106:109], v141, v55, v[106:109]
	v_pk_fma_f32 v[180:181], v[18:19], v[116:117], v[180:181] op_sel:[0,1,0]
	v_pk_fma_f32 v[192:193], v[20:21], v[116:117], v[192:193] op_sel:[0,1,0]
	v_pk_fma_f32 v[180:181], v[14:15], v[176:177], v[180:181] op_sel_hi:[1,0,1]
	v_pk_fma_f32 v[192:193], v[16:17], v[176:177], v[192:193] op_sel_hi:[1,0,1]
	v_mfma_f32_16x16x4_f32 v[102:105], v141, v56, v[102:105]
	v_pk_fma_f32 v[180:181], v[10:11], v[176:177], v[180:181] op_sel:[0,1,0]
	v_pk_fma_f32 v[192:193], v[12:13], v[176:177], v[192:193] op_sel:[0,1,0]
	v_pk_fma_f32 v[180:181], v[6:7], v[178:179], v[180:181] op_sel_hi:[1,0,1]
	v_pk_fma_f32 v[192:193], v[8:9], v[178:179], v[192:193] op_sel_hi:[1,0,1]
	v_mfma_f32_16x16x4_f32 v[98:101], v141, v57, v[98:101]
	v_pk_fma_f32 v[180:181], v[2:3], v[178:179], v[180:181] op_sel:[0,1,0]
	v_pk_fma_f32 v[192:193], v[4:5], v[178:179], v[192:193] op_sel:[0,1,0]
	v_pk_mul_f32 v[180:181], v[146:147], v[180:181]
	v_pk_mul_f32 v[192:193], v[146:147], v[192:193]
	v_pk_fma_f32 v[236:237], v[144:145], v[54:55], v[180:181]
	v_pk_fma_f32 v[238:239], v[144:145], v[56:57], v[192:193]
	global_store_dwordx4 v[150:151], v[236:239], off nt
	v_lshl_add_u64 v[150:151], v[150:151], 0, s[74:75]
	global_load_dwordx4 v[54:57], v[148:149], off nt
	v_lshl_add_u64 v[148:149], v[148:149], 0, s[74:75]
	ds_read_b32 v141, v160 offset:320
	ds_read_b128 v[114:117], v161 offset:2560
	ds_read_b128 v[176:179], v161 offset:2576
	s_waitcnt vmcnt(14)
	s_waitcnt lgkmcnt(3)
	v_cndmask_b32_e64 v143, 0, v143, s[8:9]
	v_pk_mul_f32 v[180:181], v[26:27], v[172:173] op_sel:[0,1]
	v_pk_mul_f32 v[192:193], v[28:29], v[172:173] op_sel:[0,1]
	v_mfma_f32_16x16x4_f32 v[110:113], v143, v50, v[110:113]
	v_pk_fma_f32 v[180:181], v[30:31], v[172:173], v[180:181] op_sel_hi:[1,0,1]
	v_pk_fma_f32 v[192:193], v[32:33], v[172:173], v[192:193] op_sel_hi:[1,0,1]
	v_pk_fma_f32 v[180:181], v[22:23], v[174:175], v[180:181] op_sel_hi:[1,0,1]
	v_pk_fma_f32 v[192:193], v[24:25], v[174:175], v[192:193] op_sel_hi:[1,0,1]
	v_mfma_f32_16x16x4_f32 v[106:109], v143, v51, v[106:109]
	v_pk_fma_f32 v[180:181], v[18:19], v[174:175], v[180:181] op_sel:[0,1,0]
	v_pk_fma_f32 v[192:193], v[20:21], v[174:175], v[192:193] op_sel:[0,1,0]
	v_pk_fma_f32 v[180:181], v[14:15], v[232:233], v[180:181] op_sel_hi:[1,0,1]
	v_pk_fma_f32 v[192:193], v[16:17], v[232:233], v[192:193] op_sel_hi:[1,0,1]
	v_mfma_f32_16x16x4_f32 v[102:105], v143, v52, v[102:105]
	v_pk_fma_f32 v[180:181], v[10:11], v[232:233], v[180:181] op_sel:[0,1,0]
	v_pk_fma_f32 v[192:193], v[12:13], v[232:233], v[192:193] op_sel:[0,1,0]
	v_pk_fma_f32 v[180:181], v[6:7], v[234:235], v[180:181] op_sel_hi:[1,0,1]
	v_pk_fma_f32 v[192:193], v[8:9], v[234:235], v[192:193] op_sel_hi:[1,0,1]
	v_mfma_f32_16x16x4_f32 v[98:101], v143, v53, v[98:101]
	v_pk_fma_f32 v[180:181], v[2:3], v[234:235], v[180:181] op_sel:[0,1,0]
	v_pk_fma_f32 v[192:193], v[4:5], v[234:235], v[192:193] op_sel:[0,1,0]
	v_pk_mul_f32 v[180:181], v[146:147], v[180:181]
	v_pk_mul_f32 v[192:193], v[146:147], v[192:193]
	v_pk_fma_f32 v[236:237], v[144:145], v[50:51], v[180:181]
	v_pk_fma_f32 v[238:239], v[144:145], v[52:53], v[192:193]
	global_store_dwordx4 v[150:151], v[236:239], off nt
	v_lshl_add_u64 v[150:151], v[150:151], 0, s[74:75]
	global_load_dwordx4 v[50:53], v[148:149], off nt
	v_lshl_add_u64 v[148:149], v[148:149], 0, s[74:75]
	ds_read_b32 v143, v160 offset:336
	ds_read_b128 v[172:175], v161 offset:2688
	ds_read_b128 v[232:235], v161 offset:2704
	s_waitcnt vmcnt(14)
; #define RS_LOAD(dst, it0) do { _Pragma("unroll") for (int u = 0; u < 8; ++u) dst[u] = __builtin_nontemporal_load((const f32x4*)(S0 + (size_t)(4 * ((it0) + u)) * DV)); } while (0)
; __device__ __forceinline__ void ret_sample_item(Frame& F, int item) {
;     ...
;     for (int it0 = 0; it0 < 64; it0 += 16) {
;         RS_LOAD(sb, it0 + 8);
;         RS_PROC(sa, it0);
;         { const int itn = it0 + 16 < 64 ? it0 + 16 : it0; RS_LOAD(sa, itn); }
;         RS_PROC(sb, it0 + 8);
;     }
	s_waitcnt lgkmcnt(3)
	v_cndmask_b32_e64 v141, 0, v141, s[8:9]
	v_pk_mul_f32 v[180:181], v[26:27], v[114:115] op_sel:[0,1]
	v_pk_mul_f32 v[192:193], v[28:29], v[114:115] op_sel:[0,1]
	v_mfma_f32_16x16x4_f32 v[110:113], v141, v46, v[110:113]
	v_pk_fma_f32 v[180:181], v[30:31], v[114:115], v[180:181] op_sel_hi:[1,0,1]
	v_pk_fma_f32 v[192:193], v[32:33], v[114:115], v[192:193] op_sel_hi:[1,0,1]
	v_pk_fma_f32 v[180:181], v[22:23], v[116:117], v[180:181] op_sel_hi:[1,0,1]
	v_pk_fma_f32 v[192:193], v[24:25], v[116:117], v[192:193] op_sel_hi:[1,0,1]
	v_mfma_f32_16x16x4_f32 v[106:109], v141, v47, v[106:109]
	v_pk_fma_f32 v[180:181], v[18:19], v[116:117], v[180:181] op_sel:[0,1,0]
	v_pk_fma_f32 v[192:193], v[20:21], v[116:117], v[192:193] op_sel:[0,1,0]
	v_pk_fma_f32 v[180:181], v[14:15], v[176:177], v[180:181] op_sel_hi:[1,0,1]
	v_pk_fma_f32 v[192:193], v[16:17], v[176:177], v[192:193] op_sel_hi:[1,0,1]
	v_mfma_f32_16x16x4_f32 v[102:105], v141, v48, v[102:105]
	v_pk_fma_f32 v[180:181], v[10:11], v[176:177], v[180:181] op_sel:[0,1,0]
	v_pk_fma_f32 v[192:193], v[12:13], v[176:177], v[192:193] op_sel:[0,1,0]
	v_pk_fma_f32 v[180:181], v[6:7], v[178:179], v[180:181] op_sel_hi:[1,0,1]
	v_pk_fma_f32 v[192:193], v[8:9], v[178:179], v[192:193] op_sel_hi:[1,0,1]
	v_mfma_f32_16x16x4_f32 v[98:101], v141, v49, v[98:101]
	v_pk_fma_f32 v[180:181], v[2:3], v[178:179], v[180:181] op_sel:[0,1,0]
	v_pk_fma_f32 v[192:193], v[4:5], v[178:179], v[192:193] op_sel:[0,1,0]
	v_pk_mul_f32 v[180:181], v[146:147], v[180:181]
	v_pk_mul_f32 v[192:193], v[146:147], v[192:193]
	v_pk_fma_f32 v[236:237], v[144:145], v[46:47], v[180:181]
	v_pk_fma_f32 v[238:239], v[144:145], v[48:49], v[192:193]
	global_store_dwordx4 v[150:151], v[236:239], off nt
	v_lshl_add_u64 v[150:151], v[150:151], 0, s[74:75]
	global_load_dwordx4 v[46:49], v[148:149], off nt
	v_lshl_add_u64 v[148:149], v[148:149], 0, s[74:75]
	ds_read_b32 v141, v160 offset:352
	ds_read_b128 v[114:117], v161 offset:2816
	ds_read_b128 v[176:179], v161 offset:2832
	s_waitcnt vmcnt(14)
	s_waitcnt lgkmcnt(3)
	v_cndmask_b32_e64 v143, 0, v143, s[8:9]
	v_pk_mul_f32 v[180:181], v[26:27], v[172:173] op_sel:[0,1]
	v_pk_mul_f32 v[192:193], v[28:29], v[172:173] op_sel:[0,1]
	v_mfma_f32_16x16x4_f32 v[110:113], v143, v42, v[110:113]
	v_pk_fma_f32 v[180:181], v[30:31], v[172:173], v[180:181] op_sel_hi:[1,0,1]
	v_pk_fma_f32 v[192:193], v[32:33], v[172:173], v[192:193] op_sel_hi:[1,0,1]
	v_pk_fma_f32 v[180:181], v[22:23], v[174:175], v[180:181] op_sel_hi:[1,0,1]
	v_pk_fma_f32 v[192:193], v[24:25], v[174:175], v[192:193] op_sel_hi:[1,0,1]
	v_mfma_f32_16x16x4_f32 v[106:109], v143, v43, v[106:109]
	v_pk_fma_f32 v[180:181], v[18:19], v[174:175], v[180:181] op_sel:[0,1,0]
	v_pk_fma_f32 v[192:193], v[20:21], v[174:175], v[192:193] op_sel:[0,1,0]
	v_pk_fma_f32 v[180:181], v[14:15], v[232:233], v[180:181] op_sel_hi:[1,0,1]
	v_pk_fma_f32 v[192:193], v[16:17], v[232:233], v[192:193] op_sel_hi:[1,0,1]
	v_mfma_f32_16x16x4_f32 v[102:105], v143, v44, v[102:105]
	v_pk_fma_f32 v[180:181], v[10:11], v[232:233], v[180:181] op_sel:[0,1,0]
	v_pk_fma_f32 v[192:193], v[12:13], v[232:233], v[192:193] op_sel:[0,1,0]
	v_pk_fma_f32 v[180:181], v[6:7], v[234:235], v[180:181] op_sel_hi:[1,0,1]
	v_pk_fma_f32 v[192:193], v[8:9], v[234:235], v[192:193] op_sel_hi:[1,0,1]
	v_mfma_f32_16x16x4_f32 v[98:101], v143, v45, v[98:101]
	v_pk_fma_f32 v[180:181], v[2:3], v[234:235], v[180:181] op_sel:[0,1,0]
	v_pk_fma_f32 v[192:193], v[4:5], v[234:235], v[192:193] op_sel:[0,1,0]
	v_pk_mul_f32 v[180:181], v[146:147], v[180:181]
	v_pk_mul_f32 v[192:193], v[146:147], v[192:193]
	v_pk_fma_f32 v[236:237], v[144:145], v[42:43], v[180:181]
	v_pk_fma_f32 v[238:239], v[144:145], v[44:45], v[192:193]
	global_store_dwordx4 v[150:151], v[236:239], off nt
	v_lshl_add_u64 v[150:151], v[150:151], 0, s[74:75]
	global_load_dwordx4 v[42:45], v[148:149], off nt
	v_lshl_add_u64 v[148:149], v[148:149], 0, s[74:75]
	ds_read_b32 v143, v160 offset:368
	ds_read_b128 v[172:175], v161 offset:2944
	ds_read_b128 v[232:235], v161 offset:2960
	s_waitcnt vmcnt(14)
	s_waitcnt lgkmcnt(3)
	v_cndmask_b32_e64 v141, 0, v141, s[8:9]
	v_pk_mul_f32 v[180:181], v[26:27], v[114:115] op_sel:[0,1]
	v_pk_mul_f32 v[192:193], v[28:29], v[114:115] op_sel:[0,1]
	v_mfma_f32_16x16x4_f32 v[110:113], v141, v38, v[110:113]
	v_pk_fma_f32 v[180:181], v[30:31], v[114:115], v[180:181] op_sel_hi:[1,0,1]
	v_pk_fma_f32 v[192:193], v[32:33], v[114:115], v[192:193] op_sel_hi:[1,0,1]
	v_pk_fma_f32 v[180:181], v[22:23], v[116:117], v[180:181] op_sel_hi:[1,0,1]
	v_pk_fma_f32 v[192:193], v[24:25], v[116:117], v[192:193] op_sel_hi:[1,0,1]
	v_mfma_f32_16x16x4_f32 v[106:109], v141, v39, v[106:109]
	v_pk_fma_f32 v[180:181], v[18:19], v[116:117], v[180:181] op_sel:[0,1,0]
	v_pk_fma_f32 v[192:193], v[20:21], v[116:117], v[192:193] op_sel:[0,1,0]
	v_pk_fma_f32 v[180:181], v[14:15], v[176:177], v[180:181] op_sel_hi:[1,0,1]
	v_pk_fma_f32 v[192:193], v[16:17], v[176:177], v[192:193] op_sel_hi:[1,0,1]
	v_mfma_f32_16x16x4_f32 v[102:105], v141, v40, v[102:105]
	v_pk_fma_f32 v[180:181], v[10:11], v[176:177], v[180:181] op_sel:[0,1,0]
	v_pk_fma_f32 v[192:193], v[12:13], v[176:177], v[192:193] op_sel:[0,1,0]
	v_pk_fma_f32 v[180:181], v[6:7], v[178:179], v[180:181] op_sel_hi:[1,0,1]
	v_pk_fma_f32 v[192:193], v[8:9], v[178:179], v[192:193] op_sel_hi:[1,0,1]
	v_mfma_f32_16x16x4_f32 v[98:101], v141, v41, v[98:101]
	v_pk_fma_f32 v[180:181], v[2:3], v[178:179], v[180:181] op_sel:[0,1,0]
	v_pk_fma_f32 v[192:193], v[4:5], v[178:179], v[192:193] op_sel:[0,1,0]
	v_pk_mul_f32 v[180:181], v[146:147], v[180:181]
	v_pk_mul_f32 v[192:193], v[146:147], v[192:193]
	v_pk_fma_f32 v[236:237], v[144:145], v[38:39], v[180:181]
	v_pk_fma_f32 v[238:239], v[144:145], v[40:41], v[192:193]
	global_store_dwordx4 v[150:151], v[236:239], off nt
	v_lshl_add_u64 v[150:151], v[150:151], 0, s[74:75]
	global_load_dwordx4 v[38:41], v[148:149], off nt
	v_lshl_add_u64 v[148:149], v[148:149], 0, s[74:75]
	ds_read_b32 v141, v160 offset:384
	ds_read_b128 v[114:117], v161 offset:3072
	ds_read_b128 v[176:179], v161 offset:3088
	s_waitcnt vmcnt(14)
; #define RS_LOAD(dst, it0) do { _Pragma("unroll") for (int u = 0; u < 8; ++u) dst[u] = __builtin_nontemporal_load((const f32x4*)(S0 + (size_t)(4 * ((it0) + u)) * DV)); } while (0)
; __device__ __forceinline__ void ret_sample_item(Frame& F, int item) {
;     ...
;     for (int it0 = 0; it0 < 64; it0 += 16) {
;         RS_LOAD(sb, it0 + 8);
;         RS_PROC(sa, it0);
;         { const int itn = it0 + 16 < 64 ? it0 + 16 : it0; RS_LOAD(sa, itn); }
;         RS_PROC(sb, it0 + 8);
;     }
	s_waitcnt lgkmcnt(3)
	v_cndmask_b32_e64 v143, 0, v143, s[8:9]
	v_pk_mul_f32 v[180:181], v[26:27], v[172:173] op_sel:[0,1]
	v_pk_mul_f32 v[192:193], v[28:29], v[172:173] op_sel:[0,1]
	v_mfma_f32_16x16x4_f32 v[110:113], v143, v34, v[110:113]
	v_pk_fma_f32 v[180:181], v[30:31], v[172:173], v[180:181] op_sel_hi:[1,0,1]
	v_pk_fma_f32 v[192:193], v[32:33], v[172:173], v[192:193] op_sel_hi:[1,0,1]
	v_pk_fma_f32 v[180:181], v[22:23], v[174:175], v[180:181] op_sel_hi:[1,0,1]
	v_pk_fma_f32 v[192:193], v[24:25], v[174:175], v[192:193] op_sel_hi:[1,0,1]
	v_mfma_f32_16x16x4_f32 v[106:109], v143, v35, v[106:109]
	v_pk_fma_f32 v[180:181], v[18:19], v[174:175], v[180:181] op_sel:[0,1,0]
	v_pk_fma_f32 v[192:193], v[20:21], v[174:175], v[192:193] op_sel:[0,1,0]
	v_pk_fma_f32 v[180:181], v[14:15], v[232:233], v[180:181] op_sel_hi:[1,0,1]
	v_pk_fma_f32 v[192:193], v[16:17], v[232:233], v[192:193] op_sel_hi:[1,0,1]
	v_mfma_f32_16x16x4_f32 v[102:105], v143, v36, v[102:105]
	v_pk_fma_f32 v[180:181], v[10:11], v[232:233], v[180:181] op_sel:[0,1,0]
	v_pk_fma_f32 v[192:193], v[12:13], v[232:233], v[192:193] op_sel:[0,1,0]
	v_pk_fma_f32 v[180:181], v[6:7], v[234:235], v[180:181] op_sel_hi:[1,0,1]
	v_pk_fma_f32 v[192:193], v[8:9], v[234:235], v[192:193] op_sel_hi:[1,0,1]
	v_mfma_f32_16x16x4_f32 v[98:101], v143, v37, v[98:101]
	v_pk_fma_f32 v[180:181], v[2:3], v[234:235], v[180:181] op_sel:[0,1,0]
	v_pk_fma_f32 v[192:193], v[4:5], v[234:235], v[192:193] op_sel:[0,1,0]
	v_pk_mul_f32 v[180:181], v[146:147], v[180:181]
	v_pk_mul_f32 v[192:193], v[146:147], v[192:193]
	v_pk_fma_f32 v[236:237], v[144:145], v[34:35], v[180:181]
	v_pk_fma_f32 v[238:239], v[144:145], v[36:37], v[192:193]
	global_store_dwordx4 v[150:151], v[236:239], off nt
	v_lshl_add_u64 v[150:151], v[150:151], 0, s[74:75]
	global_load_dwordx4 v[34:37], v[148:149], off nt
	v_lshl_add_u64 v[148:149], v[148:149], 0, s[74:75]
	ds_read_b32 v143, v160 offset:400
	ds_read_b128 v[172:175], v161 offset:3200
	ds_read_b128 v[232:235], v161 offset:3216
	s_waitcnt vmcnt(14)
	s_waitcnt lgkmcnt(3)
	v_cndmask_b32_e64 v141, 0, v141, s[8:9]
	v_pk_mul_f32 v[180:181], v[26:27], v[114:115] op_sel:[0,1]
	v_pk_mul_f32 v[192:193], v[28:29], v[114:115] op_sel:[0,1]
	v_mfma_f32_16x16x4_f32 v[110:113], v141, v70, v[110:113]
	v_pk_fma_f32 v[180:181], v[30:31], v[114:115], v[180:181] op_sel_hi:[1,0,1]
	v_pk_fma_f32 v[192:193], v[32:33], v[114:115], v[192:193] op_sel_hi:[1,0,1]
	v_pk_fma_f32 v[180:181], v[22:23], v[116:117], v[180:181] op_sel_hi:[1,0,1]
	v_pk_fma_f32 v[192:193], v[24:25], v[116:117], v[192:193] op_sel_hi:[1,0,1]
	v_mfma_f32_16x16x4_f32 v[106:109], v141, v71, v[106:109]
	v_pk_fma_f32 v[180:181], v[18:19], v[116:117], v[180:181] op_sel:[0,1,0]
	v_pk_fma_f32 v[192:193], v[20:21], v[116:117], v[192:193] op_sel:[0,1,0]
	v_pk_fma_f32 v[180:181], v[14:15], v[176:177], v[180:181] op_sel_hi:[1,0,1]
	v_pk_fma_f32 v[192:193], v[16:17], v[176:177], v[192:193] op_sel_hi:[1,0,1]
	v_mfma_f32_16x16x4_f32 v[102:105], v141, v72, v[102:105]
	v_pk_fma_f32 v[180:181], v[10:11], v[176:177], v[180:181] op_sel:[0,1,0]
	v_pk_fma_f32 v[192:193], v[12:13], v[176:177], v[192:193] op_sel:[0,1,0]
	v_pk_fma_f32 v[180:181], v[6:7], v[178:179], v[180:181] op_sel_hi:[1,0,1]
	v_pk_fma_f32 v[192:193], v[8:9], v[178:179], v[192:193] op_sel_hi:[1,0,1]
	v_mfma_f32_16x16x4_f32 v[98:101], v141, v73, v[98:101]
	v_pk_fma_f32 v[180:181], v[2:3], v[178:179], v[180:181] op_sel:[0,1,0]
	v_pk_fma_f32 v[192:193], v[4:5], v[178:179], v[192:193] op_sel:[0,1,0]
	v_pk_mul_f32 v[180:181], v[146:147], v[180:181]
	v_pk_mul_f32 v[192:193], v[146:147], v[192:193]
	v_pk_fma_f32 v[236:237], v[144:145], v[70:71], v[180:181]
	v_pk_fma_f32 v[238:239], v[144:145], v[72:73], v[192:193]
	global_store_dwordx4 v[150:151], v[236:239], off nt
	v_lshl_add_u64 v[150:151], v[150:151], 0, s[74:75]
	global_load_dwordx4 v[70:73], v[148:149], off nt
	v_lshl_add_u64 v[148:149], v[148:149], 0, s[74:75]
	ds_read_b32 v141, v160 offset:416
	ds_read_b128 v[114:117], v161 offset:3328
	ds_read_b128 v[176:179], v161 offset:3344
	s_waitcnt vmcnt(14)
	s_waitcnt lgkmcnt(3)
	v_cndmask_b32_e64 v143, 0, v143, s[8:9]
	v_pk_mul_f32 v[180:181], v[26:27], v[172:173] op_sel:[0,1]
	v_pk_mul_f32 v[192:193], v[28:29], v[172:173] op_sel:[0,1]
	v_mfma_f32_16x16x4_f32 v[110:113], v143, v62, v[110:113]
	v_pk_fma_f32 v[180:181], v[30:31], v[172:173], v[180:181] op_sel_hi:[1,0,1]
	v_pk_fma_f32 v[192:193], v[32:33], v[172:173], v[192:193] op_sel_hi:[1,0,1]
	v_pk_fma_f32 v[180:181], v[22:23], v[174:175], v[180:181] op_sel_hi:[1,0,1]
	v_pk_fma_f32 v[192:193], v[24:25], v[174:175], v[192:193] op_sel_hi:[1,0,1]
	v_mfma_f32_16x16x4_f32 v[106:109], v143, v63, v[106:109]
	v_pk_fma_f32 v[180:181], v[18:19], v[174:175], v[180:181] op_sel:[0,1,0]
	v_pk_fma_f32 v[192:193], v[20:21], v[174:175], v[192:193] op_sel:[0,1,0]
	v_pk_fma_f32 v[180:181], v[14:15], v[232:233], v[180:181] op_sel_hi:[1,0,1]
	v_pk_fma_f32 v[192:193], v[16:17], v[232:233], v[192:193] op_sel_hi:[1,0,1]
	v_mfma_f32_16x16x4_f32 v[102:105], v143, v64, v[102:105]
	v_pk_fma_f32 v[180:181], v[10:11], v[232:233], v[180:181] op_sel:[0,1,0]
	v_pk_fma_f32 v[192:193], v[12:13], v[232:233], v[192:193] op_sel:[0,1,0]
	v_pk_fma_f32 v[180:181], v[6:7], v[234:235], v[180:181] op_sel_hi:[1,0,1]
	v_pk_fma_f32 v[192:193], v[8:9], v[234:235], v[192:193] op_sel_hi:[1,0,1]
	v_mfma_f32_16x16x4_f32 v[98:101], v143, v65, v[98:101]
	v_pk_fma_f32 v[180:181], v[2:3], v[234:235], v[180:181] op_sel:[0,1,0]
	v_pk_fma_f32 v[192:193], v[4:5], v[234:235], v[192:193] op_sel:[0,1,0]
	v_pk_mul_f32 v[180:181], v[146:147], v[180:181]
	v_pk_mul_f32 v[192:193], v[146:147], v[192:193]
	v_pk_fma_f32 v[236:237], v[144:145], v[62:63], v[180:181]
	v_pk_fma_f32 v[238:239], v[144:145], v[64:65], v[192:193]
	global_store_dwordx4 v[150:151], v[236:239], off nt
	v_lshl_add_u64 v[150:151], v[150:151], 0, s[74:75]
	global_load_dwordx4 v[62:65], v[148:149], off nt
	v_lshl_add_u64 v[148:149], v[148:149], 0, s[74:75]
	ds_read_b32 v143, v160 offset:432
	ds_read_b128 v[172:175], v161 offset:3456
	ds_read_b128 v[232:235], v161 offset:3472
	s_waitcnt vmcnt(14)
; #define RS_LOAD(dst, it0) do { _Pragma("unroll") for (int u = 0; u < 8; ++u) dst[u] = __builtin_nontemporal_load((const f32x4*)(S0 + (size_t)(4 * ((it0) + u)) * DV)); } while (0)
; __device__ __forceinline__ void ret_sample_item(Frame& F, int item) {
;     ...
;     for (int it0 = 0; it0 < 64; it0 += 16) {
;         RS_LOAD(sb, it0 + 8);
;         RS_PROC(sa, it0);
;         { const int itn = it0 + 16 < 64 ? it0 + 16 : it0; RS_LOAD(sa, itn); }
;         RS_PROC(sb, it0 + 8);
;     }
	s_waitcnt lgkmcnt(3)
	v_cndmask_b32_e64 v141, 0, v141, s[8:9]
	v_pk_mul_f32 v[180:181], v[26:27], v[114:115] op_sel:[0,1]
	v_pk_mul_f32 v[192:193], v[28:29], v[114:115] op_sel:[0,1]
	v_mfma_f32_16x16x4_f32 v[110:113], v141, v54, v[110:113]
	v_pk_fma_f32 v[180:181], v[30:31], v[114:115], v[180:181] op_sel_hi:[1,0,1]
	v_pk_fma_f32 v[192:193], v[32:33], v[114:115], v[192:193] op_sel_hi:[1,0,1]
	v_pk_fma_f32 v[180:181], v[22:23], v[116:117], v[180:181] op_sel_hi:[1,0,1]
	v_pk_fma_f32 v[192:193], v[24:25], v[116:117], v[192:193] op_sel_hi:[1,0,1]
	v_mfma_f32_16x16x4_f32 v[106:109], v141, v55, v[106:109]
	v_pk_fma_f32 v[180:181], v[18:19], v[116:117], v[180:181] op_sel:[0,1,0]
	v_pk_fma_f32 v[192:193], v[20:21], v[116:117], v[192:193] op_sel:[0,1,0]
	v_pk_fma_f32 v[180:181], v[14:15], v[176:177], v[180:181] op_sel_hi:[1,0,1]
	v_pk_fma_f32 v[192:193], v[16:17], v[176:177], v[192:193] op_sel_hi:[1,0,1]
	v_mfma_f32_16x16x4_f32 v[102:105], v141, v56, v[102:105]
	v_pk_fma_f32 v[180:181], v[10:11], v[176:177], v[180:181] op_sel:[0,1,0]
	v_pk_fma_f32 v[192:193], v[12:13], v[176:177], v[192:193] op_sel:[0,1,0]
	v_pk_fma_f32 v[180:181], v[6:7], v[178:179], v[180:181] op_sel_hi:[1,0,1]
	v_pk_fma_f32 v[192:193], v[8:9], v[178:179], v[192:193] op_sel_hi:[1,0,1]
	v_mfma_f32_16x16x4_f32 v[98:101], v141, v57, v[98:101]
	v_pk_fma_f32 v[180:181], v[2:3], v[178:179], v[180:181] op_sel:[0,1,0]
	v_pk_fma_f32 v[192:193], v[4:5], v[178:179], v[192:193] op_sel:[0,1,0]
	v_pk_mul_f32 v[180:181], v[146:147], v[180:181]
	v_pk_mul_f32 v[192:193], v[146:147], v[192:193]
	v_pk_fma_f32 v[236:237], v[144:145], v[54:55], v[180:181]
	v_pk_fma_f32 v[238:239], v[144:145], v[56:57], v[192:193]
	global_store_dwordx4 v[150:151], v[236:239], off nt
	v_lshl_add_u64 v[150:151], v[150:151], 0, s[74:75]
	global_load_dwordx4 v[54:57], v[148:149], off nt
	v_lshl_add_u64 v[148:149], v[148:149], 0, s[74:75]
	ds_read_b32 v141, v160 offset:448
	ds_read_b128 v[114:117], v161 offset:3584
	ds_read_b128 v[176:179], v161 offset:3600
	s_waitcnt vmcnt(14)
	s_waitcnt lgkmcnt(3)
	v_cndmask_b32_e64 v143, 0, v143, s[8:9]
	v_pk_mul_f32 v[180:181], v[26:27], v[172:173] op_sel:[0,1]
	v_pk_mul_f32 v[192:193], v[28:29], v[172:173] op_sel:[0,1]
	v_mfma_f32_16x16x4_f32 v[110:113], v143, v50, v[110:113]
	v_pk_fma_f32 v[180:181], v[30:31], v[172:173], v[180:181] op_sel_hi:[1,0,1]
	v_pk_fma_f32 v[192:193], v[32:33], v[172:173], v[192:193] op_sel_hi:[1,0,1]
	v_pk_fma_f32 v[180:181], v[22:23], v[174:175], v[180:181] op_sel_hi:[1,0,1]
	v_pk_fma_f32 v[192:193], v[24:25], v[174:175], v[192:193] op_sel_hi:[1,0,1]
	v_mfma_f32_16x16x4_f32 v[106:109], v143, v51, v[106:109]
	v_pk_fma_f32 v[180:181], v[18:19], v[174:175], v[180:181] op_sel:[0,1,0]
	v_pk_fma_f32 v[192:193], v[20:21], v[174:175], v[192:193] op_sel:[0,1,0]
	v_pk_fma_f32 v[180:181], v[14:15], v[232:233], v[180:181] op_sel_hi:[1,0,1]
	v_pk_fma_f32 v[192:193], v[16:17], v[232:233], v[192:193] op_sel_hi:[1,0,1]
	v_mfma_f32_16x16x4_f32 v[102:105], v143, v52, v[102:105]
	v_pk_fma_f32 v[180:181], v[10:11], v[232:233], v[180:181] op_sel:[0,1,0]
	v_pk_fma_f32 v[192:193], v[12:13], v[232:233], v[192:193] op_sel:[0,1,0]
	v_pk_fma_f32 v[180:181], v[6:7], v[234:235], v[180:181] op_sel_hi:[1,0,1]
	v_pk_fma_f32 v[192:193], v[8:9], v[234:235], v[192:193] op_sel_hi:[1,0,1]
	v_mfma_f32_16x16x4_f32 v[98:101], v143, v53, v[98:101]
	v_pk_fma_f32 v[180:181], v[2:3], v[234:235], v[180:181] op_sel:[0,1,0]
	v_pk_fma_f32 v[192:193], v[4:5], v[234:235], v[192:193] op_sel:[0,1,0]
	v_pk_mul_f32 v[180:181], v[146:147], v[180:181]
	v_pk_mul_f32 v[192:193], v[146:147], v[192:193]
	v_pk_fma_f32 v[236:237], v[144:145], v[50:51], v[180:181]
	v_pk_fma_f32 v[238:239], v[144:145], v[52:53], v[192:193]
	global_store_dwordx4 v[150:151], v[236:239], off nt
	v_lshl_add_u64 v[150:151], v[150:151], 0, s[74:75]
	global_load_dwordx4 v[50:53], v[148:149], off nt
	v_lshl_add_u64 v[148:149], v[148:149], 0, s[74:75]
	ds_read_b32 v143, v160 offset:464
	ds_read_b128 v[172:175], v161 offset:3712
	ds_read_b128 v[232:235], v161 offset:3728
	s_waitcnt vmcnt(14)
	s_waitcnt lgkmcnt(3)
	v_cndmask_b32_e64 v141, 0, v141, s[8:9]
	v_pk_mul_f32 v[180:181], v[26:27], v[114:115] op_sel:[0,1]
	v_pk_mul_f32 v[192:193], v[28:29], v[114:115] op_sel:[0,1]
	v_mfma_f32_16x16x4_f32 v[110:113], v141, v46, v[110:113]
	v_pk_fma_f32 v[180:181], v[30:31], v[114:115], v[180:181] op_sel_hi:[1,0,1]
	v_pk_fma_f32 v[192:193], v[32:33], v[114:115], v[192:193] op_sel_hi:[1,0,1]
	v_pk_fma_f32 v[180:181], v[22:23], v[116:117], v[180:181] op_sel_hi:[1,0,1]
	v_pk_fma_f32 v[192:193], v[24:25], v[116:117], v[192:193] op_sel_hi:[1,0,1]
	v_mfma_f32_16x16x4_f32 v[106:109], v141, v47, v[106:109]
	v_pk_fma_f32 v[180:181], v[18:19], v[116:117], v[180:181] op_sel:[0,1,0]
	v_pk_fma_f32 v[192:193], v[20:21], v[116:117], v[192:193] op_sel:[0,1,0]
	v_pk_fma_f32 v[180:181], v[14:15], v[176:177], v[180:181] op_sel_hi:[1,0,1]
	v_pk_fma_f32 v[192:193], v[16:17], v[176:177], v[192:193] op_sel_hi:[1,0,1]
	v_mfma_f32_16x16x4_f32 v[102:105], v141, v48, v[102:105]
	v_pk_fma_f32 v[180:181], v[10:11], v[176:177], v[180:181] op_sel:[0,1,0]
	v_pk_fma_f32 v[192:193], v[12:13], v[176:177], v[192:193] op_sel:[0,1,0]
	v_pk_fma_f32 v[180:181], v[6:7], v[178:179], v[180:181] op_sel_hi:[1,0,1]
	v_pk_fma_f32 v[192:193], v[8:9], v[178:179], v[192:193] op_sel_hi:[1,0,1]
	v_mfma_f32_16x16x4_f32 v[98:101], v141, v49, v[98:101]
	v_pk_fma_f32 v[180:181], v[2:3], v[178:179], v[180:181] op_sel:[0,1,0]
	v_pk_fma_f32 v[192:193], v[4:5], v[178:179], v[192:193] op_sel:[0,1,0]
	v_pk_mul_f32 v[180:181], v[146:147], v[180:181]
	v_pk_mul_f32 v[192:193], v[146:147], v[192:193]
	v_pk_fma_f32 v[236:237], v[144:145], v[46:47], v[180:181]
	v_pk_fma_f32 v[238:239], v[144:145], v[48:49], v[192:193]
	global_store_dwordx4 v[150:151], v[236:239], off nt
	v_lshl_add_u64 v[150:151], v[150:151], 0, s[74:75]
	global_load_dwordx4 v[46:49], v[148:149], off nt
	v_lshl_add_u64 v[148:149], v[148:149], 0, s[74:75]
	ds_read_b32 v141, v160 offset:480
	ds_read_b128 v[114:117], v161 offset:3840
	ds_read_b128 v[176:179], v161 offset:3856
	s_waitcnt vmcnt(14)
; #define RS_LOAD(dst, it0) do { _Pragma("unroll") for (int u = 0; u < 8; ++u) dst[u] = __builtin_nontemporal_load((const f32x4*)(S0 + (size_t)(4 * ((it0) + u)) * DV)); } while (0)
; __device__ __forceinline__ void ret_sample_item(Frame& F, int item) {
;     ...
;     for (int it0 = 0; it0 < 64; it0 += 16) {
;         RS_LOAD(sb, it0 + 8);
;         RS_PROC(sa, it0);
;         { const int itn = it0 + 16 < 64 ? it0 + 16 : it0; RS_LOAD(sa, itn); }
;         RS_PROC(sb, it0 + 8);
;     }
	s_waitcnt lgkmcnt(3)
	v_cndmask_b32_e64 v143, 0, v143, s[8:9]
	v_pk_mul_f32 v[180:181], v[26:27], v[172:173] op_sel:[0,1]
	v_pk_mul_f32 v[192:193], v[28:29], v[172:173] op_sel:[0,1]
	v_mfma_f32_16x16x4_f32 v[110:113], v143, v42, v[110:113]
	v_pk_fma_f32 v[180:181], v[30:31], v[172:173], v[180:181] op_sel_hi:[1,0,1]
	v_pk_fma_f32 v[192:193], v[32:33], v[172:173], v[192:193] op_sel_hi:[1,0,1]
	v_pk_fma_f32 v[180:181], v[22:23], v[174:175], v[180:181] op_sel_hi:[1,0,1]
	v_pk_fma_f32 v[192:193], v[24:25], v[174:175], v[192:193] op_sel_hi:[1,0,1]
	v_mfma_f32_16x16x4_f32 v[106:109], v143, v43, v[106:109]
	v_pk_fma_f32 v[180:181], v[18:19], v[174:175], v[180:181] op_sel:[0,1,0]
	v_pk_fma_f32 v[192:193], v[20:21], v[174:175], v[192:193] op_sel:[0,1,0]
	v_pk_fma_f32 v[180:181], v[14:15], v[232:233], v[180:181] op_sel_hi:[1,0,1]
	v_pk_fma_f32 v[192:193], v[16:17], v[232:233], v[192:193] op_sel_hi:[1,0,1]
	v_mfma_f32_16x16x4_f32 v[102:105], v143, v44, v[102:105]
	v_pk_fma_f32 v[180:181], v[10:11], v[232:233], v[180:181] op_sel:[0,1,0]
	v_pk_fma_f32 v[192:193], v[12:13], v[232:233], v[192:193] op_sel:[0,1,0]
	v_pk_fma_f32 v[180:181], v[6:7], v[234:235], v[180:181] op_sel_hi:[1,0,1]
	v_pk_fma_f32 v[192:193], v[8:9], v[234:235], v[192:193] op_sel_hi:[1,0,1]
	v_mfma_f32_16x16x4_f32 v[98:101], v143, v45, v[98:101]
	v_pk_fma_f32 v[180:181], v[2:3], v[234:235], v[180:181] op_sel:[0,1,0]
	v_pk_fma_f32 v[192:193], v[4:5], v[234:235], v[192:193] op_sel:[0,1,0]
	v_pk_mul_f32 v[180:181], v[146:147], v[180:181]
	v_pk_mul_f32 v[192:193], v[146:147], v[192:193]
	v_pk_fma_f32 v[236:237], v[144:145], v[42:43], v[180:181]
	v_pk_fma_f32 v[238:239], v[144:145], v[44:45], v[192:193]
	global_store_dwordx4 v[150:151], v[236:239], off nt
	v_lshl_add_u64 v[150:151], v[150:151], 0, s[74:75]
	global_load_dwordx4 v[42:45], v[148:149], off nt
	v_lshl_add_u64 v[148:149], v[148:149], 0, s[74:75]
	ds_read_b32 v143, v160 offset:496
	ds_read_b128 v[172:175], v161 offset:3968
	ds_read_b128 v[232:235], v161 offset:3984
	s_waitcnt vmcnt(14)
	s_waitcnt lgkmcnt(3)
	v_cndmask_b32_e64 v141, 0, v141, s[8:9]
	v_pk_mul_f32 v[180:181], v[26:27], v[114:115] op_sel:[0,1]
	v_pk_mul_f32 v[192:193], v[28:29], v[114:115] op_sel:[0,1]
	v_mfma_f32_16x16x4_f32 v[110:113], v141, v38, v[110:113]
	v_pk_fma_f32 v[180:181], v[30:31], v[114:115], v[180:181] op_sel_hi:[1,0,1]
	v_pk_fma_f32 v[192:193], v[32:33], v[114:115], v[192:193] op_sel_hi:[1,0,1]
	v_pk_fma_f32 v[180:181], v[22:23], v[116:117], v[180:181] op_sel_hi:[1,0,1]
	v_pk_fma_f32 v[192:193], v[24:25], v[116:117], v[192:193] op_sel_hi:[1,0,1]
	v_mfma_f32_16x16x4_f32 v[106:109], v141, v39, v[106:109]
	v_pk_fma_f32 v[180:181], v[18:19], v[116:117], v[180:181] op_sel:[0,1,0]
	v_pk_fma_f32 v[192:193], v[20:21], v[116:117], v[192:193] op_sel:[0,1,0]
	v_pk_fma_f32 v[180:181], v[14:15], v[176:177], v[180:181] op_sel_hi:[1,0,1]
	v_pk_fma_f32 v[192:193], v[16:17], v[176:177], v[192:193] op_sel_hi:[1,0,1]
	v_mfma_f32_16x16x4_f32 v[102:105], v141, v40, v[102:105]
	v_pk_fma_f32 v[180:181], v[10:11], v[176:177], v[180:181] op_sel:[0,1,0]
	v_pk_fma_f32 v[192:193], v[12:13], v[176:177], v[192:193] op_sel:[0,1,0]
	v_pk_fma_f32 v[180:181], v[6:7], v[178:179], v[180:181] op_sel_hi:[1,0,1]
	v_pk_fma_f32 v[192:193], v[8:9], v[178:179], v[192:193] op_sel_hi:[1,0,1]
	v_mfma_f32_16x16x4_f32 v[98:101], v141, v41, v[98:101]
	v_pk_fma_f32 v[180:181], v[2:3], v[178:179], v[180:181] op_sel:[0,1,0]
	v_pk_fma_f32 v[192:193], v[4:5], v[178:179], v[192:193] op_sel:[0,1,0]
	v_pk_mul_f32 v[180:181], v[146:147], v[180:181]
	v_pk_mul_f32 v[192:193], v[146:147], v[192:193]
	v_pk_fma_f32 v[236:237], v[144:145], v[38:39], v[180:181]
	v_pk_fma_f32 v[238:239], v[144:145], v[40:41], v[192:193]
	global_store_dwordx4 v[150:151], v[236:239], off nt
	v_lshl_add_u64 v[150:151], v[150:151], 0, s[74:75]
	global_load_dwordx4 v[38:41], v[148:149], off nt
	v_lshl_add_u64 v[148:149], v[148:149], 0, s[74:75]
	ds_read_b32 v141, v160 offset:512
	ds_read_b128 v[114:117], v161 offset:4096
	ds_read_b128 v[176:179], v161 offset:4112
	s_waitcnt vmcnt(14)
	s_waitcnt lgkmcnt(3)
	v_cndmask_b32_e64 v143, 0, v143, s[8:9]
	v_pk_mul_f32 v[180:181], v[26:27], v[172:173] op_sel:[0,1]
	v_pk_mul_f32 v[192:193], v[28:29], v[172:173] op_sel:[0,1]
	v_mfma_f32_16x16x4_f32 v[110:113], v143, v34, v[110:113]
	v_pk_fma_f32 v[180:181], v[30:31], v[172:173], v[180:181] op_sel_hi:[1,0,1]
	v_pk_fma_f32 v[192:193], v[32:33], v[172:173], v[192:193] op_sel_hi:[1,0,1]
	v_pk_fma_f32 v[180:181], v[22:23], v[174:175], v[180:181] op_sel_hi:[1,0,1]
	v_pk_fma_f32 v[192:193], v[24:25], v[174:175], v[192:193] op_sel_hi:[1,0,1]
	v_mfma_f32_16x16x4_f32 v[106:109], v143, v35, v[106:109]
	v_pk_fma_f32 v[180:181], v[18:19], v[174:175], v[180:181] op_sel:[0,1,0]
	v_pk_fma_f32 v[192:193], v[20:21], v[174:175], v[192:193] op_sel:[0,1,0]
	v_pk_fma_f32 v[180:181], v[14:15], v[232:233], v[180:181] op_sel_hi:[1,0,1]
	v_pk_fma_f32 v[192:193], v[16:17], v[232:233], v[192:193] op_sel_hi:[1,0,1]
	v_mfma_f32_16x16x4_f32 v[102:105], v143, v36, v[102:105]
	v_pk_fma_f32 v[180:181], v[10:11], v[232:233], v[180:181] op_sel:[0,1,0]
	v_pk_fma_f32 v[192:193], v[12:13], v[232:233], v[192:193] op_sel:[0,1,0]
	v_pk_fma_f32 v[180:181], v[6:7], v[234:235], v[180:181] op_sel_hi:[1,0,1]
	v_pk_fma_f32 v[192:193], v[8:9], v[234:235], v[192:193] op_sel_hi:[1,0,1]
	v_mfma_f32_16x16x4_f32 v[98:101], v143, v37, v[98:101]
	v_pk_fma_f32 v[180:181], v[2:3], v[234:235], v[180:181] op_sel:[0,1,0]
	v_pk_fma_f32 v[192:193], v[4:5], v[234:235], v[192:193] op_sel:[0,1,0]
	v_pk_mul_f32 v[180:181], v[146:147], v[180:181]
	v_pk_mul_f32 v[192:193], v[146:147], v[192:193]
	v_pk_fma_f32 v[236:237], v[144:145], v[34:35], v[180:181]
	v_pk_fma_f32 v[238:239], v[144:145], v[36:37], v[192:193]
	global_store_dwordx4 v[150:151], v[236:239], off nt
	v_lshl_add_u64 v[150:151], v[150:151], 0, s[74:75]
	global_load_dwordx4 v[34:37], v[148:149], off nt
	v_lshl_add_u64 v[148:149], v[148:149], 0, s[74:75]
	ds_read_b32 v143, v160 offset:528
	ds_read_b128 v[172:175], v161 offset:4224
	ds_read_b128 v[232:235], v161 offset:4240
	s_waitcnt vmcnt(14)
; #define RS_LOAD(dst, it0) do { _Pragma("unroll") for (int u = 0; u < 8; ++u) dst[u] = __builtin_nontemporal_load((const f32x4*)(S0 + (size_t)(4 * ((it0) + u)) * DV)); } while (0)
; __device__ __forceinline__ void ret_sample_item(Frame& F, int item) {
;     ...
;     for (int it0 = 0; it0 < 64; it0 += 16) {
;         RS_LOAD(sb, it0 + 8);
;         RS_PROC(sa, it0);
;         { const int itn = it0 + 16 < 64 ? it0 + 16 : it0; RS_LOAD(sa, itn); }
;         RS_PROC(sb, it0 + 8);
;     }
	s_waitcnt lgkmcnt(3)
	v_cndmask_b32_e64 v141, 0, v141, s[8:9]
	v_pk_mul_f32 v[180:181], v[26:27], v[114:115] op_sel:[0,1]
	v_pk_mul_f32 v[192:193], v[28:29], v[114:115] op_sel:[0,1]
	v_mfma_f32_16x16x4_f32 v[110:113], v141, v70, v[110:113]
	v_pk_fma_f32 v[180:181], v[30:31], v[114:115], v[180:181] op_sel_hi:[1,0,1]
	v_pk_fma_f32 v[192:193], v[32:33], v[114:115], v[192:193] op_sel_hi:[1,0,1]
	v_pk_fma_f32 v[180:181], v[22:23], v[116:117], v[180:181] op_sel_hi:[1,0,1]
	v_pk_fma_f32 v[192:193], v[24:25], v[116:117], v[192:193] op_sel_hi:[1,0,1]
	v_mfma_f32_16x16x4_f32 v[106:109], v141, v71, v[106:109]
	v_pk_fma_f32 v[180:181], v[18:19], v[116:117], v[180:181] op_sel:[0,1,0]
	v_pk_fma_f32 v[192:193], v[20:21], v[116:117], v[192:193] op_sel:[0,1,0]
	v_pk_fma_f32 v[180:181], v[14:15], v[176:177], v[180:181] op_sel_hi:[1,0,1]
	v_pk_fma_f32 v[192:193], v[16:17], v[176:177], v[192:193] op_sel_hi:[1,0,1]
	v_mfma_f32_16x16x4_f32 v[102:105], v141, v72, v[102:105]
	v_pk_fma_f32 v[180:181], v[10:11], v[176:177], v[180:181] op_sel:[0,1,0]
	v_pk_fma_f32 v[192:193], v[12:13], v[176:177], v[192:193] op_sel:[0,1,0]
	v_pk_fma_f32 v[180:181], v[6:7], v[178:179], v[180:181] op_sel_hi:[1,0,1]
	v_pk_fma_f32 v[192:193], v[8:9], v[178:179], v[192:193] op_sel_hi:[1,0,1]
	v_mfma_f32_16x16x4_f32 v[98:101], v141, v73, v[98:101]
	v_pk_fma_f32 v[180:181], v[2:3], v[178:179], v[180:181] op_sel:[0,1,0]
	v_pk_fma_f32 v[192:193], v[4:5], v[178:179], v[192:193] op_sel:[0,1,0]
	v_pk_mul_f32 v[180:181], v[146:147], v[180:181]
	v_pk_mul_f32 v[192:193], v[146:147], v[192:193]
	v_pk_fma_f32 v[236:237], v[144:145], v[70:71], v[180:181]
	v_pk_fma_f32 v[238:239], v[144:145], v[72:73], v[192:193]
	global_store_dwordx4 v[150:151], v[236:239], off nt
	v_lshl_add_u64 v[150:151], v[150:151], 0, s[74:75]
	global_load_dwordx4 v[70:73], v[148:149], off nt
	v_lshl_add_u64 v[148:149], v[148:149], 0, s[74:75]
	ds_read_b32 v141, v160 offset:544
	ds_read_b128 v[114:117], v161 offset:4352
	ds_read_b128 v[176:179], v161 offset:4368
	s_waitcnt vmcnt(14)
	s_waitcnt lgkmcnt(3)
	v_cndmask_b32_e64 v143, 0, v143, s[8:9]
	v_pk_mul_f32 v[180:181], v[26:27], v[172:173] op_sel:[0,1]
	v_pk_mul_f32 v[192:193], v[28:29], v[172:173] op_sel:[0,1]
	v_mfma_f32_16x16x4_f32 v[110:113], v143, v62, v[110:113]
	v_pk_fma_f32 v[180:181], v[30:31], v[172:173], v[180:181] op_sel_hi:[1,0,1]
	v_pk_fma_f32 v[192:193], v[32:33], v[172:173], v[192:193] op_sel_hi:[1,0,1]
	v_pk_fma_f32 v[180:181], v[22:23], v[174:175], v[180:181] op_sel_hi:[1,0,1]
	v_pk_fma_f32 v[192:193], v[24:25], v[174:175], v[192:193] op_sel_hi:[1,0,1]
	v_mfma_f32_16x16x4_f32 v[106:109], v143, v63, v[106:109]
	v_pk_fma_f32 v[180:181], v[18:19], v[174:175], v[180:181] op_sel:[0,1,0]
	v_pk_fma_f32 v[192:193], v[20:21], v[174:175], v[192:193] op_sel:[0,1,0]
	v_pk_fma_f32 v[180:181], v[14:15], v[232:233], v[180:181] op_sel_hi:[1,0,1]
	v_pk_fma_f32 v[192:193], v[16:17], v[232:233], v[192:193] op_sel_hi:[1,0,1]
	v_mfma_f32_16x16x4_f32 v[102:105], v143, v64, v[102:105]
	v_pk_fma_f32 v[180:181], v[10:11], v[232:233], v[180:181] op_sel:[0,1,0]
	v_pk_fma_f32 v[192:193], v[12:13], v[232:233], v[192:193] op_sel:[0,1,0]
	v_pk_fma_f32 v[180:181], v[6:7], v[234:235], v[180:181] op_sel_hi:[1,0,1]
	v_pk_fma_f32 v[192:193], v[8:9], v[234:235], v[192:193] op_sel_hi:[1,0,1]
	v_mfma_f32_16x16x4_f32 v[98:101], v143, v65, v[98:101]
	v_pk_fma_f32 v[180:181], v[2:3], v[234:235], v[180:181] op_sel:[0,1,0]
	v_pk_fma_f32 v[192:193], v[4:5], v[234:235], v[192:193] op_sel:[0,1,0]
	v_pk_mul_f32 v[180:181], v[146:147], v[180:181]
	v_pk_mul_f32 v[192:193], v[146:147], v[192:193]
	v_pk_fma_f32 v[236:237], v[144:145], v[62:63], v[180:181]
	v_pk_fma_f32 v[238:239], v[144:145], v[64:65], v[192:193]
	global_store_dwordx4 v[150:151], v[236:239], off nt
	v_lshl_add_u64 v[150:151], v[150:151], 0, s[74:75]
	global_load_dwordx4 v[62:65], v[148:149], off nt
	v_lshl_add_u64 v[148:149], v[148:149], 0, s[74:75]
	ds_read_b32 v143, v160 offset:560
	ds_read_b128 v[172:175], v161 offset:4480
	ds_read_b128 v[232:235], v161 offset:4496
	s_waitcnt vmcnt(14)
	s_waitcnt lgkmcnt(3)
	v_cndmask_b32_e64 v141, 0, v141, s[8:9]
	v_pk_mul_f32 v[180:181], v[26:27], v[114:115] op_sel:[0,1]
	v_pk_mul_f32 v[192:193], v[28:29], v[114:115] op_sel:[0,1]
	v_mfma_f32_16x16x4_f32 v[110:113], v141, v54, v[110:113]
	v_pk_fma_f32 v[180:181], v[30:31], v[114:115], v[180:181] op_sel_hi:[1,0,1]
	v_pk_fma_f32 v[192:193], v[32:33], v[114:115], v[192:193] op_sel_hi:[1,0,1]
	v_pk_fma_f32 v[180:181], v[22:23], v[116:117], v[180:181] op_sel_hi:[1,0,1]
	v_pk_fma_f32 v[192:193], v[24:25], v[116:117], v[192:193] op_sel_hi:[1,0,1]
	v_mfma_f32_16x16x4_f32 v[106:109], v141, v55, v[106:109]
	v_pk_fma_f32 v[180:181], v[18:19], v[116:117], v[180:181] op_sel:[0,1,0]
	v_pk_fma_f32 v[192:193], v[20:21], v[116:117], v[192:193] op_sel:[0,1,0]
	v_pk_fma_f32 v[180:181], v[14:15], v[176:177], v[180:181] op_sel_hi:[1,0,1]
	v_pk_fma_f32 v[192:193], v[16:17], v[176:177], v[192:193] op_sel_hi:[1,0,1]
	v_mfma_f32_16x16x4_f32 v[102:105], v141, v56, v[102:105]
	v_pk_fma_f32 v[180:181], v[10:11], v[176:177], v[180:181] op_sel:[0,1,0]
	v_pk_fma_f32 v[192:193], v[12:13], v[176:177], v[192:193] op_sel:[0,1,0]
	v_pk_fma_f32 v[180:181], v[6:7], v[178:179], v[180:181] op_sel_hi:[1,0,1]
	v_pk_fma_f32 v[192:193], v[8:9], v[178:179], v[192:193] op_sel_hi:[1,0,1]
	v_mfma_f32_16x16x4_f32 v[98:101], v141, v57, v[98:101]
	v_pk_fma_f32 v[180:181], v[2:3], v[178:179], v[180:181] op_sel:[0,1,0]
	v_pk_fma_f32 v[192:193], v[4:5], v[178:179], v[192:193] op_sel:[0,1,0]
	v_pk_mul_f32 v[180:181], v[146:147], v[180:181]
	v_pk_mul_f32 v[192:193], v[146:147], v[192:193]
	v_pk_fma_f32 v[236:237], v[144:145], v[54:55], v[180:181]
	v_pk_fma_f32 v[238:239], v[144:145], v[56:57], v[192:193]
	global_store_dwordx4 v[150:151], v[236:239], off nt
	v_lshl_add_u64 v[150:151], v[150:151], 0, s[74:75]
	global_load_dwordx4 v[54:57], v[148:149], off nt
	v_lshl_add_u64 v[148:149], v[148:149], 0, s[74:75]
	ds_read_b32 v141, v160 offset:576
	ds_read_b128 v[114:117], v161 offset:4608
	ds_read_b128 v[176:179], v161 offset:4624
	s_waitcnt vmcnt(14)
; #define RS_LOAD(dst, it0) do { _Pragma("unroll") for (int u = 0; u < 8; ++u) dst[u] = __builtin_nontemporal_load((const f32x4*)(S0 + (size_t)(4 * ((it0) + u)) * DV)); } while (0)
; __device__ __forceinline__ void ret_sample_item(Frame& F, int item) {
;     ...
;     for (int it0 = 0; it0 < 64; it0 += 16) {
;         RS_LOAD(sb, it0 + 8);
;         RS_PROC(sa, it0);
;         { const int itn = it0 + 16 < 64 ? it0 + 16 : it0; RS_LOAD(sa, itn); }
;         RS_PROC(sb, it0 + 8);
;     }
	s_waitcnt lgkmcnt(3)
	v_cndmask_b32_e64 v143, 0, v143, s[8:9]
	v_pk_mul_f32 v[180:181], v[26:27], v[172:173] op_sel:[0,1]
	v_pk_mul_f32 v[192:193], v[28:29], v[172:173] op_sel:[0,1]
	v_mfma_f32_16x16x4_f32 v[110:113], v143, v50, v[110:113]
	v_pk_fma_f32 v[180:181], v[30:31], v[172:173], v[180:181] op_sel_hi:[1,0,1]
	v_pk_fma_f32 v[192:193], v[32:33], v[172:173], v[192:193] op_sel_hi:[1,0,1]
	v_pk_fma_f32 v[180:181], v[22:23], v[174:175], v[180:181] op_sel_hi:[1,0,1]
	v_pk_fma_f32 v[192:193], v[24:25], v[174:175], v[192:193] op_sel_hi:[1,0,1]
	v_mfma_f32_16x16x4_f32 v[106:109], v143, v51, v[106:109]
	v_pk_fma_f32 v[180:181], v[18:19], v[174:175], v[180:181] op_sel:[0,1,0]
	v_pk_fma_f32 v[192:193], v[20:21], v[174:175], v[192:193] op_sel:[0,1,0]
	v_pk_fma_f32 v[180:181], v[14:15], v[232:233], v[180:181] op_sel_hi:[1,0,1]
	v_pk_fma_f32 v[192:193], v[16:17], v[232:233], v[192:193] op_sel_hi:[1,0,1]
	v_mfma_f32_16x16x4_f32 v[102:105], v143, v52, v[102:105]
	v_pk_fma_f32 v[180:181], v[10:11], v[232:233], v[180:181] op_sel:[0,1,0]
	v_pk_fma_f32 v[192:193], v[12:13], v[232:233], v[192:193] op_sel:[0,1,0]
	v_pk_fma_f32 v[180:181], v[6:7], v[234:235], v[180:181] op_sel_hi:[1,0,1]
	v_pk_fma_f32 v[192:193], v[8:9], v[234:235], v[192:193] op_sel_hi:[1,0,1]
	v_mfma_f32_16x16x4_f32 v[98:101], v143, v53, v[98:101]
	v_pk_fma_f32 v[180:181], v[2:3], v[234:235], v[180:181] op_sel:[0,1,0]
	v_pk_fma_f32 v[192:193], v[4:5], v[234:235], v[192:193] op_sel:[0,1,0]
	v_pk_mul_f32 v[180:181], v[146:147], v[180:181]
	v_pk_mul_f32 v[192:193], v[146:147], v[192:193]
	v_pk_fma_f32 v[236:237], v[144:145], v[50:51], v[180:181]
	v_pk_fma_f32 v[238:239], v[144:145], v[52:53], v[192:193]
	global_store_dwordx4 v[150:151], v[236:239], off nt
	v_lshl_add_u64 v[150:151], v[150:151], 0, s[74:75]
	global_load_dwordx4 v[50:53], v[148:149], off nt
	v_lshl_add_u64 v[148:149], v[148:149], 0, s[74:75]
	ds_read_b32 v143, v160 offset:592
	ds_read_b128 v[172:175], v161 offset:4736
	ds_read_b128 v[232:235], v161 offset:4752
	s_waitcnt vmcnt(14)
	s_waitcnt lgkmcnt(3)
	v_cndmask_b32_e64 v141, 0, v141, s[8:9]
	v_pk_mul_f32 v[180:181], v[26:27], v[114:115] op_sel:[0,1]
	v_pk_mul_f32 v[192:193], v[28:29], v[114:115] op_sel:[0,1]
	v_mfma_f32_16x16x4_f32 v[110:113], v141, v46, v[110:113]
	v_pk_fma_f32 v[180:181], v[30:31], v[114:115], v[180:181] op_sel_hi:[1,0,1]
	v_pk_fma_f32 v[192:193], v[32:33], v[114:115], v[192:193] op_sel_hi:[1,0,1]
	v_pk_fma_f32 v[180:181], v[22:23], v[116:117], v[180:181] op_sel_hi:[1,0,1]
	v_pk_fma_f32 v[192:193], v[24:25], v[116:117], v[192:193] op_sel_hi:[1,0,1]
	v_mfma_f32_16x16x4_f32 v[106:109], v141, v47, v[106:109]
	v_pk_fma_f32 v[180:181], v[18:19], v[116:117], v[180:181] op_sel:[0,1,0]
	v_pk_fma_f32 v[192:193], v[20:21], v[116:117], v[192:193] op_sel:[0,1,0]
	v_pk_fma_f32 v[180:181], v[14:15], v[176:177], v[180:181] op_sel_hi:[1,0,1]
	v_pk_fma_f32 v[192:193], v[16:17], v[176:177], v[192:193] op_sel_hi:[1,0,1]
	v_mfma_f32_16x16x4_f32 v[102:105], v141, v48, v[102:105]
	v_pk_fma_f32 v[180:181], v[10:11], v[176:177], v[180:181] op_sel:[0,1,0]
	v_pk_fma_f32 v[192:193], v[12:13], v[176:177], v[192:193] op_sel:[0,1,0]
	v_pk_fma_f32 v[180:181], v[6:7], v[178:179], v[180:181] op_sel_hi:[1,0,1]
	v_pk_fma_f32 v[192:193], v[8:9], v[178:179], v[192:193] op_sel_hi:[1,0,1]
	v_mfma_f32_16x16x4_f32 v[98:101], v141, v49, v[98:101]
	v_pk_fma_f32 v[180:181], v[2:3], v[178:179], v[180:181] op_sel:[0,1,0]
	v_pk_fma_f32 v[192:193], v[4:5], v[178:179], v[192:193] op_sel:[0,1,0]
	v_pk_mul_f32 v[180:181], v[146:147], v[180:181]
	v_pk_mul_f32 v[192:193], v[146:147], v[192:193]
	v_pk_fma_f32 v[236:237], v[144:145], v[46:47], v[180:181]
	v_pk_fma_f32 v[238:239], v[144:145], v[48:49], v[192:193]
	global_store_dwordx4 v[150:151], v[236:239], off nt
	v_lshl_add_u64 v[150:151], v[150:151], 0, s[74:75]
	global_load_dwordx4 v[46:49], v[148:149], off nt
	v_lshl_add_u64 v[148:149], v[148:149], 0, s[74:75]
	ds_read_b32 v141, v160 offset:608
	ds_read_b128 v[114:117], v161 offset:4864
	ds_read_b128 v[176:179], v161 offset:4880
	s_waitcnt vmcnt(14)
	s_waitcnt lgkmcnt(3)
	v_cndmask_b32_e64 v143, 0, v143, s[8:9]
	v_pk_mul_f32 v[180:181], v[26:27], v[172:173] op_sel:[0,1]
	v_pk_mul_f32 v[192:193], v[28:29], v[172:173] op_sel:[0,1]
	v_mfma_f32_16x16x4_f32 v[110:113], v143, v42, v[110:113]
	v_pk_fma_f32 v[180:181], v[30:31], v[172:173], v[180:181] op_sel_hi:[1,0,1]
	v_pk_fma_f32 v[192:193], v[32:33], v[172:173], v[192:193] op_sel_hi:[1,0,1]
	v_pk_fma_f32 v[180:181], v[22:23], v[174:175], v[180:181] op_sel_hi:[1,0,1]
	v_pk_fma_f32 v[192:193], v[24:25], v[174:175], v[192:193] op_sel_hi:[1,0,1]
	v_mfma_f32_16x16x4_f32 v[106:109], v143, v43, v[106:109]
	v_pk_fma_f32 v[180:181], v[18:19], v[174:175], v[180:181] op_sel:[0,1,0]
	v_pk_fma_f32 v[192:193], v[20:21], v[174:175], v[192:193] op_sel:[0,1,0]
	v_pk_fma_f32 v[180:181], v[14:15], v[232:233], v[180:181] op_sel_hi:[1,0,1]
	v_pk_fma_f32 v[192:193], v[16:17], v[232:233], v[192:193] op_sel_hi:[1,0,1]
	v_mfma_f32_16x16x4_f32 v[102:105], v143, v44, v[102:105]
	v_pk_fma_f32 v[180:181], v[10:11], v[232:233], v[180:181] op_sel:[0,1,0]
	v_pk_fma_f32 v[192:193], v[12:13], v[232:233], v[192:193] op_sel:[0,1,0]
	v_pk_fma_f32 v[180:181], v[6:7], v[234:235], v[180:181] op_sel_hi:[1,0,1]
	v_pk_fma_f32 v[192:193], v[8:9], v[234:235], v[192:193] op_sel_hi:[1,0,1]
	v_mfma_f32_16x16x4_f32 v[98:101], v143, v45, v[98:101]
	v_pk_fma_f32 v[180:181], v[2:3], v[234:235], v[180:181] op_sel:[0,1,0]
	v_pk_fma_f32 v[192:193], v[4:5], v[234:235], v[192:193] op_sel:[0,1,0]
	v_pk_mul_f32 v[180:181], v[146:147], v[180:181]
	v_pk_mul_f32 v[192:193], v[146:147], v[192:193]
	v_pk_fma_f32 v[236:237], v[144:145], v[42:43], v[180:181]
	v_pk_fma_f32 v[238:239], v[144:145], v[44:45], v[192:193]
	global_store_dwordx4 v[150:151], v[236:239], off nt
	v_lshl_add_u64 v[150:151], v[150:151], 0, s[74:75]
	global_load_dwordx4 v[42:45], v[148:149], off nt
	v_lshl_add_u64 v[148:149], v[148:149], 0, s[74:75]
	ds_read_b32 v143, v160 offset:624
	ds_read_b128 v[172:175], v161 offset:4992
	ds_read_b128 v[232:235], v161 offset:5008
	s_waitcnt vmcnt(14)
; #define RS_LOAD(dst, it0) do { _Pragma("unroll") for (int u = 0; u < 8; ++u) dst[u] = __builtin_nontemporal_load((const f32x4*)(S0 + (size_t)(4 * ((it0) + u)) * DV)); } while (0)
; __device__ __forceinline__ void ret_sample_item(Frame& F, int item) {
;     ...
;     for (int it0 = 0; it0 < 64; it0 += 16) {
;         RS_LOAD(sb, it0 + 8);
;         RS_PROC(sa, it0);
;         { const int itn = it0 + 16 < 64 ? it0 + 16 : it0; RS_LOAD(sa, itn); }
;         RS_PROC(sb, it0 + 8);
;     }
	s_waitcnt lgkmcnt(3)
	v_cndmask_b32_e64 v141, 0, v141, s[8:9]
	v_pk_mul_f32 v[180:181], v[26:27], v[114:115] op_sel:[0,1]
	v_pk_mul_f32 v[192:193], v[28:29], v[114:115] op_sel:[0,1]
	v_mfma_f32_16x16x4_f32 v[110:113], v141, v38, v[110:113]
	v_pk_fma_f32 v[180:181], v[30:31], v[114:115], v[180:181] op_sel_hi:[1,0,1]
	v_pk_fma_f32 v[192:193], v[32:33], v[114:115], v[192:193] op_sel_hi:[1,0,1]
	v_pk_fma_f32 v[180:181], v[22:23], v[116:117], v[180:181] op_sel_hi:[1,0,1]
	v_pk_fma_f32 v[192:193], v[24:25], v[116:117], v[192:193] op_sel_hi:[1,0,1]
	v_mfma_f32_16x16x4_f32 v[106:109], v141, v39, v[106:109]
	v_pk_fma_f32 v[180:181], v[18:19], v[116:117], v[180:181] op_sel:[0,1,0]
	v_pk_fma_f32 v[192:193], v[20:21], v[116:117], v[192:193] op_sel:[0,1,0]
	v_pk_fma_f32 v[180:181], v[14:15], v[176:177], v[180:181] op_sel_hi:[1,0,1]
	v_pk_fma_f32 v[192:193], v[16:17], v[176:177], v[192:193] op_sel_hi:[1,0,1]
	v_mfma_f32_16x16x4_f32 v[102:105], v141, v40, v[102:105]
	v_pk_fma_f32 v[180:181], v[10:11], v[176:177], v[180:181] op_sel:[0,1,0]
	v_pk_fma_f32 v[192:193], v[12:13], v[176:177], v[192:193] op_sel:[0,1,0]
	v_pk_fma_f32 v[180:181], v[6:7], v[178:179], v[180:181] op_sel_hi:[1,0,1]
	v_pk_fma_f32 v[192:193], v[8:9], v[178:179], v[192:193] op_sel_hi:[1,0,1]
	v_mfma_f32_16x16x4_f32 v[98:101], v141, v41, v[98:101]
	v_pk_fma_f32 v[180:181], v[2:3], v[178:179], v[180:181] op_sel:[0,1,0]
	v_pk_fma_f32 v[192:193], v[4:5], v[178:179], v[192:193] op_sel:[0,1,0]
	v_pk_mul_f32 v[180:181], v[146:147], v[180:181]
	v_pk_mul_f32 v[192:193], v[146:147], v[192:193]
	v_pk_fma_f32 v[236:237], v[144:145], v[38:39], v[180:181]
	v_pk_fma_f32 v[238:239], v[144:145], v[40:41], v[192:193]
	global_store_dwordx4 v[150:151], v[236:239], off nt
	v_lshl_add_u64 v[150:151], v[150:151], 0, s[74:75]
	global_load_dwordx4 v[38:41], v[148:149], off nt
	v_lshl_add_u64 v[148:149], v[148:149], 0, s[74:75]
	ds_read_b32 v141, v160 offset:640
	ds_read_b128 v[114:117], v161 offset:5120
	ds_read_b128 v[176:179], v161 offset:5136
	s_waitcnt vmcnt(14)
	s_waitcnt lgkmcnt(3)
	v_cndmask_b32_e64 v143, 0, v143, s[8:9]
	v_pk_mul_f32 v[180:181], v[26:27], v[172:173] op_sel:[0,1]
	v_pk_mul_f32 v[192:193], v[28:29], v[172:173] op_sel:[0,1]
	v_mfma_f32_16x16x4_f32 v[110:113], v143, v34, v[110:113]
	v_pk_fma_f32 v[180:181], v[30:31], v[172:173], v[180:181] op_sel_hi:[1,0,1]
	v_pk_fma_f32 v[192:193], v[32:33], v[172:173], v[192:193] op_sel_hi:[1,0,1]
	v_pk_fma_f32 v[180:181], v[22:23], v[174:175], v[180:181] op_sel_hi:[1,0,1]
	v_pk_fma_f32 v[192:193], v[24:25], v[174:175], v[192:193] op_sel_hi:[1,0,1]
	v_mfma_f32_16x16x4_f32 v[106:109], v143, v35, v[106:109]
	v_pk_fma_f32 v[180:181], v[18:19], v[174:175], v[180:181] op_sel:[0,1,0]
	v_pk_fma_f32 v[192:193], v[20:21], v[174:175], v[192:193] op_sel:[0,1,0]
	v_pk_fma_f32 v[180:181], v[14:15], v[232:233], v[180:181] op_sel_hi:[1,0,1]
	v_pk_fma_f32 v[192:193], v[16:17], v[232:233], v[192:193] op_sel_hi:[1,0,1]
	v_mfma_f32_16x16x4_f32 v[102:105], v143, v36, v[102:105]
	v_pk_fma_f32 v[180:181], v[10:11], v[232:233], v[180:181] op_sel:[0,1,0]
	v_pk_fma_f32 v[192:193], v[12:13], v[232:233], v[192:193] op_sel:[0,1,0]
	v_pk_fma_f32 v[180:181], v[6:7], v[234:235], v[180:181] op_sel_hi:[1,0,1]
	v_pk_fma_f32 v[192:193], v[8:9], v[234:235], v[192:193] op_sel_hi:[1,0,1]
	v_mfma_f32_16x16x4_f32 v[98:101], v143, v37, v[98:101]
	v_pk_fma_f32 v[180:181], v[2:3], v[234:235], v[180:181] op_sel:[0,1,0]
	v_pk_fma_f32 v[192:193], v[4:5], v[234:235], v[192:193] op_sel:[0,1,0]
	v_pk_mul_f32 v[180:181], v[146:147], v[180:181]
	v_pk_mul_f32 v[192:193], v[146:147], v[192:193]
	v_pk_fma_f32 v[236:237], v[144:145], v[34:35], v[180:181]
	v_pk_fma_f32 v[238:239], v[144:145], v[36:37], v[192:193]
	global_store_dwordx4 v[150:151], v[236:239], off nt
	v_lshl_add_u64 v[150:151], v[150:151], 0, s[74:75]
	global_load_dwordx4 v[34:37], v[148:149], off nt
	v_lshl_add_u64 v[148:149], v[148:149], 0, s[74:75]
	ds_read_b32 v143, v160 offset:656
	ds_read_b128 v[172:175], v161 offset:5248
	ds_read_b128 v[232:235], v161 offset:5264
	s_waitcnt vmcnt(14)
	s_waitcnt lgkmcnt(3)
	v_cndmask_b32_e64 v141, 0, v141, s[8:9]
	v_pk_mul_f32 v[180:181], v[26:27], v[114:115] op_sel:[0,1]
	v_pk_mul_f32 v[192:193], v[28:29], v[114:115] op_sel:[0,1]
	v_mfma_f32_16x16x4_f32 v[110:113], v141, v70, v[110:113]
	v_pk_fma_f32 v[180:181], v[30:31], v[114:115], v[180:181] op_sel_hi:[1,0,1]
	v_pk_fma_f32 v[192:193], v[32:33], v[114:115], v[192:193] op_sel_hi:[1,0,1]
	v_pk_fma_f32 v[180:181], v[22:23], v[116:117], v[180:181] op_sel_hi:[1,0,1]
	v_pk_fma_f32 v[192:193], v[24:25], v[116:117], v[192:193] op_sel_hi:[1,0,1]
	v_mfma_f32_16x16x4_f32 v[106:109], v141, v71, v[106:109]
	v_pk_fma_f32 v[180:181], v[18:19], v[116:117], v[180:181] op_sel:[0,1,0]
	v_pk_fma_f32 v[192:193], v[20:21], v[116:117], v[192:193] op_sel:[0,1,0]
	v_pk_fma_f32 v[180:181], v[14:15], v[176:177], v[180:181] op_sel_hi:[1,0,1]
	v_pk_fma_f32 v[192:193], v[16:17], v[176:177], v[192:193] op_sel_hi:[1,0,1]
	v_mfma_f32_16x16x4_f32 v[102:105], v141, v72, v[102:105]
	v_pk_fma_f32 v[180:181], v[10:11], v[176:177], v[180:181] op_sel:[0,1,0]
	v_pk_fma_f32 v[192:193], v[12:13], v[176:177], v[192:193] op_sel:[0,1,0]
	v_pk_fma_f32 v[180:181], v[6:7], v[178:179], v[180:181] op_sel_hi:[1,0,1]
	v_pk_fma_f32 v[192:193], v[8:9], v[178:179], v[192:193] op_sel_hi:[1,0,1]
	v_mfma_f32_16x16x4_f32 v[98:101], v141, v73, v[98:101]
	v_pk_fma_f32 v[180:181], v[2:3], v[178:179], v[180:181] op_sel:[0,1,0]
	v_pk_fma_f32 v[192:193], v[4:5], v[178:179], v[192:193] op_sel:[0,1,0]
	v_pk_mul_f32 v[180:181], v[146:147], v[180:181]
	v_pk_mul_f32 v[192:193], v[146:147], v[192:193]
	v_pk_fma_f32 v[236:237], v[144:145], v[70:71], v[180:181]
	v_pk_fma_f32 v[238:239], v[144:145], v[72:73], v[192:193]
	global_store_dwordx4 v[150:151], v[236:239], off nt
	v_lshl_add_u64 v[150:151], v[150:151], 0, s[74:75]
	global_load_dwordx4 v[70:73], v[148:149], off nt
	v_lshl_add_u64 v[148:149], v[148:149], 0, s[74:75]
	ds_read_b32 v141, v160 offset:672
	ds_read_b128 v[114:117], v161 offset:5376
	ds_read_b128 v[176:179], v161 offset:5392
	s_waitcnt vmcnt(14)
; #define RS_LOAD(dst, it0) do { _Pragma("unroll") for (int u = 0; u < 8; ++u) dst[u] = __builtin_nontemporal_load((const f32x4*)(S0 + (size_t)(4 * ((it0) + u)) * DV)); } while (0)
; __device__ __forceinline__ void ret_sample_item(Frame& F, int item) {
;     ...
;     for (int it0 = 0; it0 < 64; it0 += 16) {
;         RS_LOAD(sb, it0 + 8);
;         RS_PROC(sa, it0);
;         { const int itn = it0 + 16 < 64 ? it0 + 16 : it0; RS_LOAD(sa, itn); }
;         RS_PROC(sb, it0 + 8);
;     }
	s_waitcnt lgkmcnt(3)
	v_cndmask_b32_e64 v143, 0, v143, s[8:9]
	v_pk_mul_f32 v[180:181], v[26:27], v[172:173] op_sel:[0,1]
	v_pk_mul_f32 v[192:193], v[28:29], v[172:173] op_sel:[0,1]
	v_mfma_f32_16x16x4_f32 v[110:113], v143, v62, v[110:113]
	v_pk_fma_f32 v[180:181], v[30:31], v[172:173], v[180:181] op_sel_hi:[1,0,1]
	v_pk_fma_f32 v[192:193], v[32:33], v[172:173], v[192:193] op_sel_hi:[1,0,1]
	v_pk_fma_f32 v[180:181], v[22:23], v[174:175], v[180:181] op_sel_hi:[1,0,1]
	v_pk_fma_f32 v[192:193], v[24:25], v[174:175], v[192:193] op_sel_hi:[1,0,1]
	v_mfma_f32_16x16x4_f32 v[106:109], v143, v63, v[106:109]
	v_pk_fma_f32 v[180:181], v[18:19], v[174:175], v[180:181] op_sel:[0,1,0]
	v_pk_fma_f32 v[192:193], v[20:21], v[174:175], v[192:193] op_sel:[0,1,0]
	v_pk_fma_f32 v[180:181], v[14:15], v[232:233], v[180:181] op_sel_hi:[1,0,1]
	v_pk_fma_f32 v[192:193], v[16:17], v[232:233], v[192:193] op_sel_hi:[1,0,1]
	v_mfma_f32_16x16x4_f32 v[102:105], v143, v64, v[102:105]
	v_pk_fma_f32 v[180:181], v[10:11], v[232:233], v[180:181] op_sel:[0,1,0]
	v_pk_fma_f32 v[192:193], v[12:13], v[232:233], v[192:193] op_sel:[0,1,0]
	v_pk_fma_f32 v[180:181], v[6:7], v[234:235], v[180:181] op_sel_hi:[1,0,1]
	v_pk_fma_f32 v[192:193], v[8:9], v[234:235], v[192:193] op_sel_hi:[1,0,1]
	v_mfma_f32_16x16x4_f32 v[98:101], v143, v65, v[98:101]
	v_pk_fma_f32 v[180:181], v[2:3], v[234:235], v[180:181] op_sel:[0,1,0]
	v_pk_fma_f32 v[192:193], v[4:5], v[234:235], v[192:193] op_sel:[0,1,0]
	v_pk_mul_f32 v[180:181], v[146:147], v[180:181]
	v_pk_mul_f32 v[192:193], v[146:147], v[192:193]
	v_pk_fma_f32 v[236:237], v[144:145], v[62:63], v[180:181]
	v_pk_fma_f32 v[238:239], v[144:145], v[64:65], v[192:193]
	global_store_dwordx4 v[150:151], v[236:239], off nt
	v_lshl_add_u64 v[150:151], v[150:151], 0, s[74:75]
	global_load_dwordx4 v[62:65], v[148:149], off nt
	v_lshl_add_u64 v[148:149], v[148:149], 0, s[74:75]
	ds_read_b32 v143, v160 offset:688
	ds_read_b128 v[172:175], v161 offset:5504
	ds_read_b128 v[232:235], v161 offset:5520
	s_waitcnt vmcnt(14)
	s_waitcnt lgkmcnt(3)
	v_cndmask_b32_e64 v141, 0, v141, s[8:9]
	v_pk_mul_f32 v[180:181], v[26:27], v[114:115] op_sel:[0,1]
	v_pk_mul_f32 v[192:193], v[28:29], v[114:115] op_sel:[0,1]
	v_mfma_f32_16x16x4_f32 v[110:113], v141, v54, v[110:113]
	v_pk_fma_f32 v[180:181], v[30:31], v[114:115], v[180:181] op_sel_hi:[1,0,1]
	v_pk_fma_f32 v[192:193], v[32:33], v[114:115], v[192:193] op_sel_hi:[1,0,1]
	v_pk_fma_f32 v[180:181], v[22:23], v[116:117], v[180:181] op_sel_hi:[1,0,1]
	v_pk_fma_f32 v[192:193], v[24:25], v[116:117], v[192:193] op_sel_hi:[1,0,1]
	v_mfma_f32_16x16x4_f32 v[106:109], v141, v55, v[106:109]
	v_pk_fma_f32 v[180:181], v[18:19], v[116:117], v[180:181] op_sel:[0,1,0]
	v_pk_fma_f32 v[192:193], v[20:21], v[116:117], v[192:193] op_sel:[0,1,0]
	v_pk_fma_f32 v[180:181], v[14:15], v[176:177], v[180:181] op_sel_hi:[1,0,1]
	v_pk_fma_f32 v[192:193], v[16:17], v[176:177], v[192:193] op_sel_hi:[1,0,1]
	v_mfma_f32_16x16x4_f32 v[102:105], v141, v56, v[102:105]
	v_pk_fma_f32 v[180:181], v[10:11], v[176:177], v[180:181] op_sel:[0,1,0]
	v_pk_fma_f32 v[192:193], v[12:13], v[176:177], v[192:193] op_sel:[0,1,0]
	v_pk_fma_f32 v[180:181], v[6:7], v[178:179], v[180:181] op_sel_hi:[1,0,1]
	v_pk_fma_f32 v[192:193], v[8:9], v[178:179], v[192:193] op_sel_hi:[1,0,1]
	v_mfma_f32_16x16x4_f32 v[98:101], v141, v57, v[98:101]
	v_pk_fma_f32 v[180:181], v[2:3], v[178:179], v[180:181] op_sel:[0,1,0]
	v_pk_fma_f32 v[192:193], v[4:5], v[178:179], v[192:193] op_sel:[0,1,0]
	v_pk_mul_f32 v[180:181], v[146:147], v[180:181]
	v_pk_mul_f32 v[192:193], v[146:147], v[192:193]
	v_pk_fma_f32 v[236:237], v[144:145], v[54:55], v[180:181]
	v_pk_fma_f32 v[238:239], v[144:145], v[56:57], v[192:193]
	global_store_dwordx4 v[150:151], v[236:239], off nt
	v_lshl_add_u64 v[150:151], v[150:151], 0, s[74:75]
	global_load_dwordx4 v[54:57], v[148:149], off nt
	v_lshl_add_u64 v[148:149], v[148:149], 0, s[74:75]
	ds_read_b32 v141, v160 offset:704
	ds_read_b128 v[114:117], v161 offset:5632
	ds_read_b128 v[176:179], v161 offset:5648
	s_waitcnt vmcnt(14)
	s_waitcnt lgkmcnt(3)
	v_cndmask_b32_e64 v143, 0, v143, s[8:9]
	v_pk_mul_f32 v[180:181], v[26:27], v[172:173] op_sel:[0,1]
	v_pk_mul_f32 v[192:193], v[28:29], v[172:173] op_sel:[0,1]
	v_mfma_f32_16x16x4_f32 v[110:113], v143, v50, v[110:113]
	v_pk_fma_f32 v[180:181], v[30:31], v[172:173], v[180:181] op_sel_hi:[1,0,1]
	v_pk_fma_f32 v[192:193], v[32:33], v[172:173], v[192:193] op_sel_hi:[1,0,1]
	v_pk_fma_f32 v[180:181], v[22:23], v[174:175], v[180:181] op_sel_hi:[1,0,1]
	v_pk_fma_f32 v[192:193], v[24:25], v[174:175], v[192:193] op_sel_hi:[1,0,1]
	v_mfma_f32_16x16x4_f32 v[106:109], v143, v51, v[106:109]
	v_pk_fma_f32 v[180:181], v[18:19], v[174:175], v[180:181] op_sel:[0,1,0]
	v_pk_fma_f32 v[192:193], v[20:21], v[174:175], v[192:193] op_sel:[0,1,0]
	v_pk_fma_f32 v[180:181], v[14:15], v[232:233], v[180:181] op_sel_hi:[1,0,1]
	v_pk_fma_f32 v[192:193], v[16:17], v[232:233], v[192:193] op_sel_hi:[1,0,1]
	v_mfma_f32_16x16x4_f32 v[102:105], v143, v52, v[102:105]
	v_pk_fma_f32 v[180:181], v[10:11], v[232:233], v[180:181] op_sel:[0,1,0]
	v_pk_fma_f32 v[192:193], v[12:13], v[232:233], v[192:193] op_sel:[0,1,0]
	v_pk_fma_f32 v[180:181], v[6:7], v[234:235], v[180:181] op_sel_hi:[1,0,1]
	v_pk_fma_f32 v[192:193], v[8:9], v[234:235], v[192:193] op_sel_hi:[1,0,1]
	v_mfma_f32_16x16x4_f32 v[98:101], v143, v53, v[98:101]
	v_pk_fma_f32 v[180:181], v[2:3], v[234:235], v[180:181] op_sel:[0,1,0]
	v_pk_fma_f32 v[192:193], v[4:5], v[234:235], v[192:193] op_sel:[0,1,0]
	v_pk_mul_f32 v[180:181], v[146:147], v[180:181]
	v_pk_mul_f32 v[192:193], v[146:147], v[192:193]
	v_pk_fma_f32 v[236:237], v[144:145], v[50:51], v[180:181]
	v_pk_fma_f32 v[238:239], v[144:145], v[52:53], v[192:193]
	global_store_dwordx4 v[150:151], v[236:239], off nt
	v_lshl_add_u64 v[150:151], v[150:151], 0, s[74:75]
	global_load_dwordx4 v[50:53], v[148:149], off nt
	v_lshl_add_u64 v[148:149], v[148:149], 0, s[74:75]
	ds_read_b32 v143, v160 offset:720
	ds_read_b128 v[172:175], v161 offset:5760
	ds_read_b128 v[232:235], v161 offset:5776
	s_waitcnt vmcnt(14)
; #define RS_LOAD(dst, it0) do { _Pragma("unroll") for (int u = 0; u < 8; ++u) dst[u] = __builtin_nontemporal_load((const f32x4*)(S0 + (size_t)(4 * ((it0) + u)) * DV)); } while (0)
; __device__ __forceinline__ void ret_sample_item(Frame& F, int item) {
;     ...
;     for (int it0 = 0; it0 < 64; it0 += 16) {
;         RS_LOAD(sb, it0 + 8);
;         RS_PROC(sa, it0);
;         { const int itn = it0 + 16 < 64 ? it0 + 16 : it0; RS_LOAD(sa, itn); }
;         RS_PROC(sb, it0 + 8);
;     }
	s_waitcnt lgkmcnt(3)
	v_cndmask_b32_e64 v141, 0, v141, s[8:9]
	v_pk_mul_f32 v[180:181], v[26:27], v[114:115] op_sel:[0,1]
	v_pk_mul_f32 v[192:193], v[28:29], v[114:115] op_sel:[0,1]
	v_mfma_f32_16x16x4_f32 v[110:113], v141, v46, v[110:113]
	v_pk_fma_f32 v[180:181], v[30:31], v[114:115], v[180:181] op_sel_hi:[1,0,1]
	v_pk_fma_f32 v[192:193], v[32:33], v[114:115], v[192:193] op_sel_hi:[1,0,1]
	v_pk_fma_f32 v[180:181], v[22:23], v[116:117], v[180:181] op_sel_hi:[1,0,1]
	v_pk_fma_f32 v[192:193], v[24:25], v[116:117], v[192:193] op_sel_hi:[1,0,1]
	v_mfma_f32_16x16x4_f32 v[106:109], v141, v47, v[106:109]
	v_pk_fma_f32 v[180:181], v[18:19], v[116:117], v[180:181] op_sel:[0,1,0]
	v_pk_fma_f32 v[192:193], v[20:21], v[116:117], v[192:193] op_sel:[0,1,0]
	v_pk_fma_f32 v[180:181], v[14:15], v[176:177], v[180:181] op_sel_hi:[1,0,1]
	v_pk_fma_f32 v[192:193], v[16:17], v[176:177], v[192:193] op_sel_hi:[1,0,1]
	v_mfma_f32_16x16x4_f32 v[102:105], v141, v48, v[102:105]
	v_pk_fma_f32 v[180:181], v[10:11], v[176:177], v[180:181] op_sel:[0,1,0]
	v_pk_fma_f32 v[192:193], v[12:13], v[176:177], v[192:193] op_sel:[0,1,0]
	v_pk_fma_f32 v[180:181], v[6:7], v[178:179], v[180:181] op_sel_hi:[1,0,1]
	v_pk_fma_f32 v[192:193], v[8:9], v[178:179], v[192:193] op_sel_hi:[1,0,1]
	v_mfma_f32_16x16x4_f32 v[98:101], v141, v49, v[98:101]
	v_pk_fma_f32 v[180:181], v[2:3], v[178:179], v[180:181] op_sel:[0,1,0]
	v_pk_fma_f32 v[192:193], v[4:5], v[178:179], v[192:193] op_sel:[0,1,0]
	v_pk_mul_f32 v[180:181], v[146:147], v[180:181]
	v_pk_mul_f32 v[192:193], v[146:147], v[192:193]
	v_pk_fma_f32 v[236:237], v[144:145], v[46:47], v[180:181]
	v_pk_fma_f32 v[238:239], v[144:145], v[48:49], v[192:193]
	global_store_dwordx4 v[150:151], v[236:239], off nt
	v_lshl_add_u64 v[150:151], v[150:151], 0, s[74:75]
	global_load_dwordx4 v[46:49], v[148:149], off nt
	v_lshl_add_u64 v[148:149], v[148:149], 0, s[74:75]
	ds_read_b32 v141, v160 offset:736
	ds_read_b128 v[114:117], v161 offset:5888
	ds_read_b128 v[176:179], v161 offset:5904
	s_waitcnt vmcnt(14)
	s_waitcnt lgkmcnt(3)
	v_cndmask_b32_e64 v143, 0, v143, s[8:9]
	v_pk_mul_f32 v[180:181], v[26:27], v[172:173] op_sel:[0,1]
	v_pk_mul_f32 v[192:193], v[28:29], v[172:173] op_sel:[0,1]
	v_mfma_f32_16x16x4_f32 v[110:113], v143, v42, v[110:113]
	v_pk_fma_f32 v[180:181], v[30:31], v[172:173], v[180:181] op_sel_hi:[1,0,1]
	v_pk_fma_f32 v[192:193], v[32:33], v[172:173], v[192:193] op_sel_hi:[1,0,1]
	v_pk_fma_f32 v[180:181], v[22:23], v[174:175], v[180:181] op_sel_hi:[1,0,1]
	v_pk_fma_f32 v[192:193], v[24:25], v[174:175], v[192:193] op_sel_hi:[1,0,1]
	v_mfma_f32_16x16x4_f32 v[106:109], v143, v43, v[106:109]
	v_pk_fma_f32 v[180:181], v[18:19], v[174:175], v[180:181] op_sel:[0,1,0]
	v_pk_fma_f32 v[192:193], v[20:21], v[174:175], v[192:193] op_sel:[0,1,0]
	v_pk_fma_f32 v[180:181], v[14:15], v[232:233], v[180:181] op_sel_hi:[1,0,1]
	v_pk_fma_f32 v[192:193], v[16:17], v[232:233], v[192:193] op_sel_hi:[1,0,1]
	v_mfma_f32_16x16x4_f32 v[102:105], v143, v44, v[102:105]
	v_pk_fma_f32 v[180:181], v[10:11], v[232:233], v[180:181] op_sel:[0,1,0]
	v_pk_fma_f32 v[192:193], v[12:13], v[232:233], v[192:193] op_sel:[0,1,0]
	v_pk_fma_f32 v[180:181], v[6:7], v[234:235], v[180:181] op_sel_hi:[1,0,1]
	v_pk_fma_f32 v[192:193], v[8:9], v[234:235], v[192:193] op_sel_hi:[1,0,1]
	v_mfma_f32_16x16x4_f32 v[98:101], v143, v45, v[98:101]
	v_pk_fma_f32 v[180:181], v[2:3], v[234:235], v[180:181] op_sel:[0,1,0]
	v_pk_fma_f32 v[192:193], v[4:5], v[234:235], v[192:193] op_sel:[0,1,0]
	v_pk_mul_f32 v[180:181], v[146:147], v[180:181]
	v_pk_mul_f32 v[192:193], v[146:147], v[192:193]
	v_pk_fma_f32 v[236:237], v[144:145], v[42:43], v[180:181]
	v_pk_fma_f32 v[238:239], v[144:145], v[44:45], v[192:193]
	global_store_dwordx4 v[150:151], v[236:239], off nt
	v_lshl_add_u64 v[150:151], v[150:151], 0, s[74:75]
	global_load_dwordx4 v[42:45], v[148:149], off nt
	v_lshl_add_u64 v[148:149], v[148:149], 0, s[74:75]
	ds_read_b32 v143, v160 offset:752
	ds_read_b128 v[172:175], v161 offset:6016
	ds_read_b128 v[232:235], v161 offset:6032
	s_waitcnt vmcnt(14)
	s_waitcnt lgkmcnt(3)
	v_cndmask_b32_e64 v141, 0, v141, s[8:9]
	v_pk_mul_f32 v[180:181], v[26:27], v[114:115] op_sel:[0,1]
	v_pk_mul_f32 v[192:193], v[28:29], v[114:115] op_sel:[0,1]
	v_mfma_f32_16x16x4_f32 v[110:113], v141, v38, v[110:113]
	v_pk_fma_f32 v[180:181], v[30:31], v[114:115], v[180:181] op_sel_hi:[1,0,1]
	v_pk_fma_f32 v[192:193], v[32:33], v[114:115], v[192:193] op_sel_hi:[1,0,1]
	v_pk_fma_f32 v[180:181], v[22:23], v[116:117], v[180:181] op_sel_hi:[1,0,1]
	v_pk_fma_f32 v[192:193], v[24:25], v[116:117], v[192:193] op_sel_hi:[1,0,1]
	v_mfma_f32_16x16x4_f32 v[106:109], v141, v39, v[106:109]
	v_pk_fma_f32 v[180:181], v[18:19], v[116:117], v[180:181] op_sel:[0,1,0]
	v_pk_fma_f32 v[192:193], v[20:21], v[116:117], v[192:193] op_sel:[0,1,0]
	v_pk_fma_f32 v[180:181], v[14:15], v[176:177], v[180:181] op_sel_hi:[1,0,1]
	v_pk_fma_f32 v[192:193], v[16:17], v[176:177], v[192:193] op_sel_hi:[1,0,1]
	v_mfma_f32_16x16x4_f32 v[102:105], v141, v40, v[102:105]
	v_pk_fma_f32 v[180:181], v[10:11], v[176:177], v[180:181] op_sel:[0,1,0]
	v_pk_fma_f32 v[192:193], v[12:13], v[176:177], v[192:193] op_sel:[0,1,0]
	v_pk_fma_f32 v[180:181], v[6:7], v[178:179], v[180:181] op_sel_hi:[1,0,1]
	v_pk_fma_f32 v[192:193], v[8:9], v[178:179], v[192:193] op_sel_hi:[1,0,1]
	v_mfma_f32_16x16x4_f32 v[98:101], v141, v41, v[98:101]
	v_pk_fma_f32 v[180:181], v[2:3], v[178:179], v[180:181] op_sel:[0,1,0]
	v_pk_fma_f32 v[192:193], v[4:5], v[178:179], v[192:193] op_sel:[0,1,0]
	v_pk_mul_f32 v[180:181], v[146:147], v[180:181]
	v_pk_mul_f32 v[192:193], v[146:147], v[192:193]
	v_pk_fma_f32 v[236:237], v[144:145], v[38:39], v[180:181]
	v_pk_fma_f32 v[238:239], v[144:145], v[40:41], v[192:193]
	global_store_dwordx4 v[150:151], v[236:239], off nt
	v_lshl_add_u64 v[150:151], v[150:151], 0, s[74:75]
	global_load_dwordx4 v[38:41], v[148:149], off nt
	v_lshl_add_u64 v[148:149], v[148:149], 0, s[74:75]
	ds_read_b32 v141, v160 offset:768
	ds_read_b128 v[114:117], v161 offset:6144
	ds_read_b128 v[176:179], v161 offset:6160
	s_waitcnt vmcnt(14)
; #define RS_LOAD(dst, it0) do { _Pragma("unroll") for (int u = 0; u < 8; ++u) dst[u] = __builtin_nontemporal_load((const f32x4*)(S0 + (size_t)(4 * ((it0) + u)) * DV)); } while (0)
; __device__ __forceinline__ void ret_sample_item(Frame& F, int item) {
;     ...
;     for (int it0 = 0; it0 < 64; it0 += 16) {
;         RS_LOAD(sb, it0 + 8);
;         RS_PROC(sa, it0);
;         { const int itn = it0 + 16 < 64 ? it0 + 16 : it0; RS_LOAD(sa, itn); }
;         RS_PROC(sb, it0 + 8);
;     }
	s_waitcnt lgkmcnt(3)
	v_cndmask_b32_e64 v143, 0, v143, s[8:9]
	v_pk_mul_f32 v[180:181], v[26:27], v[172:173] op_sel:[0,1]
	v_pk_mul_f32 v[192:193], v[28:29], v[172:173] op_sel:[0,1]
	v_mfma_f32_16x16x4_f32 v[110:113], v143, v34, v[110:113]
	v_pk_fma_f32 v[180:181], v[30:31], v[172:173], v[180:181] op_sel_hi:[1,0,1]
	v_pk_fma_f32 v[192:193], v[32:33], v[172:173], v[192:193] op_sel_hi:[1,0,1]
	v_pk_fma_f32 v[180:181], v[22:23], v[174:175], v[180:181] op_sel_hi:[1,0,1]
	v_pk_fma_f32 v[192:193], v[24:25], v[174:175], v[192:193] op_sel_hi:[1,0,1]
	v_mfma_f32_16x16x4_f32 v[106:109], v143, v35, v[106:109]
	v_pk_fma_f32 v[180:181], v[18:19], v[174:175], v[180:181] op_sel:[0,1,0]
	v_pk_fma_f32 v[192:193], v[20:21], v[174:175], v[192:193] op_sel:[0,1,0]
	v_pk_fma_f32 v[180:181], v[14:15], v[232:233], v[180:181] op_sel_hi:[1,0,1]
	v_pk_fma_f32 v[192:193], v[16:17], v[232:233], v[192:193] op_sel_hi:[1,0,1]
	v_mfma_f32_16x16x4_f32 v[102:105], v143, v36, v[102:105]
	v_pk_fma_f32 v[180:181], v[10:11], v[232:233], v[180:181] op_sel:[0,1,0]
	v_pk_fma_f32 v[192:193], v[12:13], v[232:233], v[192:193] op_sel:[0,1,0]
	v_pk_fma_f32 v[180:181], v[6:7], v[234:235], v[180:181] op_sel_hi:[1,0,1]
	v_pk_fma_f32 v[192:193], v[8:9], v[234:235], v[192:193] op_sel_hi:[1,0,1]
	v_mfma_f32_16x16x4_f32 v[98:101], v143, v37, v[98:101]
	v_pk_fma_f32 v[180:181], v[2:3], v[234:235], v[180:181] op_sel:[0,1,0]
	v_pk_fma_f32 v[192:193], v[4:5], v[234:235], v[192:193] op_sel:[0,1,0]
	v_pk_mul_f32 v[180:181], v[146:147], v[180:181]
	v_pk_mul_f32 v[192:193], v[146:147], v[192:193]
	v_pk_fma_f32 v[236:237], v[144:145], v[34:35], v[180:181]
	v_pk_fma_f32 v[238:239], v[144:145], v[36:37], v[192:193]
	global_store_dwordx4 v[150:151], v[236:239], off nt
	v_lshl_add_u64 v[150:151], v[150:151], 0, s[74:75]
	global_load_dwordx4 v[34:37], v[148:149], off nt
	v_lshl_add_u64 v[148:149], v[148:149], 0, s[74:75]
	ds_read_b32 v143, v160 offset:784
	ds_read_b128 v[172:175], v161 offset:6272
	ds_read_b128 v[232:235], v161 offset:6288
	s_waitcnt vmcnt(14)
	s_waitcnt lgkmcnt(3)
	v_cndmask_b32_e64 v141, 0, v141, s[8:9]
	v_pk_mul_f32 v[180:181], v[26:27], v[114:115] op_sel:[0,1]
	v_pk_mul_f32 v[192:193], v[28:29], v[114:115] op_sel:[0,1]
	v_mfma_f32_16x16x4_f32 v[110:113], v141, v70, v[110:113]
	v_pk_fma_f32 v[180:181], v[30:31], v[114:115], v[180:181] op_sel_hi:[1,0,1]
	v_pk_fma_f32 v[192:193], v[32:33], v[114:115], v[192:193] op_sel_hi:[1,0,1]
	v_pk_fma_f32 v[180:181], v[22:23], v[116:117], v[180:181] op_sel_hi:[1,0,1]
	v_pk_fma_f32 v[192:193], v[24:25], v[116:117], v[192:193] op_sel_hi:[1,0,1]
	v_mfma_f32_16x16x4_f32 v[106:109], v141, v71, v[106:109]
	v_pk_fma_f32 v[180:181], v[18:19], v[116:117], v[180:181] op_sel:[0,1,0]
	v_pk_fma_f32 v[192:193], v[20:21], v[116:117], v[192:193] op_sel:[0,1,0]
	v_pk_fma_f32 v[180:181], v[14:15], v[176:177], v[180:181] op_sel_hi:[1,0,1]
	v_pk_fma_f32 v[192:193], v[16:17], v[176:177], v[192:193] op_sel_hi:[1,0,1]
	v_mfma_f32_16x16x4_f32 v[102:105], v141, v72, v[102:105]
	v_pk_fma_f32 v[180:181], v[10:11], v[176:177], v[180:181] op_sel:[0,1,0]
	v_pk_fma_f32 v[192:193], v[12:13], v[176:177], v[192:193] op_sel:[0,1,0]
	v_pk_fma_f32 v[180:181], v[6:7], v[178:179], v[180:181] op_sel_hi:[1,0,1]
	v_pk_fma_f32 v[192:193], v[8:9], v[178:179], v[192:193] op_sel_hi:[1,0,1]
	v_mfma_f32_16x16x4_f32 v[98:101], v141, v73, v[98:101]
	v_pk_fma_f32 v[180:181], v[2:3], v[178:179], v[180:181] op_sel:[0,1,0]
	v_pk_fma_f32 v[192:193], v[4:5], v[178:179], v[192:193] op_sel:[0,1,0]
	v_pk_mul_f32 v[180:181], v[146:147], v[180:181]
	v_pk_mul_f32 v[192:193], v[146:147], v[192:193]
	v_pk_fma_f32 v[236:237], v[144:145], v[70:71], v[180:181]
	v_pk_fma_f32 v[238:239], v[144:145], v[72:73], v[192:193]
	global_store_dwordx4 v[150:151], v[236:239], off nt
	v_lshl_add_u64 v[150:151], v[150:151], 0, s[74:75]
	global_load_dwordx4 v[70:73], v[148:149], off nt
	v_lshl_add_u64 v[148:149], v[148:149], 0, s[74:75]
	ds_read_b32 v141, v160 offset:800
	ds_read_b128 v[114:117], v161 offset:6400
	ds_read_b128 v[176:179], v161 offset:6416
	s_waitcnt vmcnt(14)
	s_waitcnt lgkmcnt(3)
	v_cndmask_b32_e64 v143, 0, v143, s[8:9]
	v_pk_mul_f32 v[180:181], v[26:27], v[172:173] op_sel:[0,1]
	v_pk_mul_f32 v[192:193], v[28:29], v[172:173] op_sel:[0,1]
	v_mfma_f32_16x16x4_f32 v[110:113], v143, v62, v[110:113]
	v_pk_fma_f32 v[180:181], v[30:31], v[172:173], v[180:181] op_sel_hi:[1,0,1]
	v_pk_fma_f32 v[192:193], v[32:33], v[172:173], v[192:193] op_sel_hi:[1,0,1]
	v_pk_fma_f32 v[180:181], v[22:23], v[174:175], v[180:181] op_sel_hi:[1,0,1]
	v_pk_fma_f32 v[192:193], v[24:25], v[174:175], v[192:193] op_sel_hi:[1,0,1]
	v_mfma_f32_16x16x4_f32 v[106:109], v143, v63, v[106:109]
	v_pk_fma_f32 v[180:181], v[18:19], v[174:175], v[180:181] op_sel:[0,1,0]
	v_pk_fma_f32 v[192:193], v[20:21], v[174:175], v[192:193] op_sel:[0,1,0]
	v_pk_fma_f32 v[180:181], v[14:15], v[232:233], v[180:181] op_sel_hi:[1,0,1]
	v_pk_fma_f32 v[192:193], v[16:17], v[232:233], v[192:193] op_sel_hi:[1,0,1]
	v_mfma_f32_16x16x4_f32 v[102:105], v143, v64, v[102:105]
	v_pk_fma_f32 v[180:181], v[10:11], v[232:233], v[180:181] op_sel:[0,1,0]
	v_pk_fma_f32 v[192:193], v[12:13], v[232:233], v[192:193] op_sel:[0,1,0]
	v_pk_fma_f32 v[180:181], v[6:7], v[234:235], v[180:181] op_sel_hi:[1,0,1]
	v_pk_fma_f32 v[192:193], v[8:9], v[234:235], v[192:193] op_sel_hi:[1,0,1]
	v_mfma_f32_16x16x4_f32 v[98:101], v143, v65, v[98:101]
	v_pk_fma_f32 v[180:181], v[2:3], v[234:235], v[180:181] op_sel:[0,1,0]
	v_pk_fma_f32 v[192:193], v[4:5], v[234:235], v[192:193] op_sel:[0,1,0]
	v_pk_mul_f32 v[180:181], v[146:147], v[180:181]
	v_pk_mul_f32 v[192:193], v[146:147], v[192:193]
	v_pk_fma_f32 v[236:237], v[144:145], v[62:63], v[180:181]
	v_pk_fma_f32 v[238:239], v[144:145], v[64:65], v[192:193]
	global_store_dwordx4 v[150:151], v[236:239], off nt
	v_lshl_add_u64 v[150:151], v[150:151], 0, s[74:75]
	global_load_dwordx4 v[62:65], v[148:149], off nt
	v_lshl_add_u64 v[148:149], v[148:149], 0, s[74:75]
	ds_read_b32 v143, v160 offset:816
	ds_read_b128 v[172:175], v161 offset:6528
	ds_read_b128 v[232:235], v161 offset:6544
	s_waitcnt vmcnt(14)
; #define RS_LOAD(dst, it0) do { _Pragma("unroll") for (int u = 0; u < 8; ++u) dst[u] = __builtin_nontemporal_load((const f32x4*)(S0 + (size_t)(4 * ((it0) + u)) * DV)); } while (0)
; __device__ __forceinline__ void ret_sample_item(Frame& F, int item) {
;     ...
;     for (int it0 = 0; it0 < 64; it0 += 16) {
;         RS_LOAD(sb, it0 + 8);
;         RS_PROC(sa, it0);
;         { const int itn = it0 + 16 < 64 ? it0 + 16 : it0; RS_LOAD(sa, itn); }
;         RS_PROC(sb, it0 + 8);
;     }
	s_waitcnt lgkmcnt(3)
	v_cndmask_b32_e64 v141, 0, v141, s[8:9]
	v_pk_mul_f32 v[180:181], v[26:27], v[114:115] op_sel:[0,1]
	v_pk_mul_f32 v[192:193], v[28:29], v[114:115] op_sel:[0,1]
	v_mfma_f32_16x16x4_f32 v[110:113], v141, v54, v[110:113]
	v_pk_fma_f32 v[180:181], v[30:31], v[114:115], v[180:181] op_sel_hi:[1,0,1]
	v_pk_fma_f32 v[192:193], v[32:33], v[114:115], v[192:193] op_sel_hi:[1,0,1]
	v_pk_fma_f32 v[180:181], v[22:23], v[116:117], v[180:181] op_sel_hi:[1,0,1]
	v_pk_fma_f32 v[192:193], v[24:25], v[116:117], v[192:193] op_sel_hi:[1,0,1]
	v_mfma_f32_16x16x4_f32 v[106:109], v141, v55, v[106:109]
	v_pk_fma_f32 v[180:181], v[18:19], v[116:117], v[180:181] op_sel:[0,1,0]
	v_pk_fma_f32 v[192:193], v[20:21], v[116:117], v[192:193] op_sel:[0,1,0]
	v_pk_fma_f32 v[180:181], v[14:15], v[176:177], v[180:181] op_sel_hi:[1,0,1]
	v_pk_fma_f32 v[192:193], v[16:17], v[176:177], v[192:193] op_sel_hi:[1,0,1]
	v_mfma_f32_16x16x4_f32 v[102:105], v141, v56, v[102:105]
	v_pk_fma_f32 v[180:181], v[10:11], v[176:177], v[180:181] op_sel:[0,1,0]
	v_pk_fma_f32 v[192:193], v[12:13], v[176:177], v[192:193] op_sel:[0,1,0]
	v_pk_fma_f32 v[180:181], v[6:7], v[178:179], v[180:181] op_sel_hi:[1,0,1]
	v_pk_fma_f32 v[192:193], v[8:9], v[178:179], v[192:193] op_sel_hi:[1,0,1]
	v_mfma_f32_16x16x4_f32 v[98:101], v141, v57, v[98:101]
	v_pk_fma_f32 v[180:181], v[2:3], v[178:179], v[180:181] op_sel:[0,1,0]
	v_pk_fma_f32 v[192:193], v[4:5], v[178:179], v[192:193] op_sel:[0,1,0]
	v_pk_mul_f32 v[180:181], v[146:147], v[180:181]
	v_pk_mul_f32 v[192:193], v[146:147], v[192:193]
	v_pk_fma_f32 v[236:237], v[144:145], v[54:55], v[180:181]
	v_pk_fma_f32 v[238:239], v[144:145], v[56:57], v[192:193]
	global_store_dwordx4 v[150:151], v[236:239], off nt
	v_lshl_add_u64 v[150:151], v[150:151], 0, s[74:75]
	global_load_dwordx4 v[54:57], v[148:149], off nt
	v_lshl_add_u64 v[148:149], v[148:149], 0, s[74:75]
	ds_read_b32 v141, v160 offset:832
	ds_read_b128 v[114:117], v161 offset:6656
	ds_read_b128 v[176:179], v161 offset:6672
	s_waitcnt vmcnt(14)
	s_waitcnt lgkmcnt(3)
	v_cndmask_b32_e64 v143, 0, v143, s[8:9]
	v_pk_mul_f32 v[180:181], v[26:27], v[172:173] op_sel:[0,1]
	v_pk_mul_f32 v[192:193], v[28:29], v[172:173] op_sel:[0,1]
	v_mfma_f32_16x16x4_f32 v[110:113], v143, v50, v[110:113]
	v_pk_fma_f32 v[180:181], v[30:31], v[172:173], v[180:181] op_sel_hi:[1,0,1]
	v_pk_fma_f32 v[192:193], v[32:33], v[172:173], v[192:193] op_sel_hi:[1,0,1]
	v_pk_fma_f32 v[180:181], v[22:23], v[174:175], v[180:181] op_sel_hi:[1,0,1]
	v_pk_fma_f32 v[192:193], v[24:25], v[174:175], v[192:193] op_sel_hi:[1,0,1]
	v_mfma_f32_16x16x4_f32 v[106:109], v143, v51, v[106:109]
	v_pk_fma_f32 v[180:181], v[18:19], v[174:175], v[180:181] op_sel:[0,1,0]
	v_pk_fma_f32 v[192:193], v[20:21], v[174:175], v[192:193] op_sel:[0,1,0]
	v_pk_fma_f32 v[180:181], v[14:15], v[232:233], v[180:181] op_sel_hi:[1,0,1]
	v_pk_fma_f32 v[192:193], v[16:17], v[232:233], v[192:193] op_sel_hi:[1,0,1]
	v_mfma_f32_16x16x4_f32 v[102:105], v143, v52, v[102:105]
	v_pk_fma_f32 v[180:181], v[10:11], v[232:233], v[180:181] op_sel:[0,1,0]
	v_pk_fma_f32 v[192:193], v[12:13], v[232:233], v[192:193] op_sel:[0,1,0]
	v_pk_fma_f32 v[180:181], v[6:7], v[234:235], v[180:181] op_sel_hi:[1,0,1]
	v_pk_fma_f32 v[192:193], v[8:9], v[234:235], v[192:193] op_sel_hi:[1,0,1]
	v_mfma_f32_16x16x4_f32 v[98:101], v143, v53, v[98:101]
	v_pk_fma_f32 v[180:181], v[2:3], v[234:235], v[180:181] op_sel:[0,1,0]
	v_pk_fma_f32 v[192:193], v[4:5], v[234:235], v[192:193] op_sel:[0,1,0]
	v_pk_mul_f32 v[180:181], v[146:147], v[180:181]
	v_pk_mul_f32 v[192:193], v[146:147], v[192:193]
	v_pk_fma_f32 v[236:237], v[144:145], v[50:51], v[180:181]
	v_pk_fma_f32 v[238:239], v[144:145], v[52:53], v[192:193]
	global_store_dwordx4 v[150:151], v[236:239], off nt
	v_lshl_add_u64 v[150:151], v[150:151], 0, s[74:75]
	global_load_dwordx4 v[50:53], v[148:149], off nt
	v_lshl_add_u64 v[148:149], v[148:149], 0, s[74:75]
	ds_read_b32 v143, v160 offset:848
	ds_read_b128 v[172:175], v161 offset:6784
	ds_read_b128 v[232:235], v161 offset:6800
	s_waitcnt vmcnt(14)
	s_waitcnt lgkmcnt(3)
	v_cndmask_b32_e64 v141, 0, v141, s[8:9]
	v_pk_mul_f32 v[180:181], v[26:27], v[114:115] op_sel:[0,1]
	v_pk_mul_f32 v[192:193], v[28:29], v[114:115] op_sel:[0,1]
	v_mfma_f32_16x16x4_f32 v[110:113], v141, v46, v[110:113]
	v_pk_fma_f32 v[180:181], v[30:31], v[114:115], v[180:181] op_sel_hi:[1,0,1]
	v_pk_fma_f32 v[192:193], v[32:33], v[114:115], v[192:193] op_sel_hi:[1,0,1]
	v_pk_fma_f32 v[180:181], v[22:23], v[116:117], v[180:181] op_sel_hi:[1,0,1]
	v_pk_fma_f32 v[192:193], v[24:25], v[116:117], v[192:193] op_sel_hi:[1,0,1]
	v_mfma_f32_16x16x4_f32 v[106:109], v141, v47, v[106:109]
	v_pk_fma_f32 v[180:181], v[18:19], v[116:117], v[180:181] op_sel:[0,1,0]
	v_pk_fma_f32 v[192:193], v[20:21], v[116:117], v[192:193] op_sel:[0,1,0]
	v_pk_fma_f32 v[180:181], v[14:15], v[176:177], v[180:181] op_sel_hi:[1,0,1]
	v_pk_fma_f32 v[192:193], v[16:17], v[176:177], v[192:193] op_sel_hi:[1,0,1]
	v_mfma_f32_16x16x4_f32 v[102:105], v141, v48, v[102:105]
	v_pk_fma_f32 v[180:181], v[10:11], v[176:177], v[180:181] op_sel:[0,1,0]
	v_pk_fma_f32 v[192:193], v[12:13], v[176:177], v[192:193] op_sel:[0,1,0]
	v_pk_fma_f32 v[180:181], v[6:7], v[178:179], v[180:181] op_sel_hi:[1,0,1]
	v_pk_fma_f32 v[192:193], v[8:9], v[178:179], v[192:193] op_sel_hi:[1,0,1]
	v_mfma_f32_16x16x4_f32 v[98:101], v141, v49, v[98:101]
	v_pk_fma_f32 v[180:181], v[2:3], v[178:179], v[180:181] op_sel:[0,1,0]
	v_pk_fma_f32 v[192:193], v[4:5], v[178:179], v[192:193] op_sel:[0,1,0]
	v_pk_mul_f32 v[180:181], v[146:147], v[180:181]
	v_pk_mul_f32 v[192:193], v[146:147], v[192:193]
	v_pk_fma_f32 v[236:237], v[144:145], v[46:47], v[180:181]
	v_pk_fma_f32 v[238:239], v[144:145], v[48:49], v[192:193]
	global_store_dwordx4 v[150:151], v[236:239], off nt
	v_lshl_add_u64 v[150:151], v[150:151], 0, s[74:75]
	global_load_dwordx4 v[46:49], v[148:149], off nt
	v_lshl_add_u64 v[148:149], v[148:149], 0, s[74:75]
	ds_read_b32 v141, v160 offset:864
	ds_read_b128 v[114:117], v161 offset:6912
	ds_read_b128 v[176:179], v161 offset:6928
	s_waitcnt vmcnt(14)
; #define RS_LOAD(dst, it0) do { _Pragma("unroll") for (int u = 0; u < 8; ++u) dst[u] = __builtin_nontemporal_load((const f32x4*)(S0 + (size_t)(4 * ((it0) + u)) * DV)); } while (0)
; __device__ __forceinline__ void ret_sample_item(Frame& F, int item) {
;     ...
;     for (int it0 = 0; it0 < 64; it0 += 16) {
;         RS_LOAD(sb, it0 + 8);
;         RS_PROC(sa, it0);
;         { const int itn = it0 + 16 < 64 ? it0 + 16 : it0; RS_LOAD(sa, itn); }
;         RS_PROC(sb, it0 + 8);
;     }
	s_waitcnt lgkmcnt(3)
	v_cndmask_b32_e64 v143, 0, v143, s[8:9]
	v_pk_mul_f32 v[180:181], v[26:27], v[172:173] op_sel:[0,1]
	v_pk_mul_f32 v[192:193], v[28:29], v[172:173] op_sel:[0,1]
	v_mfma_f32_16x16x4_f32 v[110:113], v143, v42, v[110:113]
	v_pk_fma_f32 v[180:181], v[30:31], v[172:173], v[180:181] op_sel_hi:[1,0,1]
	v_pk_fma_f32 v[192:193], v[32:33], v[172:173], v[192:193] op_sel_hi:[1,0,1]
	v_pk_fma_f32 v[180:181], v[22:23], v[174:175], v[180:181] op_sel_hi:[1,0,1]
	v_pk_fma_f32 v[192:193], v[24:25], v[174:175], v[192:193] op_sel_hi:[1,0,1]
	v_mfma_f32_16x16x4_f32 v[106:109], v143, v43, v[106:109]
	v_pk_fma_f32 v[180:181], v[18:19], v[174:175], v[180:181] op_sel:[0,1,0]
	v_pk_fma_f32 v[192:193], v[20:21], v[174:175], v[192:193] op_sel:[0,1,0]
	v_pk_fma_f32 v[180:181], v[14:15], v[232:233], v[180:181] op_sel_hi:[1,0,1]
	v_pk_fma_f32 v[192:193], v[16:17], v[232:233], v[192:193] op_sel_hi:[1,0,1]
	v_mfma_f32_16x16x4_f32 v[102:105], v143, v44, v[102:105]
	v_pk_fma_f32 v[180:181], v[10:11], v[232:233], v[180:181] op_sel:[0,1,0]
	v_pk_fma_f32 v[192:193], v[12:13], v[232:233], v[192:193] op_sel:[0,1,0]
	v_pk_fma_f32 v[180:181], v[6:7], v[234:235], v[180:181] op_sel_hi:[1,0,1]
	v_pk_fma_f32 v[192:193], v[8:9], v[234:235], v[192:193] op_sel_hi:[1,0,1]
	v_mfma_f32_16x16x4_f32 v[98:101], v143, v45, v[98:101]
	v_pk_fma_f32 v[180:181], v[2:3], v[234:235], v[180:181] op_sel:[0,1,0]
	v_pk_fma_f32 v[192:193], v[4:5], v[234:235], v[192:193] op_sel:[0,1,0]
	v_pk_mul_f32 v[180:181], v[146:147], v[180:181]
	v_pk_mul_f32 v[192:193], v[146:147], v[192:193]
	v_pk_fma_f32 v[236:237], v[144:145], v[42:43], v[180:181]
	v_pk_fma_f32 v[238:239], v[144:145], v[44:45], v[192:193]
	global_store_dwordx4 v[150:151], v[236:239], off nt
	v_lshl_add_u64 v[150:151], v[150:151], 0, s[74:75]
	global_load_dwordx4 v[42:45], v[148:149], off nt
	v_lshl_add_u64 v[148:149], v[148:149], 0, s[74:75]
	ds_read_b32 v143, v160 offset:880
	ds_read_b128 v[172:175], v161 offset:7040
	ds_read_b128 v[232:235], v161 offset:7056
	s_waitcnt vmcnt(14)
	s_waitcnt lgkmcnt(3)
	v_cndmask_b32_e64 v141, 0, v141, s[8:9]
	v_pk_mul_f32 v[180:181], v[26:27], v[114:115] op_sel:[0,1]
	v_pk_mul_f32 v[192:193], v[28:29], v[114:115] op_sel:[0,1]
	v_mfma_f32_16x16x4_f32 v[110:113], v141, v38, v[110:113]
	v_pk_fma_f32 v[180:181], v[30:31], v[114:115], v[180:181] op_sel_hi:[1,0,1]
	v_pk_fma_f32 v[192:193], v[32:33], v[114:115], v[192:193] op_sel_hi:[1,0,1]
	v_pk_fma_f32 v[180:181], v[22:23], v[116:117], v[180:181] op_sel_hi:[1,0,1]
	v_pk_fma_f32 v[192:193], v[24:25], v[116:117], v[192:193] op_sel_hi:[1,0,1]
	v_mfma_f32_16x16x4_f32 v[106:109], v141, v39, v[106:109]
	v_pk_fma_f32 v[180:181], v[18:19], v[116:117], v[180:181] op_sel:[0,1,0]
	v_pk_fma_f32 v[192:193], v[20:21], v[116:117], v[192:193] op_sel:[0,1,0]
	v_pk_fma_f32 v[180:181], v[14:15], v[176:177], v[180:181] op_sel_hi:[1,0,1]
	v_pk_fma_f32 v[192:193], v[16:17], v[176:177], v[192:193] op_sel_hi:[1,0,1]
	v_mfma_f32_16x16x4_f32 v[102:105], v141, v40, v[102:105]
	v_pk_fma_f32 v[180:181], v[10:11], v[176:177], v[180:181] op_sel:[0,1,0]
	v_pk_fma_f32 v[192:193], v[12:13], v[176:177], v[192:193] op_sel:[0,1,0]
	v_pk_fma_f32 v[180:181], v[6:7], v[178:179], v[180:181] op_sel_hi:[1,0,1]
	v_pk_fma_f32 v[192:193], v[8:9], v[178:179], v[192:193] op_sel_hi:[1,0,1]
	v_mfma_f32_16x16x4_f32 v[98:101], v141, v41, v[98:101]
	v_pk_fma_f32 v[180:181], v[2:3], v[178:179], v[180:181] op_sel:[0,1,0]
	v_pk_fma_f32 v[192:193], v[4:5], v[178:179], v[192:193] op_sel:[0,1,0]
	v_pk_mul_f32 v[180:181], v[146:147], v[180:181]
	v_pk_mul_f32 v[192:193], v[146:147], v[192:193]
	v_pk_fma_f32 v[236:237], v[144:145], v[38:39], v[180:181]
	v_pk_fma_f32 v[238:239], v[144:145], v[40:41], v[192:193]
	global_store_dwordx4 v[150:151], v[236:239], off nt
	v_lshl_add_u64 v[150:151], v[150:151], 0, s[74:75]
	global_load_dwordx4 v[38:41], v[148:149], off nt
	v_lshl_add_u64 v[148:149], v[148:149], 0, s[74:75]
	ds_read_b32 v141, v160 offset:896
	ds_read_b128 v[114:117], v161 offset:7168
	ds_read_b128 v[176:179], v161 offset:7184
	s_waitcnt vmcnt(14)
	s_waitcnt lgkmcnt(3)
	v_cndmask_b32_e64 v143, 0, v143, s[8:9]
	v_pk_mul_f32 v[180:181], v[26:27], v[172:173] op_sel:[0,1]
	v_pk_mul_f32 v[192:193], v[28:29], v[172:173] op_sel:[0,1]
	v_mfma_f32_16x16x4_f32 v[110:113], v143, v34, v[110:113]
	v_pk_fma_f32 v[180:181], v[30:31], v[172:173], v[180:181] op_sel_hi:[1,0,1]
	v_pk_fma_f32 v[192:193], v[32:33], v[172:173], v[192:193] op_sel_hi:[1,0,1]
	v_pk_fma_f32 v[180:181], v[22:23], v[174:175], v[180:181] op_sel_hi:[1,0,1]
	v_pk_fma_f32 v[192:193], v[24:25], v[174:175], v[192:193] op_sel_hi:[1,0,1]
	v_mfma_f32_16x16x4_f32 v[106:109], v143, v35, v[106:109]
	v_pk_fma_f32 v[180:181], v[18:19], v[174:175], v[180:181] op_sel:[0,1,0]
	v_pk_fma_f32 v[192:193], v[20:21], v[174:175], v[192:193] op_sel:[0,1,0]
	v_pk_fma_f32 v[180:181], v[14:15], v[232:233], v[180:181] op_sel_hi:[1,0,1]
	v_pk_fma_f32 v[192:193], v[16:17], v[232:233], v[192:193] op_sel_hi:[1,0,1]
	v_mfma_f32_16x16x4_f32 v[102:105], v143, v36, v[102:105]
	v_pk_fma_f32 v[180:181], v[10:11], v[232:233], v[180:181] op_sel:[0,1,0]
	v_pk_fma_f32 v[192:193], v[12:13], v[232:233], v[192:193] op_sel:[0,1,0]
	v_pk_fma_f32 v[180:181], v[6:7], v[234:235], v[180:181] op_sel_hi:[1,0,1]
	v_pk_fma_f32 v[192:193], v[8:9], v[234:235], v[192:193] op_sel_hi:[1,0,1]
	v_mfma_f32_16x16x4_f32 v[98:101], v143, v37, v[98:101]
	v_pk_fma_f32 v[180:181], v[2:3], v[234:235], v[180:181] op_sel:[0,1,0]
	v_pk_fma_f32 v[192:193], v[4:5], v[234:235], v[192:193] op_sel:[0,1,0]
	v_pk_mul_f32 v[180:181], v[146:147], v[180:181]
	v_pk_mul_f32 v[192:193], v[146:147], v[192:193]
	v_pk_fma_f32 v[236:237], v[144:145], v[34:35], v[180:181]
	v_pk_fma_f32 v[238:239], v[144:145], v[36:37], v[192:193]
	global_store_dwordx4 v[150:151], v[236:239], off nt
	v_lshl_add_u64 v[150:151], v[150:151], 0, s[74:75]
	global_load_dwordx4 v[34:37], v[148:149], off nt
	v_lshl_add_u64 v[148:149], v[148:149], 0, s[74:75]
	ds_read_b32 v143, v160 offset:912
	ds_read_b128 v[172:175], v161 offset:7296
	ds_read_b128 v[232:235], v161 offset:7312
	s_waitcnt vmcnt(14)
; #define RS_LOAD(dst, it0) do { _Pragma("unroll") for (int u = 0; u < 8; ++u) dst[u] = __builtin_nontemporal_load((const f32x4*)(S0 + (size_t)(4 * ((it0) + u)) * DV)); } while (0)
; __device__ __forceinline__ void ret_sample_item(Frame& F, int item) {
;     ...
;     for (int it0 = 0; it0 < 64; it0 += 16) {
;         RS_LOAD(sb, it0 + 8);
;         RS_PROC(sa, it0);
;         { const int itn = it0 + 16 < 64 ? it0 + 16 : it0; RS_LOAD(sa, itn); }
;         RS_PROC(sb, it0 + 8);
;     }
	s_waitcnt lgkmcnt(3)
	v_cndmask_b32_e64 v141, 0, v141, s[8:9]
	v_pk_mul_f32 v[180:181], v[26:27], v[114:115] op_sel:[0,1]
	v_pk_mul_f32 v[192:193], v[28:29], v[114:115] op_sel:[0,1]
	v_mfma_f32_16x16x4_f32 v[110:113], v141, v70, v[110:113]
	v_pk_fma_f32 v[180:181], v[30:31], v[114:115], v[180:181] op_sel_hi:[1,0,1]
	v_pk_fma_f32 v[192:193], v[32:33], v[114:115], v[192:193] op_sel_hi:[1,0,1]
	v_pk_fma_f32 v[180:181], v[22:23], v[116:117], v[180:181] op_sel_hi:[1,0,1]
	v_pk_fma_f32 v[192:193], v[24:25], v[116:117], v[192:193] op_sel_hi:[1,0,1]
	v_mfma_f32_16x16x4_f32 v[106:109], v141, v71, v[106:109]
	v_pk_fma_f32 v[180:181], v[18:19], v[116:117], v[180:181] op_sel:[0,1,0]
	v_pk_fma_f32 v[192:193], v[20:21], v[116:117], v[192:193] op_sel:[0,1,0]
	v_pk_fma_f32 v[180:181], v[14:15], v[176:177], v[180:181] op_sel_hi:[1,0,1]
	v_pk_fma_f32 v[192:193], v[16:17], v[176:177], v[192:193] op_sel_hi:[1,0,1]
	v_mfma_f32_16x16x4_f32 v[102:105], v141, v72, v[102:105]
	v_pk_fma_f32 v[180:181], v[10:11], v[176:177], v[180:181] op_sel:[0,1,0]
	v_pk_fma_f32 v[192:193], v[12:13], v[176:177], v[192:193] op_sel:[0,1,0]
	v_pk_fma_f32 v[180:181], v[6:7], v[178:179], v[180:181] op_sel_hi:[1,0,1]
	v_pk_fma_f32 v[192:193], v[8:9], v[178:179], v[192:193] op_sel_hi:[1,0,1]
	v_mfma_f32_16x16x4_f32 v[98:101], v141, v73, v[98:101]
	v_pk_fma_f32 v[180:181], v[2:3], v[178:179], v[180:181] op_sel:[0,1,0]
	v_pk_fma_f32 v[192:193], v[4:5], v[178:179], v[192:193] op_sel:[0,1,0]
	v_pk_mul_f32 v[180:181], v[146:147], v[180:181]
	v_pk_mul_f32 v[192:193], v[146:147], v[192:193]
	v_pk_fma_f32 v[236:237], v[144:145], v[70:71], v[180:181]
	v_pk_fma_f32 v[238:239], v[144:145], v[72:73], v[192:193]
	global_store_dwordx4 v[150:151], v[236:239], off nt
	v_lshl_add_u64 v[150:151], v[150:151], 0, s[74:75]
	ds_read_b32 v141, v160 offset:928
	ds_read_b128 v[114:117], v161 offset:7424
	ds_read_b128 v[176:179], v161 offset:7440
	s_waitcnt vmcnt(13)
	s_waitcnt lgkmcnt(3)
	v_cndmask_b32_e64 v143, 0, v143, s[8:9]
	v_pk_mul_f32 v[180:181], v[26:27], v[172:173] op_sel:[0,1]
	v_pk_mul_f32 v[192:193], v[28:29], v[172:173] op_sel:[0,1]
	v_mfma_f32_16x16x4_f32 v[110:113], v143, v62, v[110:113]
	v_pk_fma_f32 v[180:181], v[30:31], v[172:173], v[180:181] op_sel_hi:[1,0,1]
	v_pk_fma_f32 v[192:193], v[32:33], v[172:173], v[192:193] op_sel_hi:[1,0,1]
	v_pk_fma_f32 v[180:181], v[22:23], v[174:175], v[180:181] op_sel_hi:[1,0,1]
	v_pk_fma_f32 v[192:193], v[24:25], v[174:175], v[192:193] op_sel_hi:[1,0,1]
	v_mfma_f32_16x16x4_f32 v[106:109], v143, v63, v[106:109]
	v_pk_fma_f32 v[180:181], v[18:19], v[174:175], v[180:181] op_sel:[0,1,0]
	v_pk_fma_f32 v[192:193], v[20:21], v[174:175], v[192:193] op_sel:[0,1,0]
	v_pk_fma_f32 v[180:181], v[14:15], v[232:233], v[180:181] op_sel_hi:[1,0,1]
	v_pk_fma_f32 v[192:193], v[16:17], v[232:233], v[192:193] op_sel_hi:[1,0,1]
	v_mfma_f32_16x16x4_f32 v[102:105], v143, v64, v[102:105]
	v_pk_fma_f32 v[180:181], v[10:11], v[232:233], v[180:181] op_sel:[0,1,0]
	v_pk_fma_f32 v[192:193], v[12:13], v[232:233], v[192:193] op_sel:[0,1,0]
	v_pk_fma_f32 v[180:181], v[6:7], v[234:235], v[180:181] op_sel_hi:[1,0,1]
	v_pk_fma_f32 v[192:193], v[8:9], v[234:235], v[192:193] op_sel_hi:[1,0,1]
	v_mfma_f32_16x16x4_f32 v[98:101], v143, v65, v[98:101]
	v_pk_fma_f32 v[180:181], v[2:3], v[234:235], v[180:181] op_sel:[0,1,0]
	v_pk_fma_f32 v[192:193], v[4:5], v[234:235], v[192:193] op_sel:[0,1,0]
	v_pk_mul_f32 v[180:181], v[146:147], v[180:181]
	v_pk_mul_f32 v[192:193], v[146:147], v[192:193]
	v_pk_fma_f32 v[236:237], v[144:145], v[62:63], v[180:181]
	v_pk_fma_f32 v[238:239], v[144:145], v[64:65], v[192:193]
	global_store_dwordx4 v[150:151], v[236:239], off nt
	v_lshl_add_u64 v[150:151], v[150:151], 0, s[74:75]
	ds_read_b32 v143, v160 offset:944
	ds_read_b128 v[172:175], v161 offset:7552
	ds_read_b128 v[232:235], v161 offset:7568
	s_waitcnt vmcnt(12)
	s_waitcnt lgkmcnt(3)
	v_cndmask_b32_e64 v141, 0, v141, s[8:9]
	v_pk_mul_f32 v[180:181], v[26:27], v[114:115] op_sel:[0,1]
	v_pk_mul_f32 v[192:193], v[28:29], v[114:115] op_sel:[0,1]
	v_mfma_f32_16x16x4_f32 v[110:113], v141, v54, v[110:113]
	v_pk_fma_f32 v[180:181], v[30:31], v[114:115], v[180:181] op_sel_hi:[1,0,1]
	v_pk_fma_f32 v[192:193], v[32:33], v[114:115], v[192:193] op_sel_hi:[1,0,1]
	v_pk_fma_f32 v[180:181], v[22:23], v[116:117], v[180:181] op_sel_hi:[1,0,1]
	v_pk_fma_f32 v[192:193], v[24:25], v[116:117], v[192:193] op_sel_hi:[1,0,1]
	v_mfma_f32_16x16x4_f32 v[106:109], v141, v55, v[106:109]
	v_pk_fma_f32 v[180:181], v[18:19], v[116:117], v[180:181] op_sel:[0,1,0]
	v_pk_fma_f32 v[192:193], v[20:21], v[116:117], v[192:193] op_sel:[0,1,0]
	v_pk_fma_f32 v[180:181], v[14:15], v[176:177], v[180:181] op_sel_hi:[1,0,1]
	v_pk_fma_f32 v[192:193], v[16:17], v[176:177], v[192:193] op_sel_hi:[1,0,1]
	v_mfma_f32_16x16x4_f32 v[102:105], v141, v56, v[102:105]
	v_pk_fma_f32 v[180:181], v[10:11], v[176:177], v[180:181] op_sel:[0,1,0]
	v_pk_fma_f32 v[192:193], v[12:13], v[176:177], v[192:193] op_sel:[0,1,0]
	v_pk_fma_f32 v[180:181], v[6:7], v[178:179], v[180:181] op_sel_hi:[1,0,1]
	v_pk_fma_f32 v[192:193], v[8:9], v[178:179], v[192:193] op_sel_hi:[1,0,1]
	v_mfma_f32_16x16x4_f32 v[98:101], v141, v57, v[98:101]
	v_pk_fma_f32 v[180:181], v[2:3], v[178:179], v[180:181] op_sel:[0,1,0]
	v_pk_fma_f32 v[192:193], v[4:5], v[178:179], v[192:193] op_sel:[0,1,0]
	v_pk_mul_f32 v[180:181], v[146:147], v[180:181]
	v_pk_mul_f32 v[192:193], v[146:147], v[192:193]
	v_pk_fma_f32 v[236:237], v[144:145], v[54:55], v[180:181]
	v_pk_fma_f32 v[238:239], v[144:145], v[56:57], v[192:193]
	global_store_dwordx4 v[150:151], v[236:239], off nt
	v_lshl_add_u64 v[150:151], v[150:151], 0, s[74:75]
	ds_read_b32 v141, v160 offset:960
	ds_read_b128 v[114:117], v161 offset:7680
	ds_read_b128 v[176:179], v161 offset:7696
	s_waitcnt vmcnt(11)
; #define RS_LOAD(dst, it0) do { _Pragma("unroll") for (int u = 0; u < 8; ++u) dst[u] = __builtin_nontemporal_load((const f32x4*)(S0 + (size_t)(4 * ((it0) + u)) * DV)); } while (0)
; __device__ __forceinline__ void ret_sample_item(Frame& F, int item) {
;     ...
;     for (int it0 = 0; it0 < 64; it0 += 16) {
;         RS_LOAD(sb, it0 + 8);
;         RS_PROC(sa, it0);
;         { const int itn = it0 + 16 < 64 ? it0 + 16 : it0; RS_LOAD(sa, itn); }
;         RS_PROC(sb, it0 + 8);
;     }
	s_waitcnt lgkmcnt(3)
	v_cndmask_b32_e64 v143, 0, v143, s[8:9]
	v_pk_mul_f32 v[180:181], v[26:27], v[172:173] op_sel:[0,1]
	v_pk_mul_f32 v[192:193], v[28:29], v[172:173] op_sel:[0,1]
	v_mfma_f32_16x16x4_f32 v[110:113], v143, v50, v[110:113]
	v_pk_fma_f32 v[180:181], v[30:31], v[172:173], v[180:181] op_sel_hi:[1,0,1]
	v_pk_fma_f32 v[192:193], v[32:33], v[172:173], v[192:193] op_sel_hi:[1,0,1]
	v_pk_fma_f32 v[180:181], v[22:23], v[174:175], v[180:181] op_sel_hi:[1,0,1]
	v_pk_fma_f32 v[192:193], v[24:25], v[174:175], v[192:193] op_sel_hi:[1,0,1]
	v_mfma_f32_16x16x4_f32 v[106:109], v143, v51, v[106:109]
	v_pk_fma_f32 v[180:181], v[18:19], v[174:175], v[180:181] op_sel:[0,1,0]
	v_pk_fma_f32 v[192:193], v[20:21], v[174:175], v[192:193] op_sel:[0,1,0]
	v_pk_fma_f32 v[180:181], v[14:15], v[232:233], v[180:181] op_sel_hi:[1,0,1]
	v_pk_fma_f32 v[192:193], v[16:17], v[232:233], v[192:193] op_sel_hi:[1,0,1]
	v_mfma_f32_16x16x4_f32 v[102:105], v143, v52, v[102:105]
	v_pk_fma_f32 v[180:181], v[10:11], v[232:233], v[180:181] op_sel:[0,1,0]
	v_pk_fma_f32 v[192:193], v[12:13], v[232:233], v[192:193] op_sel:[0,1,0]
	v_pk_fma_f32 v[180:181], v[6:7], v[234:235], v[180:181] op_sel_hi:[1,0,1]
	v_pk_fma_f32 v[192:193], v[8:9], v[234:235], v[192:193] op_sel_hi:[1,0,1]
	v_mfma_f32_16x16x4_f32 v[98:101], v143, v53, v[98:101]
	v_pk_fma_f32 v[180:181], v[2:3], v[234:235], v[180:181] op_sel:[0,1,0]
	v_pk_fma_f32 v[192:193], v[4:5], v[234:235], v[192:193] op_sel:[0,1,0]
	v_pk_mul_f32 v[180:181], v[146:147], v[180:181]
	v_pk_mul_f32 v[192:193], v[146:147], v[192:193]
	v_pk_fma_f32 v[236:237], v[144:145], v[50:51], v[180:181]
	v_pk_fma_f32 v[238:239], v[144:145], v[52:53], v[192:193]
	global_store_dwordx4 v[150:151], v[236:239], off nt
	v_lshl_add_u64 v[150:151], v[150:151], 0, s[74:75]
	ds_read_b32 v143, v160 offset:976
	ds_read_b128 v[172:175], v161 offset:7808
	ds_read_b128 v[232:235], v161 offset:7824
	s_waitcnt vmcnt(10)
	s_waitcnt lgkmcnt(3)
	v_cndmask_b32_e64 v141, 0, v141, s[8:9]
	v_pk_mul_f32 v[180:181], v[26:27], v[114:115] op_sel:[0,1]
	v_pk_mul_f32 v[192:193], v[28:29], v[114:115] op_sel:[0,1]
	v_mfma_f32_16x16x4_f32 v[110:113], v141, v46, v[110:113]
	v_pk_fma_f32 v[180:181], v[30:31], v[114:115], v[180:181] op_sel_hi:[1,0,1]
	v_pk_fma_f32 v[192:193], v[32:33], v[114:115], v[192:193] op_sel_hi:[1,0,1]
	v_pk_fma_f32 v[180:181], v[22:23], v[116:117], v[180:181] op_sel_hi:[1,0,1]
	v_pk_fma_f32 v[192:193], v[24:25], v[116:117], v[192:193] op_sel_hi:[1,0,1]
	v_mfma_f32_16x16x4_f32 v[106:109], v141, v47, v[106:109]
	v_pk_fma_f32 v[180:181], v[18:19], v[116:117], v[180:181] op_sel:[0,1,0]
	v_pk_fma_f32 v[192:193], v[20:21], v[116:117], v[192:193] op_sel:[0,1,0]
	v_pk_fma_f32 v[180:181], v[14:15], v[176:177], v[180:181] op_sel_hi:[1,0,1]
	v_pk_fma_f32 v[192:193], v[16:17], v[176:177], v[192:193] op_sel_hi:[1,0,1]
	v_mfma_f32_16x16x4_f32 v[102:105], v141, v48, v[102:105]
	v_pk_fma_f32 v[180:181], v[10:11], v[176:177], v[180:181] op_sel:[0,1,0]
	v_pk_fma_f32 v[192:193], v[12:13], v[176:177], v[192:193] op_sel:[0,1,0]
	v_pk_fma_f32 v[180:181], v[6:7], v[178:179], v[180:181] op_sel_hi:[1,0,1]
	v_pk_fma_f32 v[192:193], v[8:9], v[178:179], v[192:193] op_sel_hi:[1,0,1]
	v_mfma_f32_16x16x4_f32 v[98:101], v141, v49, v[98:101]
	v_pk_fma_f32 v[180:181], v[2:3], v[178:179], v[180:181] op_sel:[0,1,0]
	v_pk_fma_f32 v[192:193], v[4:5], v[178:179], v[192:193] op_sel:[0,1,0]
	v_pk_mul_f32 v[180:181], v[146:147], v[180:181]
	v_pk_mul_f32 v[192:193], v[146:147], v[192:193]
	v_pk_fma_f32 v[236:237], v[144:145], v[46:47], v[180:181]
	v_pk_fma_f32 v[238:239], v[144:145], v[48:49], v[192:193]
	global_store_dwordx4 v[150:151], v[236:239], off nt
	v_lshl_add_u64 v[150:151], v[150:151], 0, s[74:75]
	ds_read_b32 v141, v160 offset:992
	ds_read_b128 v[114:117], v161 offset:7936
	ds_read_b128 v[176:179], v161 offset:7952
	s_waitcnt vmcnt(9)
	s_waitcnt lgkmcnt(3)
; __device__ __forceinline__ unsigned pk2(float lo, float hi) { unsigned r; asm("v_cvt_pk_bf16_f32 %0, %1, %2" : "=v"(r) : "v"(lo), "v"(hi)); return r; }
; __device__ __forceinline__ void ret_sample_item(Frame& F, int item) {
;     ...
;     if (fq < 2) {
; #pragma unroll
;         for (int j = 0; j < 4; ++j) { const int n = 4 * fq + j;
;             f32x4 o = (f32x4){oacc[0][j], oacc[1][j], oacc[2][j], oacc[3][j]} * gam;
; #pragma unroll
;             for (int m = 0; m < 8; ++m) o += pm[n * 8 + m] * v4[m];
;             u32x2 o2; o2.x = pk2(o[0], o[1]); o2.y = pk2(o[2], o[3]);
;             *(u32x2*)(WSP(bf16, WS_O) + (size_t)(r0 + n) * HV + h * DV + e4) = o2; }
	v_cndmask_b32_e64 v143, 0, v143, s[8:9]
	v_pk_mul_f32 v[180:181], v[26:27], v[172:173] op_sel:[0,1]
	v_pk_mul_f32 v[192:193], v[28:29], v[172:173] op_sel:[0,1]
	v_mfma_f32_16x16x4_f32 v[110:113], v143, v42, v[110:113]
	v_pk_fma_f32 v[180:181], v[30:31], v[172:173], v[180:181] op_sel_hi:[1,0,1]
	v_pk_fma_f32 v[192:193], v[32:33], v[172:173], v[192:193] op_sel_hi:[1,0,1]
	v_pk_fma_f32 v[180:181], v[22:23], v[174:175], v[180:181] op_sel_hi:[1,0,1]
	v_pk_fma_f32 v[192:193], v[24:25], v[174:175], v[192:193] op_sel_hi:[1,0,1]
	v_mfma_f32_16x16x4_f32 v[106:109], v143, v43, v[106:109]
	v_pk_fma_f32 v[180:181], v[18:19], v[174:175], v[180:181] op_sel:[0,1,0]
	v_pk_fma_f32 v[192:193], v[20:21], v[174:175], v[192:193] op_sel:[0,1,0]
	v_pk_fma_f32 v[180:181], v[14:15], v[232:233], v[180:181] op_sel_hi:[1,0,1]
	v_pk_fma_f32 v[192:193], v[16:17], v[232:233], v[192:193] op_sel_hi:[1,0,1]
	v_mfma_f32_16x16x4_f32 v[102:105], v143, v44, v[102:105]
	v_pk_fma_f32 v[180:181], v[10:11], v[232:233], v[180:181] op_sel:[0,1,0]
	v_pk_fma_f32 v[192:193], v[12:13], v[232:233], v[192:193] op_sel:[0,1,0]
	v_pk_fma_f32 v[180:181], v[6:7], v[234:235], v[180:181] op_sel_hi:[1,0,1]
	v_pk_fma_f32 v[192:193], v[8:9], v[234:235], v[192:193] op_sel_hi:[1,0,1]
	v_mfma_f32_16x16x4_f32 v[98:101], v143, v45, v[98:101]
	v_pk_fma_f32 v[180:181], v[2:3], v[234:235], v[180:181] op_sel:[0,1,0]
	v_pk_fma_f32 v[192:193], v[4:5], v[234:235], v[192:193] op_sel:[0,1,0]
	v_pk_mul_f32 v[180:181], v[146:147], v[180:181]
	v_pk_mul_f32 v[192:193], v[146:147], v[192:193]
	v_pk_fma_f32 v[236:237], v[144:145], v[42:43], v[180:181]
	v_pk_fma_f32 v[238:239], v[144:145], v[44:45], v[192:193]
	global_store_dwordx4 v[150:151], v[236:239], off nt
	v_lshl_add_u64 v[150:151], v[150:151], 0, s[74:75]
	ds_read_b32 v143, v160 offset:1008
	ds_read_b128 v[172:175], v161 offset:8064
	ds_read_b128 v[232:235], v161 offset:8080
	s_waitcnt vmcnt(8)
	s_waitcnt lgkmcnt(3)
	v_cndmask_b32_e64 v141, 0, v141, s[8:9]
	v_pk_mul_f32 v[180:181], v[26:27], v[114:115] op_sel:[0,1]
	v_pk_mul_f32 v[192:193], v[28:29], v[114:115] op_sel:[0,1]
	v_mfma_f32_16x16x4_f32 v[110:113], v141, v38, v[110:113]
	v_pk_fma_f32 v[180:181], v[30:31], v[114:115], v[180:181] op_sel_hi:[1,0,1]
	v_pk_fma_f32 v[192:193], v[32:33], v[114:115], v[192:193] op_sel_hi:[1,0,1]
	v_pk_fma_f32 v[180:181], v[22:23], v[116:117], v[180:181] op_sel_hi:[1,0,1]
	v_pk_fma_f32 v[192:193], v[24:25], v[116:117], v[192:193] op_sel_hi:[1,0,1]
	v_mfma_f32_16x16x4_f32 v[106:109], v141, v39, v[106:109]
	v_pk_fma_f32 v[180:181], v[18:19], v[116:117], v[180:181] op_sel:[0,1,0]
	v_pk_fma_f32 v[192:193], v[20:21], v[116:117], v[192:193] op_sel:[0,1,0]
	v_pk_fma_f32 v[180:181], v[14:15], v[176:177], v[180:181] op_sel_hi:[1,0,1]
	v_pk_fma_f32 v[192:193], v[16:17], v[176:177], v[192:193] op_sel_hi:[1,0,1]
	v_mfma_f32_16x16x4_f32 v[102:105], v141, v40, v[102:105]
	v_pk_fma_f32 v[180:181], v[10:11], v[176:177], v[180:181] op_sel:[0,1,0]
	v_pk_fma_f32 v[192:193], v[12:13], v[176:177], v[192:193] op_sel:[0,1,0]
	v_pk_fma_f32 v[180:181], v[6:7], v[178:179], v[180:181] op_sel_hi:[1,0,1]
	v_pk_fma_f32 v[192:193], v[8:9], v[178:179], v[192:193] op_sel_hi:[1,0,1]
	v_mfma_f32_16x16x4_f32 v[98:101], v141, v41, v[98:101]
	v_pk_fma_f32 v[180:181], v[2:3], v[178:179], v[180:181] op_sel:[0,1,0]
	v_pk_fma_f32 v[192:193], v[4:5], v[178:179], v[192:193] op_sel:[0,1,0]
	v_pk_mul_f32 v[180:181], v[146:147], v[180:181]
	v_pk_mul_f32 v[192:193], v[146:147], v[192:193]
	v_pk_fma_f32 v[236:237], v[144:145], v[38:39], v[180:181]
	v_pk_fma_f32 v[238:239], v[144:145], v[40:41], v[192:193]
	global_store_dwordx4 v[150:151], v[236:239], off nt
	v_lshl_add_u64 v[150:151], v[150:151], 0, s[74:75]
	s_waitcnt vmcnt(7)
	s_waitcnt lgkmcnt(0)
	v_cndmask_b32_e64 v143, 0, v143, s[8:9]
	v_pk_mul_f32 v[180:181], v[26:27], v[172:173] op_sel:[0,1]
	v_pk_mul_f32 v[192:193], v[28:29], v[172:173] op_sel:[0,1]
	v_mfma_f32_16x16x4_f32 v[110:113], v143, v34, v[110:113]
	v_pk_fma_f32 v[180:181], v[30:31], v[172:173], v[180:181] op_sel_hi:[1,0,1]
	v_pk_fma_f32 v[192:193], v[32:33], v[172:173], v[192:193] op_sel_hi:[1,0,1]
	v_pk_fma_f32 v[180:181], v[22:23], v[174:175], v[180:181] op_sel_hi:[1,0,1]
	v_pk_fma_f32 v[192:193], v[24:25], v[174:175], v[192:193] op_sel_hi:[1,0,1]
	v_mfma_f32_16x16x4_f32 v[106:109], v143, v35, v[106:109]
	v_pk_fma_f32 v[180:181], v[18:19], v[174:175], v[180:181] op_sel:[0,1,0]
	v_pk_fma_f32 v[192:193], v[20:21], v[174:175], v[192:193] op_sel:[0,1,0]
	v_pk_fma_f32 v[180:181], v[14:15], v[232:233], v[180:181] op_sel_hi:[1,0,1]
	v_pk_fma_f32 v[192:193], v[16:17], v[232:233], v[192:193] op_sel_hi:[1,0,1]
	v_mfma_f32_16x16x4_f32 v[102:105], v143, v36, v[102:105]
	v_pk_fma_f32 v[180:181], v[10:11], v[232:233], v[180:181] op_sel:[0,1,0]
	v_pk_fma_f32 v[192:193], v[12:13], v[232:233], v[192:193] op_sel:[0,1,0]
	v_pk_fma_f32 v[180:181], v[6:7], v[234:235], v[180:181] op_sel_hi:[1,0,1]
	v_pk_fma_f32 v[192:193], v[8:9], v[234:235], v[192:193] op_sel_hi:[1,0,1]
	v_mfma_f32_16x16x4_f32 v[98:101], v143, v37, v[98:101]
	v_pk_fma_f32 v[180:181], v[2:3], v[234:235], v[180:181] op_sel:[0,1,0]
	v_pk_fma_f32 v[192:193], v[4:5], v[234:235], v[192:193] op_sel:[0,1,0]
	v_pk_mul_f32 v[180:181], v[146:147], v[180:181]
	v_pk_mul_f32 v[192:193], v[146:147], v[192:193]
	v_pk_fma_f32 v[236:237], v[144:145], v[34:35], v[180:181]
	v_pk_fma_f32 v[238:239], v[144:145], v[36:37], v[192:193]
	global_store_dwordx4 v[150:151], v[236:239], off nt
	v_lshl_add_u64 v[150:151], v[150:151], 0, s[74:75]
	s_nop 7
	s_nop 3
	s_branch .LBB0_618
	s_nop 0
	s_nop 0
	s_nop 0
	s_nop 0
	s_nop 0
	s_nop 0

; #define LAS __attribute__((address_space(3)))
; #define RS_LOAD(dst, it0) do { _Pragma("unroll") for (int u = 0; u < 8; ++u) dst[u] = __builtin_nontemporal_load((const f32x4*)(S0 + (size_t)(4 * ((it0) + u)) * DV)); } while (0)
; __device__ __forceinline__ void ret_sample_item(Frame& F, int item) {
;     ...
;     const float gam = 1.0f - exp2f(-5.0f - (float)h);
;     const float g7 = exp2f(7.0f * log2f(gam)), g8 = g7 * gam;
;     ...
;     f32x4 v4[8];
; #pragma unroll
;     for (int m = 0; m < 8; ++m) v4[m] = *(const LAS f32x4*)(vs + m * 512 + e4);
;     f32x4 oacc[4];
; #pragma unroll
;     for (int i = 0; i < 4; ++i) oacc[i] = (f32x4){0.f, 0.f, 0.f, 0.f};
;     ...
;     for (int it0 = 0; it0 < 64; it0 += 16) {
;         RS_LOAD(sb, it0 + 8);
;         RS_PROC(sa, it0);
;         { const int itn = it0 + 16 < 64 ? it0 + 16 : it0; RS_LOAD(sa, itn); }
;         RS_PROC(sb, it0 + 8);
;     }
.LBB0_643:
	s_or_b64 exec, exec, s[58:59]
	v_cvt_f32_ubyte0_e32 v2, s10
	v_sub_f32_e32 v2, 0xc0a00000, v2
	v_cmp_gt_f32_e32 vcc, s75, v2
	s_and_b64 s[58:59], vcc, exec
	s_cselect_b32 s10, 0xffffffc0, 0
	v_cndmask_b32_e32 v3, 0, v169, vcc
	v_add_f32_e32 v2, v2, v3
	v_exp_f32_e32 v2, v2
	s_waitcnt lgkmcnt(0)
	s_barrier
	v_ldexp_f32 v2, v2, s10
	v_sub_f32_e32 v138, 1.0, v2
	v_cmp_gt_f32_e32 vcc, s76, v138
	s_and_b64 s[58:59], vcc, exec
	s_cselect_b32 s10, 32, 0
	v_ldexp_f32 v3, v138, s10
	v_log_f32_e32 v3, v3
	v_cndmask_b32_e32 v2, 0, v170, vcc
	v_mov_b32_e32 v98, 0
	s_mov_b32 s10, 0
	v_sub_f32_e32 v2, v3, v2
	v_mul_f32_e32 v3, 0x40e00000, v2
	v_cmp_gt_f32_e32 vcc, s75, v3
	s_and_b64 s[58:59], vcc, exec
	s_cselect_b32 s18, 0xffffffc0, 0
	v_cndmask_b32_e32 v3, 0, v169, vcc
	v_fmac_f32_e32 v3, 0x40e00000, v2
	v_exp_f32_e32 v2, v3
	v_mov_b64_e32 v[148:149], v[130:131]
	v_mov_b64_e32 v[150:151], v[128:129]
	v_mov_b32_e32 v171, v161
	v_ldexp_f32 v140, v2, s18
	ds_read_b128 v[30:33], v139 offset:16512
	ds_read_b128 v[26:29], v139 offset:18560
	ds_read_b128 v[22:25], v139 offset:20608
	ds_read_b128 v[18:21], v139 offset:22656
	ds_read_b128 v[14:17], v139 offset:24704
	ds_read_b128 v[10:13], v139 offset:26752
	ds_read_b128 v[6:9], v139 offset:28800
	ds_read_b128 v[2:5], v139 offset:30848
	v_mul_f32_e32 v142, v138, v140
	v_mov_b32_e32 v144, v142
	v_mov_b32_e32 v145, v142
	v_mov_b32_e32 v146, v140
	v_mov_b32_e32 v147, v140
	v_mov_b32_e32 v172, v160
	v_mov_b32_e32 v99, v98
	v_mov_b32_e32 v100, v98
	v_mov_b32_e32 v101, v98
	v_mov_b32_e32 v102, v98
	v_mov_b32_e32 v103, v98
	v_mov_b32_e32 v104, v98
	v_mov_b32_e32 v105, v98
	v_mov_b32_e32 v106, v98
	v_mov_b32_e32 v107, v98
	v_mov_b32_e32 v108, v98
	v_mov_b32_e32 v109, v98
	v_mov_b32_e32 v110, v98
	v_mov_b32_e32 v111, v98
	v_mov_b32_e32 v112, v98
	v_mov_b32_e32 v113, v98
	v_lshl_add_u64 v[148:149], v[130:131], 0, v[122:123]
	v_lshl_add_u64 v[150:151], v[128:129], 0, v[122:123]
	s_mov_b32 s58, 0x10000
	s_mov_b32 s59, 0
	v_add_co_u32_e32 v150, vcc, 0x5878000, v150
	v_lshl_add_u64 v[148:149], v[148:149], 0, s[58:59]
	s_mov_b32 s58, 0x2000
	v_addc_co_u32_e32 v151, vcc, 0, v151, vcc
	ds_read_b32 v141, v160
	ds_read_b128 v[114:117], v161
	ds_read_b128 v[176:179], v161 offset:16
	ds_read_b32 v143, v160 offset:16
	ds_read_b128 v[172:175], v161 offset:128
	ds_read_b128 v[232:235], v161 offset:144
	s_waitcnt lgkmcnt(3)
	v_cndmask_b32_e64 v141, 0, v141, s[6:7]
	v_pk_mul_f32 v[180:181], v[26:27], v[114:115] op_sel:[0,1]
	v_pk_mul_f32 v[192:193], v[28:29], v[114:115] op_sel:[0,1]
	v_mfma_f32_16x16x4_f32 v[110:113], v141, v70, v[110:113]
	v_pk_fma_f32 v[180:181], v[30:31], v[114:115], v[180:181] op_sel_hi:[1,0,1]
	v_pk_fma_f32 v[192:193], v[32:33], v[114:115], v[192:193] op_sel_hi:[1,0,1]
	v_pk_fma_f32 v[180:181], v[22:23], v[116:117], v[180:181] op_sel_hi:[1,0,1]
	v_pk_fma_f32 v[192:193], v[24:25], v[116:117], v[192:193] op_sel_hi:[1,0,1]
	v_mfma_f32_16x16x4_f32 v[106:109], v141, v71, v[106:109]
	v_pk_fma_f32 v[180:181], v[18:19], v[116:117], v[180:181] op_sel:[0,1,0]
	v_pk_fma_f32 v[192:193], v[20:21], v[116:117], v[192:193] op_sel:[0,1,0]
	v_pk_fma_f32 v[180:181], v[14:15], v[176:177], v[180:181] op_sel_hi:[1,0,1]
	v_pk_fma_f32 v[192:193], v[16:17], v[176:177], v[192:193] op_sel_hi:[1,0,1]
	v_mfma_f32_16x16x4_f32 v[102:105], v141, v72, v[102:105]
	v_pk_fma_f32 v[180:181], v[10:11], v[176:177], v[180:181] op_sel:[0,1,0]
	v_pk_fma_f32 v[192:193], v[12:13], v[176:177], v[192:193] op_sel:[0,1,0]
	v_pk_fma_f32 v[180:181], v[6:7], v[178:179], v[180:181] op_sel_hi:[1,0,1]
	v_pk_fma_f32 v[192:193], v[8:9], v[178:179], v[192:193] op_sel_hi:[1,0,1]
	v_mfma_f32_16x16x4_f32 v[98:101], v141, v73, v[98:101]
	v_pk_fma_f32 v[180:181], v[2:3], v[178:179], v[180:181] op_sel:[0,1,0]
	v_pk_fma_f32 v[192:193], v[4:5], v[178:179], v[192:193] op_sel:[0,1,0]
	v_pk_mul_f32 v[180:181], v[146:147], v[180:181]
	v_pk_mul_f32 v[192:193], v[146:147], v[192:193]
	v_pk_fma_f32 v[236:237], v[144:145], v[70:71], v[180:181]
	v_pk_fma_f32 v[238:239], v[144:145], v[72:73], v[192:193]
	global_store_dwordx4 v[150:151], v[236:239], off nt
	v_lshl_add_u64 v[150:151], v[150:151], 0, s[58:59]
	global_load_dwordx4 v[70:73], v[148:149], off nt
	v_lshl_add_u64 v[148:149], v[148:149], 0, s[58:59]
	ds_read_b32 v141, v160 offset:32
	ds_read_b128 v[114:117], v161 offset:256
	ds_read_b128 v[176:179], v161 offset:272
	s_waitcnt lgkmcnt(3)
	v_cndmask_b32_e64 v143, 0, v143, s[6:7]
	v_pk_mul_f32 v[180:181], v[26:27], v[172:173] op_sel:[0,1]
	v_pk_mul_f32 v[192:193], v[28:29], v[172:173] op_sel:[0,1]
	v_mfma_f32_16x16x4_f32 v[110:113], v143, v62, v[110:113]
	v_pk_fma_f32 v[180:181], v[30:31], v[172:173], v[180:181] op_sel_hi:[1,0,1]
	v_pk_fma_f32 v[192:193], v[32:33], v[172:173], v[192:193] op_sel_hi:[1,0,1]
	v_pk_fma_f32 v[180:181], v[22:23], v[174:175], v[180:181] op_sel_hi:[1,0,1]
	v_pk_fma_f32 v[192:193], v[24:25], v[174:175], v[192:193] op_sel_hi:[1,0,1]
	v_mfma_f32_16x16x4_f32 v[106:109], v143, v63, v[106:109]
	v_pk_fma_f32 v[180:181], v[18:19], v[174:175], v[180:181] op_sel:[0,1,0]
	v_pk_fma_f32 v[192:193], v[20:21], v[174:175], v[192:193] op_sel:[0,1,0]
	v_pk_fma_f32 v[180:181], v[14:15], v[232:233], v[180:181] op_sel_hi:[1,0,1]
	v_pk_fma_f32 v[192:193], v[16:17], v[232:233], v[192:193] op_sel_hi:[1,0,1]
	v_mfma_f32_16x16x4_f32 v[102:105], v143, v64, v[102:105]
	v_pk_fma_f32 v[180:181], v[10:11], v[232:233], v[180:181] op_sel:[0,1,0]
	v_pk_fma_f32 v[192:193], v[12:13], v[232:233], v[192:193] op_sel:[0,1,0]
	v_pk_fma_f32 v[180:181], v[6:7], v[234:235], v[180:181] op_sel_hi:[1,0,1]
	v_pk_fma_f32 v[192:193], v[8:9], v[234:235], v[192:193] op_sel_hi:[1,0,1]
	v_mfma_f32_16x16x4_f32 v[98:101], v143, v65, v[98:101]
	v_pk_fma_f32 v[180:181], v[2:3], v[234:235], v[180:181] op_sel:[0,1,0]
	v_pk_fma_f32 v[192:193], v[4:5], v[234:235], v[192:193] op_sel:[0,1,0]
	v_pk_mul_f32 v[180:181], v[146:147], v[180:181]
	v_pk_mul_f32 v[192:193], v[146:147], v[192:193]
	v_pk_fma_f32 v[236:237], v[144:145], v[62:63], v[180:181]
	v_pk_fma_f32 v[238:239], v[144:145], v[64:65], v[192:193]
	global_store_dwordx4 v[150:151], v[236:239], off nt
	v_lshl_add_u64 v[150:151], v[150:151], 0, s[58:59]
	global_load_dwordx4 v[62:65], v[148:149], off nt
	v_lshl_add_u64 v[148:149], v[148:149], 0, s[58:59]
	ds_read_b32 v143, v160 offset:48
	ds_read_b128 v[172:175], v161 offset:384
	ds_read_b128 v[232:235], v161 offset:400
	s_waitcnt lgkmcnt(3)
; #define RS_LOAD(dst, it0) do { _Pragma("unroll") for (int u = 0; u < 8; ++u) dst[u] = __builtin_nontemporal_load((const f32x4*)(S0 + (size_t)(4 * ((it0) + u)) * DV)); } while (0)
; __device__ __forceinline__ void ret_sample_item(Frame& F, int item) {
;     ...
;     for (int it0 = 0; it0 < 64; it0 += 16) {
;         RS_LOAD(sb, it0 + 8);
;         RS_PROC(sa, it0);
;         { const int itn = it0 + 16 < 64 ? it0 + 16 : it0; RS_LOAD(sa, itn); }
;         RS_PROC(sb, it0 + 8);
;     }
	v_cndmask_b32_e64 v141, 0, v141, s[6:7]
	v_pk_mul_f32 v[180:181], v[26:27], v[114:115] op_sel:[0,1]
	v_pk_mul_f32 v[192:193], v[28:29], v[114:115] op_sel:[0,1]
	v_mfma_f32_16x16x4_f32 v[110:113], v141, v54, v[110:113]
	v_pk_fma_f32 v[180:181], v[30:31], v[114:115], v[180:181] op_sel_hi:[1,0,1]
	v_pk_fma_f32 v[192:193], v[32:33], v[114:115], v[192:193] op_sel_hi:[1,0,1]
	v_pk_fma_f32 v[180:181], v[22:23], v[116:117], v[180:181] op_sel_hi:[1,0,1]
	v_pk_fma_f32 v[192:193], v[24:25], v[116:117], v[192:193] op_sel_hi:[1,0,1]
	v_mfma_f32_16x16x4_f32 v[106:109], v141, v55, v[106:109]
	v_pk_fma_f32 v[180:181], v[18:19], v[116:117], v[180:181] op_sel:[0,1,0]
	v_pk_fma_f32 v[192:193], v[20:21], v[116:117], v[192:193] op_sel:[0,1,0]
	v_pk_fma_f32 v[180:181], v[14:15], v[176:177], v[180:181] op_sel_hi:[1,0,1]
	v_pk_fma_f32 v[192:193], v[16:17], v[176:177], v[192:193] op_sel_hi:[1,0,1]
	v_mfma_f32_16x16x4_f32 v[102:105], v141, v56, v[102:105]
	v_pk_fma_f32 v[180:181], v[10:11], v[176:177], v[180:181] op_sel:[0,1,0]
	v_pk_fma_f32 v[192:193], v[12:13], v[176:177], v[192:193] op_sel:[0,1,0]
	v_pk_fma_f32 v[180:181], v[6:7], v[178:179], v[180:181] op_sel_hi:[1,0,1]
	v_pk_fma_f32 v[192:193], v[8:9], v[178:179], v[192:193] op_sel_hi:[1,0,1]
	v_mfma_f32_16x16x4_f32 v[98:101], v141, v57, v[98:101]
	v_pk_fma_f32 v[180:181], v[2:3], v[178:179], v[180:181] op_sel:[0,1,0]
	v_pk_fma_f32 v[192:193], v[4:5], v[178:179], v[192:193] op_sel:[0,1,0]
	v_pk_mul_f32 v[180:181], v[146:147], v[180:181]
	v_pk_mul_f32 v[192:193], v[146:147], v[192:193]
	v_pk_fma_f32 v[236:237], v[144:145], v[54:55], v[180:181]
	v_pk_fma_f32 v[238:239], v[144:145], v[56:57], v[192:193]
	global_store_dwordx4 v[150:151], v[236:239], off nt
	v_lshl_add_u64 v[150:151], v[150:151], 0, s[58:59]
	global_load_dwordx4 v[54:57], v[148:149], off nt
	v_lshl_add_u64 v[148:149], v[148:149], 0, s[58:59]
	ds_read_b32 v141, v160 offset:64
	ds_read_b128 v[114:117], v161 offset:512
	ds_read_b128 v[176:179], v161 offset:528
	s_waitcnt lgkmcnt(3)
	v_cndmask_b32_e64 v143, 0, v143, s[6:7]
	v_pk_mul_f32 v[180:181], v[26:27], v[172:173] op_sel:[0,1]
	v_pk_mul_f32 v[192:193], v[28:29], v[172:173] op_sel:[0,1]
	v_mfma_f32_16x16x4_f32 v[110:113], v143, v50, v[110:113]
	v_pk_fma_f32 v[180:181], v[30:31], v[172:173], v[180:181] op_sel_hi:[1,0,1]
	v_pk_fma_f32 v[192:193], v[32:33], v[172:173], v[192:193] op_sel_hi:[1,0,1]
	v_pk_fma_f32 v[180:181], v[22:23], v[174:175], v[180:181] op_sel_hi:[1,0,1]
	v_pk_fma_f32 v[192:193], v[24:25], v[174:175], v[192:193] op_sel_hi:[1,0,1]
	v_mfma_f32_16x16x4_f32 v[106:109], v143, v51, v[106:109]
	v_pk_fma_f32 v[180:181], v[18:19], v[174:175], v[180:181] op_sel:[0,1,0]
	v_pk_fma_f32 v[192:193], v[20:21], v[174:175], v[192:193] op_sel:[0,1,0]
	v_pk_fma_f32 v[180:181], v[14:15], v[232:233], v[180:181] op_sel_hi:[1,0,1]
	v_pk_fma_f32 v[192:193], v[16:17], v[232:233], v[192:193] op_sel_hi:[1,0,1]
	v_mfma_f32_16x16x4_f32 v[102:105], v143, v52, v[102:105]
	v_pk_fma_f32 v[180:181], v[10:11], v[232:233], v[180:181] op_sel:[0,1,0]
	v_pk_fma_f32 v[192:193], v[12:13], v[232:233], v[192:193] op_sel:[0,1,0]
	v_pk_fma_f32 v[180:181], v[6:7], v[234:235], v[180:181] op_sel_hi:[1,0,1]
	v_pk_fma_f32 v[192:193], v[8:9], v[234:235], v[192:193] op_sel_hi:[1,0,1]
	v_mfma_f32_16x16x4_f32 v[98:101], v143, v53, v[98:101]
	v_pk_fma_f32 v[180:181], v[2:3], v[234:235], v[180:181] op_sel:[0,1,0]
	v_pk_fma_f32 v[192:193], v[4:5], v[234:235], v[192:193] op_sel:[0,1,0]
	v_pk_mul_f32 v[180:181], v[146:147], v[180:181]
	v_pk_mul_f32 v[192:193], v[146:147], v[192:193]
	v_pk_fma_f32 v[236:237], v[144:145], v[50:51], v[180:181]
	v_pk_fma_f32 v[238:239], v[144:145], v[52:53], v[192:193]
	global_store_dwordx4 v[150:151], v[236:239], off nt
	v_lshl_add_u64 v[150:151], v[150:151], 0, s[58:59]
	global_load_dwordx4 v[50:53], v[148:149], off nt
	v_lshl_add_u64 v[148:149], v[148:149], 0, s[58:59]
	ds_read_b32 v143, v160 offset:80
	ds_read_b128 v[172:175], v161 offset:640
	ds_read_b128 v[232:235], v161 offset:656
	s_waitcnt lgkmcnt(3)
	v_cndmask_b32_e64 v141, 0, v141, s[6:7]
	v_pk_mul_f32 v[180:181], v[26:27], v[114:115] op_sel:[0,1]
	v_pk_mul_f32 v[192:193], v[28:29], v[114:115] op_sel:[0,1]
	v_mfma_f32_16x16x4_f32 v[110:113], v141, v46, v[110:113]
	v_pk_fma_f32 v[180:181], v[30:31], v[114:115], v[180:181] op_sel_hi:[1,0,1]
	v_pk_fma_f32 v[192:193], v[32:33], v[114:115], v[192:193] op_sel_hi:[1,0,1]
	v_pk_fma_f32 v[180:181], v[22:23], v[116:117], v[180:181] op_sel_hi:[1,0,1]
	v_pk_fma_f32 v[192:193], v[24:25], v[116:117], v[192:193] op_sel_hi:[1,0,1]
	v_mfma_f32_16x16x4_f32 v[106:109], v141, v47, v[106:109]
	v_pk_fma_f32 v[180:181], v[18:19], v[116:117], v[180:181] op_sel:[0,1,0]
	v_pk_fma_f32 v[192:193], v[20:21], v[116:117], v[192:193] op_sel:[0,1,0]
	v_pk_fma_f32 v[180:181], v[14:15], v[176:177], v[180:181] op_sel_hi:[1,0,1]
	v_pk_fma_f32 v[192:193], v[16:17], v[176:177], v[192:193] op_sel_hi:[1,0,1]
	v_mfma_f32_16x16x4_f32 v[102:105], v141, v48, v[102:105]
	v_pk_fma_f32 v[180:181], v[10:11], v[176:177], v[180:181] op_sel:[0,1,0]
	v_pk_fma_f32 v[192:193], v[12:13], v[176:177], v[192:193] op_sel:[0,1,0]
	v_pk_fma_f32 v[180:181], v[6:7], v[178:179], v[180:181] op_sel_hi:[1,0,1]
	v_pk_fma_f32 v[192:193], v[8:9], v[178:179], v[192:193] op_sel_hi:[1,0,1]
	v_mfma_f32_16x16x4_f32 v[98:101], v141, v49, v[98:101]
	v_pk_fma_f32 v[180:181], v[2:3], v[178:179], v[180:181] op_sel:[0,1,0]
	v_pk_fma_f32 v[192:193], v[4:5], v[178:179], v[192:193] op_sel:[0,1,0]
	v_pk_mul_f32 v[180:181], v[146:147], v[180:181]
	v_pk_mul_f32 v[192:193], v[146:147], v[192:193]
	v_pk_fma_f32 v[236:237], v[144:145], v[46:47], v[180:181]
	v_pk_fma_f32 v[238:239], v[144:145], v[48:49], v[192:193]
	global_store_dwordx4 v[150:151], v[236:239], off nt
	v_lshl_add_u64 v[150:151], v[150:151], 0, s[58:59]
	global_load_dwordx4 v[46:49], v[148:149], off nt
	v_lshl_add_u64 v[148:149], v[148:149], 0, s[58:59]
	ds_read_b32 v141, v160 offset:96
	ds_read_b128 v[114:117], v161 offset:768
	ds_read_b128 v[176:179], v161 offset:784
	s_waitcnt lgkmcnt(3)
; #define RS_LOAD(dst, it0) do { _Pragma("unroll") for (int u = 0; u < 8; ++u) dst[u] = __builtin_nontemporal_load((const f32x4*)(S0 + (size_t)(4 * ((it0) + u)) * DV)); } while (0)
; __device__ __forceinline__ void ret_sample_item(Frame& F, int item) {
;     ...
;     for (int it0 = 0; it0 < 64; it0 += 16) {
;         RS_LOAD(sb, it0 + 8);
;         RS_PROC(sa, it0);
;         { const int itn = it0 + 16 < 64 ? it0 + 16 : it0; RS_LOAD(sa, itn); }
;         RS_PROC(sb, it0 + 8);
;     }
	v_cndmask_b32_e64 v143, 0, v143, s[6:7]
	v_pk_mul_f32 v[180:181], v[26:27], v[172:173] op_sel:[0,1]
	v_pk_mul_f32 v[192:193], v[28:29], v[172:173] op_sel:[0,1]
	v_mfma_f32_16x16x4_f32 v[110:113], v143, v42, v[110:113]
	v_pk_fma_f32 v[180:181], v[30:31], v[172:173], v[180:181] op_sel_hi:[1,0,1]
	v_pk_fma_f32 v[192:193], v[32:33], v[172:173], v[192:193] op_sel_hi:[1,0,1]
	v_pk_fma_f32 v[180:181], v[22:23], v[174:175], v[180:181] op_sel_hi:[1,0,1]
	v_pk_fma_f32 v[192:193], v[24:25], v[174:175], v[192:193] op_sel_hi:[1,0,1]
	v_mfma_f32_16x16x4_f32 v[106:109], v143, v43, v[106:109]
	v_pk_fma_f32 v[180:181], v[18:19], v[174:175], v[180:181] op_sel:[0,1,0]
	v_pk_fma_f32 v[192:193], v[20:21], v[174:175], v[192:193] op_sel:[0,1,0]
	v_pk_fma_f32 v[180:181], v[14:15], v[232:233], v[180:181] op_sel_hi:[1,0,1]
	v_pk_fma_f32 v[192:193], v[16:17], v[232:233], v[192:193] op_sel_hi:[1,0,1]
	v_mfma_f32_16x16x4_f32 v[102:105], v143, v44, v[102:105]
	v_pk_fma_f32 v[180:181], v[10:11], v[232:233], v[180:181] op_sel:[0,1,0]
	v_pk_fma_f32 v[192:193], v[12:13], v[232:233], v[192:193] op_sel:[0,1,0]
	v_pk_fma_f32 v[180:181], v[6:7], v[234:235], v[180:181] op_sel_hi:[1,0,1]
	v_pk_fma_f32 v[192:193], v[8:9], v[234:235], v[192:193] op_sel_hi:[1,0,1]
	v_mfma_f32_16x16x4_f32 v[98:101], v143, v45, v[98:101]
	v_pk_fma_f32 v[180:181], v[2:3], v[234:235], v[180:181] op_sel:[0,1,0]
	v_pk_fma_f32 v[192:193], v[4:5], v[234:235], v[192:193] op_sel:[0,1,0]
	v_pk_mul_f32 v[180:181], v[146:147], v[180:181]
	v_pk_mul_f32 v[192:193], v[146:147], v[192:193]
	v_pk_fma_f32 v[236:237], v[144:145], v[42:43], v[180:181]
	v_pk_fma_f32 v[238:239], v[144:145], v[44:45], v[192:193]
	global_store_dwordx4 v[150:151], v[236:239], off nt
	v_lshl_add_u64 v[150:151], v[150:151], 0, s[58:59]
	global_load_dwordx4 v[42:45], v[148:149], off nt
	v_lshl_add_u64 v[148:149], v[148:149], 0, s[58:59]
	ds_read_b32 v143, v160 offset:112
	ds_read_b128 v[172:175], v161 offset:896
	ds_read_b128 v[232:235], v161 offset:912
	s_waitcnt lgkmcnt(3)
	v_cndmask_b32_e64 v141, 0, v141, s[6:7]
	v_pk_mul_f32 v[180:181], v[26:27], v[114:115] op_sel:[0,1]
	v_pk_mul_f32 v[192:193], v[28:29], v[114:115] op_sel:[0,1]
	v_mfma_f32_16x16x4_f32 v[110:113], v141, v38, v[110:113]
	v_pk_fma_f32 v[180:181], v[30:31], v[114:115], v[180:181] op_sel_hi:[1,0,1]
	v_pk_fma_f32 v[192:193], v[32:33], v[114:115], v[192:193] op_sel_hi:[1,0,1]
	v_pk_fma_f32 v[180:181], v[22:23], v[116:117], v[180:181] op_sel_hi:[1,0,1]
	v_pk_fma_f32 v[192:193], v[24:25], v[116:117], v[192:193] op_sel_hi:[1,0,1]
	v_mfma_f32_16x16x4_f32 v[106:109], v141, v39, v[106:109]
	v_pk_fma_f32 v[180:181], v[18:19], v[116:117], v[180:181] op_sel:[0,1,0]
	v_pk_fma_f32 v[192:193], v[20:21], v[116:117], v[192:193] op_sel:[0,1,0]
	v_pk_fma_f32 v[180:181], v[14:15], v[176:177], v[180:181] op_sel_hi:[1,0,1]
	v_pk_fma_f32 v[192:193], v[16:17], v[176:177], v[192:193] op_sel_hi:[1,0,1]
	v_mfma_f32_16x16x4_f32 v[102:105], v141, v40, v[102:105]
	v_pk_fma_f32 v[180:181], v[10:11], v[176:177], v[180:181] op_sel:[0,1,0]
	v_pk_fma_f32 v[192:193], v[12:13], v[176:177], v[192:193] op_sel:[0,1,0]
	v_pk_fma_f32 v[180:181], v[6:7], v[178:179], v[180:181] op_sel_hi:[1,0,1]
	v_pk_fma_f32 v[192:193], v[8:9], v[178:179], v[192:193] op_sel_hi:[1,0,1]
	v_mfma_f32_16x16x4_f32 v[98:101], v141, v41, v[98:101]
	v_pk_fma_f32 v[180:181], v[2:3], v[178:179], v[180:181] op_sel:[0,1,0]
	v_pk_fma_f32 v[192:193], v[4:5], v[178:179], v[192:193] op_sel:[0,1,0]
	v_pk_mul_f32 v[180:181], v[146:147], v[180:181]
	v_pk_mul_f32 v[192:193], v[146:147], v[192:193]
	v_pk_fma_f32 v[236:237], v[144:145], v[38:39], v[180:181]
	v_pk_fma_f32 v[238:239], v[144:145], v[40:41], v[192:193]
	global_store_dwordx4 v[150:151], v[236:239], off nt
	v_lshl_add_u64 v[150:151], v[150:151], 0, s[58:59]
	global_load_dwordx4 v[38:41], v[148:149], off nt
	v_lshl_add_u64 v[148:149], v[148:149], 0, s[58:59]
	ds_read_b32 v141, v160 offset:128
	ds_read_b128 v[114:117], v161 offset:1024
	ds_read_b128 v[176:179], v161 offset:1040
	s_waitcnt lgkmcnt(3)
	v_cndmask_b32_e64 v143, 0, v143, s[6:7]
	v_pk_mul_f32 v[180:181], v[26:27], v[172:173] op_sel:[0,1]
	v_pk_mul_f32 v[192:193], v[28:29], v[172:173] op_sel:[0,1]
	v_mfma_f32_16x16x4_f32 v[110:113], v143, v34, v[110:113]
	v_pk_fma_f32 v[180:181], v[30:31], v[172:173], v[180:181] op_sel_hi:[1,0,1]
	v_pk_fma_f32 v[192:193], v[32:33], v[172:173], v[192:193] op_sel_hi:[1,0,1]
	v_pk_fma_f32 v[180:181], v[22:23], v[174:175], v[180:181] op_sel_hi:[1,0,1]
	v_pk_fma_f32 v[192:193], v[24:25], v[174:175], v[192:193] op_sel_hi:[1,0,1]
	v_mfma_f32_16x16x4_f32 v[106:109], v143, v35, v[106:109]
	v_pk_fma_f32 v[180:181], v[18:19], v[174:175], v[180:181] op_sel:[0,1,0]
	v_pk_fma_f32 v[192:193], v[20:21], v[174:175], v[192:193] op_sel:[0,1,0]
	v_pk_fma_f32 v[180:181], v[14:15], v[232:233], v[180:181] op_sel_hi:[1,0,1]
	v_pk_fma_f32 v[192:193], v[16:17], v[232:233], v[192:193] op_sel_hi:[1,0,1]
	v_mfma_f32_16x16x4_f32 v[102:105], v143, v36, v[102:105]
	v_pk_fma_f32 v[180:181], v[10:11], v[232:233], v[180:181] op_sel:[0,1,0]
	v_pk_fma_f32 v[192:193], v[12:13], v[232:233], v[192:193] op_sel:[0,1,0]
	v_pk_fma_f32 v[180:181], v[6:7], v[234:235], v[180:181] op_sel_hi:[1,0,1]
	v_pk_fma_f32 v[192:193], v[8:9], v[234:235], v[192:193] op_sel_hi:[1,0,1]
	v_mfma_f32_16x16x4_f32 v[98:101], v143, v37, v[98:101]
	v_pk_fma_f32 v[180:181], v[2:3], v[234:235], v[180:181] op_sel:[0,1,0]
	v_pk_fma_f32 v[192:193], v[4:5], v[234:235], v[192:193] op_sel:[0,1,0]
	v_pk_mul_f32 v[180:181], v[146:147], v[180:181]
	v_pk_mul_f32 v[192:193], v[146:147], v[192:193]
	v_pk_fma_f32 v[236:237], v[144:145], v[34:35], v[180:181]
	v_pk_fma_f32 v[238:239], v[144:145], v[36:37], v[192:193]
	global_store_dwordx4 v[150:151], v[236:239], off nt
	v_lshl_add_u64 v[150:151], v[150:151], 0, s[58:59]
	global_load_dwordx4 v[34:37], v[148:149], off nt
	v_lshl_add_u64 v[148:149], v[148:149], 0, s[58:59]
	ds_read_b32 v143, v160 offset:144
	ds_read_b128 v[172:175], v161 offset:1152
	ds_read_b128 v[232:235], v161 offset:1168
	s_waitcnt vmcnt(14)
; #define RS_LOAD(dst, it0) do { _Pragma("unroll") for (int u = 0; u < 8; ++u) dst[u] = __builtin_nontemporal_load((const f32x4*)(S0 + (size_t)(4 * ((it0) + u)) * DV)); } while (0)
; __device__ __forceinline__ void ret_sample_item(Frame& F, int item) {
;     ...
;     for (int it0 = 0; it0 < 64; it0 += 16) {
;         RS_LOAD(sb, it0 + 8);
;         RS_PROC(sa, it0);
;         { const int itn = it0 + 16 < 64 ? it0 + 16 : it0; RS_LOAD(sa, itn); }
;         RS_PROC(sb, it0 + 8);
;     }
	s_waitcnt lgkmcnt(3)
	v_cndmask_b32_e64 v141, 0, v141, s[6:7]
	v_pk_mul_f32 v[180:181], v[26:27], v[114:115] op_sel:[0,1]
	v_pk_mul_f32 v[192:193], v[28:29], v[114:115] op_sel:[0,1]
	v_mfma_f32_16x16x4_f32 v[110:113], v141, v70, v[110:113]
	v_pk_fma_f32 v[180:181], v[30:31], v[114:115], v[180:181] op_sel_hi:[1,0,1]
	v_pk_fma_f32 v[192:193], v[32:33], v[114:115], v[192:193] op_sel_hi:[1,0,1]
	v_pk_fma_f32 v[180:181], v[22:23], v[116:117], v[180:181] op_sel_hi:[1,0,1]
	v_pk_fma_f32 v[192:193], v[24:25], v[116:117], v[192:193] op_sel_hi:[1,0,1]
	v_mfma_f32_16x16x4_f32 v[106:109], v141, v71, v[106:109]
	v_pk_fma_f32 v[180:181], v[18:19], v[116:117], v[180:181] op_sel:[0,1,0]
	v_pk_fma_f32 v[192:193], v[20:21], v[116:117], v[192:193] op_sel:[0,1,0]
	v_pk_fma_f32 v[180:181], v[14:15], v[176:177], v[180:181] op_sel_hi:[1,0,1]
	v_pk_fma_f32 v[192:193], v[16:17], v[176:177], v[192:193] op_sel_hi:[1,0,1]
	v_mfma_f32_16x16x4_f32 v[102:105], v141, v72, v[102:105]
	v_pk_fma_f32 v[180:181], v[10:11], v[176:177], v[180:181] op_sel:[0,1,0]
	v_pk_fma_f32 v[192:193], v[12:13], v[176:177], v[192:193] op_sel:[0,1,0]
	v_pk_fma_f32 v[180:181], v[6:7], v[178:179], v[180:181] op_sel_hi:[1,0,1]
	v_pk_fma_f32 v[192:193], v[8:9], v[178:179], v[192:193] op_sel_hi:[1,0,1]
	v_mfma_f32_16x16x4_f32 v[98:101], v141, v73, v[98:101]
	v_pk_fma_f32 v[180:181], v[2:3], v[178:179], v[180:181] op_sel:[0,1,0]
	v_pk_fma_f32 v[192:193], v[4:5], v[178:179], v[192:193] op_sel:[0,1,0]
	v_pk_mul_f32 v[180:181], v[146:147], v[180:181]
	v_pk_mul_f32 v[192:193], v[146:147], v[192:193]
	v_pk_fma_f32 v[236:237], v[144:145], v[70:71], v[180:181]
	v_pk_fma_f32 v[238:239], v[144:145], v[72:73], v[192:193]
	global_store_dwordx4 v[150:151], v[236:239], off nt
	v_lshl_add_u64 v[150:151], v[150:151], 0, s[58:59]
	global_load_dwordx4 v[70:73], v[148:149], off nt
	v_lshl_add_u64 v[148:149], v[148:149], 0, s[58:59]
	ds_read_b32 v141, v160 offset:160
	ds_read_b128 v[114:117], v161 offset:1280
	ds_read_b128 v[176:179], v161 offset:1296
	s_waitcnt vmcnt(14)
	s_waitcnt lgkmcnt(3)
	v_cndmask_b32_e64 v143, 0, v143, s[6:7]
	v_pk_mul_f32 v[180:181], v[26:27], v[172:173] op_sel:[0,1]
	v_pk_mul_f32 v[192:193], v[28:29], v[172:173] op_sel:[0,1]
	v_mfma_f32_16x16x4_f32 v[110:113], v143, v62, v[110:113]
	v_pk_fma_f32 v[180:181], v[30:31], v[172:173], v[180:181] op_sel_hi:[1,0,1]
	v_pk_fma_f32 v[192:193], v[32:33], v[172:173], v[192:193] op_sel_hi:[1,0,1]
	v_pk_fma_f32 v[180:181], v[22:23], v[174:175], v[180:181] op_sel_hi:[1,0,1]
	v_pk_fma_f32 v[192:193], v[24:25], v[174:175], v[192:193] op_sel_hi:[1,0,1]
	v_mfma_f32_16x16x4_f32 v[106:109], v143, v63, v[106:109]
	v_pk_fma_f32 v[180:181], v[18:19], v[174:175], v[180:181] op_sel:[0,1,0]
	v_pk_fma_f32 v[192:193], v[20:21], v[174:175], v[192:193] op_sel:[0,1,0]
	v_pk_fma_f32 v[180:181], v[14:15], v[232:233], v[180:181] op_sel_hi:[1,0,1]
	v_pk_fma_f32 v[192:193], v[16:17], v[232:233], v[192:193] op_sel_hi:[1,0,1]
	v_mfma_f32_16x16x4_f32 v[102:105], v143, v64, v[102:105]
	v_pk_fma_f32 v[180:181], v[10:11], v[232:233], v[180:181] op_sel:[0,1,0]
	v_pk_fma_f32 v[192:193], v[12:13], v[232:233], v[192:193] op_sel:[0,1,0]
	v_pk_fma_f32 v[180:181], v[6:7], v[234:235], v[180:181] op_sel_hi:[1,0,1]
	v_pk_fma_f32 v[192:193], v[8:9], v[234:235], v[192:193] op_sel_hi:[1,0,1]
	v_mfma_f32_16x16x4_f32 v[98:101], v143, v65, v[98:101]
	v_pk_fma_f32 v[180:181], v[2:3], v[234:235], v[180:181] op_sel:[0,1,0]
	v_pk_fma_f32 v[192:193], v[4:5], v[234:235], v[192:193] op_sel:[0,1,0]
	v_pk_mul_f32 v[180:181], v[146:147], v[180:181]
	v_pk_mul_f32 v[192:193], v[146:147], v[192:193]
	v_pk_fma_f32 v[236:237], v[144:145], v[62:63], v[180:181]
	v_pk_fma_f32 v[238:239], v[144:145], v[64:65], v[192:193]
	global_store_dwordx4 v[150:151], v[236:239], off nt
	v_lshl_add_u64 v[150:151], v[150:151], 0, s[58:59]
	global_load_dwordx4 v[62:65], v[148:149], off nt
	v_lshl_add_u64 v[148:149], v[148:149], 0, s[58:59]
	ds_read_b32 v143, v160 offset:176
	ds_read_b128 v[172:175], v161 offset:1408
	ds_read_b128 v[232:235], v161 offset:1424
	s_waitcnt vmcnt(14)
	s_waitcnt lgkmcnt(3)
	v_cndmask_b32_e64 v141, 0, v141, s[6:7]
	v_pk_mul_f32 v[180:181], v[26:27], v[114:115] op_sel:[0,1]
	v_pk_mul_f32 v[192:193], v[28:29], v[114:115] op_sel:[0,1]
	v_mfma_f32_16x16x4_f32 v[110:113], v141, v54, v[110:113]
	v_pk_fma_f32 v[180:181], v[30:31], v[114:115], v[180:181] op_sel_hi:[1,0,1]
	v_pk_fma_f32 v[192:193], v[32:33], v[114:115], v[192:193] op_sel_hi:[1,0,1]
	v_pk_fma_f32 v[180:181], v[22:23], v[116:117], v[180:181] op_sel_hi:[1,0,1]
	v_pk_fma_f32 v[192:193], v[24:25], v[116:117], v[192:193] op_sel_hi:[1,0,1]
	v_mfma_f32_16x16x4_f32 v[106:109], v141, v55, v[106:109]
	v_pk_fma_f32 v[180:181], v[18:19], v[116:117], v[180:181] op_sel:[0,1,0]
	v_pk_fma_f32 v[192:193], v[20:21], v[116:117], v[192:193] op_sel:[0,1,0]
	v_pk_fma_f32 v[180:181], v[14:15], v[176:177], v[180:181] op_sel_hi:[1,0,1]
	v_pk_fma_f32 v[192:193], v[16:17], v[176:177], v[192:193] op_sel_hi:[1,0,1]
	v_mfma_f32_16x16x4_f32 v[102:105], v141, v56, v[102:105]
	v_pk_fma_f32 v[180:181], v[10:11], v[176:177], v[180:181] op_sel:[0,1,0]
	v_pk_fma_f32 v[192:193], v[12:13], v[176:177], v[192:193] op_sel:[0,1,0]
	v_pk_fma_f32 v[180:181], v[6:7], v[178:179], v[180:181] op_sel_hi:[1,0,1]
	v_pk_fma_f32 v[192:193], v[8:9], v[178:179], v[192:193] op_sel_hi:[1,0,1]
	v_mfma_f32_16x16x4_f32 v[98:101], v141, v57, v[98:101]
	v_pk_fma_f32 v[180:181], v[2:3], v[178:179], v[180:181] op_sel:[0,1,0]
	v_pk_fma_f32 v[192:193], v[4:5], v[178:179], v[192:193] op_sel:[0,1,0]
	v_pk_mul_f32 v[180:181], v[146:147], v[180:181]
	v_pk_mul_f32 v[192:193], v[146:147], v[192:193]
	v_pk_fma_f32 v[236:237], v[144:145], v[54:55], v[180:181]
	v_pk_fma_f32 v[238:239], v[144:145], v[56:57], v[192:193]
	global_store_dwordx4 v[150:151], v[236:239], off nt
	v_lshl_add_u64 v[150:151], v[150:151], 0, s[58:59]
	global_load_dwordx4 v[54:57], v[148:149], off nt
	v_lshl_add_u64 v[148:149], v[148:149], 0, s[58:59]
	ds_read_b32 v141, v160 offset:192
	ds_read_b128 v[114:117], v161 offset:1536
	ds_read_b128 v[176:179], v161 offset:1552
	s_waitcnt vmcnt(14)
; #define RS_LOAD(dst, it0) do { _Pragma("unroll") for (int u = 0; u < 8; ++u) dst[u] = __builtin_nontemporal_load((const f32x4*)(S0 + (size_t)(4 * ((it0) + u)) * DV)); } while (0)
; __device__ __forceinline__ void ret_sample_item(Frame& F, int item) {
;     ...
;     for (int it0 = 0; it0 < 64; it0 += 16) {
;         RS_LOAD(sb, it0 + 8);
;         RS_PROC(sa, it0);
;         { const int itn = it0 + 16 < 64 ? it0 + 16 : it0; RS_LOAD(sa, itn); }
;         RS_PROC(sb, it0 + 8);
;     }
	s_waitcnt lgkmcnt(3)
	v_cndmask_b32_e64 v143, 0, v143, s[6:7]
	v_pk_mul_f32 v[180:181], v[26:27], v[172:173] op_sel:[0,1]
	v_pk_mul_f32 v[192:193], v[28:29], v[172:173] op_sel:[0,1]
	v_mfma_f32_16x16x4_f32 v[110:113], v143, v50, v[110:113]
	v_pk_fma_f32 v[180:181], v[30:31], v[172:173], v[180:181] op_sel_hi:[1,0,1]
	v_pk_fma_f32 v[192:193], v[32:33], v[172:173], v[192:193] op_sel_hi:[1,0,1]
	v_pk_fma_f32 v[180:181], v[22:23], v[174:175], v[180:181] op_sel_hi:[1,0,1]
	v_pk_fma_f32 v[192:193], v[24:25], v[174:175], v[192:193] op_sel_hi:[1,0,1]
	v_mfma_f32_16x16x4_f32 v[106:109], v143, v51, v[106:109]
	v_pk_fma_f32 v[180:181], v[18:19], v[174:175], v[180:181] op_sel:[0,1,0]
	v_pk_fma_f32 v[192:193], v[20:21], v[174:175], v[192:193] op_sel:[0,1,0]
	v_pk_fma_f32 v[180:181], v[14:15], v[232:233], v[180:181] op_sel_hi:[1,0,1]
	v_pk_fma_f32 v[192:193], v[16:17], v[232:233], v[192:193] op_sel_hi:[1,0,1]
	v_mfma_f32_16x16x4_f32 v[102:105], v143, v52, v[102:105]
	v_pk_fma_f32 v[180:181], v[10:11], v[232:233], v[180:181] op_sel:[0,1,0]
	v_pk_fma_f32 v[192:193], v[12:13], v[232:233], v[192:193] op_sel:[0,1,0]
	v_pk_fma_f32 v[180:181], v[6:7], v[234:235], v[180:181] op_sel_hi:[1,0,1]
	v_pk_fma_f32 v[192:193], v[8:9], v[234:235], v[192:193] op_sel_hi:[1,0,1]
	v_mfma_f32_16x16x4_f32 v[98:101], v143, v53, v[98:101]
	v_pk_fma_f32 v[180:181], v[2:3], v[234:235], v[180:181] op_sel:[0,1,0]
	v_pk_fma_f32 v[192:193], v[4:5], v[234:235], v[192:193] op_sel:[0,1,0]
	v_pk_mul_f32 v[180:181], v[146:147], v[180:181]
	v_pk_mul_f32 v[192:193], v[146:147], v[192:193]
	v_pk_fma_f32 v[236:237], v[144:145], v[50:51], v[180:181]
	v_pk_fma_f32 v[238:239], v[144:145], v[52:53], v[192:193]
	global_store_dwordx4 v[150:151], v[236:239], off nt
	v_lshl_add_u64 v[150:151], v[150:151], 0, s[58:59]
	global_load_dwordx4 v[50:53], v[148:149], off nt
	v_lshl_add_u64 v[148:149], v[148:149], 0, s[58:59]
	ds_read_b32 v143, v160 offset:208
	ds_read_b128 v[172:175], v161 offset:1664
	ds_read_b128 v[232:235], v161 offset:1680
	s_waitcnt vmcnt(14)
	s_waitcnt lgkmcnt(3)
	v_cndmask_b32_e64 v141, 0, v141, s[6:7]
	v_pk_mul_f32 v[180:181], v[26:27], v[114:115] op_sel:[0,1]
	v_pk_mul_f32 v[192:193], v[28:29], v[114:115] op_sel:[0,1]
	v_mfma_f32_16x16x4_f32 v[110:113], v141, v46, v[110:113]
	v_pk_fma_f32 v[180:181], v[30:31], v[114:115], v[180:181] op_sel_hi:[1,0,1]
	v_pk_fma_f32 v[192:193], v[32:33], v[114:115], v[192:193] op_sel_hi:[1,0,1]
	v_pk_fma_f32 v[180:181], v[22:23], v[116:117], v[180:181] op_sel_hi:[1,0,1]
	v_pk_fma_f32 v[192:193], v[24:25], v[116:117], v[192:193] op_sel_hi:[1,0,1]
	v_mfma_f32_16x16x4_f32 v[106:109], v141, v47, v[106:109]
	v_pk_fma_f32 v[180:181], v[18:19], v[116:117], v[180:181] op_sel:[0,1,0]
	v_pk_fma_f32 v[192:193], v[20:21], v[116:117], v[192:193] op_sel:[0,1,0]
	v_pk_fma_f32 v[180:181], v[14:15], v[176:177], v[180:181] op_sel_hi:[1,0,1]
	v_pk_fma_f32 v[192:193], v[16:17], v[176:177], v[192:193] op_sel_hi:[1,0,1]
	v_mfma_f32_16x16x4_f32 v[102:105], v141, v48, v[102:105]
	v_pk_fma_f32 v[180:181], v[10:11], v[176:177], v[180:181] op_sel:[0,1,0]
	v_pk_fma_f32 v[192:193], v[12:13], v[176:177], v[192:193] op_sel:[0,1,0]
	v_pk_fma_f32 v[180:181], v[6:7], v[178:179], v[180:181] op_sel_hi:[1,0,1]
	v_pk_fma_f32 v[192:193], v[8:9], v[178:179], v[192:193] op_sel_hi:[1,0,1]
	v_mfma_f32_16x16x4_f32 v[98:101], v141, v49, v[98:101]
	v_pk_fma_f32 v[180:181], v[2:3], v[178:179], v[180:181] op_sel:[0,1,0]
	v_pk_fma_f32 v[192:193], v[4:5], v[178:179], v[192:193] op_sel:[0,1,0]
	v_pk_mul_f32 v[180:181], v[146:147], v[180:181]
	v_pk_mul_f32 v[192:193], v[146:147], v[192:193]
	v_pk_fma_f32 v[236:237], v[144:145], v[46:47], v[180:181]
	v_pk_fma_f32 v[238:239], v[144:145], v[48:49], v[192:193]
	global_store_dwordx4 v[150:151], v[236:239], off nt
	v_lshl_add_u64 v[150:151], v[150:151], 0, s[58:59]
	global_load_dwordx4 v[46:49], v[148:149], off nt
	v_lshl_add_u64 v[148:149], v[148:149], 0, s[58:59]
	ds_read_b32 v141, v160 offset:224
	ds_read_b128 v[114:117], v161 offset:1792
	ds_read_b128 v[176:179], v161 offset:1808
	s_waitcnt vmcnt(14)
	s_waitcnt lgkmcnt(3)
	v_cndmask_b32_e64 v143, 0, v143, s[6:7]
	v_pk_mul_f32 v[180:181], v[26:27], v[172:173] op_sel:[0,1]
	v_pk_mul_f32 v[192:193], v[28:29], v[172:173] op_sel:[0,1]
	v_mfma_f32_16x16x4_f32 v[110:113], v143, v42, v[110:113]
	v_pk_fma_f32 v[180:181], v[30:31], v[172:173], v[180:181] op_sel_hi:[1,0,1]
	v_pk_fma_f32 v[192:193], v[32:33], v[172:173], v[192:193] op_sel_hi:[1,0,1]
	v_pk_fma_f32 v[180:181], v[22:23], v[174:175], v[180:181] op_sel_hi:[1,0,1]
	v_pk_fma_f32 v[192:193], v[24:25], v[174:175], v[192:193] op_sel_hi:[1,0,1]
	v_mfma_f32_16x16x4_f32 v[106:109], v143, v43, v[106:109]
	v_pk_fma_f32 v[180:181], v[18:19], v[174:175], v[180:181] op_sel:[0,1,0]
	v_pk_fma_f32 v[192:193], v[20:21], v[174:175], v[192:193] op_sel:[0,1,0]
	v_pk_fma_f32 v[180:181], v[14:15], v[232:233], v[180:181] op_sel_hi:[1,0,1]
	v_pk_fma_f32 v[192:193], v[16:17], v[232:233], v[192:193] op_sel_hi:[1,0,1]
	v_mfma_f32_16x16x4_f32 v[102:105], v143, v44, v[102:105]
	v_pk_fma_f32 v[180:181], v[10:11], v[232:233], v[180:181] op_sel:[0,1,0]
	v_pk_fma_f32 v[192:193], v[12:13], v[232:233], v[192:193] op_sel:[0,1,0]
	v_pk_fma_f32 v[180:181], v[6:7], v[234:235], v[180:181] op_sel_hi:[1,0,1]
	v_pk_fma_f32 v[192:193], v[8:9], v[234:235], v[192:193] op_sel_hi:[1,0,1]
	v_mfma_f32_16x16x4_f32 v[98:101], v143, v45, v[98:101]
	v_pk_fma_f32 v[180:181], v[2:3], v[234:235], v[180:181] op_sel:[0,1,0]
	v_pk_fma_f32 v[192:193], v[4:5], v[234:235], v[192:193] op_sel:[0,1,0]
	v_pk_mul_f32 v[180:181], v[146:147], v[180:181]
	v_pk_mul_f32 v[192:193], v[146:147], v[192:193]
	v_pk_fma_f32 v[236:237], v[144:145], v[42:43], v[180:181]
	v_pk_fma_f32 v[238:239], v[144:145], v[44:45], v[192:193]
	global_store_dwordx4 v[150:151], v[236:239], off nt
	v_lshl_add_u64 v[150:151], v[150:151], 0, s[58:59]
	global_load_dwordx4 v[42:45], v[148:149], off nt
	v_lshl_add_u64 v[148:149], v[148:149], 0, s[58:59]
	ds_read_b32 v143, v160 offset:240
	ds_read_b128 v[172:175], v161 offset:1920
	ds_read_b128 v[232:235], v161 offset:1936
	s_waitcnt vmcnt(14)
; #define RS_LOAD(dst, it0) do { _Pragma("unroll") for (int u = 0; u < 8; ++u) dst[u] = __builtin_nontemporal_load((const f32x4*)(S0 + (size_t)(4 * ((it0) + u)) * DV)); } while (0)
; __device__ __forceinline__ void ret_sample_item(Frame& F, int item) {
;     ...
;     for (int it0 = 0; it0 < 64; it0 += 16) {
;         RS_LOAD(sb, it0 + 8);
;         RS_PROC(sa, it0);
;         { const int itn = it0 + 16 < 64 ? it0 + 16 : it0; RS_LOAD(sa, itn); }
;         RS_PROC(sb, it0 + 8);
;     }
	s_waitcnt lgkmcnt(3)
	v_cndmask_b32_e64 v141, 0, v141, s[6:7]
	v_pk_mul_f32 v[180:181], v[26:27], v[114:115] op_sel:[0,1]
	v_pk_mul_f32 v[192:193], v[28:29], v[114:115] op_sel:[0,1]
	v_mfma_f32_16x16x4_f32 v[110:113], v141, v38, v[110:113]
	v_pk_fma_f32 v[180:181], v[30:31], v[114:115], v[180:181] op_sel_hi:[1,0,1]
	v_pk_fma_f32 v[192:193], v[32:33], v[114:115], v[192:193] op_sel_hi:[1,0,1]
	v_pk_fma_f32 v[180:181], v[22:23], v[116:117], v[180:181] op_sel_hi:[1,0,1]
	v_pk_fma_f32 v[192:193], v[24:25], v[116:117], v[192:193] op_sel_hi:[1,0,1]
	v_mfma_f32_16x16x4_f32 v[106:109], v141, v39, v[106:109]
	v_pk_fma_f32 v[180:181], v[18:19], v[116:117], v[180:181] op_sel:[0,1,0]
	v_pk_fma_f32 v[192:193], v[20:21], v[116:117], v[192:193] op_sel:[0,1,0]
	v_pk_fma_f32 v[180:181], v[14:15], v[176:177], v[180:181] op_sel_hi:[1,0,1]
	v_pk_fma_f32 v[192:193], v[16:17], v[176:177], v[192:193] op_sel_hi:[1,0,1]
	v_mfma_f32_16x16x4_f32 v[102:105], v141, v40, v[102:105]
	v_pk_fma_f32 v[180:181], v[10:11], v[176:177], v[180:181] op_sel:[0,1,0]
	v_pk_fma_f32 v[192:193], v[12:13], v[176:177], v[192:193] op_sel:[0,1,0]
	v_pk_fma_f32 v[180:181], v[6:7], v[178:179], v[180:181] op_sel_hi:[1,0,1]
	v_pk_fma_f32 v[192:193], v[8:9], v[178:179], v[192:193] op_sel_hi:[1,0,1]
	v_mfma_f32_16x16x4_f32 v[98:101], v141, v41, v[98:101]
	v_pk_fma_f32 v[180:181], v[2:3], v[178:179], v[180:181] op_sel:[0,1,0]
	v_pk_fma_f32 v[192:193], v[4:5], v[178:179], v[192:193] op_sel:[0,1,0]
	v_pk_mul_f32 v[180:181], v[146:147], v[180:181]
	v_pk_mul_f32 v[192:193], v[146:147], v[192:193]
	v_pk_fma_f32 v[236:237], v[144:145], v[38:39], v[180:181]
	v_pk_fma_f32 v[238:239], v[144:145], v[40:41], v[192:193]
	global_store_dwordx4 v[150:151], v[236:239], off nt
	v_lshl_add_u64 v[150:151], v[150:151], 0, s[58:59]
	global_load_dwordx4 v[38:41], v[148:149], off nt
	v_lshl_add_u64 v[148:149], v[148:149], 0, s[58:59]
	ds_read_b32 v141, v160 offset:256
	ds_read_b128 v[114:117], v161 offset:2048
	ds_read_b128 v[176:179], v161 offset:2064
	s_waitcnt vmcnt(14)
	s_waitcnt lgkmcnt(3)
	v_cndmask_b32_e64 v143, 0, v143, s[6:7]
	v_pk_mul_f32 v[180:181], v[26:27], v[172:173] op_sel:[0,1]
	v_pk_mul_f32 v[192:193], v[28:29], v[172:173] op_sel:[0,1]
	v_mfma_f32_16x16x4_f32 v[110:113], v143, v34, v[110:113]
	v_pk_fma_f32 v[180:181], v[30:31], v[172:173], v[180:181] op_sel_hi:[1,0,1]
	v_pk_fma_f32 v[192:193], v[32:33], v[172:173], v[192:193] op_sel_hi:[1,0,1]
	v_pk_fma_f32 v[180:181], v[22:23], v[174:175], v[180:181] op_sel_hi:[1,0,1]
	v_pk_fma_f32 v[192:193], v[24:25], v[174:175], v[192:193] op_sel_hi:[1,0,1]
	v_mfma_f32_16x16x4_f32 v[106:109], v143, v35, v[106:109]
	v_pk_fma_f32 v[180:181], v[18:19], v[174:175], v[180:181] op_sel:[0,1,0]
	v_pk_fma_f32 v[192:193], v[20:21], v[174:175], v[192:193] op_sel:[0,1,0]
	v_pk_fma_f32 v[180:181], v[14:15], v[232:233], v[180:181] op_sel_hi:[1,0,1]
	v_pk_fma_f32 v[192:193], v[16:17], v[232:233], v[192:193] op_sel_hi:[1,0,1]
	v_mfma_f32_16x16x4_f32 v[102:105], v143, v36, v[102:105]
	v_pk_fma_f32 v[180:181], v[10:11], v[232:233], v[180:181] op_sel:[0,1,0]
	v_pk_fma_f32 v[192:193], v[12:13], v[232:233], v[192:193] op_sel:[0,1,0]
	v_pk_fma_f32 v[180:181], v[6:7], v[234:235], v[180:181] op_sel_hi:[1,0,1]
	v_pk_fma_f32 v[192:193], v[8:9], v[234:235], v[192:193] op_sel_hi:[1,0,1]
	v_mfma_f32_16x16x4_f32 v[98:101], v143, v37, v[98:101]
	v_pk_fma_f32 v[180:181], v[2:3], v[234:235], v[180:181] op_sel:[0,1,0]
	v_pk_fma_f32 v[192:193], v[4:5], v[234:235], v[192:193] op_sel:[0,1,0]
	v_pk_mul_f32 v[180:181], v[146:147], v[180:181]
	v_pk_mul_f32 v[192:193], v[146:147], v[192:193]
	v_pk_fma_f32 v[236:237], v[144:145], v[34:35], v[180:181]
	v_pk_fma_f32 v[238:239], v[144:145], v[36:37], v[192:193]
	global_store_dwordx4 v[150:151], v[236:239], off nt
	v_lshl_add_u64 v[150:151], v[150:151], 0, s[58:59]
	global_load_dwordx4 v[34:37], v[148:149], off nt
	v_lshl_add_u64 v[148:149], v[148:149], 0, s[58:59]
	ds_read_b32 v143, v160 offset:272
	ds_read_b128 v[172:175], v161 offset:2176
	ds_read_b128 v[232:235], v161 offset:2192
	s_waitcnt vmcnt(14)
	s_waitcnt lgkmcnt(3)
	v_cndmask_b32_e64 v141, 0, v141, s[6:7]
	v_pk_mul_f32 v[180:181], v[26:27], v[114:115] op_sel:[0,1]
	v_pk_mul_f32 v[192:193], v[28:29], v[114:115] op_sel:[0,1]
	v_mfma_f32_16x16x4_f32 v[110:113], v141, v70, v[110:113]
	v_pk_fma_f32 v[180:181], v[30:31], v[114:115], v[180:181] op_sel_hi:[1,0,1]
	v_pk_fma_f32 v[192:193], v[32:33], v[114:115], v[192:193] op_sel_hi:[1,0,1]
	v_pk_fma_f32 v[180:181], v[22:23], v[116:117], v[180:181] op_sel_hi:[1,0,1]
	v_pk_fma_f32 v[192:193], v[24:25], v[116:117], v[192:193] op_sel_hi:[1,0,1]
	v_mfma_f32_16x16x4_f32 v[106:109], v141, v71, v[106:109]
	v_pk_fma_f32 v[180:181], v[18:19], v[116:117], v[180:181] op_sel:[0,1,0]
	v_pk_fma_f32 v[192:193], v[20:21], v[116:117], v[192:193] op_sel:[0,1,0]
	v_pk_fma_f32 v[180:181], v[14:15], v[176:177], v[180:181] op_sel_hi:[1,0,1]
	v_pk_fma_f32 v[192:193], v[16:17], v[176:177], v[192:193] op_sel_hi:[1,0,1]
	v_mfma_f32_16x16x4_f32 v[102:105], v141, v72, v[102:105]
	v_pk_fma_f32 v[180:181], v[10:11], v[176:177], v[180:181] op_sel:[0,1,0]
	v_pk_fma_f32 v[192:193], v[12:13], v[176:177], v[192:193] op_sel:[0,1,0]
	v_pk_fma_f32 v[180:181], v[6:7], v[178:179], v[180:181] op_sel_hi:[1,0,1]
	v_pk_fma_f32 v[192:193], v[8:9], v[178:179], v[192:193] op_sel_hi:[1,0,1]
	v_mfma_f32_16x16x4_f32 v[98:101], v141, v73, v[98:101]
	v_pk_fma_f32 v[180:181], v[2:3], v[178:179], v[180:181] op_sel:[0,1,0]
	v_pk_fma_f32 v[192:193], v[4:5], v[178:179], v[192:193] op_sel:[0,1,0]
	v_pk_mul_f32 v[180:181], v[146:147], v[180:181]
	v_pk_mul_f32 v[192:193], v[146:147], v[192:193]
	v_pk_fma_f32 v[236:237], v[144:145], v[70:71], v[180:181]
	v_pk_fma_f32 v[238:239], v[144:145], v[72:73], v[192:193]
	global_store_dwordx4 v[150:151], v[236:239], off nt
	v_lshl_add_u64 v[150:151], v[150:151], 0, s[58:59]
	global_load_dwordx4 v[70:73], v[148:149], off nt
	v_lshl_add_u64 v[148:149], v[148:149], 0, s[58:59]
	ds_read_b32 v141, v160 offset:288
	ds_read_b128 v[114:117], v161 offset:2304
	ds_read_b128 v[176:179], v161 offset:2320
	s_waitcnt vmcnt(14)
; #define RS_LOAD(dst, it0) do { _Pragma("unroll") for (int u = 0; u < 8; ++u) dst[u] = __builtin_nontemporal_load((const f32x4*)(S0 + (size_t)(4 * ((it0) + u)) * DV)); } while (0)
; __device__ __forceinline__ void ret_sample_item(Frame& F, int item) {
;     ...
;     for (int it0 = 0; it0 < 64; it0 += 16) {
;         RS_LOAD(sb, it0 + 8);
;         RS_PROC(sa, it0);
;         { const int itn = it0 + 16 < 64 ? it0 + 16 : it0; RS_LOAD(sa, itn); }
;         RS_PROC(sb, it0 + 8);
;     }
	s_waitcnt lgkmcnt(3)
	v_cndmask_b32_e64 v143, 0, v143, s[6:7]
	v_pk_mul_f32 v[180:181], v[26:27], v[172:173] op_sel:[0,1]
	v_pk_mul_f32 v[192:193], v[28:29], v[172:173] op_sel:[0,1]
	v_mfma_f32_16x16x4_f32 v[110:113], v143, v62, v[110:113]
	v_pk_fma_f32 v[180:181], v[30:31], v[172:173], v[180:181] op_sel_hi:[1,0,1]
	v_pk_fma_f32 v[192:193], v[32:33], v[172:173], v[192:193] op_sel_hi:[1,0,1]
	v_pk_fma_f32 v[180:181], v[22:23], v[174:175], v[180:181] op_sel_hi:[1,0,1]
	v_pk_fma_f32 v[192:193], v[24:25], v[174:175], v[192:193] op_sel_hi:[1,0,1]
	v_mfma_f32_16x16x4_f32 v[106:109], v143, v63, v[106:109]
	v_pk_fma_f32 v[180:181], v[18:19], v[174:175], v[180:181] op_sel:[0,1,0]
	v_pk_fma_f32 v[192:193], v[20:21], v[174:175], v[192:193] op_sel:[0,1,0]
	v_pk_fma_f32 v[180:181], v[14:15], v[232:233], v[180:181] op_sel_hi:[1,0,1]
	v_pk_fma_f32 v[192:193], v[16:17], v[232:233], v[192:193] op_sel_hi:[1,0,1]
	v_mfma_f32_16x16x4_f32 v[102:105], v143, v64, v[102:105]
	v_pk_fma_f32 v[180:181], v[10:11], v[232:233], v[180:181] op_sel:[0,1,0]
	v_pk_fma_f32 v[192:193], v[12:13], v[232:233], v[192:193] op_sel:[0,1,0]
	v_pk_fma_f32 v[180:181], v[6:7], v[234:235], v[180:181] op_sel_hi:[1,0,1]
	v_pk_fma_f32 v[192:193], v[8:9], v[234:235], v[192:193] op_sel_hi:[1,0,1]
	v_mfma_f32_16x16x4_f32 v[98:101], v143, v65, v[98:101]
	v_pk_fma_f32 v[180:181], v[2:3], v[234:235], v[180:181] op_sel:[0,1,0]
	v_pk_fma_f32 v[192:193], v[4:5], v[234:235], v[192:193] op_sel:[0,1,0]
	v_pk_mul_f32 v[180:181], v[146:147], v[180:181]
	v_pk_mul_f32 v[192:193], v[146:147], v[192:193]
	v_pk_fma_f32 v[236:237], v[144:145], v[62:63], v[180:181]
	v_pk_fma_f32 v[238:239], v[144:145], v[64:65], v[192:193]
	global_store_dwordx4 v[150:151], v[236:239], off nt
	v_lshl_add_u64 v[150:151], v[150:151], 0, s[58:59]
	global_load_dwordx4 v[62:65], v[148:149], off nt
	v_lshl_add_u64 v[148:149], v[148:149], 0, s[58:59]
	ds_read_b32 v143, v160 offset:304
	ds_read_b128 v[172:175], v161 offset:2432
	ds_read_b128 v[232:235], v161 offset:2448
	s_waitcnt vmcnt(14)
	s_waitcnt lgkmcnt(3)
	v_cndmask_b32_e64 v141, 0, v141, s[6:7]
	v_pk_mul_f32 v[180:181], v[26:27], v[114:115] op_sel:[0,1]
	v_pk_mul_f32 v[192:193], v[28:29], v[114:115] op_sel:[0,1]
	v_mfma_f32_16x16x4_f32 v[110:113], v141, v54, v[110:113]
	v_pk_fma_f32 v[180:181], v[30:31], v[114:115], v[180:181] op_sel_hi:[1,0,1]
	v_pk_fma_f32 v[192:193], v[32:33], v[114:115], v[192:193] op_sel_hi:[1,0,1]
	v_pk_fma_f32 v[180:181], v[22:23], v[116:117], v[180:181] op_sel_hi:[1,0,1]
	v_pk_fma_f32 v[192:193], v[24:25], v[116:117], v[192:193] op_sel_hi:[1,0,1]
	v_mfma_f32_16x16x4_f32 v[106:109], v141, v55, v[106:109]
	v_pk_fma_f32 v[180:181], v[18:19], v[116:117], v[180:181] op_sel:[0,1,0]
	v_pk_fma_f32 v[192:193], v[20:21], v[116:117], v[192:193] op_sel:[0,1,0]
	v_pk_fma_f32 v[180:181], v[14:15], v[176:177], v[180:181] op_sel_hi:[1,0,1]
	v_pk_fma_f32 v[192:193], v[16:17], v[176:177], v[192:193] op_sel_hi:[1,0,1]
	v_mfma_f32_16x16x4_f32 v[102:105], v141, v56, v[102:105]
	v_pk_fma_f32 v[180:181], v[10:11], v[176:177], v[180:181] op_sel:[0,1,0]
	v_pk_fma_f32 v[192:193], v[12:13], v[176:177], v[192:193] op_sel:[0,1,0]
	v_pk_fma_f32 v[180:181], v[6:7], v[178:179], v[180:181] op_sel_hi:[1,0,1]
	v_pk_fma_f32 v[192:193], v[8:9], v[178:179], v[192:193] op_sel_hi:[1,0,1]
	v_mfma_f32_16x16x4_f32 v[98:101], v141, v57, v[98:101]
	v_pk_fma_f32 v[180:181], v[2:3], v[178:179], v[180:181] op_sel:[0,1,0]
	v_pk_fma_f32 v[192:193], v[4:5], v[178:179], v[192:193] op_sel:[0,1,0]
	v_pk_mul_f32 v[180:181], v[146:147], v[180:181]
	v_pk_mul_f32 v[192:193], v[146:147], v[192:193]
	v_pk_fma_f32 v[236:237], v[144:145], v[54:55], v[180:181]
	v_pk_fma_f32 v[238:239], v[144:145], v[56:57], v[192:193]
	global_store_dwordx4 v[150:151], v[236:239], off nt
	v_lshl_add_u64 v[150:151], v[150:151], 0, s[58:59]
	global_load_dwordx4 v[54:57], v[148:149], off nt
	v_lshl_add_u64 v[148:149], v[148:149], 0, s[58:59]
	ds_read_b32 v141, v160 offset:320
	ds_read_b128 v[114:117], v161 offset:2560
	ds_read_b128 v[176:179], v161 offset:2576
	s_waitcnt vmcnt(14)
	s_waitcnt lgkmcnt(3)
	v_cndmask_b32_e64 v143, 0, v143, s[6:7]
	v_pk_mul_f32 v[180:181], v[26:27], v[172:173] op_sel:[0,1]
	v_pk_mul_f32 v[192:193], v[28:29], v[172:173] op_sel:[0,1]
	v_mfma_f32_16x16x4_f32 v[110:113], v143, v50, v[110:113]
	v_pk_fma_f32 v[180:181], v[30:31], v[172:173], v[180:181] op_sel_hi:[1,0,1]
	v_pk_fma_f32 v[192:193], v[32:33], v[172:173], v[192:193] op_sel_hi:[1,0,1]
	v_pk_fma_f32 v[180:181], v[22:23], v[174:175], v[180:181] op_sel_hi:[1,0,1]
	v_pk_fma_f32 v[192:193], v[24:25], v[174:175], v[192:193] op_sel_hi:[1,0,1]
	v_mfma_f32_16x16x4_f32 v[106:109], v143, v51, v[106:109]
	v_pk_fma_f32 v[180:181], v[18:19], v[174:175], v[180:181] op_sel:[0,1,0]
	v_pk_fma_f32 v[192:193], v[20:21], v[174:175], v[192:193] op_sel:[0,1,0]
	v_pk_fma_f32 v[180:181], v[14:15], v[232:233], v[180:181] op_sel_hi:[1,0,1]
	v_pk_fma_f32 v[192:193], v[16:17], v[232:233], v[192:193] op_sel_hi:[1,0,1]
	v_mfma_f32_16x16x4_f32 v[102:105], v143, v52, v[102:105]
	v_pk_fma_f32 v[180:181], v[10:11], v[232:233], v[180:181] op_sel:[0,1,0]
	v_pk_fma_f32 v[192:193], v[12:13], v[232:233], v[192:193] op_sel:[0,1,0]
	v_pk_fma_f32 v[180:181], v[6:7], v[234:235], v[180:181] op_sel_hi:[1,0,1]
	v_pk_fma_f32 v[192:193], v[8:9], v[234:235], v[192:193] op_sel_hi:[1,0,1]
	v_mfma_f32_16x16x4_f32 v[98:101], v143, v53, v[98:101]
	v_pk_fma_f32 v[180:181], v[2:3], v[234:235], v[180:181] op_sel:[0,1,0]
	v_pk_fma_f32 v[192:193], v[4:5], v[234:235], v[192:193] op_sel:[0,1,0]
	v_pk_mul_f32 v[180:181], v[146:147], v[180:181]
	v_pk_mul_f32 v[192:193], v[146:147], v[192:193]
	v_pk_fma_f32 v[236:237], v[144:145], v[50:51], v[180:181]
	v_pk_fma_f32 v[238:239], v[144:145], v[52:53], v[192:193]
	global_store_dwordx4 v[150:151], v[236:239], off nt
	v_lshl_add_u64 v[150:151], v[150:151], 0, s[58:59]
	global_load_dwordx4 v[50:53], v[148:149], off nt
	v_lshl_add_u64 v[148:149], v[148:149], 0, s[58:59]
	ds_read_b32 v143, v160 offset:336
	ds_read_b128 v[172:175], v161 offset:2688
	ds_read_b128 v[232:235], v161 offset:2704
	s_waitcnt vmcnt(14)
; #define RS_LOAD(dst, it0) do { _Pragma("unroll") for (int u = 0; u < 8; ++u) dst[u] = __builtin_nontemporal_load((const f32x4*)(S0 + (size_t)(4 * ((it0) + u)) * DV)); } while (0)
; __device__ __forceinline__ void ret_sample_item(Frame& F, int item) {
;     ...
;     for (int it0 = 0; it0 < 64; it0 += 16) {
;         RS_LOAD(sb, it0 + 8);
;         RS_PROC(sa, it0);
;         { const int itn = it0 + 16 < 64 ? it0 + 16 : it0; RS_LOAD(sa, itn); }
;         RS_PROC(sb, it0 + 8);
;     }
	s_waitcnt lgkmcnt(3)
	v_cndmask_b32_e64 v141, 0, v141, s[6:7]
	v_pk_mul_f32 v[180:181], v[26:27], v[114:115] op_sel:[0,1]
	v_pk_mul_f32 v[192:193], v[28:29], v[114:115] op_sel:[0,1]
	v_mfma_f32_16x16x4_f32 v[110:113], v141, v46, v[110:113]
	v_pk_fma_f32 v[180:181], v[30:31], v[114:115], v[180:181] op_sel_hi:[1,0,1]
	v_pk_fma_f32 v[192:193], v[32:33], v[114:115], v[192:193] op_sel_hi:[1,0,1]
	v_pk_fma_f32 v[180:181], v[22:23], v[116:117], v[180:181] op_sel_hi:[1,0,1]
	v_pk_fma_f32 v[192:193], v[24:25], v[116:117], v[192:193] op_sel_hi:[1,0,1]
	v_mfma_f32_16x16x4_f32 v[106:109], v141, v47, v[106:109]
	v_pk_fma_f32 v[180:181], v[18:19], v[116:117], v[180:181] op_sel:[0,1,0]
	v_pk_fma_f32 v[192:193], v[20:21], v[116:117], v[192:193] op_sel:[0,1,0]
	v_pk_fma_f32 v[180:181], v[14:15], v[176:177], v[180:181] op_sel_hi:[1,0,1]
	v_pk_fma_f32 v[192:193], v[16:17], v[176:177], v[192:193] op_sel_hi:[1,0,1]
	v_mfma_f32_16x16x4_f32 v[102:105], v141, v48, v[102:105]
	v_pk_fma_f32 v[180:181], v[10:11], v[176:177], v[180:181] op_sel:[0,1,0]
	v_pk_fma_f32 v[192:193], v[12:13], v[176:177], v[192:193] op_sel:[0,1,0]
	v_pk_fma_f32 v[180:181], v[6:7], v[178:179], v[180:181] op_sel_hi:[1,0,1]
	v_pk_fma_f32 v[192:193], v[8:9], v[178:179], v[192:193] op_sel_hi:[1,0,1]
	v_mfma_f32_16x16x4_f32 v[98:101], v141, v49, v[98:101]
	v_pk_fma_f32 v[180:181], v[2:3], v[178:179], v[180:181] op_sel:[0,1,0]
	v_pk_fma_f32 v[192:193], v[4:5], v[178:179], v[192:193] op_sel:[0,1,0]
	v_pk_mul_f32 v[180:181], v[146:147], v[180:181]
	v_pk_mul_f32 v[192:193], v[146:147], v[192:193]
	v_pk_fma_f32 v[236:237], v[144:145], v[46:47], v[180:181]
	v_pk_fma_f32 v[238:239], v[144:145], v[48:49], v[192:193]
	global_store_dwordx4 v[150:151], v[236:239], off nt
	v_lshl_add_u64 v[150:151], v[150:151], 0, s[58:59]
	global_load_dwordx4 v[46:49], v[148:149], off nt
	v_lshl_add_u64 v[148:149], v[148:149], 0, s[58:59]
	ds_read_b32 v141, v160 offset:352
	ds_read_b128 v[114:117], v161 offset:2816
	ds_read_b128 v[176:179], v161 offset:2832
	s_waitcnt vmcnt(14)
	s_waitcnt lgkmcnt(3)
	v_cndmask_b32_e64 v143, 0, v143, s[6:7]
	v_pk_mul_f32 v[180:181], v[26:27], v[172:173] op_sel:[0,1]
	v_pk_mul_f32 v[192:193], v[28:29], v[172:173] op_sel:[0,1]
	v_mfma_f32_16x16x4_f32 v[110:113], v143, v42, v[110:113]
	v_pk_fma_f32 v[180:181], v[30:31], v[172:173], v[180:181] op_sel_hi:[1,0,1]
	v_pk_fma_f32 v[192:193], v[32:33], v[172:173], v[192:193] op_sel_hi:[1,0,1]
	v_pk_fma_f32 v[180:181], v[22:23], v[174:175], v[180:181] op_sel_hi:[1,0,1]
	v_pk_fma_f32 v[192:193], v[24:25], v[174:175], v[192:193] op_sel_hi:[1,0,1]
	v_mfma_f32_16x16x4_f32 v[106:109], v143, v43, v[106:109]
	v_pk_fma_f32 v[180:181], v[18:19], v[174:175], v[180:181] op_sel:[0,1,0]
	v_pk_fma_f32 v[192:193], v[20:21], v[174:175], v[192:193] op_sel:[0,1,0]
	v_pk_fma_f32 v[180:181], v[14:15], v[232:233], v[180:181] op_sel_hi:[1,0,1]
	v_pk_fma_f32 v[192:193], v[16:17], v[232:233], v[192:193] op_sel_hi:[1,0,1]
	v_mfma_f32_16x16x4_f32 v[102:105], v143, v44, v[102:105]
	v_pk_fma_f32 v[180:181], v[10:11], v[232:233], v[180:181] op_sel:[0,1,0]
	v_pk_fma_f32 v[192:193], v[12:13], v[232:233], v[192:193] op_sel:[0,1,0]
	v_pk_fma_f32 v[180:181], v[6:7], v[234:235], v[180:181] op_sel_hi:[1,0,1]
	v_pk_fma_f32 v[192:193], v[8:9], v[234:235], v[192:193] op_sel_hi:[1,0,1]
	v_mfma_f32_16x16x4_f32 v[98:101], v143, v45, v[98:101]
	v_pk_fma_f32 v[180:181], v[2:3], v[234:235], v[180:181] op_sel:[0,1,0]
	v_pk_fma_f32 v[192:193], v[4:5], v[234:235], v[192:193] op_sel:[0,1,0]
	v_pk_mul_f32 v[180:181], v[146:147], v[180:181]
	v_pk_mul_f32 v[192:193], v[146:147], v[192:193]
	v_pk_fma_f32 v[236:237], v[144:145], v[42:43], v[180:181]
	v_pk_fma_f32 v[238:239], v[144:145], v[44:45], v[192:193]
	global_store_dwordx4 v[150:151], v[236:239], off nt
	v_lshl_add_u64 v[150:151], v[150:151], 0, s[58:59]
	global_load_dwordx4 v[42:45], v[148:149], off nt
	v_lshl_add_u64 v[148:149], v[148:149], 0, s[58:59]
	ds_read_b32 v143, v160 offset:368
	ds_read_b128 v[172:175], v161 offset:2944
	ds_read_b128 v[232:235], v161 offset:2960
	s_waitcnt vmcnt(14)
	s_waitcnt lgkmcnt(3)
	v_cndmask_b32_e64 v141, 0, v141, s[6:7]
	v_pk_mul_f32 v[180:181], v[26:27], v[114:115] op_sel:[0,1]
	v_pk_mul_f32 v[192:193], v[28:29], v[114:115] op_sel:[0,1]
	v_mfma_f32_16x16x4_f32 v[110:113], v141, v38, v[110:113]
	v_pk_fma_f32 v[180:181], v[30:31], v[114:115], v[180:181] op_sel_hi:[1,0,1]
	v_pk_fma_f32 v[192:193], v[32:33], v[114:115], v[192:193] op_sel_hi:[1,0,1]
	v_pk_fma_f32 v[180:181], v[22:23], v[116:117], v[180:181] op_sel_hi:[1,0,1]
	v_pk_fma_f32 v[192:193], v[24:25], v[116:117], v[192:193] op_sel_hi:[1,0,1]
	v_mfma_f32_16x16x4_f32 v[106:109], v141, v39, v[106:109]
	v_pk_fma_f32 v[180:181], v[18:19], v[116:117], v[180:181] op_sel:[0,1,0]
	v_pk_fma_f32 v[192:193], v[20:21], v[116:117], v[192:193] op_sel:[0,1,0]
	v_pk_fma_f32 v[180:181], v[14:15], v[176:177], v[180:181] op_sel_hi:[1,0,1]
	v_pk_fma_f32 v[192:193], v[16:17], v[176:177], v[192:193] op_sel_hi:[1,0,1]
	v_mfma_f32_16x16x4_f32 v[102:105], v141, v40, v[102:105]
	v_pk_fma_f32 v[180:181], v[10:11], v[176:177], v[180:181] op_sel:[0,1,0]
	v_pk_fma_f32 v[192:193], v[12:13], v[176:177], v[192:193] op_sel:[0,1,0]
	v_pk_fma_f32 v[180:181], v[6:7], v[178:179], v[180:181] op_sel_hi:[1,0,1]
	v_pk_fma_f32 v[192:193], v[8:9], v[178:179], v[192:193] op_sel_hi:[1,0,1]
	v_mfma_f32_16x16x4_f32 v[98:101], v141, v41, v[98:101]
	v_pk_fma_f32 v[180:181], v[2:3], v[178:179], v[180:181] op_sel:[0,1,0]
	v_pk_fma_f32 v[192:193], v[4:5], v[178:179], v[192:193] op_sel:[0,1,0]
	v_pk_mul_f32 v[180:181], v[146:147], v[180:181]
	v_pk_mul_f32 v[192:193], v[146:147], v[192:193]
	v_pk_fma_f32 v[236:237], v[144:145], v[38:39], v[180:181]
	v_pk_fma_f32 v[238:239], v[144:145], v[40:41], v[192:193]
	global_store_dwordx4 v[150:151], v[236:239], off nt
	v_lshl_add_u64 v[150:151], v[150:151], 0, s[58:59]
	global_load_dwordx4 v[38:41], v[148:149], off nt
	v_lshl_add_u64 v[148:149], v[148:149], 0, s[58:59]
	ds_read_b32 v141, v160 offset:384
	ds_read_b128 v[114:117], v161 offset:3072
	ds_read_b128 v[176:179], v161 offset:3088
	s_waitcnt vmcnt(14)
; #define RS_LOAD(dst, it0) do { _Pragma("unroll") for (int u = 0; u < 8; ++u) dst[u] = __builtin_nontemporal_load((const f32x4*)(S0 + (size_t)(4 * ((it0) + u)) * DV)); } while (0)
; __device__ __forceinline__ void ret_sample_item(Frame& F, int item) {
;     ...
;     for (int it0 = 0; it0 < 64; it0 += 16) {
;         RS_LOAD(sb, it0 + 8);
;         RS_PROC(sa, it0);
;         { const int itn = it0 + 16 < 64 ? it0 + 16 : it0; RS_LOAD(sa, itn); }
;         RS_PROC(sb, it0 + 8);
;     }
	s_waitcnt lgkmcnt(3)
	v_cndmask_b32_e64 v143, 0, v143, s[6:7]
	v_pk_mul_f32 v[180:181], v[26:27], v[172:173] op_sel:[0,1]
	v_pk_mul_f32 v[192:193], v[28:29], v[172:173] op_sel:[0,1]
	v_mfma_f32_16x16x4_f32 v[110:113], v143, v34, v[110:113]
	v_pk_fma_f32 v[180:181], v[30:31], v[172:173], v[180:181] op_sel_hi:[1,0,1]
	v_pk_fma_f32 v[192:193], v[32:33], v[172:173], v[192:193] op_sel_hi:[1,0,1]
	v_pk_fma_f32 v[180:181], v[22:23], v[174:175], v[180:181] op_sel_hi:[1,0,1]
	v_pk_fma_f32 v[192:193], v[24:25], v[174:175], v[192:193] op_sel_hi:[1,0,1]
	v_mfma_f32_16x16x4_f32 v[106:109], v143, v35, v[106:109]
	v_pk_fma_f32 v[180:181], v[18:19], v[174:175], v[180:181] op_sel:[0,1,0]
	v_pk_fma_f32 v[192:193], v[20:21], v[174:175], v[192:193] op_sel:[0,1,0]
	v_pk_fma_f32 v[180:181], v[14:15], v[232:233], v[180:181] op_sel_hi:[1,0,1]
	v_pk_fma_f32 v[192:193], v[16:17], v[232:233], v[192:193] op_sel_hi:[1,0,1]
	v_mfma_f32_16x16x4_f32 v[102:105], v143, v36, v[102:105]
	v_pk_fma_f32 v[180:181], v[10:11], v[232:233], v[180:181] op_sel:[0,1,0]
	v_pk_fma_f32 v[192:193], v[12:13], v[232:233], v[192:193] op_sel:[0,1,0]
	v_pk_fma_f32 v[180:181], v[6:7], v[234:235], v[180:181] op_sel_hi:[1,0,1]
	v_pk_fma_f32 v[192:193], v[8:9], v[234:235], v[192:193] op_sel_hi:[1,0,1]
	v_mfma_f32_16x16x4_f32 v[98:101], v143, v37, v[98:101]
	v_pk_fma_f32 v[180:181], v[2:3], v[234:235], v[180:181] op_sel:[0,1,0]
	v_pk_fma_f32 v[192:193], v[4:5], v[234:235], v[192:193] op_sel:[0,1,0]
	v_pk_mul_f32 v[180:181], v[146:147], v[180:181]
	v_pk_mul_f32 v[192:193], v[146:147], v[192:193]
	v_pk_fma_f32 v[236:237], v[144:145], v[34:35], v[180:181]
	v_pk_fma_f32 v[238:239], v[144:145], v[36:37], v[192:193]
	global_store_dwordx4 v[150:151], v[236:239], off nt
	v_lshl_add_u64 v[150:151], v[150:151], 0, s[58:59]
	global_load_dwordx4 v[34:37], v[148:149], off nt
	v_lshl_add_u64 v[148:149], v[148:149], 0, s[58:59]
	ds_read_b32 v143, v160 offset:400
	ds_read_b128 v[172:175], v161 offset:3200
	ds_read_b128 v[232:235], v161 offset:3216
	s_waitcnt vmcnt(14)
	s_waitcnt lgkmcnt(3)
	v_cndmask_b32_e64 v141, 0, v141, s[6:7]
	v_pk_mul_f32 v[180:181], v[26:27], v[114:115] op_sel:[0,1]
	v_pk_mul_f32 v[192:193], v[28:29], v[114:115] op_sel:[0,1]
	v_mfma_f32_16x16x4_f32 v[110:113], v141, v70, v[110:113]
	v_pk_fma_f32 v[180:181], v[30:31], v[114:115], v[180:181] op_sel_hi:[1,0,1]
	v_pk_fma_f32 v[192:193], v[32:33], v[114:115], v[192:193] op_sel_hi:[1,0,1]
	v_pk_fma_f32 v[180:181], v[22:23], v[116:117], v[180:181] op_sel_hi:[1,0,1]
	v_pk_fma_f32 v[192:193], v[24:25], v[116:117], v[192:193] op_sel_hi:[1,0,1]
	v_mfma_f32_16x16x4_f32 v[106:109], v141, v71, v[106:109]
	v_pk_fma_f32 v[180:181], v[18:19], v[116:117], v[180:181] op_sel:[0,1,0]
	v_pk_fma_f32 v[192:193], v[20:21], v[116:117], v[192:193] op_sel:[0,1,0]
	v_pk_fma_f32 v[180:181], v[14:15], v[176:177], v[180:181] op_sel_hi:[1,0,1]
	v_pk_fma_f32 v[192:193], v[16:17], v[176:177], v[192:193] op_sel_hi:[1,0,1]
	v_mfma_f32_16x16x4_f32 v[102:105], v141, v72, v[102:105]
	v_pk_fma_f32 v[180:181], v[10:11], v[176:177], v[180:181] op_sel:[0,1,0]
	v_pk_fma_f32 v[192:193], v[12:13], v[176:177], v[192:193] op_sel:[0,1,0]
	v_pk_fma_f32 v[180:181], v[6:7], v[178:179], v[180:181] op_sel_hi:[1,0,1]
	v_pk_fma_f32 v[192:193], v[8:9], v[178:179], v[192:193] op_sel_hi:[1,0,1]
	v_mfma_f32_16x16x4_f32 v[98:101], v141, v73, v[98:101]
	v_pk_fma_f32 v[180:181], v[2:3], v[178:179], v[180:181] op_sel:[0,1,0]
	v_pk_fma_f32 v[192:193], v[4:5], v[178:179], v[192:193] op_sel:[0,1,0]
	v_pk_mul_f32 v[180:181], v[146:147], v[180:181]
	v_pk_mul_f32 v[192:193], v[146:147], v[192:193]
	v_pk_fma_f32 v[236:237], v[144:145], v[70:71], v[180:181]
	v_pk_fma_f32 v[238:239], v[144:145], v[72:73], v[192:193]
	global_store_dwordx4 v[150:151], v[236:239], off nt
	v_lshl_add_u64 v[150:151], v[150:151], 0, s[58:59]
	global_load_dwordx4 v[70:73], v[148:149], off nt
	v_lshl_add_u64 v[148:149], v[148:149], 0, s[58:59]
	ds_read_b32 v141, v160 offset:416
	ds_read_b128 v[114:117], v161 offset:3328
	ds_read_b128 v[176:179], v161 offset:3344
	s_waitcnt vmcnt(14)
	s_waitcnt lgkmcnt(3)
	v_cndmask_b32_e64 v143, 0, v143, s[6:7]
	v_pk_mul_f32 v[180:181], v[26:27], v[172:173] op_sel:[0,1]
	v_pk_mul_f32 v[192:193], v[28:29], v[172:173] op_sel:[0,1]
	v_mfma_f32_16x16x4_f32 v[110:113], v143, v62, v[110:113]
	v_pk_fma_f32 v[180:181], v[30:31], v[172:173], v[180:181] op_sel_hi:[1,0,1]
	v_pk_fma_f32 v[192:193], v[32:33], v[172:173], v[192:193] op_sel_hi:[1,0,1]
	v_pk_fma_f32 v[180:181], v[22:23], v[174:175], v[180:181] op_sel_hi:[1,0,1]
	v_pk_fma_f32 v[192:193], v[24:25], v[174:175], v[192:193] op_sel_hi:[1,0,1]
	v_mfma_f32_16x16x4_f32 v[106:109], v143, v63, v[106:109]
	v_pk_fma_f32 v[180:181], v[18:19], v[174:175], v[180:181] op_sel:[0,1,0]
	v_pk_fma_f32 v[192:193], v[20:21], v[174:175], v[192:193] op_sel:[0,1,0]
	v_pk_fma_f32 v[180:181], v[14:15], v[232:233], v[180:181] op_sel_hi:[1,0,1]
	v_pk_fma_f32 v[192:193], v[16:17], v[232:233], v[192:193] op_sel_hi:[1,0,1]
	v_mfma_f32_16x16x4_f32 v[102:105], v143, v64, v[102:105]
	v_pk_fma_f32 v[180:181], v[10:11], v[232:233], v[180:181] op_sel:[0,1,0]
	v_pk_fma_f32 v[192:193], v[12:13], v[232:233], v[192:193] op_sel:[0,1,0]
	v_pk_fma_f32 v[180:181], v[6:7], v[234:235], v[180:181] op_sel_hi:[1,0,1]
	v_pk_fma_f32 v[192:193], v[8:9], v[234:235], v[192:193] op_sel_hi:[1,0,1]
	v_mfma_f32_16x16x4_f32 v[98:101], v143, v65, v[98:101]
	v_pk_fma_f32 v[180:181], v[2:3], v[234:235], v[180:181] op_sel:[0,1,0]
	v_pk_fma_f32 v[192:193], v[4:5], v[234:235], v[192:193] op_sel:[0,1,0]
	v_pk_mul_f32 v[180:181], v[146:147], v[180:181]
	v_pk_mul_f32 v[192:193], v[146:147], v[192:193]
	v_pk_fma_f32 v[236:237], v[144:145], v[62:63], v[180:181]
	v_pk_fma_f32 v[238:239], v[144:145], v[64:65], v[192:193]
	global_store_dwordx4 v[150:151], v[236:239], off nt
	v_lshl_add_u64 v[150:151], v[150:151], 0, s[58:59]
	global_load_dwordx4 v[62:65], v[148:149], off nt
	v_lshl_add_u64 v[148:149], v[148:149], 0, s[58:59]
	ds_read_b32 v143, v160 offset:432
	ds_read_b128 v[172:175], v161 offset:3456
	ds_read_b128 v[232:235], v161 offset:3472
	s_waitcnt vmcnt(14)
; #define RS_LOAD(dst, it0) do { _Pragma("unroll") for (int u = 0; u < 8; ++u) dst[u] = __builtin_nontemporal_load((const f32x4*)(S0 + (size_t)(4 * ((it0) + u)) * DV)); } while (0)
; __device__ __forceinline__ void ret_sample_item(Frame& F, int item) {
;     ...
;     for (int it0 = 0; it0 < 64; it0 += 16) {
;         RS_LOAD(sb, it0 + 8);
;         RS_PROC(sa, it0);
;         { const int itn = it0 + 16 < 64 ? it0 + 16 : it0; RS_LOAD(sa, itn); }
;         RS_PROC(sb, it0 + 8);
;     }
	s_waitcnt lgkmcnt(3)
	v_cndmask_b32_e64 v141, 0, v141, s[6:7]
	v_pk_mul_f32 v[180:181], v[26:27], v[114:115] op_sel:[0,1]
	v_pk_mul_f32 v[192:193], v[28:29], v[114:115] op_sel:[0,1]
	v_mfma_f32_16x16x4_f32 v[110:113], v141, v54, v[110:113]
	v_pk_fma_f32 v[180:181], v[30:31], v[114:115], v[180:181] op_sel_hi:[1,0,1]
	v_pk_fma_f32 v[192:193], v[32:33], v[114:115], v[192:193] op_sel_hi:[1,0,1]
	v_pk_fma_f32 v[180:181], v[22:23], v[116:117], v[180:181] op_sel_hi:[1,0,1]
	v_pk_fma_f32 v[192:193], v[24:25], v[116:117], v[192:193] op_sel_hi:[1,0,1]
	v_mfma_f32_16x16x4_f32 v[106:109], v141, v55, v[106:109]
	v_pk_fma_f32 v[180:181], v[18:19], v[116:117], v[180:181] op_sel:[0,1,0]
	v_pk_fma_f32 v[192:193], v[20:21], v[116:117], v[192:193] op_sel:[0,1,0]
	v_pk_fma_f32 v[180:181], v[14:15], v[176:177], v[180:181] op_sel_hi:[1,0,1]
	v_pk_fma_f32 v[192:193], v[16:17], v[176:177], v[192:193] op_sel_hi:[1,0,1]
	v_mfma_f32_16x16x4_f32 v[102:105], v141, v56, v[102:105]
	v_pk_fma_f32 v[180:181], v[10:11], v[176:177], v[180:181] op_sel:[0,1,0]
	v_pk_fma_f32 v[192:193], v[12:13], v[176:177], v[192:193] op_sel:[0,1,0]
	v_pk_fma_f32 v[180:181], v[6:7], v[178:179], v[180:181] op_sel_hi:[1,0,1]
	v_pk_fma_f32 v[192:193], v[8:9], v[178:179], v[192:193] op_sel_hi:[1,0,1]
	v_mfma_f32_16x16x4_f32 v[98:101], v141, v57, v[98:101]
	v_pk_fma_f32 v[180:181], v[2:3], v[178:179], v[180:181] op_sel:[0,1,0]
	v_pk_fma_f32 v[192:193], v[4:5], v[178:179], v[192:193] op_sel:[0,1,0]
	v_pk_mul_f32 v[180:181], v[146:147], v[180:181]
	v_pk_mul_f32 v[192:193], v[146:147], v[192:193]
	v_pk_fma_f32 v[236:237], v[144:145], v[54:55], v[180:181]
	v_pk_fma_f32 v[238:239], v[144:145], v[56:57], v[192:193]
	global_store_dwordx4 v[150:151], v[236:239], off nt
	v_lshl_add_u64 v[150:151], v[150:151], 0, s[58:59]
	global_load_dwordx4 v[54:57], v[148:149], off nt
	v_lshl_add_u64 v[148:149], v[148:149], 0, s[58:59]
	ds_read_b32 v141, v160 offset:448
	ds_read_b128 v[114:117], v161 offset:3584
	ds_read_b128 v[176:179], v161 offset:3600
	s_waitcnt vmcnt(14)
	s_waitcnt lgkmcnt(3)
	v_cndmask_b32_e64 v143, 0, v143, s[6:7]
	v_pk_mul_f32 v[180:181], v[26:27], v[172:173] op_sel:[0,1]
	v_pk_mul_f32 v[192:193], v[28:29], v[172:173] op_sel:[0,1]
	v_mfma_f32_16x16x4_f32 v[110:113], v143, v50, v[110:113]
	v_pk_fma_f32 v[180:181], v[30:31], v[172:173], v[180:181] op_sel_hi:[1,0,1]
	v_pk_fma_f32 v[192:193], v[32:33], v[172:173], v[192:193] op_sel_hi:[1,0,1]
	v_pk_fma_f32 v[180:181], v[22:23], v[174:175], v[180:181] op_sel_hi:[1,0,1]
	v_pk_fma_f32 v[192:193], v[24:25], v[174:175], v[192:193] op_sel_hi:[1,0,1]
	v_mfma_f32_16x16x4_f32 v[106:109], v143, v51, v[106:109]
	v_pk_fma_f32 v[180:181], v[18:19], v[174:175], v[180:181] op_sel:[0,1,0]
	v_pk_fma_f32 v[192:193], v[20:21], v[174:175], v[192:193] op_sel:[0,1,0]
	v_pk_fma_f32 v[180:181], v[14:15], v[232:233], v[180:181] op_sel_hi:[1,0,1]
	v_pk_fma_f32 v[192:193], v[16:17], v[232:233], v[192:193] op_sel_hi:[1,0,1]
	v_mfma_f32_16x16x4_f32 v[102:105], v143, v52, v[102:105]
	v_pk_fma_f32 v[180:181], v[10:11], v[232:233], v[180:181] op_sel:[0,1,0]
	v_pk_fma_f32 v[192:193], v[12:13], v[232:233], v[192:193] op_sel:[0,1,0]
	v_pk_fma_f32 v[180:181], v[6:7], v[234:235], v[180:181] op_sel_hi:[1,0,1]
	v_pk_fma_f32 v[192:193], v[8:9], v[234:235], v[192:193] op_sel_hi:[1,0,1]
	v_mfma_f32_16x16x4_f32 v[98:101], v143, v53, v[98:101]
	v_pk_fma_f32 v[180:181], v[2:3], v[234:235], v[180:181] op_sel:[0,1,0]
	v_pk_fma_f32 v[192:193], v[4:5], v[234:235], v[192:193] op_sel:[0,1,0]
	v_pk_mul_f32 v[180:181], v[146:147], v[180:181]
	v_pk_mul_f32 v[192:193], v[146:147], v[192:193]
	v_pk_fma_f32 v[236:237], v[144:145], v[50:51], v[180:181]
	v_pk_fma_f32 v[238:239], v[144:145], v[52:53], v[192:193]
	global_store_dwordx4 v[150:151], v[236:239], off nt
	v_lshl_add_u64 v[150:151], v[150:151], 0, s[58:59]
	global_load_dwordx4 v[50:53], v[148:149], off nt
	v_lshl_add_u64 v[148:149], v[148:149], 0, s[58:59]
	ds_read_b32 v143, v160 offset:464
	ds_read_b128 v[172:175], v161 offset:3712
	ds_read_b128 v[232:235], v161 offset:3728
	s_waitcnt vmcnt(14)
	s_waitcnt lgkmcnt(3)
	v_cndmask_b32_e64 v141, 0, v141, s[6:7]
	v_pk_mul_f32 v[180:181], v[26:27], v[114:115] op_sel:[0,1]
	v_pk_mul_f32 v[192:193], v[28:29], v[114:115] op_sel:[0,1]
	v_mfma_f32_16x16x4_f32 v[110:113], v141, v46, v[110:113]
	v_pk_fma_f32 v[180:181], v[30:31], v[114:115], v[180:181] op_sel_hi:[1,0,1]
	v_pk_fma_f32 v[192:193], v[32:33], v[114:115], v[192:193] op_sel_hi:[1,0,1]
	v_pk_fma_f32 v[180:181], v[22:23], v[116:117], v[180:181] op_sel_hi:[1,0,1]
	v_pk_fma_f32 v[192:193], v[24:25], v[116:117], v[192:193] op_sel_hi:[1,0,1]
	v_mfma_f32_16x16x4_f32 v[106:109], v141, v47, v[106:109]
	v_pk_fma_f32 v[180:181], v[18:19], v[116:117], v[180:181] op_sel:[0,1,0]
	v_pk_fma_f32 v[192:193], v[20:21], v[116:117], v[192:193] op_sel:[0,1,0]
	v_pk_fma_f32 v[180:181], v[14:15], v[176:177], v[180:181] op_sel_hi:[1,0,1]
	v_pk_fma_f32 v[192:193], v[16:17], v[176:177], v[192:193] op_sel_hi:[1,0,1]
	v_mfma_f32_16x16x4_f32 v[102:105], v141, v48, v[102:105]
	v_pk_fma_f32 v[180:181], v[10:11], v[176:177], v[180:181] op_sel:[0,1,0]
	v_pk_fma_f32 v[192:193], v[12:13], v[176:177], v[192:193] op_sel:[0,1,0]
	v_pk_fma_f32 v[180:181], v[6:7], v[178:179], v[180:181] op_sel_hi:[1,0,1]
	v_pk_fma_f32 v[192:193], v[8:9], v[178:179], v[192:193] op_sel_hi:[1,0,1]
	v_mfma_f32_16x16x4_f32 v[98:101], v141, v49, v[98:101]
	v_pk_fma_f32 v[180:181], v[2:3], v[178:179], v[180:181] op_sel:[0,1,0]
	v_pk_fma_f32 v[192:193], v[4:5], v[178:179], v[192:193] op_sel:[0,1,0]
	v_pk_mul_f32 v[180:181], v[146:147], v[180:181]
	v_pk_mul_f32 v[192:193], v[146:147], v[192:193]
	v_pk_fma_f32 v[236:237], v[144:145], v[46:47], v[180:181]
	v_pk_fma_f32 v[238:239], v[144:145], v[48:49], v[192:193]
	global_store_dwordx4 v[150:151], v[236:239], off nt
	v_lshl_add_u64 v[150:151], v[150:151], 0, s[58:59]
	global_load_dwordx4 v[46:49], v[148:149], off nt
	v_lshl_add_u64 v[148:149], v[148:149], 0, s[58:59]
	ds_read_b32 v141, v160 offset:480
	ds_read_b128 v[114:117], v161 offset:3840
	ds_read_b128 v[176:179], v161 offset:3856
	s_waitcnt vmcnt(14)
; #define RS_LOAD(dst, it0) do { _Pragma("unroll") for (int u = 0; u < 8; ++u) dst[u] = __builtin_nontemporal_load((const f32x4*)(S0 + (size_t)(4 * ((it0) + u)) * DV)); } while (0)
; __device__ __forceinline__ void ret_sample_item(Frame& F, int item) {
;     ...
;     for (int it0 = 0; it0 < 64; it0 += 16) {
;         RS_LOAD(sb, it0 + 8);
;         RS_PROC(sa, it0);
;         { const int itn = it0 + 16 < 64 ? it0 + 16 : it0; RS_LOAD(sa, itn); }
;         RS_PROC(sb, it0 + 8);
;     }
	s_waitcnt lgkmcnt(3)
	v_cndmask_b32_e64 v143, 0, v143, s[6:7]
	v_pk_mul_f32 v[180:181], v[26:27], v[172:173] op_sel:[0,1]
	v_pk_mul_f32 v[192:193], v[28:29], v[172:173] op_sel:[0,1]
	v_mfma_f32_16x16x4_f32 v[110:113], v143, v42, v[110:113]
	v_pk_fma_f32 v[180:181], v[30:31], v[172:173], v[180:181] op_sel_hi:[1,0,1]
	v_pk_fma_f32 v[192:193], v[32:33], v[172:173], v[192:193] op_sel_hi:[1,0,1]
	v_pk_fma_f32 v[180:181], v[22:23], v[174:175], v[180:181] op_sel_hi:[1,0,1]
	v_pk_fma_f32 v[192:193], v[24:25], v[174:175], v[192:193] op_sel_hi:[1,0,1]
	v_mfma_f32_16x16x4_f32 v[106:109], v143, v43, v[106:109]
	v_pk_fma_f32 v[180:181], v[18:19], v[174:175], v[180:181] op_sel:[0,1,0]
	v_pk_fma_f32 v[192:193], v[20:21], v[174:175], v[192:193] op_sel:[0,1,0]
	v_pk_fma_f32 v[180:181], v[14:15], v[232:233], v[180:181] op_sel_hi:[1,0,1]
	v_pk_fma_f32 v[192:193], v[16:17], v[232:233], v[192:193] op_sel_hi:[1,0,1]
	v_mfma_f32_16x16x4_f32 v[102:105], v143, v44, v[102:105]
	v_pk_fma_f32 v[180:181], v[10:11], v[232:233], v[180:181] op_sel:[0,1,0]
	v_pk_fma_f32 v[192:193], v[12:13], v[232:233], v[192:193] op_sel:[0,1,0]
	v_pk_fma_f32 v[180:181], v[6:7], v[234:235], v[180:181] op_sel_hi:[1,0,1]
	v_pk_fma_f32 v[192:193], v[8:9], v[234:235], v[192:193] op_sel_hi:[1,0,1]
	v_mfma_f32_16x16x4_f32 v[98:101], v143, v45, v[98:101]
	v_pk_fma_f32 v[180:181], v[2:3], v[234:235], v[180:181] op_sel:[0,1,0]
	v_pk_fma_f32 v[192:193], v[4:5], v[234:235], v[192:193] op_sel:[0,1,0]
	v_pk_mul_f32 v[180:181], v[146:147], v[180:181]
	v_pk_mul_f32 v[192:193], v[146:147], v[192:193]
	v_pk_fma_f32 v[236:237], v[144:145], v[42:43], v[180:181]
	v_pk_fma_f32 v[238:239], v[144:145], v[44:45], v[192:193]
	global_store_dwordx4 v[150:151], v[236:239], off nt
	v_lshl_add_u64 v[150:151], v[150:151], 0, s[58:59]
	global_load_dwordx4 v[42:45], v[148:149], off nt
	v_lshl_add_u64 v[148:149], v[148:149], 0, s[58:59]
	ds_read_b32 v143, v160 offset:496
	ds_read_b128 v[172:175], v161 offset:3968
	ds_read_b128 v[232:235], v161 offset:3984
	s_waitcnt vmcnt(14)
	s_waitcnt lgkmcnt(3)
	v_cndmask_b32_e64 v141, 0, v141, s[6:7]
	v_pk_mul_f32 v[180:181], v[26:27], v[114:115] op_sel:[0,1]
	v_pk_mul_f32 v[192:193], v[28:29], v[114:115] op_sel:[0,1]
	v_mfma_f32_16x16x4_f32 v[110:113], v141, v38, v[110:113]
	v_pk_fma_f32 v[180:181], v[30:31], v[114:115], v[180:181] op_sel_hi:[1,0,1]
	v_pk_fma_f32 v[192:193], v[32:33], v[114:115], v[192:193] op_sel_hi:[1,0,1]
	v_pk_fma_f32 v[180:181], v[22:23], v[116:117], v[180:181] op_sel_hi:[1,0,1]
	v_pk_fma_f32 v[192:193], v[24:25], v[116:117], v[192:193] op_sel_hi:[1,0,1]
	v_mfma_f32_16x16x4_f32 v[106:109], v141, v39, v[106:109]
	v_pk_fma_f32 v[180:181], v[18:19], v[116:117], v[180:181] op_sel:[0,1,0]
	v_pk_fma_f32 v[192:193], v[20:21], v[116:117], v[192:193] op_sel:[0,1,0]
	v_pk_fma_f32 v[180:181], v[14:15], v[176:177], v[180:181] op_sel_hi:[1,0,1]
	v_pk_fma_f32 v[192:193], v[16:17], v[176:177], v[192:193] op_sel_hi:[1,0,1]
	v_mfma_f32_16x16x4_f32 v[102:105], v141, v40, v[102:105]
	v_pk_fma_f32 v[180:181], v[10:11], v[176:177], v[180:181] op_sel:[0,1,0]
	v_pk_fma_f32 v[192:193], v[12:13], v[176:177], v[192:193] op_sel:[0,1,0]
	v_pk_fma_f32 v[180:181], v[6:7], v[178:179], v[180:181] op_sel_hi:[1,0,1]
	v_pk_fma_f32 v[192:193], v[8:9], v[178:179], v[192:193] op_sel_hi:[1,0,1]
	v_mfma_f32_16x16x4_f32 v[98:101], v141, v41, v[98:101]
	v_pk_fma_f32 v[180:181], v[2:3], v[178:179], v[180:181] op_sel:[0,1,0]
	v_pk_fma_f32 v[192:193], v[4:5], v[178:179], v[192:193] op_sel:[0,1,0]
	v_pk_mul_f32 v[180:181], v[146:147], v[180:181]
	v_pk_mul_f32 v[192:193], v[146:147], v[192:193]
	v_pk_fma_f32 v[236:237], v[144:145], v[38:39], v[180:181]
	v_pk_fma_f32 v[238:239], v[144:145], v[40:41], v[192:193]
	global_store_dwordx4 v[150:151], v[236:239], off nt
	v_lshl_add_u64 v[150:151], v[150:151], 0, s[58:59]
	global_load_dwordx4 v[38:41], v[148:149], off nt
	v_lshl_add_u64 v[148:149], v[148:149], 0, s[58:59]
	ds_read_b32 v141, v160 offset:512
	ds_read_b128 v[114:117], v161 offset:4096
	ds_read_b128 v[176:179], v161 offset:4112
	s_waitcnt vmcnt(14)
	s_waitcnt lgkmcnt(3)
	v_cndmask_b32_e64 v143, 0, v143, s[6:7]
	v_pk_mul_f32 v[180:181], v[26:27], v[172:173] op_sel:[0,1]
	v_pk_mul_f32 v[192:193], v[28:29], v[172:173] op_sel:[0,1]
	v_mfma_f32_16x16x4_f32 v[110:113], v143, v34, v[110:113]
	v_pk_fma_f32 v[180:181], v[30:31], v[172:173], v[180:181] op_sel_hi:[1,0,1]
	v_pk_fma_f32 v[192:193], v[32:33], v[172:173], v[192:193] op_sel_hi:[1,0,1]
	v_pk_fma_f32 v[180:181], v[22:23], v[174:175], v[180:181] op_sel_hi:[1,0,1]
	v_pk_fma_f32 v[192:193], v[24:25], v[174:175], v[192:193] op_sel_hi:[1,0,1]
	v_mfma_f32_16x16x4_f32 v[106:109], v143, v35, v[106:109]
	v_pk_fma_f32 v[180:181], v[18:19], v[174:175], v[180:181] op_sel:[0,1,0]
	v_pk_fma_f32 v[192:193], v[20:21], v[174:175], v[192:193] op_sel:[0,1,0]
	v_pk_fma_f32 v[180:181], v[14:15], v[232:233], v[180:181] op_sel_hi:[1,0,1]
	v_pk_fma_f32 v[192:193], v[16:17], v[232:233], v[192:193] op_sel_hi:[1,0,1]
	v_mfma_f32_16x16x4_f32 v[102:105], v143, v36, v[102:105]
	v_pk_fma_f32 v[180:181], v[10:11], v[232:233], v[180:181] op_sel:[0,1,0]
	v_pk_fma_f32 v[192:193], v[12:13], v[232:233], v[192:193] op_sel:[0,1,0]
	v_pk_fma_f32 v[180:181], v[6:7], v[234:235], v[180:181] op_sel_hi:[1,0,1]
	v_pk_fma_f32 v[192:193], v[8:9], v[234:235], v[192:193] op_sel_hi:[1,0,1]
	v_mfma_f32_16x16x4_f32 v[98:101], v143, v37, v[98:101]
	v_pk_fma_f32 v[180:181], v[2:3], v[234:235], v[180:181] op_sel:[0,1,0]
	v_pk_fma_f32 v[192:193], v[4:5], v[234:235], v[192:193] op_sel:[0,1,0]
	v_pk_mul_f32 v[180:181], v[146:147], v[180:181]
	v_pk_mul_f32 v[192:193], v[146:147], v[192:193]
	v_pk_fma_f32 v[236:237], v[144:145], v[34:35], v[180:181]
	v_pk_fma_f32 v[238:239], v[144:145], v[36:37], v[192:193]
	global_store_dwordx4 v[150:151], v[236:239], off nt
	v_lshl_add_u64 v[150:151], v[150:151], 0, s[58:59]
	global_load_dwordx4 v[34:37], v[148:149], off nt
	v_lshl_add_u64 v[148:149], v[148:149], 0, s[58:59]
	ds_read_b32 v143, v160 offset:528
	ds_read_b128 v[172:175], v161 offset:4224
	ds_read_b128 v[232:235], v161 offset:4240
	s_waitcnt vmcnt(14)
; #define RS_LOAD(dst, it0) do { _Pragma("unroll") for (int u = 0; u < 8; ++u) dst[u] = __builtin_nontemporal_load((const f32x4*)(S0 + (size_t)(4 * ((it0) + u)) * DV)); } while (0)
; __device__ __forceinline__ void ret_sample_item(Frame& F, int item) {
;     ...
;     for (int it0 = 0; it0 < 64; it0 += 16) {
;         RS_LOAD(sb, it0 + 8);
;         RS_PROC(sa, it0);
;         { const int itn = it0 + 16 < 64 ? it0 + 16 : it0; RS_LOAD(sa, itn); }
;         RS_PROC(sb, it0 + 8);
;     }
	s_waitcnt lgkmcnt(3)
	v_cndmask_b32_e64 v141, 0, v141, s[6:7]
	v_pk_mul_f32 v[180:181], v[26:27], v[114:115] op_sel:[0,1]
	v_pk_mul_f32 v[192:193], v[28:29], v[114:115] op_sel:[0,1]
	v_mfma_f32_16x16x4_f32 v[110:113], v141, v70, v[110:113]
	v_pk_fma_f32 v[180:181], v[30:31], v[114:115], v[180:181] op_sel_hi:[1,0,1]
	v_pk_fma_f32 v[192:193], v[32:33], v[114:115], v[192:193] op_sel_hi:[1,0,1]
	v_pk_fma_f32 v[180:181], v[22:23], v[116:117], v[180:181] op_sel_hi:[1,0,1]
	v_pk_fma_f32 v[192:193], v[24:25], v[116:117], v[192:193] op_sel_hi:[1,0,1]
	v_mfma_f32_16x16x4_f32 v[106:109], v141, v71, v[106:109]
	v_pk_fma_f32 v[180:181], v[18:19], v[116:117], v[180:181] op_sel:[0,1,0]
	v_pk_fma_f32 v[192:193], v[20:21], v[116:117], v[192:193] op_sel:[0,1,0]
	v_pk_fma_f32 v[180:181], v[14:15], v[176:177], v[180:181] op_sel_hi:[1,0,1]
	v_pk_fma_f32 v[192:193], v[16:17], v[176:177], v[192:193] op_sel_hi:[1,0,1]
	v_mfma_f32_16x16x4_f32 v[102:105], v141, v72, v[102:105]
	v_pk_fma_f32 v[180:181], v[10:11], v[176:177], v[180:181] op_sel:[0,1,0]
	v_pk_fma_f32 v[192:193], v[12:13], v[176:177], v[192:193] op_sel:[0,1,0]
	v_pk_fma_f32 v[180:181], v[6:7], v[178:179], v[180:181] op_sel_hi:[1,0,1]
	v_pk_fma_f32 v[192:193], v[8:9], v[178:179], v[192:193] op_sel_hi:[1,0,1]
	v_mfma_f32_16x16x4_f32 v[98:101], v141, v73, v[98:101]
	v_pk_fma_f32 v[180:181], v[2:3], v[178:179], v[180:181] op_sel:[0,1,0]
	v_pk_fma_f32 v[192:193], v[4:5], v[178:179], v[192:193] op_sel:[0,1,0]
	v_pk_mul_f32 v[180:181], v[146:147], v[180:181]
	v_pk_mul_f32 v[192:193], v[146:147], v[192:193]
	v_pk_fma_f32 v[236:237], v[144:145], v[70:71], v[180:181]
	v_pk_fma_f32 v[238:239], v[144:145], v[72:73], v[192:193]
	global_store_dwordx4 v[150:151], v[236:239], off nt
	v_lshl_add_u64 v[150:151], v[150:151], 0, s[58:59]
	global_load_dwordx4 v[70:73], v[148:149], off nt
	v_lshl_add_u64 v[148:149], v[148:149], 0, s[58:59]
	ds_read_b32 v141, v160 offset:544
	ds_read_b128 v[114:117], v161 offset:4352
	ds_read_b128 v[176:179], v161 offset:4368
	s_waitcnt vmcnt(14)
	s_waitcnt lgkmcnt(3)
	v_cndmask_b32_e64 v143, 0, v143, s[6:7]
	v_pk_mul_f32 v[180:181], v[26:27], v[172:173] op_sel:[0,1]
	v_pk_mul_f32 v[192:193], v[28:29], v[172:173] op_sel:[0,1]
	v_mfma_f32_16x16x4_f32 v[110:113], v143, v62, v[110:113]
	v_pk_fma_f32 v[180:181], v[30:31], v[172:173], v[180:181] op_sel_hi:[1,0,1]
	v_pk_fma_f32 v[192:193], v[32:33], v[172:173], v[192:193] op_sel_hi:[1,0,1]
	v_pk_fma_f32 v[180:181], v[22:23], v[174:175], v[180:181] op_sel_hi:[1,0,1]
	v_pk_fma_f32 v[192:193], v[24:25], v[174:175], v[192:193] op_sel_hi:[1,0,1]
	v_mfma_f32_16x16x4_f32 v[106:109], v143, v63, v[106:109]
	v_pk_fma_f32 v[180:181], v[18:19], v[174:175], v[180:181] op_sel:[0,1,0]
	v_pk_fma_f32 v[192:193], v[20:21], v[174:175], v[192:193] op_sel:[0,1,0]
	v_pk_fma_f32 v[180:181], v[14:15], v[232:233], v[180:181] op_sel_hi:[1,0,1]
	v_pk_fma_f32 v[192:193], v[16:17], v[232:233], v[192:193] op_sel_hi:[1,0,1]
	v_mfma_f32_16x16x4_f32 v[102:105], v143, v64, v[102:105]
	v_pk_fma_f32 v[180:181], v[10:11], v[232:233], v[180:181] op_sel:[0,1,0]
	v_pk_fma_f32 v[192:193], v[12:13], v[232:233], v[192:193] op_sel:[0,1,0]
	v_pk_fma_f32 v[180:181], v[6:7], v[234:235], v[180:181] op_sel_hi:[1,0,1]
	v_pk_fma_f32 v[192:193], v[8:9], v[234:235], v[192:193] op_sel_hi:[1,0,1]
	v_mfma_f32_16x16x4_f32 v[98:101], v143, v65, v[98:101]
	v_pk_fma_f32 v[180:181], v[2:3], v[234:235], v[180:181] op_sel:[0,1,0]
	v_pk_fma_f32 v[192:193], v[4:5], v[234:235], v[192:193] op_sel:[0,1,0]
	v_pk_mul_f32 v[180:181], v[146:147], v[180:181]
	v_pk_mul_f32 v[192:193], v[146:147], v[192:193]
	v_pk_fma_f32 v[236:237], v[144:145], v[62:63], v[180:181]
	v_pk_fma_f32 v[238:239], v[144:145], v[64:65], v[192:193]
	global_store_dwordx4 v[150:151], v[236:239], off nt
	v_lshl_add_u64 v[150:151], v[150:151], 0, s[58:59]
	global_load_dwordx4 v[62:65], v[148:149], off nt
	v_lshl_add_u64 v[148:149], v[148:149], 0, s[58:59]
	ds_read_b32 v143, v160 offset:560
	ds_read_b128 v[172:175], v161 offset:4480
	ds_read_b128 v[232:235], v161 offset:4496
	s_waitcnt vmcnt(14)
	s_waitcnt lgkmcnt(3)
	v_cndmask_b32_e64 v141, 0, v141, s[6:7]
	v_pk_mul_f32 v[180:181], v[26:27], v[114:115] op_sel:[0,1]
	v_pk_mul_f32 v[192:193], v[28:29], v[114:115] op_sel:[0,1]
	v_mfma_f32_16x16x4_f32 v[110:113], v141, v54, v[110:113]
	v_pk_fma_f32 v[180:181], v[30:31], v[114:115], v[180:181] op_sel_hi:[1,0,1]
	v_pk_fma_f32 v[192:193], v[32:33], v[114:115], v[192:193] op_sel_hi:[1,0,1]
	v_pk_fma_f32 v[180:181], v[22:23], v[116:117], v[180:181] op_sel_hi:[1,0,1]
	v_pk_fma_f32 v[192:193], v[24:25], v[116:117], v[192:193] op_sel_hi:[1,0,1]
	v_mfma_f32_16x16x4_f32 v[106:109], v141, v55, v[106:109]
	v_pk_fma_f32 v[180:181], v[18:19], v[116:117], v[180:181] op_sel:[0,1,0]
	v_pk_fma_f32 v[192:193], v[20:21], v[116:117], v[192:193] op_sel:[0,1,0]
	v_pk_fma_f32 v[180:181], v[14:15], v[176:177], v[180:181] op_sel_hi:[1,0,1]
	v_pk_fma_f32 v[192:193], v[16:17], v[176:177], v[192:193] op_sel_hi:[1,0,1]
	v_mfma_f32_16x16x4_f32 v[102:105], v141, v56, v[102:105]
	v_pk_fma_f32 v[180:181], v[10:11], v[176:177], v[180:181] op_sel:[0,1,0]
	v_pk_fma_f32 v[192:193], v[12:13], v[176:177], v[192:193] op_sel:[0,1,0]
	v_pk_fma_f32 v[180:181], v[6:7], v[178:179], v[180:181] op_sel_hi:[1,0,1]
	v_pk_fma_f32 v[192:193], v[8:9], v[178:179], v[192:193] op_sel_hi:[1,0,1]
	v_mfma_f32_16x16x4_f32 v[98:101], v141, v57, v[98:101]
	v_pk_fma_f32 v[180:181], v[2:3], v[178:179], v[180:181] op_sel:[0,1,0]
	v_pk_fma_f32 v[192:193], v[4:5], v[178:179], v[192:193] op_sel:[0,1,0]
	v_pk_mul_f32 v[180:181], v[146:147], v[180:181]
	v_pk_mul_f32 v[192:193], v[146:147], v[192:193]
	v_pk_fma_f32 v[236:237], v[144:145], v[54:55], v[180:181]
	v_pk_fma_f32 v[238:239], v[144:145], v[56:57], v[192:193]
	global_store_dwordx4 v[150:151], v[236:239], off nt
	v_lshl_add_u64 v[150:151], v[150:151], 0, s[58:59]
	global_load_dwordx4 v[54:57], v[148:149], off nt
	v_lshl_add_u64 v[148:149], v[148:149], 0, s[58:59]
	ds_read_b32 v141, v160 offset:576
	ds_read_b128 v[114:117], v161 offset:4608
	ds_read_b128 v[176:179], v161 offset:4624
	s_waitcnt vmcnt(14)
; #define RS_LOAD(dst, it0) do { _Pragma("unroll") for (int u = 0; u < 8; ++u) dst[u] = __builtin_nontemporal_load((const f32x4*)(S0 + (size_t)(4 * ((it0) + u)) * DV)); } while (0)
; __device__ __forceinline__ void ret_sample_item(Frame& F, int item) {
;     ...
;     for (int it0 = 0; it0 < 64; it0 += 16) {
;         RS_LOAD(sb, it0 + 8);
;         RS_PROC(sa, it0);
;         { const int itn = it0 + 16 < 64 ? it0 + 16 : it0; RS_LOAD(sa, itn); }
;         RS_PROC(sb, it0 + 8);
;     }
	s_waitcnt lgkmcnt(3)
	v_cndmask_b32_e64 v143, 0, v143, s[6:7]
	v_pk_mul_f32 v[180:181], v[26:27], v[172:173] op_sel:[0,1]
	v_pk_mul_f32 v[192:193], v[28:29], v[172:173] op_sel:[0,1]
	v_mfma_f32_16x16x4_f32 v[110:113], v143, v50, v[110:113]
	v_pk_fma_f32 v[180:181], v[30:31], v[172:173], v[180:181] op_sel_hi:[1,0,1]
	v_pk_fma_f32 v[192:193], v[32:33], v[172:173], v[192:193] op_sel_hi:[1,0,1]
	v_pk_fma_f32 v[180:181], v[22:23], v[174:175], v[180:181] op_sel_hi:[1,0,1]
	v_pk_fma_f32 v[192:193], v[24:25], v[174:175], v[192:193] op_sel_hi:[1,0,1]
	v_mfma_f32_16x16x4_f32 v[106:109], v143, v51, v[106:109]
	v_pk_fma_f32 v[180:181], v[18:19], v[174:175], v[180:181] op_sel:[0,1,0]
	v_pk_fma_f32 v[192:193], v[20:21], v[174:175], v[192:193] op_sel:[0,1,0]
	v_pk_fma_f32 v[180:181], v[14:15], v[232:233], v[180:181] op_sel_hi:[1,0,1]
	v_pk_fma_f32 v[192:193], v[16:17], v[232:233], v[192:193] op_sel_hi:[1,0,1]
	v_mfma_f32_16x16x4_f32 v[102:105], v143, v52, v[102:105]
	v_pk_fma_f32 v[180:181], v[10:11], v[232:233], v[180:181] op_sel:[0,1,0]
	v_pk_fma_f32 v[192:193], v[12:13], v[232:233], v[192:193] op_sel:[0,1,0]
	v_pk_fma_f32 v[180:181], v[6:7], v[234:235], v[180:181] op_sel_hi:[1,0,1]
	v_pk_fma_f32 v[192:193], v[8:9], v[234:235], v[192:193] op_sel_hi:[1,0,1]
	v_mfma_f32_16x16x4_f32 v[98:101], v143, v53, v[98:101]
	v_pk_fma_f32 v[180:181], v[2:3], v[234:235], v[180:181] op_sel:[0,1,0]
	v_pk_fma_f32 v[192:193], v[4:5], v[234:235], v[192:193] op_sel:[0,1,0]
	v_pk_mul_f32 v[180:181], v[146:147], v[180:181]
	v_pk_mul_f32 v[192:193], v[146:147], v[192:193]
	v_pk_fma_f32 v[236:237], v[144:145], v[50:51], v[180:181]
	v_pk_fma_f32 v[238:239], v[144:145], v[52:53], v[192:193]
	global_store_dwordx4 v[150:151], v[236:239], off nt
	v_lshl_add_u64 v[150:151], v[150:151], 0, s[58:59]
	global_load_dwordx4 v[50:53], v[148:149], off nt
	v_lshl_add_u64 v[148:149], v[148:149], 0, s[58:59]
	ds_read_b32 v143, v160 offset:592
	ds_read_b128 v[172:175], v161 offset:4736
	ds_read_b128 v[232:235], v161 offset:4752
	s_waitcnt vmcnt(14)
	s_waitcnt lgkmcnt(3)
	v_cndmask_b32_e64 v141, 0, v141, s[6:7]
	v_pk_mul_f32 v[180:181], v[26:27], v[114:115] op_sel:[0,1]
	v_pk_mul_f32 v[192:193], v[28:29], v[114:115] op_sel:[0,1]
	v_mfma_f32_16x16x4_f32 v[110:113], v141, v46, v[110:113]
	v_pk_fma_f32 v[180:181], v[30:31], v[114:115], v[180:181] op_sel_hi:[1,0,1]
	v_pk_fma_f32 v[192:193], v[32:33], v[114:115], v[192:193] op_sel_hi:[1,0,1]
	v_pk_fma_f32 v[180:181], v[22:23], v[116:117], v[180:181] op_sel_hi:[1,0,1]
	v_pk_fma_f32 v[192:193], v[24:25], v[116:117], v[192:193] op_sel_hi:[1,0,1]
	v_mfma_f32_16x16x4_f32 v[106:109], v141, v47, v[106:109]
	v_pk_fma_f32 v[180:181], v[18:19], v[116:117], v[180:181] op_sel:[0,1,0]
	v_pk_fma_f32 v[192:193], v[20:21], v[116:117], v[192:193] op_sel:[0,1,0]
	v_pk_fma_f32 v[180:181], v[14:15], v[176:177], v[180:181] op_sel_hi:[1,0,1]
	v_pk_fma_f32 v[192:193], v[16:17], v[176:177], v[192:193] op_sel_hi:[1,0,1]
	v_mfma_f32_16x16x4_f32 v[102:105], v141, v48, v[102:105]
	v_pk_fma_f32 v[180:181], v[10:11], v[176:177], v[180:181] op_sel:[0,1,0]
	v_pk_fma_f32 v[192:193], v[12:13], v[176:177], v[192:193] op_sel:[0,1,0]
	v_pk_fma_f32 v[180:181], v[6:7], v[178:179], v[180:181] op_sel_hi:[1,0,1]
	v_pk_fma_f32 v[192:193], v[8:9], v[178:179], v[192:193] op_sel_hi:[1,0,1]
	v_mfma_f32_16x16x4_f32 v[98:101], v141, v49, v[98:101]
	v_pk_fma_f32 v[180:181], v[2:3], v[178:179], v[180:181] op_sel:[0,1,0]
	v_pk_fma_f32 v[192:193], v[4:5], v[178:179], v[192:193] op_sel:[0,1,0]
	v_pk_mul_f32 v[180:181], v[146:147], v[180:181]
	v_pk_mul_f32 v[192:193], v[146:147], v[192:193]
	v_pk_fma_f32 v[236:237], v[144:145], v[46:47], v[180:181]
	v_pk_fma_f32 v[238:239], v[144:145], v[48:49], v[192:193]
	global_store_dwordx4 v[150:151], v[236:239], off nt
	v_lshl_add_u64 v[150:151], v[150:151], 0, s[58:59]
	global_load_dwordx4 v[46:49], v[148:149], off nt
	v_lshl_add_u64 v[148:149], v[148:149], 0, s[58:59]
	ds_read_b32 v141, v160 offset:608
	ds_read_b128 v[114:117], v161 offset:4864
	ds_read_b128 v[176:179], v161 offset:4880
	s_waitcnt vmcnt(14)
	s_waitcnt lgkmcnt(3)
	v_cndmask_b32_e64 v143, 0, v143, s[6:7]
	v_pk_mul_f32 v[180:181], v[26:27], v[172:173] op_sel:[0,1]
	v_pk_mul_f32 v[192:193], v[28:29], v[172:173] op_sel:[0,1]
	v_mfma_f32_16x16x4_f32 v[110:113], v143, v42, v[110:113]
	v_pk_fma_f32 v[180:181], v[30:31], v[172:173], v[180:181] op_sel_hi:[1,0,1]
	v_pk_fma_f32 v[192:193], v[32:33], v[172:173], v[192:193] op_sel_hi:[1,0,1]
	v_pk_fma_f32 v[180:181], v[22:23], v[174:175], v[180:181] op_sel_hi:[1,0,1]
	v_pk_fma_f32 v[192:193], v[24:25], v[174:175], v[192:193] op_sel_hi:[1,0,1]
	v_mfma_f32_16x16x4_f32 v[106:109], v143, v43, v[106:109]
	v_pk_fma_f32 v[180:181], v[18:19], v[174:175], v[180:181] op_sel:[0,1,0]
	v_pk_fma_f32 v[192:193], v[20:21], v[174:175], v[192:193] op_sel:[0,1,0]
	v_pk_fma_f32 v[180:181], v[14:15], v[232:233], v[180:181] op_sel_hi:[1,0,1]
	v_pk_fma_f32 v[192:193], v[16:17], v[232:233], v[192:193] op_sel_hi:[1,0,1]
	v_mfma_f32_16x16x4_f32 v[102:105], v143, v44, v[102:105]
	v_pk_fma_f32 v[180:181], v[10:11], v[232:233], v[180:181] op_sel:[0,1,0]
	v_pk_fma_f32 v[192:193], v[12:13], v[232:233], v[192:193] op_sel:[0,1,0]
	v_pk_fma_f32 v[180:181], v[6:7], v[234:235], v[180:181] op_sel_hi:[1,0,1]
	v_pk_fma_f32 v[192:193], v[8:9], v[234:235], v[192:193] op_sel_hi:[1,0,1]
	v_mfma_f32_16x16x4_f32 v[98:101], v143, v45, v[98:101]
	v_pk_fma_f32 v[180:181], v[2:3], v[234:235], v[180:181] op_sel:[0,1,0]
	v_pk_fma_f32 v[192:193], v[4:5], v[234:235], v[192:193] op_sel:[0,1,0]
	v_pk_mul_f32 v[180:181], v[146:147], v[180:181]
	v_pk_mul_f32 v[192:193], v[146:147], v[192:193]
	v_pk_fma_f32 v[236:237], v[144:145], v[42:43], v[180:181]
	v_pk_fma_f32 v[238:239], v[144:145], v[44:45], v[192:193]
	global_store_dwordx4 v[150:151], v[236:239], off nt
	v_lshl_add_u64 v[150:151], v[150:151], 0, s[58:59]
	global_load_dwordx4 v[42:45], v[148:149], off nt
	v_lshl_add_u64 v[148:149], v[148:149], 0, s[58:59]
	ds_read_b32 v143, v160 offset:624
	ds_read_b128 v[172:175], v161 offset:4992
	ds_read_b128 v[232:235], v161 offset:5008
	s_waitcnt vmcnt(14)
; #define RS_LOAD(dst, it0) do { _Pragma("unroll") for (int u = 0; u < 8; ++u) dst[u] = __builtin_nontemporal_load((const f32x4*)(S0 + (size_t)(4 * ((it0) + u)) * DV)); } while (0)
; __device__ __forceinline__ void ret_sample_item(Frame& F, int item) {
;     ...
;     for (int it0 = 0; it0 < 64; it0 += 16) {
;         RS_LOAD(sb, it0 + 8);
;         RS_PROC(sa, it0);
;         { const int itn = it0 + 16 < 64 ? it0 + 16 : it0; RS_LOAD(sa, itn); }
;         RS_PROC(sb, it0 + 8);
;     }
	s_waitcnt lgkmcnt(3)
	v_cndmask_b32_e64 v141, 0, v141, s[6:7]
	v_pk_mul_f32 v[180:181], v[26:27], v[114:115] op_sel:[0,1]
	v_pk_mul_f32 v[192:193], v[28:29], v[114:115] op_sel:[0,1]
	v_mfma_f32_16x16x4_f32 v[110:113], v141, v38, v[110:113]
	v_pk_fma_f32 v[180:181], v[30:31], v[114:115], v[180:181] op_sel_hi:[1,0,1]
	v_pk_fma_f32 v[192:193], v[32:33], v[114:115], v[192:193] op_sel_hi:[1,0,1]
	v_pk_fma_f32 v[180:181], v[22:23], v[116:117], v[180:181] op_sel_hi:[1,0,1]
	v_pk_fma_f32 v[192:193], v[24:25], v[116:117], v[192:193] op_sel_hi:[1,0,1]
	v_mfma_f32_16x16x4_f32 v[106:109], v141, v39, v[106:109]
	v_pk_fma_f32 v[180:181], v[18:19], v[116:117], v[180:181] op_sel:[0,1,0]
	v_pk_fma_f32 v[192:193], v[20:21], v[116:117], v[192:193] op_sel:[0,1,0]
	v_pk_fma_f32 v[180:181], v[14:15], v[176:177], v[180:181] op_sel_hi:[1,0,1]
	v_pk_fma_f32 v[192:193], v[16:17], v[176:177], v[192:193] op_sel_hi:[1,0,1]
	v_mfma_f32_16x16x4_f32 v[102:105], v141, v40, v[102:105]
	v_pk_fma_f32 v[180:181], v[10:11], v[176:177], v[180:181] op_sel:[0,1,0]
	v_pk_fma_f32 v[192:193], v[12:13], v[176:177], v[192:193] op_sel:[0,1,0]
	v_pk_fma_f32 v[180:181], v[6:7], v[178:179], v[180:181] op_sel_hi:[1,0,1]
	v_pk_fma_f32 v[192:193], v[8:9], v[178:179], v[192:193] op_sel_hi:[1,0,1]
	v_mfma_f32_16x16x4_f32 v[98:101], v141, v41, v[98:101]
	v_pk_fma_f32 v[180:181], v[2:3], v[178:179], v[180:181] op_sel:[0,1,0]
	v_pk_fma_f32 v[192:193], v[4:5], v[178:179], v[192:193] op_sel:[0,1,0]
	v_pk_mul_f32 v[180:181], v[146:147], v[180:181]
	v_pk_mul_f32 v[192:193], v[146:147], v[192:193]
	v_pk_fma_f32 v[236:237], v[144:145], v[38:39], v[180:181]
	v_pk_fma_f32 v[238:239], v[144:145], v[40:41], v[192:193]
	global_store_dwordx4 v[150:151], v[236:239], off nt
	v_lshl_add_u64 v[150:151], v[150:151], 0, s[58:59]
	global_load_dwordx4 v[38:41], v[148:149], off nt
	v_lshl_add_u64 v[148:149], v[148:149], 0, s[58:59]
	ds_read_b32 v141, v160 offset:640
	ds_read_b128 v[114:117], v161 offset:5120
	ds_read_b128 v[176:179], v161 offset:5136
	s_waitcnt vmcnt(14)
	s_waitcnt lgkmcnt(3)
	v_cndmask_b32_e64 v143, 0, v143, s[6:7]
	v_pk_mul_f32 v[180:181], v[26:27], v[172:173] op_sel:[0,1]
	v_pk_mul_f32 v[192:193], v[28:29], v[172:173] op_sel:[0,1]
	v_mfma_f32_16x16x4_f32 v[110:113], v143, v34, v[110:113]
	v_pk_fma_f32 v[180:181], v[30:31], v[172:173], v[180:181] op_sel_hi:[1,0,1]
	v_pk_fma_f32 v[192:193], v[32:33], v[172:173], v[192:193] op_sel_hi:[1,0,1]
	v_pk_fma_f32 v[180:181], v[22:23], v[174:175], v[180:181] op_sel_hi:[1,0,1]
	v_pk_fma_f32 v[192:193], v[24:25], v[174:175], v[192:193] op_sel_hi:[1,0,1]
	v_mfma_f32_16x16x4_f32 v[106:109], v143, v35, v[106:109]
	v_pk_fma_f32 v[180:181], v[18:19], v[174:175], v[180:181] op_sel:[0,1,0]
	v_pk_fma_f32 v[192:193], v[20:21], v[174:175], v[192:193] op_sel:[0,1,0]
	v_pk_fma_f32 v[180:181], v[14:15], v[232:233], v[180:181] op_sel_hi:[1,0,1]
	v_pk_fma_f32 v[192:193], v[16:17], v[232:233], v[192:193] op_sel_hi:[1,0,1]
	v_mfma_f32_16x16x4_f32 v[102:105], v143, v36, v[102:105]
	v_pk_fma_f32 v[180:181], v[10:11], v[232:233], v[180:181] op_sel:[0,1,0]
	v_pk_fma_f32 v[192:193], v[12:13], v[232:233], v[192:193] op_sel:[0,1,0]
	v_pk_fma_f32 v[180:181], v[6:7], v[234:235], v[180:181] op_sel_hi:[1,0,1]
	v_pk_fma_f32 v[192:193], v[8:9], v[234:235], v[192:193] op_sel_hi:[1,0,1]
	v_mfma_f32_16x16x4_f32 v[98:101], v143, v37, v[98:101]
	v_pk_fma_f32 v[180:181], v[2:3], v[234:235], v[180:181] op_sel:[0,1,0]
	v_pk_fma_f32 v[192:193], v[4:5], v[234:235], v[192:193] op_sel:[0,1,0]
	v_pk_mul_f32 v[180:181], v[146:147], v[180:181]
	v_pk_mul_f32 v[192:193], v[146:147], v[192:193]
	v_pk_fma_f32 v[236:237], v[144:145], v[34:35], v[180:181]
	v_pk_fma_f32 v[238:239], v[144:145], v[36:37], v[192:193]
	global_store_dwordx4 v[150:151], v[236:239], off nt
	v_lshl_add_u64 v[150:151], v[150:151], 0, s[58:59]
	global_load_dwordx4 v[34:37], v[148:149], off nt
	v_lshl_add_u64 v[148:149], v[148:149], 0, s[58:59]
	ds_read_b32 v143, v160 offset:656
	ds_read_b128 v[172:175], v161 offset:5248
	ds_read_b128 v[232:235], v161 offset:5264
	s_waitcnt vmcnt(14)
	s_waitcnt lgkmcnt(3)
	v_cndmask_b32_e64 v141, 0, v141, s[6:7]
	v_pk_mul_f32 v[180:181], v[26:27], v[114:115] op_sel:[0,1]
	v_pk_mul_f32 v[192:193], v[28:29], v[114:115] op_sel:[0,1]
	v_mfma_f32_16x16x4_f32 v[110:113], v141, v70, v[110:113]
	v_pk_fma_f32 v[180:181], v[30:31], v[114:115], v[180:181] op_sel_hi:[1,0,1]
	v_pk_fma_f32 v[192:193], v[32:33], v[114:115], v[192:193] op_sel_hi:[1,0,1]
	v_pk_fma_f32 v[180:181], v[22:23], v[116:117], v[180:181] op_sel_hi:[1,0,1]
	v_pk_fma_f32 v[192:193], v[24:25], v[116:117], v[192:193] op_sel_hi:[1,0,1]
	v_mfma_f32_16x16x4_f32 v[106:109], v141, v71, v[106:109]
	v_pk_fma_f32 v[180:181], v[18:19], v[116:117], v[180:181] op_sel:[0,1,0]
	v_pk_fma_f32 v[192:193], v[20:21], v[116:117], v[192:193] op_sel:[0,1,0]
	v_pk_fma_f32 v[180:181], v[14:15], v[176:177], v[180:181] op_sel_hi:[1,0,1]
	v_pk_fma_f32 v[192:193], v[16:17], v[176:177], v[192:193] op_sel_hi:[1,0,1]
	v_mfma_f32_16x16x4_f32 v[102:105], v141, v72, v[102:105]
	v_pk_fma_f32 v[180:181], v[10:11], v[176:177], v[180:181] op_sel:[0,1,0]
	v_pk_fma_f32 v[192:193], v[12:13], v[176:177], v[192:193] op_sel:[0,1,0]
	v_pk_fma_f32 v[180:181], v[6:7], v[178:179], v[180:181] op_sel_hi:[1,0,1]
	v_pk_fma_f32 v[192:193], v[8:9], v[178:179], v[192:193] op_sel_hi:[1,0,1]
	v_mfma_f32_16x16x4_f32 v[98:101], v141, v73, v[98:101]
	v_pk_fma_f32 v[180:181], v[2:3], v[178:179], v[180:181] op_sel:[0,1,0]
	v_pk_fma_f32 v[192:193], v[4:5], v[178:179], v[192:193] op_sel:[0,1,0]
	v_pk_mul_f32 v[180:181], v[146:147], v[180:181]
	v_pk_mul_f32 v[192:193], v[146:147], v[192:193]
	v_pk_fma_f32 v[236:237], v[144:145], v[70:71], v[180:181]
	v_pk_fma_f32 v[238:239], v[144:145], v[72:73], v[192:193]
	global_store_dwordx4 v[150:151], v[236:239], off nt
	v_lshl_add_u64 v[150:151], v[150:151], 0, s[58:59]
	global_load_dwordx4 v[70:73], v[148:149], off nt
	v_lshl_add_u64 v[148:149], v[148:149], 0, s[58:59]
	ds_read_b32 v141, v160 offset:672
	ds_read_b128 v[114:117], v161 offset:5376
	ds_read_b128 v[176:179], v161 offset:5392
	s_waitcnt vmcnt(14)
; #define RS_LOAD(dst, it0) do { _Pragma("unroll") for (int u = 0; u < 8; ++u) dst[u] = __builtin_nontemporal_load((const f32x4*)(S0 + (size_t)(4 * ((it0) + u)) * DV)); } while (0)
; __device__ __forceinline__ void ret_sample_item(Frame& F, int item) {
;     ...
;     for (int it0 = 0; it0 < 64; it0 += 16) {
;         RS_LOAD(sb, it0 + 8);
;         RS_PROC(sa, it0);
;         { const int itn = it0 + 16 < 64 ? it0 + 16 : it0; RS_LOAD(sa, itn); }
;         RS_PROC(sb, it0 + 8);
;     }
	s_waitcnt lgkmcnt(3)
	v_cndmask_b32_e64 v143, 0, v143, s[6:7]
	v_pk_mul_f32 v[180:181], v[26:27], v[172:173] op_sel:[0,1]
	v_pk_mul_f32 v[192:193], v[28:29], v[172:173] op_sel:[0,1]
	v_mfma_f32_16x16x4_f32 v[110:113], v143, v62, v[110:113]
	v_pk_fma_f32 v[180:181], v[30:31], v[172:173], v[180:181] op_sel_hi:[1,0,1]
	v_pk_fma_f32 v[192:193], v[32:33], v[172:173], v[192:193] op_sel_hi:[1,0,1]
	v_pk_fma_f32 v[180:181], v[22:23], v[174:175], v[180:181] op_sel_hi:[1,0,1]
	v_pk_fma_f32 v[192:193], v[24:25], v[174:175], v[192:193] op_sel_hi:[1,0,1]
	v_mfma_f32_16x16x4_f32 v[106:109], v143, v63, v[106:109]
	v_pk_fma_f32 v[180:181], v[18:19], v[174:175], v[180:181] op_sel:[0,1,0]
	v_pk_fma_f32 v[192:193], v[20:21], v[174:175], v[192:193] op_sel:[0,1,0]
	v_pk_fma_f32 v[180:181], v[14:15], v[232:233], v[180:181] op_sel_hi:[1,0,1]
	v_pk_fma_f32 v[192:193], v[16:17], v[232:233], v[192:193] op_sel_hi:[1,0,1]
	v_mfma_f32_16x16x4_f32 v[102:105], v143, v64, v[102:105]
	v_pk_fma_f32 v[180:181], v[10:11], v[232:233], v[180:181] op_sel:[0,1,0]
	v_pk_fma_f32 v[192:193], v[12:13], v[232:233], v[192:193] op_sel:[0,1,0]
	v_pk_fma_f32 v[180:181], v[6:7], v[234:235], v[180:181] op_sel_hi:[1,0,1]
	v_pk_fma_f32 v[192:193], v[8:9], v[234:235], v[192:193] op_sel_hi:[1,0,1]
	v_mfma_f32_16x16x4_f32 v[98:101], v143, v65, v[98:101]
	v_pk_fma_f32 v[180:181], v[2:3], v[234:235], v[180:181] op_sel:[0,1,0]
	v_pk_fma_f32 v[192:193], v[4:5], v[234:235], v[192:193] op_sel:[0,1,0]
	v_pk_mul_f32 v[180:181], v[146:147], v[180:181]
	v_pk_mul_f32 v[192:193], v[146:147], v[192:193]
	v_pk_fma_f32 v[236:237], v[144:145], v[62:63], v[180:181]
	v_pk_fma_f32 v[238:239], v[144:145], v[64:65], v[192:193]
	global_store_dwordx4 v[150:151], v[236:239], off nt
	v_lshl_add_u64 v[150:151], v[150:151], 0, s[58:59]
	global_load_dwordx4 v[62:65], v[148:149], off nt
	v_lshl_add_u64 v[148:149], v[148:149], 0, s[58:59]
	ds_read_b32 v143, v160 offset:688
	ds_read_b128 v[172:175], v161 offset:5504
	ds_read_b128 v[232:235], v161 offset:5520
	s_waitcnt vmcnt(14)
	s_waitcnt lgkmcnt(3)
	v_cndmask_b32_e64 v141, 0, v141, s[6:7]
	v_pk_mul_f32 v[180:181], v[26:27], v[114:115] op_sel:[0,1]
	v_pk_mul_f32 v[192:193], v[28:29], v[114:115] op_sel:[0,1]
	v_mfma_f32_16x16x4_f32 v[110:113], v141, v54, v[110:113]
	v_pk_fma_f32 v[180:181], v[30:31], v[114:115], v[180:181] op_sel_hi:[1,0,1]
	v_pk_fma_f32 v[192:193], v[32:33], v[114:115], v[192:193] op_sel_hi:[1,0,1]
	v_pk_fma_f32 v[180:181], v[22:23], v[116:117], v[180:181] op_sel_hi:[1,0,1]
	v_pk_fma_f32 v[192:193], v[24:25], v[116:117], v[192:193] op_sel_hi:[1,0,1]
	v_mfma_f32_16x16x4_f32 v[106:109], v141, v55, v[106:109]
	v_pk_fma_f32 v[180:181], v[18:19], v[116:117], v[180:181] op_sel:[0,1,0]
	v_pk_fma_f32 v[192:193], v[20:21], v[116:117], v[192:193] op_sel:[0,1,0]
	v_pk_fma_f32 v[180:181], v[14:15], v[176:177], v[180:181] op_sel_hi:[1,0,1]
	v_pk_fma_f32 v[192:193], v[16:17], v[176:177], v[192:193] op_sel_hi:[1,0,1]
	v_mfma_f32_16x16x4_f32 v[102:105], v141, v56, v[102:105]
	v_pk_fma_f32 v[180:181], v[10:11], v[176:177], v[180:181] op_sel:[0,1,0]
	v_pk_fma_f32 v[192:193], v[12:13], v[176:177], v[192:193] op_sel:[0,1,0]
	v_pk_fma_f32 v[180:181], v[6:7], v[178:179], v[180:181] op_sel_hi:[1,0,1]
	v_pk_fma_f32 v[192:193], v[8:9], v[178:179], v[192:193] op_sel_hi:[1,0,1]
	v_mfma_f32_16x16x4_f32 v[98:101], v141, v57, v[98:101]
	v_pk_fma_f32 v[180:181], v[2:3], v[178:179], v[180:181] op_sel:[0,1,0]
	v_pk_fma_f32 v[192:193], v[4:5], v[178:179], v[192:193] op_sel:[0,1,0]
	v_pk_mul_f32 v[180:181], v[146:147], v[180:181]
	v_pk_mul_f32 v[192:193], v[146:147], v[192:193]
	v_pk_fma_f32 v[236:237], v[144:145], v[54:55], v[180:181]
	v_pk_fma_f32 v[238:239], v[144:145], v[56:57], v[192:193]
	global_store_dwordx4 v[150:151], v[236:239], off nt
	v_lshl_add_u64 v[150:151], v[150:151], 0, s[58:59]
	global_load_dwordx4 v[54:57], v[148:149], off nt
	v_lshl_add_u64 v[148:149], v[148:149], 0, s[58:59]
	ds_read_b32 v141, v160 offset:704
	ds_read_b128 v[114:117], v161 offset:5632
	ds_read_b128 v[176:179], v161 offset:5648
	s_waitcnt vmcnt(14)
	s_waitcnt lgkmcnt(3)
	v_cndmask_b32_e64 v143, 0, v143, s[6:7]
	v_pk_mul_f32 v[180:181], v[26:27], v[172:173] op_sel:[0,1]
	v_pk_mul_f32 v[192:193], v[28:29], v[172:173] op_sel:[0,1]
	v_mfma_f32_16x16x4_f32 v[110:113], v143, v50, v[110:113]
	v_pk_fma_f32 v[180:181], v[30:31], v[172:173], v[180:181] op_sel_hi:[1,0,1]
	v_pk_fma_f32 v[192:193], v[32:33], v[172:173], v[192:193] op_sel_hi:[1,0,1]
	v_pk_fma_f32 v[180:181], v[22:23], v[174:175], v[180:181] op_sel_hi:[1,0,1]
	v_pk_fma_f32 v[192:193], v[24:25], v[174:175], v[192:193] op_sel_hi:[1,0,1]
	v_mfma_f32_16x16x4_f32 v[106:109], v143, v51, v[106:109]
	v_pk_fma_f32 v[180:181], v[18:19], v[174:175], v[180:181] op_sel:[0,1,0]
	v_pk_fma_f32 v[192:193], v[20:21], v[174:175], v[192:193] op_sel:[0,1,0]
	v_pk_fma_f32 v[180:181], v[14:15], v[232:233], v[180:181] op_sel_hi:[1,0,1]
	v_pk_fma_f32 v[192:193], v[16:17], v[232:233], v[192:193] op_sel_hi:[1,0,1]
	v_mfma_f32_16x16x4_f32 v[102:105], v143, v52, v[102:105]
	v_pk_fma_f32 v[180:181], v[10:11], v[232:233], v[180:181] op_sel:[0,1,0]
	v_pk_fma_f32 v[192:193], v[12:13], v[232:233], v[192:193] op_sel:[0,1,0]
	v_pk_fma_f32 v[180:181], v[6:7], v[234:235], v[180:181] op_sel_hi:[1,0,1]
	v_pk_fma_f32 v[192:193], v[8:9], v[234:235], v[192:193] op_sel_hi:[1,0,1]
	v_mfma_f32_16x16x4_f32 v[98:101], v143, v53, v[98:101]
	v_pk_fma_f32 v[180:181], v[2:3], v[234:235], v[180:181] op_sel:[0,1,0]
	v_pk_fma_f32 v[192:193], v[4:5], v[234:235], v[192:193] op_sel:[0,1,0]
	v_pk_mul_f32 v[180:181], v[146:147], v[180:181]
	v_pk_mul_f32 v[192:193], v[146:147], v[192:193]
	v_pk_fma_f32 v[236:237], v[144:145], v[50:51], v[180:181]
	v_pk_fma_f32 v[238:239], v[144:145], v[52:53], v[192:193]
	global_store_dwordx4 v[150:151], v[236:239], off nt
	v_lshl_add_u64 v[150:151], v[150:151], 0, s[58:59]
	global_load_dwordx4 v[50:53], v[148:149], off nt
	v_lshl_add_u64 v[148:149], v[148:149], 0, s[58:59]
	ds_read_b32 v143, v160 offset:720
	ds_read_b128 v[172:175], v161 offset:5760
	ds_read_b128 v[232:235], v161 offset:5776
	s_waitcnt vmcnt(14)
; #define RS_LOAD(dst, it0) do { _Pragma("unroll") for (int u = 0; u < 8; ++u) dst[u] = __builtin_nontemporal_load((const f32x4*)(S0 + (size_t)(4 * ((it0) + u)) * DV)); } while (0)
; __device__ __forceinline__ void ret_sample_item(Frame& F, int item) {
;     ...
;     for (int it0 = 0; it0 < 64; it0 += 16) {
;         RS_LOAD(sb, it0 + 8);
;         RS_PROC(sa, it0);
;         { const int itn = it0 + 16 < 64 ? it0 + 16 : it0; RS_LOAD(sa, itn); }
;         RS_PROC(sb, it0 + 8);
;     }
	s_waitcnt lgkmcnt(3)
	v_cndmask_b32_e64 v141, 0, v141, s[6:7]
	v_pk_mul_f32 v[180:181], v[26:27], v[114:115] op_sel:[0,1]
	v_pk_mul_f32 v[192:193], v[28:29], v[114:115] op_sel:[0,1]
	v_mfma_f32_16x16x4_f32 v[110:113], v141, v46, v[110:113]
	v_pk_fma_f32 v[180:181], v[30:31], v[114:115], v[180:181] op_sel_hi:[1,0,1]
	v_pk_fma_f32 v[192:193], v[32:33], v[114:115], v[192:193] op_sel_hi:[1,0,1]
	v_pk_fma_f32 v[180:181], v[22:23], v[116:117], v[180:181] op_sel_hi:[1,0,1]
	v_pk_fma_f32 v[192:193], v[24:25], v[116:117], v[192:193] op_sel_hi:[1,0,1]
	v_mfma_f32_16x16x4_f32 v[106:109], v141, v47, v[106:109]
	v_pk_fma_f32 v[180:181], v[18:19], v[116:117], v[180:181] op_sel:[0,1,0]
	v_pk_fma_f32 v[192:193], v[20:21], v[116:117], v[192:193] op_sel:[0,1,0]
	v_pk_fma_f32 v[180:181], v[14:15], v[176:177], v[180:181] op_sel_hi:[1,0,1]
	v_pk_fma_f32 v[192:193], v[16:17], v[176:177], v[192:193] op_sel_hi:[1,0,1]
	v_mfma_f32_16x16x4_f32 v[102:105], v141, v48, v[102:105]
	v_pk_fma_f32 v[180:181], v[10:11], v[176:177], v[180:181] op_sel:[0,1,0]
	v_pk_fma_f32 v[192:193], v[12:13], v[176:177], v[192:193] op_sel:[0,1,0]
	v_pk_fma_f32 v[180:181], v[6:7], v[178:179], v[180:181] op_sel_hi:[1,0,1]
	v_pk_fma_f32 v[192:193], v[8:9], v[178:179], v[192:193] op_sel_hi:[1,0,1]
	v_mfma_f32_16x16x4_f32 v[98:101], v141, v49, v[98:101]
	v_pk_fma_f32 v[180:181], v[2:3], v[178:179], v[180:181] op_sel:[0,1,0]
	v_pk_fma_f32 v[192:193], v[4:5], v[178:179], v[192:193] op_sel:[0,1,0]
	v_pk_mul_f32 v[180:181], v[146:147], v[180:181]
	v_pk_mul_f32 v[192:193], v[146:147], v[192:193]
	v_pk_fma_f32 v[236:237], v[144:145], v[46:47], v[180:181]
	v_pk_fma_f32 v[238:239], v[144:145], v[48:49], v[192:193]
	global_store_dwordx4 v[150:151], v[236:239], off nt
	v_lshl_add_u64 v[150:151], v[150:151], 0, s[58:59]
	global_load_dwordx4 v[46:49], v[148:149], off nt
	v_lshl_add_u64 v[148:149], v[148:149], 0, s[58:59]
	ds_read_b32 v141, v160 offset:736
	ds_read_b128 v[114:117], v161 offset:5888
	ds_read_b128 v[176:179], v161 offset:5904
	s_waitcnt vmcnt(14)
	s_waitcnt lgkmcnt(3)
	v_cndmask_b32_e64 v143, 0, v143, s[6:7]
	v_pk_mul_f32 v[180:181], v[26:27], v[172:173] op_sel:[0,1]
	v_pk_mul_f32 v[192:193], v[28:29], v[172:173] op_sel:[0,1]
	v_mfma_f32_16x16x4_f32 v[110:113], v143, v42, v[110:113]
	v_pk_fma_f32 v[180:181], v[30:31], v[172:173], v[180:181] op_sel_hi:[1,0,1]
	v_pk_fma_f32 v[192:193], v[32:33], v[172:173], v[192:193] op_sel_hi:[1,0,1]
	v_pk_fma_f32 v[180:181], v[22:23], v[174:175], v[180:181] op_sel_hi:[1,0,1]
	v_pk_fma_f32 v[192:193], v[24:25], v[174:175], v[192:193] op_sel_hi:[1,0,1]
	v_mfma_f32_16x16x4_f32 v[106:109], v143, v43, v[106:109]
	v_pk_fma_f32 v[180:181], v[18:19], v[174:175], v[180:181] op_sel:[0,1,0]
	v_pk_fma_f32 v[192:193], v[20:21], v[174:175], v[192:193] op_sel:[0,1,0]
	v_pk_fma_f32 v[180:181], v[14:15], v[232:233], v[180:181] op_sel_hi:[1,0,1]
	v_pk_fma_f32 v[192:193], v[16:17], v[232:233], v[192:193] op_sel_hi:[1,0,1]
	v_mfma_f32_16x16x4_f32 v[102:105], v143, v44, v[102:105]
	v_pk_fma_f32 v[180:181], v[10:11], v[232:233], v[180:181] op_sel:[0,1,0]
	v_pk_fma_f32 v[192:193], v[12:13], v[232:233], v[192:193] op_sel:[0,1,0]
	v_pk_fma_f32 v[180:181], v[6:7], v[234:235], v[180:181] op_sel_hi:[1,0,1]
	v_pk_fma_f32 v[192:193], v[8:9], v[234:235], v[192:193] op_sel_hi:[1,0,1]
	v_mfma_f32_16x16x4_f32 v[98:101], v143, v45, v[98:101]
	v_pk_fma_f32 v[180:181], v[2:3], v[234:235], v[180:181] op_sel:[0,1,0]
	v_pk_fma_f32 v[192:193], v[4:5], v[234:235], v[192:193] op_sel:[0,1,0]
	v_pk_mul_f32 v[180:181], v[146:147], v[180:181]
	v_pk_mul_f32 v[192:193], v[146:147], v[192:193]
	v_pk_fma_f32 v[236:237], v[144:145], v[42:43], v[180:181]
	v_pk_fma_f32 v[238:239], v[144:145], v[44:45], v[192:193]
	global_store_dwordx4 v[150:151], v[236:239], off nt
	v_lshl_add_u64 v[150:151], v[150:151], 0, s[58:59]
	global_load_dwordx4 v[42:45], v[148:149], off nt
	v_lshl_add_u64 v[148:149], v[148:149], 0, s[58:59]
	ds_read_b32 v143, v160 offset:752
	ds_read_b128 v[172:175], v161 offset:6016
	ds_read_b128 v[232:235], v161 offset:6032
	s_waitcnt vmcnt(14)
	s_waitcnt lgkmcnt(3)
	v_cndmask_b32_e64 v141, 0, v141, s[6:7]
	v_pk_mul_f32 v[180:181], v[26:27], v[114:115] op_sel:[0,1]
	v_pk_mul_f32 v[192:193], v[28:29], v[114:115] op_sel:[0,1]
	v_mfma_f32_16x16x4_f32 v[110:113], v141, v38, v[110:113]
	v_pk_fma_f32 v[180:181], v[30:31], v[114:115], v[180:181] op_sel_hi:[1,0,1]
	v_pk_fma_f32 v[192:193], v[32:33], v[114:115], v[192:193] op_sel_hi:[1,0,1]
	v_pk_fma_f32 v[180:181], v[22:23], v[116:117], v[180:181] op_sel_hi:[1,0,1]
	v_pk_fma_f32 v[192:193], v[24:25], v[116:117], v[192:193] op_sel_hi:[1,0,1]
	v_mfma_f32_16x16x4_f32 v[106:109], v141, v39, v[106:109]
	v_pk_fma_f32 v[180:181], v[18:19], v[116:117], v[180:181] op_sel:[0,1,0]
	v_pk_fma_f32 v[192:193], v[20:21], v[116:117], v[192:193] op_sel:[0,1,0]
	v_pk_fma_f32 v[180:181], v[14:15], v[176:177], v[180:181] op_sel_hi:[1,0,1]
	v_pk_fma_f32 v[192:193], v[16:17], v[176:177], v[192:193] op_sel_hi:[1,0,1]
	v_mfma_f32_16x16x4_f32 v[102:105], v141, v40, v[102:105]
	v_pk_fma_f32 v[180:181], v[10:11], v[176:177], v[180:181] op_sel:[0,1,0]
	v_pk_fma_f32 v[192:193], v[12:13], v[176:177], v[192:193] op_sel:[0,1,0]
	v_pk_fma_f32 v[180:181], v[6:7], v[178:179], v[180:181] op_sel_hi:[1,0,1]
	v_pk_fma_f32 v[192:193], v[8:9], v[178:179], v[192:193] op_sel_hi:[1,0,1]
	v_mfma_f32_16x16x4_f32 v[98:101], v141, v41, v[98:101]
	v_pk_fma_f32 v[180:181], v[2:3], v[178:179], v[180:181] op_sel:[0,1,0]
	v_pk_fma_f32 v[192:193], v[4:5], v[178:179], v[192:193] op_sel:[0,1,0]
	v_pk_mul_f32 v[180:181], v[146:147], v[180:181]
	v_pk_mul_f32 v[192:193], v[146:147], v[192:193]
	v_pk_fma_f32 v[236:237], v[144:145], v[38:39], v[180:181]
	v_pk_fma_f32 v[238:239], v[144:145], v[40:41], v[192:193]
	global_store_dwordx4 v[150:151], v[236:239], off nt
	v_lshl_add_u64 v[150:151], v[150:151], 0, s[58:59]
	global_load_dwordx4 v[38:41], v[148:149], off nt
	v_lshl_add_u64 v[148:149], v[148:149], 0, s[58:59]
	ds_read_b32 v141, v160 offset:768
	ds_read_b128 v[114:117], v161 offset:6144
	ds_read_b128 v[176:179], v161 offset:6160
	s_waitcnt vmcnt(14)
; #define RS_LOAD(dst, it0) do { _Pragma("unroll") for (int u = 0; u < 8; ++u) dst[u] = __builtin_nontemporal_load((const f32x4*)(S0 + (size_t)(4 * ((it0) + u)) * DV)); } while (0)
; __device__ __forceinline__ void ret_sample_item(Frame& F, int item) {
;     ...
;     for (int it0 = 0; it0 < 64; it0 += 16) {
;         RS_LOAD(sb, it0 + 8);
;         RS_PROC(sa, it0);
;         { const int itn = it0 + 16 < 64 ? it0 + 16 : it0; RS_LOAD(sa, itn); }
;         RS_PROC(sb, it0 + 8);
;     }
	s_waitcnt lgkmcnt(3)
	v_cndmask_b32_e64 v143, 0, v143, s[6:7]
	v_pk_mul_f32 v[180:181], v[26:27], v[172:173] op_sel:[0,1]
	v_pk_mul_f32 v[192:193], v[28:29], v[172:173] op_sel:[0,1]
	v_mfma_f32_16x16x4_f32 v[110:113], v143, v34, v[110:113]
	v_pk_fma_f32 v[180:181], v[30:31], v[172:173], v[180:181] op_sel_hi:[1,0,1]
	v_pk_fma_f32 v[192:193], v[32:33], v[172:173], v[192:193] op_sel_hi:[1,0,1]
	v_pk_fma_f32 v[180:181], v[22:23], v[174:175], v[180:181] op_sel_hi:[1,0,1]
	v_pk_fma_f32 v[192:193], v[24:25], v[174:175], v[192:193] op_sel_hi:[1,0,1]
	v_mfma_f32_16x16x4_f32 v[106:109], v143, v35, v[106:109]
	v_pk_fma_f32 v[180:181], v[18:19], v[174:175], v[180:181] op_sel:[0,1,0]
	v_pk_fma_f32 v[192:193], v[20:21], v[174:175], v[192:193] op_sel:[0,1,0]
	v_pk_fma_f32 v[180:181], v[14:15], v[232:233], v[180:181] op_sel_hi:[1,0,1]
	v_pk_fma_f32 v[192:193], v[16:17], v[232:233], v[192:193] op_sel_hi:[1,0,1]
	v_mfma_f32_16x16x4_f32 v[102:105], v143, v36, v[102:105]
	v_pk_fma_f32 v[180:181], v[10:11], v[232:233], v[180:181] op_sel:[0,1,0]
	v_pk_fma_f32 v[192:193], v[12:13], v[232:233], v[192:193] op_sel:[0,1,0]
	v_pk_fma_f32 v[180:181], v[6:7], v[234:235], v[180:181] op_sel_hi:[1,0,1]
	v_pk_fma_f32 v[192:193], v[8:9], v[234:235], v[192:193] op_sel_hi:[1,0,1]
	v_mfma_f32_16x16x4_f32 v[98:101], v143, v37, v[98:101]
	v_pk_fma_f32 v[180:181], v[2:3], v[234:235], v[180:181] op_sel:[0,1,0]
	v_pk_fma_f32 v[192:193], v[4:5], v[234:235], v[192:193] op_sel:[0,1,0]
	v_pk_mul_f32 v[180:181], v[146:147], v[180:181]
	v_pk_mul_f32 v[192:193], v[146:147], v[192:193]
	v_pk_fma_f32 v[236:237], v[144:145], v[34:35], v[180:181]
	v_pk_fma_f32 v[238:239], v[144:145], v[36:37], v[192:193]
	global_store_dwordx4 v[150:151], v[236:239], off nt
	v_lshl_add_u64 v[150:151], v[150:151], 0, s[58:59]
	global_load_dwordx4 v[34:37], v[148:149], off nt
	v_lshl_add_u64 v[148:149], v[148:149], 0, s[58:59]
	ds_read_b32 v143, v160 offset:784
	ds_read_b128 v[172:175], v161 offset:6272
	ds_read_b128 v[232:235], v161 offset:6288
	s_waitcnt vmcnt(14)
	s_waitcnt lgkmcnt(3)
	v_cndmask_b32_e64 v141, 0, v141, s[6:7]
	v_pk_mul_f32 v[180:181], v[26:27], v[114:115] op_sel:[0,1]
	v_pk_mul_f32 v[192:193], v[28:29], v[114:115] op_sel:[0,1]
	v_mfma_f32_16x16x4_f32 v[110:113], v141, v70, v[110:113]
	v_pk_fma_f32 v[180:181], v[30:31], v[114:115], v[180:181] op_sel_hi:[1,0,1]
	v_pk_fma_f32 v[192:193], v[32:33], v[114:115], v[192:193] op_sel_hi:[1,0,1]
	v_pk_fma_f32 v[180:181], v[22:23], v[116:117], v[180:181] op_sel_hi:[1,0,1]
	v_pk_fma_f32 v[192:193], v[24:25], v[116:117], v[192:193] op_sel_hi:[1,0,1]
	v_mfma_f32_16x16x4_f32 v[106:109], v141, v71, v[106:109]
	v_pk_fma_f32 v[180:181], v[18:19], v[116:117], v[180:181] op_sel:[0,1,0]
	v_pk_fma_f32 v[192:193], v[20:21], v[116:117], v[192:193] op_sel:[0,1,0]
	v_pk_fma_f32 v[180:181], v[14:15], v[176:177], v[180:181] op_sel_hi:[1,0,1]
	v_pk_fma_f32 v[192:193], v[16:17], v[176:177], v[192:193] op_sel_hi:[1,0,1]
	v_mfma_f32_16x16x4_f32 v[102:105], v141, v72, v[102:105]
	v_pk_fma_f32 v[180:181], v[10:11], v[176:177], v[180:181] op_sel:[0,1,0]
	v_pk_fma_f32 v[192:193], v[12:13], v[176:177], v[192:193] op_sel:[0,1,0]
	v_pk_fma_f32 v[180:181], v[6:7], v[178:179], v[180:181] op_sel_hi:[1,0,1]
	v_pk_fma_f32 v[192:193], v[8:9], v[178:179], v[192:193] op_sel_hi:[1,0,1]
	v_mfma_f32_16x16x4_f32 v[98:101], v141, v73, v[98:101]
	v_pk_fma_f32 v[180:181], v[2:3], v[178:179], v[180:181] op_sel:[0,1,0]
	v_pk_fma_f32 v[192:193], v[4:5], v[178:179], v[192:193] op_sel:[0,1,0]
	v_pk_mul_f32 v[180:181], v[146:147], v[180:181]
	v_pk_mul_f32 v[192:193], v[146:147], v[192:193]
	v_pk_fma_f32 v[236:237], v[144:145], v[70:71], v[180:181]
	v_pk_fma_f32 v[238:239], v[144:145], v[72:73], v[192:193]
	global_store_dwordx4 v[150:151], v[236:239], off nt
	v_lshl_add_u64 v[150:151], v[150:151], 0, s[58:59]
	global_load_dwordx4 v[70:73], v[148:149], off nt
	v_lshl_add_u64 v[148:149], v[148:149], 0, s[58:59]
	ds_read_b32 v141, v160 offset:800
	ds_read_b128 v[114:117], v161 offset:6400
	ds_read_b128 v[176:179], v161 offset:6416
	s_waitcnt vmcnt(14)
	s_waitcnt lgkmcnt(3)
	v_cndmask_b32_e64 v143, 0, v143, s[6:7]
	v_pk_mul_f32 v[180:181], v[26:27], v[172:173] op_sel:[0,1]
	v_pk_mul_f32 v[192:193], v[28:29], v[172:173] op_sel:[0,1]
	v_mfma_f32_16x16x4_f32 v[110:113], v143, v62, v[110:113]
	v_pk_fma_f32 v[180:181], v[30:31], v[172:173], v[180:181] op_sel_hi:[1,0,1]
	v_pk_fma_f32 v[192:193], v[32:33], v[172:173], v[192:193] op_sel_hi:[1,0,1]
	v_pk_fma_f32 v[180:181], v[22:23], v[174:175], v[180:181] op_sel_hi:[1,0,1]
	v_pk_fma_f32 v[192:193], v[24:25], v[174:175], v[192:193] op_sel_hi:[1,0,1]
	v_mfma_f32_16x16x4_f32 v[106:109], v143, v63, v[106:109]
	v_pk_fma_f32 v[180:181], v[18:19], v[174:175], v[180:181] op_sel:[0,1,0]
	v_pk_fma_f32 v[192:193], v[20:21], v[174:175], v[192:193] op_sel:[0,1,0]
	v_pk_fma_f32 v[180:181], v[14:15], v[232:233], v[180:181] op_sel_hi:[1,0,1]
	v_pk_fma_f32 v[192:193], v[16:17], v[232:233], v[192:193] op_sel_hi:[1,0,1]
	v_mfma_f32_16x16x4_f32 v[102:105], v143, v64, v[102:105]
	v_pk_fma_f32 v[180:181], v[10:11], v[232:233], v[180:181] op_sel:[0,1,0]
	v_pk_fma_f32 v[192:193], v[12:13], v[232:233], v[192:193] op_sel:[0,1,0]
	v_pk_fma_f32 v[180:181], v[6:7], v[234:235], v[180:181] op_sel_hi:[1,0,1]
	v_pk_fma_f32 v[192:193], v[8:9], v[234:235], v[192:193] op_sel_hi:[1,0,1]
	v_mfma_f32_16x16x4_f32 v[98:101], v143, v65, v[98:101]
	v_pk_fma_f32 v[180:181], v[2:3], v[234:235], v[180:181] op_sel:[0,1,0]
	v_pk_fma_f32 v[192:193], v[4:5], v[234:235], v[192:193] op_sel:[0,1,0]
	v_pk_mul_f32 v[180:181], v[146:147], v[180:181]
	v_pk_mul_f32 v[192:193], v[146:147], v[192:193]
	v_pk_fma_f32 v[236:237], v[144:145], v[62:63], v[180:181]
	v_pk_fma_f32 v[238:239], v[144:145], v[64:65], v[192:193]
	global_store_dwordx4 v[150:151], v[236:239], off nt
	v_lshl_add_u64 v[150:151], v[150:151], 0, s[58:59]
	global_load_dwordx4 v[62:65], v[148:149], off nt
	v_lshl_add_u64 v[148:149], v[148:149], 0, s[58:59]
	ds_read_b32 v143, v160 offset:816
	ds_read_b128 v[172:175], v161 offset:6528
	ds_read_b128 v[232:235], v161 offset:6544
	s_waitcnt vmcnt(14)
; #define RS_LOAD(dst, it0) do { _Pragma("unroll") for (int u = 0; u < 8; ++u) dst[u] = __builtin_nontemporal_load((const f32x4*)(S0 + (size_t)(4 * ((it0) + u)) * DV)); } while (0)
; __device__ __forceinline__ void ret_sample_item(Frame& F, int item) {
;     ...
;     for (int it0 = 0; it0 < 64; it0 += 16) {
;         RS_LOAD(sb, it0 + 8);
;         RS_PROC(sa, it0);
;         { const int itn = it0 + 16 < 64 ? it0 + 16 : it0; RS_LOAD(sa, itn); }
;         RS_PROC(sb, it0 + 8);
;     }
	s_waitcnt lgkmcnt(3)
	v_cndmask_b32_e64 v141, 0, v141, s[6:7]
	v_pk_mul_f32 v[180:181], v[26:27], v[114:115] op_sel:[0,1]
	v_pk_mul_f32 v[192:193], v[28:29], v[114:115] op_sel:[0,1]
	v_mfma_f32_16x16x4_f32 v[110:113], v141, v54, v[110:113]
	v_pk_fma_f32 v[180:181], v[30:31], v[114:115], v[180:181] op_sel_hi:[1,0,1]
	v_pk_fma_f32 v[192:193], v[32:33], v[114:115], v[192:193] op_sel_hi:[1,0,1]
	v_pk_fma_f32 v[180:181], v[22:23], v[116:117], v[180:181] op_sel_hi:[1,0,1]
	v_pk_fma_f32 v[192:193], v[24:25], v[116:117], v[192:193] op_sel_hi:[1,0,1]
	v_mfma_f32_16x16x4_f32 v[106:109], v141, v55, v[106:109]
	v_pk_fma_f32 v[180:181], v[18:19], v[116:117], v[180:181] op_sel:[0,1,0]
	v_pk_fma_f32 v[192:193], v[20:21], v[116:117], v[192:193] op_sel:[0,1,0]
	v_pk_fma_f32 v[180:181], v[14:15], v[176:177], v[180:181] op_sel_hi:[1,0,1]
	v_pk_fma_f32 v[192:193], v[16:17], v[176:177], v[192:193] op_sel_hi:[1,0,1]
	v_mfma_f32_16x16x4_f32 v[102:105], v141, v56, v[102:105]
	v_pk_fma_f32 v[180:181], v[10:11], v[176:177], v[180:181] op_sel:[0,1,0]
	v_pk_fma_f32 v[192:193], v[12:13], v[176:177], v[192:193] op_sel:[0,1,0]
	v_pk_fma_f32 v[180:181], v[6:7], v[178:179], v[180:181] op_sel_hi:[1,0,1]
	v_pk_fma_f32 v[192:193], v[8:9], v[178:179], v[192:193] op_sel_hi:[1,0,1]
	v_mfma_f32_16x16x4_f32 v[98:101], v141, v57, v[98:101]
	v_pk_fma_f32 v[180:181], v[2:3], v[178:179], v[180:181] op_sel:[0,1,0]
	v_pk_fma_f32 v[192:193], v[4:5], v[178:179], v[192:193] op_sel:[0,1,0]
	v_pk_mul_f32 v[180:181], v[146:147], v[180:181]
	v_pk_mul_f32 v[192:193], v[146:147], v[192:193]
	v_pk_fma_f32 v[236:237], v[144:145], v[54:55], v[180:181]
	v_pk_fma_f32 v[238:239], v[144:145], v[56:57], v[192:193]
	global_store_dwordx4 v[150:151], v[236:239], off nt
	v_lshl_add_u64 v[150:151], v[150:151], 0, s[58:59]
	global_load_dwordx4 v[54:57], v[148:149], off nt
	v_lshl_add_u64 v[148:149], v[148:149], 0, s[58:59]
	ds_read_b32 v141, v160 offset:832
	ds_read_b128 v[114:117], v161 offset:6656
	ds_read_b128 v[176:179], v161 offset:6672
	s_waitcnt vmcnt(14)
	s_waitcnt lgkmcnt(3)
	v_cndmask_b32_e64 v143, 0, v143, s[6:7]
	v_pk_mul_f32 v[180:181], v[26:27], v[172:173] op_sel:[0,1]
	v_pk_mul_f32 v[192:193], v[28:29], v[172:173] op_sel:[0,1]
	v_mfma_f32_16x16x4_f32 v[110:113], v143, v50, v[110:113]
	v_pk_fma_f32 v[180:181], v[30:31], v[172:173], v[180:181] op_sel_hi:[1,0,1]
	v_pk_fma_f32 v[192:193], v[32:33], v[172:173], v[192:193] op_sel_hi:[1,0,1]
	v_pk_fma_f32 v[180:181], v[22:23], v[174:175], v[180:181] op_sel_hi:[1,0,1]
	v_pk_fma_f32 v[192:193], v[24:25], v[174:175], v[192:193] op_sel_hi:[1,0,1]
	v_mfma_f32_16x16x4_f32 v[106:109], v143, v51, v[106:109]
	v_pk_fma_f32 v[180:181], v[18:19], v[174:175], v[180:181] op_sel:[0,1,0]
	v_pk_fma_f32 v[192:193], v[20:21], v[174:175], v[192:193] op_sel:[0,1,0]
	v_pk_fma_f32 v[180:181], v[14:15], v[232:233], v[180:181] op_sel_hi:[1,0,1]
	v_pk_fma_f32 v[192:193], v[16:17], v[232:233], v[192:193] op_sel_hi:[1,0,1]
	v_mfma_f32_16x16x4_f32 v[102:105], v143, v52, v[102:105]
	v_pk_fma_f32 v[180:181], v[10:11], v[232:233], v[180:181] op_sel:[0,1,0]
	v_pk_fma_f32 v[192:193], v[12:13], v[232:233], v[192:193] op_sel:[0,1,0]
	v_pk_fma_f32 v[180:181], v[6:7], v[234:235], v[180:181] op_sel_hi:[1,0,1]
	v_pk_fma_f32 v[192:193], v[8:9], v[234:235], v[192:193] op_sel_hi:[1,0,1]
	v_mfma_f32_16x16x4_f32 v[98:101], v143, v53, v[98:101]
	v_pk_fma_f32 v[180:181], v[2:3], v[234:235], v[180:181] op_sel:[0,1,0]
	v_pk_fma_f32 v[192:193], v[4:5], v[234:235], v[192:193] op_sel:[0,1,0]
	v_pk_mul_f32 v[180:181], v[146:147], v[180:181]
	v_pk_mul_f32 v[192:193], v[146:147], v[192:193]
	v_pk_fma_f32 v[236:237], v[144:145], v[50:51], v[180:181]
	v_pk_fma_f32 v[238:239], v[144:145], v[52:53], v[192:193]
	global_store_dwordx4 v[150:151], v[236:239], off nt
	v_lshl_add_u64 v[150:151], v[150:151], 0, s[58:59]
	global_load_dwordx4 v[50:53], v[148:149], off nt
	v_lshl_add_u64 v[148:149], v[148:149], 0, s[58:59]
	ds_read_b32 v143, v160 offset:848
	ds_read_b128 v[172:175], v161 offset:6784
	ds_read_b128 v[232:235], v161 offset:6800
	s_waitcnt vmcnt(14)
	s_waitcnt lgkmcnt(3)
	v_cndmask_b32_e64 v141, 0, v141, s[6:7]
	v_pk_mul_f32 v[180:181], v[26:27], v[114:115] op_sel:[0,1]
	v_pk_mul_f32 v[192:193], v[28:29], v[114:115] op_sel:[0,1]
	v_mfma_f32_16x16x4_f32 v[110:113], v141, v46, v[110:113]
	v_pk_fma_f32 v[180:181], v[30:31], v[114:115], v[180:181] op_sel_hi:[1,0,1]
	v_pk_fma_f32 v[192:193], v[32:33], v[114:115], v[192:193] op_sel_hi:[1,0,1]
	v_pk_fma_f32 v[180:181], v[22:23], v[116:117], v[180:181] op_sel_hi:[1,0,1]
	v_pk_fma_f32 v[192:193], v[24:25], v[116:117], v[192:193] op_sel_hi:[1,0,1]
	v_mfma_f32_16x16x4_f32 v[106:109], v141, v47, v[106:109]
	v_pk_fma_f32 v[180:181], v[18:19], v[116:117], v[180:181] op_sel:[0,1,0]
	v_pk_fma_f32 v[192:193], v[20:21], v[116:117], v[192:193] op_sel:[0,1,0]
	v_pk_fma_f32 v[180:181], v[14:15], v[176:177], v[180:181] op_sel_hi:[1,0,1]
	v_pk_fma_f32 v[192:193], v[16:17], v[176:177], v[192:193] op_sel_hi:[1,0,1]
	v_mfma_f32_16x16x4_f32 v[102:105], v141, v48, v[102:105]
	v_pk_fma_f32 v[180:181], v[10:11], v[176:177], v[180:181] op_sel:[0,1,0]
	v_pk_fma_f32 v[192:193], v[12:13], v[176:177], v[192:193] op_sel:[0,1,0]
	v_pk_fma_f32 v[180:181], v[6:7], v[178:179], v[180:181] op_sel_hi:[1,0,1]
	v_pk_fma_f32 v[192:193], v[8:9], v[178:179], v[192:193] op_sel_hi:[1,0,1]
	v_mfma_f32_16x16x4_f32 v[98:101], v141, v49, v[98:101]
	v_pk_fma_f32 v[180:181], v[2:3], v[178:179], v[180:181] op_sel:[0,1,0]
	v_pk_fma_f32 v[192:193], v[4:5], v[178:179], v[192:193] op_sel:[0,1,0]
	v_pk_mul_f32 v[180:181], v[146:147], v[180:181]
	v_pk_mul_f32 v[192:193], v[146:147], v[192:193]
	v_pk_fma_f32 v[236:237], v[144:145], v[46:47], v[180:181]
	v_pk_fma_f32 v[238:239], v[144:145], v[48:49], v[192:193]
	global_store_dwordx4 v[150:151], v[236:239], off nt
	v_lshl_add_u64 v[150:151], v[150:151], 0, s[58:59]
	global_load_dwordx4 v[46:49], v[148:149], off nt
	v_lshl_add_u64 v[148:149], v[148:149], 0, s[58:59]
	ds_read_b32 v141, v160 offset:864
	ds_read_b128 v[114:117], v161 offset:6912
	ds_read_b128 v[176:179], v161 offset:6928
	s_waitcnt vmcnt(14)
; #define RS_LOAD(dst, it0) do { _Pragma("unroll") for (int u = 0; u < 8; ++u) dst[u] = __builtin_nontemporal_load((const f32x4*)(S0 + (size_t)(4 * ((it0) + u)) * DV)); } while (0)
; __device__ __forceinline__ void ret_sample_item(Frame& F, int item) {
;     ...
;     for (int it0 = 0; it0 < 64; it0 += 16) {
;         RS_LOAD(sb, it0 + 8);
;         RS_PROC(sa, it0);
;         { const int itn = it0 + 16 < 64 ? it0 + 16 : it0; RS_LOAD(sa, itn); }
;         RS_PROC(sb, it0 + 8);
;     }
	s_waitcnt lgkmcnt(3)
	v_cndmask_b32_e64 v143, 0, v143, s[6:7]
	v_pk_mul_f32 v[180:181], v[26:27], v[172:173] op_sel:[0,1]
	v_pk_mul_f32 v[192:193], v[28:29], v[172:173] op_sel:[0,1]
	v_mfma_f32_16x16x4_f32 v[110:113], v143, v42, v[110:113]
	v_pk_fma_f32 v[180:181], v[30:31], v[172:173], v[180:181] op_sel_hi:[1,0,1]
	v_pk_fma_f32 v[192:193], v[32:33], v[172:173], v[192:193] op_sel_hi:[1,0,1]
	v_pk_fma_f32 v[180:181], v[22:23], v[174:175], v[180:181] op_sel_hi:[1,0,1]
	v_pk_fma_f32 v[192:193], v[24:25], v[174:175], v[192:193] op_sel_hi:[1,0,1]
	v_mfma_f32_16x16x4_f32 v[106:109], v143, v43, v[106:109]
	v_pk_fma_f32 v[180:181], v[18:19], v[174:175], v[180:181] op_sel:[0,1,0]
	v_pk_fma_f32 v[192:193], v[20:21], v[174:175], v[192:193] op_sel:[0,1,0]
	v_pk_fma_f32 v[180:181], v[14:15], v[232:233], v[180:181] op_sel_hi:[1,0,1]
	v_pk_fma_f32 v[192:193], v[16:17], v[232:233], v[192:193] op_sel_hi:[1,0,1]
	v_mfma_f32_16x16x4_f32 v[102:105], v143, v44, v[102:105]
	v_pk_fma_f32 v[180:181], v[10:11], v[232:233], v[180:181] op_sel:[0,1,0]
	v_pk_fma_f32 v[192:193], v[12:13], v[232:233], v[192:193] op_sel:[0,1,0]
	v_pk_fma_f32 v[180:181], v[6:7], v[234:235], v[180:181] op_sel_hi:[1,0,1]
	v_pk_fma_f32 v[192:193], v[8:9], v[234:235], v[192:193] op_sel_hi:[1,0,1]
	v_mfma_f32_16x16x4_f32 v[98:101], v143, v45, v[98:101]
	v_pk_fma_f32 v[180:181], v[2:3], v[234:235], v[180:181] op_sel:[0,1,0]
	v_pk_fma_f32 v[192:193], v[4:5], v[234:235], v[192:193] op_sel:[0,1,0]
	v_pk_mul_f32 v[180:181], v[146:147], v[180:181]
	v_pk_mul_f32 v[192:193], v[146:147], v[192:193]
	v_pk_fma_f32 v[236:237], v[144:145], v[42:43], v[180:181]
	v_pk_fma_f32 v[238:239], v[144:145], v[44:45], v[192:193]
	global_store_dwordx4 v[150:151], v[236:239], off nt
	v_lshl_add_u64 v[150:151], v[150:151], 0, s[58:59]
	global_load_dwordx4 v[42:45], v[148:149], off nt
	v_lshl_add_u64 v[148:149], v[148:149], 0, s[58:59]
	ds_read_b32 v143, v160 offset:880
	ds_read_b128 v[172:175], v161 offset:7040
	ds_read_b128 v[232:235], v161 offset:7056
	s_waitcnt vmcnt(14)
	s_waitcnt lgkmcnt(3)
	v_cndmask_b32_e64 v141, 0, v141, s[6:7]
	v_pk_mul_f32 v[180:181], v[26:27], v[114:115] op_sel:[0,1]
	v_pk_mul_f32 v[192:193], v[28:29], v[114:115] op_sel:[0,1]
	v_mfma_f32_16x16x4_f32 v[110:113], v141, v38, v[110:113]
	v_pk_fma_f32 v[180:181], v[30:31], v[114:115], v[180:181] op_sel_hi:[1,0,1]
	v_pk_fma_f32 v[192:193], v[32:33], v[114:115], v[192:193] op_sel_hi:[1,0,1]
	v_pk_fma_f32 v[180:181], v[22:23], v[116:117], v[180:181] op_sel_hi:[1,0,1]
	v_pk_fma_f32 v[192:193], v[24:25], v[116:117], v[192:193] op_sel_hi:[1,0,1]
	v_mfma_f32_16x16x4_f32 v[106:109], v141, v39, v[106:109]
	v_pk_fma_f32 v[180:181], v[18:19], v[116:117], v[180:181] op_sel:[0,1,0]
	v_pk_fma_f32 v[192:193], v[20:21], v[116:117], v[192:193] op_sel:[0,1,0]
	v_pk_fma_f32 v[180:181], v[14:15], v[176:177], v[180:181] op_sel_hi:[1,0,1]
	v_pk_fma_f32 v[192:193], v[16:17], v[176:177], v[192:193] op_sel_hi:[1,0,1]
	v_mfma_f32_16x16x4_f32 v[102:105], v141, v40, v[102:105]
	v_pk_fma_f32 v[180:181], v[10:11], v[176:177], v[180:181] op_sel:[0,1,0]
	v_pk_fma_f32 v[192:193], v[12:13], v[176:177], v[192:193] op_sel:[0,1,0]
	v_pk_fma_f32 v[180:181], v[6:7], v[178:179], v[180:181] op_sel_hi:[1,0,1]
	v_pk_fma_f32 v[192:193], v[8:9], v[178:179], v[192:193] op_sel_hi:[1,0,1]
	v_mfma_f32_16x16x4_f32 v[98:101], v141, v41, v[98:101]
	v_pk_fma_f32 v[180:181], v[2:3], v[178:179], v[180:181] op_sel:[0,1,0]
	v_pk_fma_f32 v[192:193], v[4:5], v[178:179], v[192:193] op_sel:[0,1,0]
	v_pk_mul_f32 v[180:181], v[146:147], v[180:181]
	v_pk_mul_f32 v[192:193], v[146:147], v[192:193]
	v_pk_fma_f32 v[236:237], v[144:145], v[38:39], v[180:181]
	v_pk_fma_f32 v[238:239], v[144:145], v[40:41], v[192:193]
	global_store_dwordx4 v[150:151], v[236:239], off nt
	v_lshl_add_u64 v[150:151], v[150:151], 0, s[58:59]
	global_load_dwordx4 v[38:41], v[148:149], off nt
	v_lshl_add_u64 v[148:149], v[148:149], 0, s[58:59]
	ds_read_b32 v141, v160 offset:896
	ds_read_b128 v[114:117], v161 offset:7168
	ds_read_b128 v[176:179], v161 offset:7184
	s_waitcnt vmcnt(14)
	s_waitcnt lgkmcnt(3)
	v_cndmask_b32_e64 v143, 0, v143, s[6:7]
	v_pk_mul_f32 v[180:181], v[26:27], v[172:173] op_sel:[0,1]
	v_pk_mul_f32 v[192:193], v[28:29], v[172:173] op_sel:[0,1]
	v_mfma_f32_16x16x4_f32 v[110:113], v143, v34, v[110:113]
	v_pk_fma_f32 v[180:181], v[30:31], v[172:173], v[180:181] op_sel_hi:[1,0,1]
	v_pk_fma_f32 v[192:193], v[32:33], v[172:173], v[192:193] op_sel_hi:[1,0,1]
	v_pk_fma_f32 v[180:181], v[22:23], v[174:175], v[180:181] op_sel_hi:[1,0,1]
	v_pk_fma_f32 v[192:193], v[24:25], v[174:175], v[192:193] op_sel_hi:[1,0,1]
	v_mfma_f32_16x16x4_f32 v[106:109], v143, v35, v[106:109]
	v_pk_fma_f32 v[180:181], v[18:19], v[174:175], v[180:181] op_sel:[0,1,0]
	v_pk_fma_f32 v[192:193], v[20:21], v[174:175], v[192:193] op_sel:[0,1,0]
	v_pk_fma_f32 v[180:181], v[14:15], v[232:233], v[180:181] op_sel_hi:[1,0,1]
	v_pk_fma_f32 v[192:193], v[16:17], v[232:233], v[192:193] op_sel_hi:[1,0,1]
	v_mfma_f32_16x16x4_f32 v[102:105], v143, v36, v[102:105]
	v_pk_fma_f32 v[180:181], v[10:11], v[232:233], v[180:181] op_sel:[0,1,0]
	v_pk_fma_f32 v[192:193], v[12:13], v[232:233], v[192:193] op_sel:[0,1,0]
	v_pk_fma_f32 v[180:181], v[6:7], v[234:235], v[180:181] op_sel_hi:[1,0,1]
	v_pk_fma_f32 v[192:193], v[8:9], v[234:235], v[192:193] op_sel_hi:[1,0,1]
	v_mfma_f32_16x16x4_f32 v[98:101], v143, v37, v[98:101]
	v_pk_fma_f32 v[180:181], v[2:3], v[234:235], v[180:181] op_sel:[0,1,0]
	v_pk_fma_f32 v[192:193], v[4:5], v[234:235], v[192:193] op_sel:[0,1,0]
	v_pk_mul_f32 v[180:181], v[146:147], v[180:181]
	v_pk_mul_f32 v[192:193], v[146:147], v[192:193]
	v_pk_fma_f32 v[236:237], v[144:145], v[34:35], v[180:181]
	v_pk_fma_f32 v[238:239], v[144:145], v[36:37], v[192:193]
	global_store_dwordx4 v[150:151], v[236:239], off nt
	v_lshl_add_u64 v[150:151], v[150:151], 0, s[58:59]
	global_load_dwordx4 v[34:37], v[148:149], off nt
	v_lshl_add_u64 v[148:149], v[148:149], 0, s[58:59]
	ds_read_b32 v143, v160 offset:912
	ds_read_b128 v[172:175], v161 offset:7296
	ds_read_b128 v[232:235], v161 offset:7312
	s_waitcnt vmcnt(14)
; #define RS_LOAD(dst, it0) do { _Pragma("unroll") for (int u = 0; u < 8; ++u) dst[u] = __builtin_nontemporal_load((const f32x4*)(S0 + (size_t)(4 * ((it0) + u)) * DV)); } while (0)
; __device__ __forceinline__ void ret_sample_item(Frame& F, int item) {
;     ...
;     for (int it0 = 0; it0 < 64; it0 += 16) {
;         RS_LOAD(sb, it0 + 8);
;         RS_PROC(sa, it0);
;         { const int itn = it0 + 16 < 64 ? it0 + 16 : it0; RS_LOAD(sa, itn); }
;         RS_PROC(sb, it0 + 8);
;     }
	s_waitcnt lgkmcnt(3)
	v_cndmask_b32_e64 v141, 0, v141, s[6:7]
	v_pk_mul_f32 v[180:181], v[26:27], v[114:115] op_sel:[0,1]
	v_pk_mul_f32 v[192:193], v[28:29], v[114:115] op_sel:[0,1]
	v_mfma_f32_16x16x4_f32 v[110:113], v141, v70, v[110:113]
	v_pk_fma_f32 v[180:181], v[30:31], v[114:115], v[180:181] op_sel_hi:[1,0,1]
	v_pk_fma_f32 v[192:193], v[32:33], v[114:115], v[192:193] op_sel_hi:[1,0,1]
	v_pk_fma_f32 v[180:181], v[22:23], v[116:117], v[180:181] op_sel_hi:[1,0,1]
	v_pk_fma_f32 v[192:193], v[24:25], v[116:117], v[192:193] op_sel_hi:[1,0,1]
	v_mfma_f32_16x16x4_f32 v[106:109], v141, v71, v[106:109]
	v_pk_fma_f32 v[180:181], v[18:19], v[116:117], v[180:181] op_sel:[0,1,0]
	v_pk_fma_f32 v[192:193], v[20:21], v[116:117], v[192:193] op_sel:[0,1,0]
	v_pk_fma_f32 v[180:181], v[14:15], v[176:177], v[180:181] op_sel_hi:[1,0,1]
	v_pk_fma_f32 v[192:193], v[16:17], v[176:177], v[192:193] op_sel_hi:[1,0,1]
	v_mfma_f32_16x16x4_f32 v[102:105], v141, v72, v[102:105]
	v_pk_fma_f32 v[180:181], v[10:11], v[176:177], v[180:181] op_sel:[0,1,0]
	v_pk_fma_f32 v[192:193], v[12:13], v[176:177], v[192:193] op_sel:[0,1,0]
	v_pk_fma_f32 v[180:181], v[6:7], v[178:179], v[180:181] op_sel_hi:[1,0,1]
	v_pk_fma_f32 v[192:193], v[8:9], v[178:179], v[192:193] op_sel_hi:[1,0,1]
	v_mfma_f32_16x16x4_f32 v[98:101], v141, v73, v[98:101]
	v_pk_fma_f32 v[180:181], v[2:3], v[178:179], v[180:181] op_sel:[0,1,0]
	v_pk_fma_f32 v[192:193], v[4:5], v[178:179], v[192:193] op_sel:[0,1,0]
	v_pk_mul_f32 v[180:181], v[146:147], v[180:181]
	v_pk_mul_f32 v[192:193], v[146:147], v[192:193]
	v_pk_fma_f32 v[236:237], v[144:145], v[70:71], v[180:181]
	v_pk_fma_f32 v[238:239], v[144:145], v[72:73], v[192:193]
	global_store_dwordx4 v[150:151], v[236:239], off nt
	v_lshl_add_u64 v[150:151], v[150:151], 0, s[58:59]
	ds_read_b32 v141, v160 offset:928
	ds_read_b128 v[114:117], v161 offset:7424
	ds_read_b128 v[176:179], v161 offset:7440
	s_waitcnt vmcnt(13)
	s_waitcnt lgkmcnt(3)
	v_cndmask_b32_e64 v143, 0, v143, s[6:7]
	v_pk_mul_f32 v[180:181], v[26:27], v[172:173] op_sel:[0,1]
	v_pk_mul_f32 v[192:193], v[28:29], v[172:173] op_sel:[0,1]
	v_mfma_f32_16x16x4_f32 v[110:113], v143, v62, v[110:113]
	v_pk_fma_f32 v[180:181], v[30:31], v[172:173], v[180:181] op_sel_hi:[1,0,1]
	v_pk_fma_f32 v[192:193], v[32:33], v[172:173], v[192:193] op_sel_hi:[1,0,1]
	v_pk_fma_f32 v[180:181], v[22:23], v[174:175], v[180:181] op_sel_hi:[1,0,1]
	v_pk_fma_f32 v[192:193], v[24:25], v[174:175], v[192:193] op_sel_hi:[1,0,1]
	v_mfma_f32_16x16x4_f32 v[106:109], v143, v63, v[106:109]
	v_pk_fma_f32 v[180:181], v[18:19], v[174:175], v[180:181] op_sel:[0,1,0]
	v_pk_fma_f32 v[192:193], v[20:21], v[174:175], v[192:193] op_sel:[0,1,0]
	v_pk_fma_f32 v[180:181], v[14:15], v[232:233], v[180:181] op_sel_hi:[1,0,1]
	v_pk_fma_f32 v[192:193], v[16:17], v[232:233], v[192:193] op_sel_hi:[1,0,1]
	v_mfma_f32_16x16x4_f32 v[102:105], v143, v64, v[102:105]
	v_pk_fma_f32 v[180:181], v[10:11], v[232:233], v[180:181] op_sel:[0,1,0]
	v_pk_fma_f32 v[192:193], v[12:13], v[232:233], v[192:193] op_sel:[0,1,0]
	v_pk_fma_f32 v[180:181], v[6:7], v[234:235], v[180:181] op_sel_hi:[1,0,1]
	v_pk_fma_f32 v[192:193], v[8:9], v[234:235], v[192:193] op_sel_hi:[1,0,1]
	v_mfma_f32_16x16x4_f32 v[98:101], v143, v65, v[98:101]
	v_pk_fma_f32 v[180:181], v[2:3], v[234:235], v[180:181] op_sel:[0,1,0]
	v_pk_fma_f32 v[192:193], v[4:5], v[234:235], v[192:193] op_sel:[0,1,0]
	v_pk_mul_f32 v[180:181], v[146:147], v[180:181]
	v_pk_mul_f32 v[192:193], v[146:147], v[192:193]
	v_pk_fma_f32 v[236:237], v[144:145], v[62:63], v[180:181]
	v_pk_fma_f32 v[238:239], v[144:145], v[64:65], v[192:193]
	global_store_dwordx4 v[150:151], v[236:239], off nt
	v_lshl_add_u64 v[150:151], v[150:151], 0, s[58:59]
	ds_read_b32 v143, v160 offset:944
	ds_read_b128 v[172:175], v161 offset:7552
	ds_read_b128 v[232:235], v161 offset:7568
	s_waitcnt vmcnt(12)
	s_waitcnt lgkmcnt(3)
	v_cndmask_b32_e64 v141, 0, v141, s[6:7]
	v_pk_mul_f32 v[180:181], v[26:27], v[114:115] op_sel:[0,1]
	v_pk_mul_f32 v[192:193], v[28:29], v[114:115] op_sel:[0,1]
	v_mfma_f32_16x16x4_f32 v[110:113], v141, v54, v[110:113]
	v_pk_fma_f32 v[180:181], v[30:31], v[114:115], v[180:181] op_sel_hi:[1,0,1]
	v_pk_fma_f32 v[192:193], v[32:33], v[114:115], v[192:193] op_sel_hi:[1,0,1]
	v_pk_fma_f32 v[180:181], v[22:23], v[116:117], v[180:181] op_sel_hi:[1,0,1]
	v_pk_fma_f32 v[192:193], v[24:25], v[116:117], v[192:193] op_sel_hi:[1,0,1]
	v_mfma_f32_16x16x4_f32 v[106:109], v141, v55, v[106:109]
	v_pk_fma_f32 v[180:181], v[18:19], v[116:117], v[180:181] op_sel:[0,1,0]
	v_pk_fma_f32 v[192:193], v[20:21], v[116:117], v[192:193] op_sel:[0,1,0]
	v_pk_fma_f32 v[180:181], v[14:15], v[176:177], v[180:181] op_sel_hi:[1,0,1]
	v_pk_fma_f32 v[192:193], v[16:17], v[176:177], v[192:193] op_sel_hi:[1,0,1]
	v_mfma_f32_16x16x4_f32 v[102:105], v141, v56, v[102:105]
	v_pk_fma_f32 v[180:181], v[10:11], v[176:177], v[180:181] op_sel:[0,1,0]
	v_pk_fma_f32 v[192:193], v[12:13], v[176:177], v[192:193] op_sel:[0,1,0]
	v_pk_fma_f32 v[180:181], v[6:7], v[178:179], v[180:181] op_sel_hi:[1,0,1]
	v_pk_fma_f32 v[192:193], v[8:9], v[178:179], v[192:193] op_sel_hi:[1,0,1]
	v_mfma_f32_16x16x4_f32 v[98:101], v141, v57, v[98:101]
	v_pk_fma_f32 v[180:181], v[2:3], v[178:179], v[180:181] op_sel:[0,1,0]
	v_pk_fma_f32 v[192:193], v[4:5], v[178:179], v[192:193] op_sel:[0,1,0]
	v_pk_mul_f32 v[180:181], v[146:147], v[180:181]
	v_pk_mul_f32 v[192:193], v[146:147], v[192:193]
	v_pk_fma_f32 v[236:237], v[144:145], v[54:55], v[180:181]
	v_pk_fma_f32 v[238:239], v[144:145], v[56:57], v[192:193]
	global_store_dwordx4 v[150:151], v[236:239], off nt
	v_lshl_add_u64 v[150:151], v[150:151], 0, s[58:59]
	ds_read_b32 v141, v160 offset:960
	ds_read_b128 v[114:117], v161 offset:7680
	ds_read_b128 v[176:179], v161 offset:7696
	s_waitcnt vmcnt(11)
; #define RS_LOAD(dst, it0) do { _Pragma("unroll") for (int u = 0; u < 8; ++u) dst[u] = __builtin_nontemporal_load((const f32x4*)(S0 + (size_t)(4 * ((it0) + u)) * DV)); } while (0)
; __device__ __forceinline__ void ret_sample_item(Frame& F, int item) {
;     ...
;     for (int it0 = 0; it0 < 64; it0 += 16) {
;         RS_LOAD(sb, it0 + 8);
;         RS_PROC(sa, it0);
;         { const int itn = it0 + 16 < 64 ? it0 + 16 : it0; RS_LOAD(sa, itn); }
;         RS_PROC(sb, it0 + 8);
;     }
	s_waitcnt lgkmcnt(3)
	v_cndmask_b32_e64 v143, 0, v143, s[6:7]
	v_pk_mul_f32 v[180:181], v[26:27], v[172:173] op_sel:[0,1]
	v_pk_mul_f32 v[192:193], v[28:29], v[172:173] op_sel:[0,1]
	v_mfma_f32_16x16x4_f32 v[110:113], v143, v50, v[110:113]
	v_pk_fma_f32 v[180:181], v[30:31], v[172:173], v[180:181] op_sel_hi:[1,0,1]
	v_pk_fma_f32 v[192:193], v[32:33], v[172:173], v[192:193] op_sel_hi:[1,0,1]
	v_pk_fma_f32 v[180:181], v[22:23], v[174:175], v[180:181] op_sel_hi:[1,0,1]
	v_pk_fma_f32 v[192:193], v[24:25], v[174:175], v[192:193] op_sel_hi:[1,0,1]
	v_mfma_f32_16x16x4_f32 v[106:109], v143, v51, v[106:109]
	v_pk_fma_f32 v[180:181], v[18:19], v[174:175], v[180:181] op_sel:[0,1,0]
	v_pk_fma_f32 v[192:193], v[20:21], v[174:175], v[192:193] op_sel:[0,1,0]
	v_pk_fma_f32 v[180:181], v[14:15], v[232:233], v[180:181] op_sel_hi:[1,0,1]
	v_pk_fma_f32 v[192:193], v[16:17], v[232:233], v[192:193] op_sel_hi:[1,0,1]
	v_mfma_f32_16x16x4_f32 v[102:105], v143, v52, v[102:105]
	v_pk_fma_f32 v[180:181], v[10:11], v[232:233], v[180:181] op_sel:[0,1,0]
	v_pk_fma_f32 v[192:193], v[12:13], v[232:233], v[192:193] op_sel:[0,1,0]
	v_pk_fma_f32 v[180:181], v[6:7], v[234:235], v[180:181] op_sel_hi:[1,0,1]
	v_pk_fma_f32 v[192:193], v[8:9], v[234:235], v[192:193] op_sel_hi:[1,0,1]
	v_mfma_f32_16x16x4_f32 v[98:101], v143, v53, v[98:101]
	v_pk_fma_f32 v[180:181], v[2:3], v[234:235], v[180:181] op_sel:[0,1,0]
	v_pk_fma_f32 v[192:193], v[4:5], v[234:235], v[192:193] op_sel:[0,1,0]
	v_pk_mul_f32 v[180:181], v[146:147], v[180:181]
	v_pk_mul_f32 v[192:193], v[146:147], v[192:193]
	v_pk_fma_f32 v[236:237], v[144:145], v[50:51], v[180:181]
	v_pk_fma_f32 v[238:239], v[144:145], v[52:53], v[192:193]
	global_store_dwordx4 v[150:151], v[236:239], off nt
	v_lshl_add_u64 v[150:151], v[150:151], 0, s[58:59]
	ds_read_b32 v143, v160 offset:976
	ds_read_b128 v[172:175], v161 offset:7808
	ds_read_b128 v[232:235], v161 offset:7824
	s_waitcnt vmcnt(10)
	s_waitcnt lgkmcnt(3)
	v_cndmask_b32_e64 v141, 0, v141, s[6:7]
	v_pk_mul_f32 v[180:181], v[26:27], v[114:115] op_sel:[0,1]
	v_pk_mul_f32 v[192:193], v[28:29], v[114:115] op_sel:[0,1]
	v_mfma_f32_16x16x4_f32 v[110:113], v141, v46, v[110:113]
	v_pk_fma_f32 v[180:181], v[30:31], v[114:115], v[180:181] op_sel_hi:[1,0,1]
	v_pk_fma_f32 v[192:193], v[32:33], v[114:115], v[192:193] op_sel_hi:[1,0,1]
	v_pk_fma_f32 v[180:181], v[22:23], v[116:117], v[180:181] op_sel_hi:[1,0,1]
	v_pk_fma_f32 v[192:193], v[24:25], v[116:117], v[192:193] op_sel_hi:[1,0,1]
	v_mfma_f32_16x16x4_f32 v[106:109], v141, v47, v[106:109]
	v_pk_fma_f32 v[180:181], v[18:19], v[116:117], v[180:181] op_sel:[0,1,0]
	v_pk_fma_f32 v[192:193], v[20:21], v[116:117], v[192:193] op_sel:[0,1,0]
	v_pk_fma_f32 v[180:181], v[14:15], v[176:177], v[180:181] op_sel_hi:[1,0,1]
	v_pk_fma_f32 v[192:193], v[16:17], v[176:177], v[192:193] op_sel_hi:[1,0,1]
	v_mfma_f32_16x16x4_f32 v[102:105], v141, v48, v[102:105]
	v_pk_fma_f32 v[180:181], v[10:11], v[176:177], v[180:181] op_sel:[0,1,0]
	v_pk_fma_f32 v[192:193], v[12:13], v[176:177], v[192:193] op_sel:[0,1,0]
	v_pk_fma_f32 v[180:181], v[6:7], v[178:179], v[180:181] op_sel_hi:[1,0,1]
	v_pk_fma_f32 v[192:193], v[8:9], v[178:179], v[192:193] op_sel_hi:[1,0,1]
	v_mfma_f32_16x16x4_f32 v[98:101], v141, v49, v[98:101]
	v_pk_fma_f32 v[180:181], v[2:3], v[178:179], v[180:181] op_sel:[0,1,0]
	v_pk_fma_f32 v[192:193], v[4:5], v[178:179], v[192:193] op_sel:[0,1,0]
	v_pk_mul_f32 v[180:181], v[146:147], v[180:181]
	v_pk_mul_f32 v[192:193], v[146:147], v[192:193]
	v_pk_fma_f32 v[236:237], v[144:145], v[46:47], v[180:181]
	v_pk_fma_f32 v[238:239], v[144:145], v[48:49], v[192:193]
	global_store_dwordx4 v[150:151], v[236:239], off nt
	v_lshl_add_u64 v[150:151], v[150:151], 0, s[58:59]
	ds_read_b32 v141, v160 offset:992
	ds_read_b128 v[114:117], v161 offset:7936
	ds_read_b128 v[176:179], v161 offset:7952
	s_waitcnt vmcnt(9)
	s_waitcnt lgkmcnt(3)
; #define RS_LOAD(dst, it0) do { _Pragma("unroll") for (int u = 0; u < 8; ++u) dst[u] = __builtin_nontemporal_load((const f32x4*)(S0 + (size_t)(4 * ((it0) + u)) * DV)); } while (0)
; __device__ __forceinline__ void ret_sample_item(Frame& F, int item) {
;     ...
;     for (int it0 = 0; it0 < 64; it0 += 16) {
;         RS_LOAD(sb, it0 + 8);
;         RS_PROC(sa, it0);
;         { const int itn = it0 + 16 < 64 ? it0 + 16 : it0; RS_LOAD(sa, itn); }
;         RS_PROC(sb, it0 + 8);
;     }
	v_cndmask_b32_e64 v143, 0, v143, s[6:7]
	v_pk_mul_f32 v[180:181], v[26:27], v[172:173] op_sel:[0,1]
	v_pk_mul_f32 v[192:193], v[28:29], v[172:173] op_sel:[0,1]
	v_mfma_f32_16x16x4_f32 v[110:113], v143, v42, v[110:113]
	v_pk_fma_f32 v[180:181], v[30:31], v[172:173], v[180:181] op_sel_hi:[1,0,1]
	v_pk_fma_f32 v[192:193], v[32:33], v[172:173], v[192:193] op_sel_hi:[1,0,1]
	v_pk_fma_f32 v[180:181], v[22:23], v[174:175], v[180:181] op_sel_hi:[1,0,1]
	v_pk_fma_f32 v[192:193], v[24:25], v[174:175], v[192:193] op_sel_hi:[1,0,1]
	v_mfma_f32_16x16x4_f32 v[106:109], v143, v43, v[106:109]
	v_pk_fma_f32 v[180:181], v[18:19], v[174:175], v[180:181] op_sel:[0,1,0]
	v_pk_fma_f32 v[192:193], v[20:21], v[174:175], v[192:193] op_sel:[0,1,0]
	v_pk_fma_f32 v[180:181], v[14:15], v[232:233], v[180:181] op_sel_hi:[1,0,1]
	v_pk_fma_f32 v[192:193], v[16:17], v[232:233], v[192:193] op_sel_hi:[1,0,1]
	v_mfma_f32_16x16x4_f32 v[102:105], v143, v44, v[102:105]
	v_pk_fma_f32 v[180:181], v[10:11], v[232:233], v[180:181] op_sel:[0,1,0]
	v_pk_fma_f32 v[192:193], v[12:13], v[232:233], v[192:193] op_sel:[0,1,0]
	v_pk_fma_f32 v[180:181], v[6:7], v[234:235], v[180:181] op_sel_hi:[1,0,1]
	v_pk_fma_f32 v[192:193], v[8:9], v[234:235], v[192:193] op_sel_hi:[1,0,1]
	v_mfma_f32_16x16x4_f32 v[98:101], v143, v45, v[98:101]
	v_pk_fma_f32 v[180:181], v[2:3], v[234:235], v[180:181] op_sel:[0,1,0]
	v_pk_fma_f32 v[192:193], v[4:5], v[234:235], v[192:193] op_sel:[0,1,0]
	v_pk_mul_f32 v[180:181], v[146:147], v[180:181]
	v_pk_mul_f32 v[192:193], v[146:147], v[192:193]
	v_pk_fma_f32 v[236:237], v[144:145], v[42:43], v[180:181]
	v_pk_fma_f32 v[238:239], v[144:145], v[44:45], v[192:193]
	global_store_dwordx4 v[150:151], v[236:239], off nt
	v_lshl_add_u64 v[150:151], v[150:151], 0, s[58:59]
	ds_read_b32 v143, v160 offset:1008
	ds_read_b128 v[172:175], v161 offset:8064
	ds_read_b128 v[232:235], v161 offset:8080
	s_waitcnt vmcnt(8)
	s_waitcnt lgkmcnt(3)
	v_cndmask_b32_e64 v141, 0, v141, s[6:7]
	v_pk_mul_f32 v[180:181], v[26:27], v[114:115] op_sel:[0,1]
	v_pk_mul_f32 v[192:193], v[28:29], v[114:115] op_sel:[0,1]
	v_mfma_f32_16x16x4_f32 v[110:113], v141, v38, v[110:113]
	v_pk_fma_f32 v[180:181], v[30:31], v[114:115], v[180:181] op_sel_hi:[1,0,1]
	v_pk_fma_f32 v[192:193], v[32:33], v[114:115], v[192:193] op_sel_hi:[1,0,1]
	v_pk_fma_f32 v[180:181], v[22:23], v[116:117], v[180:181] op_sel_hi:[1,0,1]
	v_pk_fma_f32 v[192:193], v[24:25], v[116:117], v[192:193] op_sel_hi:[1,0,1]
	v_mfma_f32_16x16x4_f32 v[106:109], v141, v39, v[106:109]
	v_pk_fma_f32 v[180:181], v[18:19], v[116:117], v[180:181] op_sel:[0,1,0]
	v_pk_fma_f32 v[192:193], v[20:21], v[116:117], v[192:193] op_sel:[0,1,0]
	v_pk_fma_f32 v[180:181], v[14:15], v[176:177], v[180:181] op_sel_hi:[1,0,1]
	v_pk_fma_f32 v[192:193], v[16:17], v[176:177], v[192:193] op_sel_hi:[1,0,1]
	v_mfma_f32_16x16x4_f32 v[102:105], v141, v40, v[102:105]
	v_pk_fma_f32 v[180:181], v[10:11], v[176:177], v[180:181] op_sel:[0,1,0]
	v_pk_fma_f32 v[192:193], v[12:13], v[176:177], v[192:193] op_sel:[0,1,0]
	v_pk_fma_f32 v[180:181], v[6:7], v[178:179], v[180:181] op_sel_hi:[1,0,1]
	v_pk_fma_f32 v[192:193], v[8:9], v[178:179], v[192:193] op_sel_hi:[1,0,1]
	v_mfma_f32_16x16x4_f32 v[98:101], v141, v41, v[98:101]
	v_pk_fma_f32 v[180:181], v[2:3], v[178:179], v[180:181] op_sel:[0,1,0]
	v_pk_fma_f32 v[192:193], v[4:5], v[178:179], v[192:193] op_sel:[0,1,0]
	v_pk_mul_f32 v[180:181], v[146:147], v[180:181]
	v_pk_mul_f32 v[192:193], v[146:147], v[192:193]
	v_pk_fma_f32 v[236:237], v[144:145], v[38:39], v[180:181]
	v_pk_fma_f32 v[238:239], v[144:145], v[40:41], v[192:193]
	global_store_dwordx4 v[150:151], v[236:239], off nt
	v_lshl_add_u64 v[150:151], v[150:151], 0, s[58:59]
	s_waitcnt vmcnt(7)
	s_waitcnt lgkmcnt(0)
	v_cndmask_b32_e64 v143, 0, v143, s[6:7]
	v_pk_mul_f32 v[180:181], v[26:27], v[172:173] op_sel:[0,1]
	v_pk_mul_f32 v[192:193], v[28:29], v[172:173] op_sel:[0,1]
	v_mfma_f32_16x16x4_f32 v[110:113], v143, v34, v[110:113]
	v_pk_fma_f32 v[180:181], v[30:31], v[172:173], v[180:181] op_sel_hi:[1,0,1]
	v_pk_fma_f32 v[192:193], v[32:33], v[172:173], v[192:193] op_sel_hi:[1,0,1]
	v_pk_fma_f32 v[180:181], v[22:23], v[174:175], v[180:181] op_sel_hi:[1,0,1]
	v_pk_fma_f32 v[192:193], v[24:25], v[174:175], v[192:193] op_sel_hi:[1,0,1]
	v_mfma_f32_16x16x4_f32 v[106:109], v143, v35, v[106:109]
	v_pk_fma_f32 v[180:181], v[18:19], v[174:175], v[180:181] op_sel:[0,1,0]
	v_pk_fma_f32 v[192:193], v[20:21], v[174:175], v[192:193] op_sel:[0,1,0]
	v_pk_fma_f32 v[180:181], v[14:15], v[232:233], v[180:181] op_sel_hi:[1,0,1]
	v_pk_fma_f32 v[192:193], v[16:17], v[232:233], v[192:193] op_sel_hi:[1,0,1]
	v_mfma_f32_16x16x4_f32 v[102:105], v143, v36, v[102:105]
	v_pk_fma_f32 v[180:181], v[10:11], v[232:233], v[180:181] op_sel:[0,1,0]
	v_pk_fma_f32 v[192:193], v[12:13], v[232:233], v[192:193] op_sel:[0,1,0]
	v_pk_fma_f32 v[180:181], v[6:7], v[234:235], v[180:181] op_sel_hi:[1,0,1]
	v_pk_fma_f32 v[192:193], v[8:9], v[234:235], v[192:193] op_sel_hi:[1,0,1]
	v_mfma_f32_16x16x4_f32 v[98:101], v143, v37, v[98:101]
	v_pk_fma_f32 v[180:181], v[2:3], v[234:235], v[180:181] op_sel:[0,1,0]
	v_pk_fma_f32 v[192:193], v[4:5], v[234:235], v[192:193] op_sel:[0,1,0]
	v_pk_mul_f32 v[180:181], v[146:147], v[180:181]
	v_pk_mul_f32 v[192:193], v[146:147], v[192:193]
	v_pk_fma_f32 v[236:237], v[144:145], v[34:35], v[180:181]
	v_pk_fma_f32 v[238:239], v[144:145], v[36:37], v[192:193]
	global_store_dwordx4 v[150:151], v[236:239], off nt
	v_lshl_add_u64 v[150:151], v[150:151], 0, s[58:59]
	s_nop 7
	s_nop 3
	s_branch .LBB0_677
	s_nop 0
	s_nop 0
	s_nop 0
	s_nop 0
	s_nop 0
	s_nop 0
